# peel + only the barrier-adjacent prio edits (mid-segment setprio flips kept, unlike v31)
# baseline (speedup 1.0000x reference)
; #define PG8_STAGE(bufoff, gbase, voff) do { _Pragma("unroll") for (int _i = 0; _i < 2; ++_i) \
;         __builtin_amdgcn_global_load_lds((const unsigned*)((const char*)(gbase) + (voff)[_i]), (PG8_LAS unsigned*)(lds + (bufoff) + ldsw + _i * 8192), 16, 0, 0); } while (0)
; #define PG8_LDA(dst, b, h) do { _Pragma("unroll") for (int m = 0; m < 4; ++m) _Pragma("unroll") for (int k = 0; k < 2; ++k) dst[m][k] = *(const PG8_LAS bf16x8*)(lds + PG8_SA(b, h) + aoff + m * 2048 + k * 1024); } while (0)
; #define PG8_LDB(dst, b, h) do { _Pragma("unroll") for (int n = 0; n < 2; ++n) _Pragma("unroll") for (int k = 0; k < 2; ++k) dst[n][k] = *(const PG8_LAS bf16x8*)(lds + PG8_SB(b, h) + boff + n * 2048 + k * 1024); } while (0)
; #define PG8_WAIT_V(n) asm volatile("s_waitcnt vmcnt(" #n ")" ::: "memory")
; #define PG8_WAIT_L(n) asm volatile("s_waitcnt lgkmcnt(" #n ")" ::: "memory")
; template <class Epi, class Sched, bool ALIGN_EPI = false, bool SP2 = false>
; __device__ __forceinline__ void gemm_phase(PG8_LAS unsigned char* lds, const Gemm g, const Sched& S, const Epi& E) {
;     ...
;         const bool has_next = S.next(ui + 1, nxt);
;         const char* nA = has_next ? (const char*)g.A + (size_t)nxt.pm * tstep : cA; const char* nB = has_next ? (const char*)g.Bt + (size_t)nxt.pn * tstep : cB;
;         for (int t = 0; t < nt; t += 2) {
;             const bool last = (t == nt - 2);
;             if constexpr (Epi::PREFETCH) { if (t == nt - 4) E.prefetch(cur, lds + STAGE_BYTES + 1024, tid); }
;             const char* a1 = cA + (size_t)(t + 1) * kstep;
;             const char* a2 = last ? nA : cA + (size_t)(t + 2) * kstep; const char* b2 = last ? nB : cB + (size_t)(t + 2) * kstep;
;             const char* a3 = a2 + kstep; const char* b3 = b2 + kstep;
;             if (last && has_next) S.a_ready(nxt);
;             if constexpr (SP2) {
;             PG8_LDB(B0, 0, 0); PG8_LDB(B1, 0, 1); PG8_SCHED; PG8_LDA(At, 0, 0); PG8_STAGE(PG8_SA(1, 1), a1 + hstep, voffA);
;             PG8_WAIT_V(8); PG8_WAIT_L(0); PG8_BAR; PG8_MMA(0, 0, At, B0); PG8_MMA(0, 1, At, B1); PG8_BAR; PG8_SCHED;
;             PG8_LDA(At, 0, 1); PG8_STAGE(PG8_SB(0, 0), b2, voffB); PG8_STAGE(PG8_SB(0, 1), b2 + hstep, voffB); PG8_STAGE(PG8_SA(0, 0), a2, voffA);
;             PG8_WAIT_V(8); PG8_WAIT_L(0); PG8_BAR; PG8_MMA(1, 0, At, B0); PG8_MMA(1, 1, At, B1); PG8_BAR; PG8_SCHED;
.LBB0_231:
	s_ashr_i32 s21, s20, 31
	s_lshl_b64 s[22:23], s[20:21], 19
	s_add_u32 s22, s44, s22
	s_addc_u32 s23, s45, s23
	s_and_b64 s[34:35], s[4:5], exec
	s_cselect_b32 s21, s23, s39
	s_cselect_b32 s64, s22, s38
	s_ashr_i32 s19, s18, 31
	s_lshl_b64 s[34:35], s[18:19], 19
	s_add_u32 s34, s46, s34
	s_addc_u32 s35, s47, s35
	s_and_b64 s[42:43], s[4:5], exec
	s_cselect_b32 s19, s35, s41
	s_cselect_b32 s65, s34, s40
	s_add_u32 s38, s38, 0x40080
	s_addc_u32 s39, s39, 0
	s_add_u32 s66, s40, 0x100
	s_addc_u32 s67, s41, 0
	s_mov_b32 s68, -2
	ds_read_b128 v[154:157], v149
	ds_read_b128 v[158:161], v149 offset:1024
	ds_read_b128 v[162:165], v149 offset:2048
	ds_read_b128 v[166:169], v149 offset:3072
	ds_read_b128 v[170:173], v150
	ds_read_b128 v[174:177], v150 offset:1024
	ds_read_b128 v[178:181], v150 offset:2048
	ds_read_b128 v[182:185], v150 offset:3072
	s_add_u32 s40, s38, 0xfffc0080
	s_addc_u32 s41, s39, -1
	s_cmp_eq_u32 s68, 12
	s_cselect_b32 s43, s21, s41
	s_cselect_b32 s42, s64, s40
	s_cselect_b32 s41, s19, s67
	s_cselect_b32 s40, s65, s66
	v_lshl_add_u64 v[144:145], s[38:39], 0, v[136:137]
	s_add_i32 m0, s37, 0xc000
	ds_read_b128 v[186:189], v151
	ds_read_b128 v[190:193], v151 offset:1024
	ds_read_b128 v[194:197], v151 offset:2048
	ds_read_b128 v[198:201], v151 offset:3072
	ds_read_b128 v[202:205], v151 offset:4096
	ds_read_b128 v[206:209], v151 offset:5120
	ds_read_b128 v[210:213], v151 offset:6144
	ds_read_b128 v[214:217], v151 offset:7168
	global_load_lds_dwordx4 v[144:145], off
	v_lshl_add_u64 v[144:145], s[38:39], 0, v[138:139]
	s_add_i32 m0, s37, 0xe000
	s_nop 0
	global_load_lds_dwordx4 v[144:145], off
	s_waitcnt vmcnt(8)
	s_waitcnt lgkmcnt(0)
	s_barrier
	s_setprio 1
	v_mfma_f32_16x16x32_bf16 v[120:123], v[154:157], v[186:189], 0
	v_mfma_f32_16x16x32_bf16 v[116:119], v[162:165], v[186:189], 0
	v_mfma_f32_16x16x32_bf16 v[108:111], v[154:157], v[194:197], 0
	v_mfma_f32_16x16x32_bf16 v[100:103], v[162:165], v[194:197], 0
	v_mfma_f32_16x16x32_bf16 v[92:95], v[154:157], v[202:205], 0
	v_mfma_f32_16x16x32_bf16 v[84:87], v[162:165], v[202:205], 0
	v_mfma_f32_16x16x32_bf16 v[76:79], v[154:157], v[210:213], 0
	v_mfma_f32_16x16x32_bf16 v[68:71], v[162:165], v[210:213], 0
	v_mfma_f32_16x16x32_bf16 v[120:123], v[158:161], v[190:193], v[120:123]
	v_mfma_f32_16x16x32_bf16 v[116:119], v[166:169], v[190:193], v[116:119]
	v_mfma_f32_16x16x32_bf16 v[108:111], v[158:161], v[198:201], v[108:111]
	v_mfma_f32_16x16x32_bf16 v[100:103], v[166:169], v[198:201], v[100:103]
	v_mfma_f32_16x16x32_bf16 v[92:95], v[158:161], v[206:209], v[92:95]
	v_mfma_f32_16x16x32_bf16 v[84:87], v[166:169], v[206:209], v[84:87]
	v_mfma_f32_16x16x32_bf16 v[76:79], v[158:161], v[214:217], v[76:79]
	v_mfma_f32_16x16x32_bf16 v[68:71], v[166:169], v[214:217], v[68:71]
	s_setprio 0
	s_setprio 1
	v_mfma_f32_16x16x32_bf16 v[124:127], v[170:173], v[186:189], 0
	v_mfma_f32_16x16x32_bf16 v[112:115], v[178:181], v[186:189], 0
	v_mfma_f32_16x16x32_bf16 v[104:107], v[170:173], v[194:197], 0
	v_mfma_f32_16x16x32_bf16 v[96:99], v[178:181], v[194:197], 0
	v_mfma_f32_16x16x32_bf16 v[88:91], v[170:173], v[202:205], 0
	v_mfma_f32_16x16x32_bf16 v[80:83], v[178:181], v[202:205], 0
	v_mfma_f32_16x16x32_bf16 v[72:75], v[170:173], v[210:213], 0
	v_mfma_f32_16x16x32_bf16 v[64:67], v[178:181], v[210:213], 0
	v_mfma_f32_16x16x32_bf16 v[124:127], v[174:177], v[190:193], v[124:127]
	v_mfma_f32_16x16x32_bf16 v[112:115], v[182:185], v[190:193], v[112:115]
	v_mfma_f32_16x16x32_bf16 v[104:107], v[174:177], v[198:201], v[104:107]
	v_mfma_f32_16x16x32_bf16 v[96:99], v[182:185], v[198:201], v[96:99]
	v_mfma_f32_16x16x32_bf16 v[88:91], v[174:177], v[206:209], v[88:91]
	v_mfma_f32_16x16x32_bf16 v[80:83], v[182:185], v[206:209], v[80:83]
	v_mfma_f32_16x16x32_bf16 v[72:75], v[174:177], v[214:217], v[72:75]
	v_mfma_f32_16x16x32_bf16 v[64:67], v[182:185], v[214:217], v[64:67]
	s_barrier
	s_setprio 0
	s_add_i32 s69, s57, s48
	v_lshl_add_u64 v[144:145], s[40:41], 0, v[132:133]
	s_mov_b32 m0, s69
	ds_read_b128 v[186:189], v151 offset:16384
	ds_read_b128 v[190:193], v151 offset:17408
	ds_read_b128 v[194:197], v151 offset:18432
	ds_read_b128 v[198:201], v151 offset:19456
	ds_read_b128 v[202:205], v151 offset:20480
	ds_read_b128 v[206:209], v151 offset:21504
	ds_read_b128 v[210:213], v151 offset:22528
	ds_read_b128 v[214:217], v151 offset:23552
	global_load_lds_dwordx4 v[144:145], off
	s_add_i32 m0, s69, 0x2000
	s_add_u32 s70, s40, 0x40000
	v_lshl_add_u64 v[218:219], s[40:41], 0, v[128:129]
	s_addc_u32 s71, s41, 0
	s_add_i32 s69, s58, s48
	global_load_lds_dwordx4 v[218:219], off
	v_lshl_add_u64 v[220:221], s[70:71], 0, v[132:133]
	s_mov_b32 m0, s69
	v_lshl_add_u64 v[222:223], s[42:43], 0, v[130:131]
	global_load_lds_dwordx4 v[220:221], off
	v_lshl_add_u64 v[220:221], s[70:71], 0, v[128:129]
	s_add_i32 m0, s69, 0x2000
	s_nop 0
	global_load_lds_dwordx4 v[220:221], off
	v_lshl_add_u64 v[220:221], s[42:43], 0, v[134:135]
	s_mov_b32 m0, s37
	s_nop 0
	global_load_lds_dwordx4 v[220:221], off
	s_mov_b32 m0, s50
	s_nop 0
	global_load_lds_dwordx4 v[222:223], off
	s_waitcnt vmcnt(8)
	s_waitcnt lgkmcnt(0)
	s_barrier
; #define PG8_STAGE(bufoff, gbase, voff) do { _Pragma("unroll") for (int _i = 0; _i < 2; ++_i) \
;         __builtin_amdgcn_global_load_lds((const unsigned*)((const char*)(gbase) + (voff)[_i]), (PG8_LAS unsigned*)(lds + (bufoff) + ldsw + _i * 8192), 16, 0, 0); } while (0)
; #define PG8_LDA(dst, b, h) do { _Pragma("unroll") for (int m = 0; m < 4; ++m) _Pragma("unroll") for (int k = 0; k < 2; ++k) dst[m][k] = *(const PG8_LAS bf16x8*)(lds + PG8_SA(b, h) + aoff + m * 2048 + k * 1024); } while (0)
; #define PG8_LDB(dst, b, h) do { _Pragma("unroll") for (int n = 0; n < 2; ++n) _Pragma("unroll") for (int k = 0; k < 2; ++k) dst[n][k] = *(const PG8_LAS bf16x8*)(lds + PG8_SB(b, h) + boff + n * 2048 + k * 1024); } while (0)
; #define PG8_MMA(ai, bj, At, Bt) do { __builtin_amdgcn_s_setprio(1); _Pragma("unroll") for (int m = 0; m < 4; ++m) _Pragma("unroll") for (int n = 0; n < 2; ++n) _Pragma("unroll") for (int k = 0; k < 2; ++k) \
;         acc[ai][bj][m][n] = __builtin_amdgcn_mfma_f32_16x16x32_bf16(Bt[n][k], At[m][k], acc[ai][bj][m][n], 0, 0, 0); __builtin_amdgcn_s_setprio(0); } while (0)
; #define PG8_WAIT_V(n) asm volatile("s_waitcnt vmcnt(" #n ")" ::: "memory")
; #define PG8_WAIT_L(n) asm volatile("s_waitcnt lgkmcnt(" #n ")" ::: "memory")
; #define PG8_BAR __builtin_amdgcn_s_barrier()
; #define PG8_SCHED __builtin_amdgcn_sched_barrier(0)
; template <class Epi, class Sched, bool ALIGN_EPI = false, bool SP2 = false>
; __device__ __forceinline__ void gemm_phase(PG8_LAS unsigned char* lds, const Gemm g, const Sched& S, const Epi& E) {
;     ...
;             PG8_WAIT_V(8); PG8_WAIT_L(0); PG8_BAR; PG8_MMA(1, 0, At, B0); PG8_MMA(1, 1, At, B1); PG8_BAR; PG8_SCHED;
;             PG8_LDB(B0, 1, 0); PG8_LDB(B1, 1, 1); PG8_SCHED; PG8_LDA(At, 1, 0); PG8_STAGE(PG8_SA(0, 1), a2 + hstep, voffA);
;             PG8_WAIT_V(8); PG8_WAIT_L(0); PG8_BAR; PG8_MMA(0, 0, At, B0); PG8_MMA(0, 1, At, B1); PG8_BAR; PG8_SCHED;
	s_setprio 1
	v_mfma_f32_16x16x32_bf16 v[60:63], v[154:157], v[186:189], 0
	v_mfma_f32_16x16x32_bf16 v[52:55], v[162:165], v[186:189], 0
	v_mfma_f32_16x16x32_bf16 v[44:47], v[154:157], v[194:197], 0
	v_mfma_f32_16x16x32_bf16 v[36:39], v[162:165], v[194:197], 0
	v_mfma_f32_16x16x32_bf16 v[28:31], v[154:157], v[202:205], 0
	v_mfma_f32_16x16x32_bf16 v[20:23], v[162:165], v[202:205], 0
	v_mfma_f32_16x16x32_bf16 v[12:15], v[154:157], v[210:213], 0
	v_mfma_f32_16x16x32_bf16 v[4:7], v[162:165], v[210:213], 0
	v_mfma_f32_16x16x32_bf16 v[60:63], v[158:161], v[190:193], v[60:63]
	v_mfma_f32_16x16x32_bf16 v[52:55], v[166:169], v[190:193], v[52:55]
	v_mfma_f32_16x16x32_bf16 v[44:47], v[158:161], v[198:201], v[44:47]
	v_mfma_f32_16x16x32_bf16 v[36:39], v[166:169], v[198:201], v[36:39]
	v_mfma_f32_16x16x32_bf16 v[28:31], v[158:161], v[206:209], v[28:31]
	v_mfma_f32_16x16x32_bf16 v[20:23], v[166:169], v[206:209], v[20:23]
	v_mfma_f32_16x16x32_bf16 v[12:15], v[158:161], v[214:217], v[12:15]
	v_mfma_f32_16x16x32_bf16 v[4:7], v[166:169], v[214:217], v[4:7]
	s_setprio 0
	s_setprio 1
	v_mfma_f32_16x16x32_bf16 v[56:59], v[170:173], v[186:189], 0
	v_mfma_f32_16x16x32_bf16 v[48:51], v[178:181], v[186:189], 0
	v_mfma_f32_16x16x32_bf16 v[40:43], v[170:173], v[194:197], 0
	v_mfma_f32_16x16x32_bf16 v[32:35], v[178:181], v[194:197], 0
	v_mfma_f32_16x16x32_bf16 v[24:27], v[170:173], v[202:205], 0
	v_mfma_f32_16x16x32_bf16 v[16:19], v[178:181], v[202:205], 0
	v_mfma_f32_16x16x32_bf16 v[8:11], v[170:173], v[210:213], 0
	v_mfma_f32_16x16x32_bf16 v[0:3], v[178:181], v[210:213], 0
	v_mfma_f32_16x16x32_bf16 v[56:59], v[174:177], v[190:193], v[56:59]
	v_mfma_f32_16x16x32_bf16 v[48:51], v[182:185], v[190:193], v[48:51]
	v_mfma_f32_16x16x32_bf16 v[40:43], v[174:177], v[198:201], v[40:43]
	v_mfma_f32_16x16x32_bf16 v[32:35], v[182:185], v[198:201], v[32:35]
	v_mfma_f32_16x16x32_bf16 v[24:27], v[174:177], v[206:209], v[24:27]
	v_mfma_f32_16x16x32_bf16 v[16:19], v[182:185], v[206:209], v[16:19]
	v_mfma_f32_16x16x32_bf16 v[8:11], v[174:177], v[214:217], v[8:11]
	v_mfma_f32_16x16x32_bf16 v[0:3], v[182:185], v[214:217], v[0:3]
	s_barrier
	s_setprio 0
	s_add_i32 s69, 0, 0x18000
	v_add_u32_e32 v153, s69, v147
	s_add_i32 s70, 0, 0x1c000
	ds_read_b128 v[154:157], v153
	ds_read_b128 v[158:161], v153 offset:1024
	ds_read_b128 v[162:165], v153 offset:2048
	ds_read_b128 v[166:169], v153 offset:3072
	v_add_u32_e32 v153, s70, v147
	ds_read_b128 v[170:173], v153
	ds_read_b128 v[174:177], v153 offset:1024
	ds_read_b128 v[178:181], v153 offset:2048
	ds_read_b128 v[182:185], v153 offset:3072
	s_add_u32 s42, s42, 0x40000
	s_addc_u32 s43, s43, 0
	s_mov_b32 m0, s51
	v_lshl_add_u64 v[224:225], s[42:43], 0, v[134:135]
	ds_read_b128 v[186:189], v151 offset:32768
	ds_read_b128 v[190:193], v151 offset:33792
	ds_read_b128 v[194:197], v151 offset:34816
	ds_read_b128 v[198:201], v151 offset:35840
	ds_read_b128 v[202:205], v151 offset:36864
	ds_read_b128 v[206:209], v151 offset:37888
	ds_read_b128 v[210:213], v151 offset:38912
	ds_read_b128 v[214:217], v151 offset:39936
	global_load_lds_dwordx4 v[224:225], off
	v_lshl_add_u64 v[224:225], s[42:43], 0, v[130:131]
	s_mov_b32 m0, s52
	s_nop 0
	global_load_lds_dwordx4 v[224:225], off
	s_waitcnt vmcnt(8)
	s_waitcnt lgkmcnt(0)
	s_barrier
	s_setprio 1
	v_mfma_f32_16x16x32_bf16 v[120:123], v[154:157], v[186:189], v[120:123]
	v_mfma_f32_16x16x32_bf16 v[116:119], v[162:165], v[186:189], v[116:119]
	v_mfma_f32_16x16x32_bf16 v[108:111], v[154:157], v[194:197], v[108:111]
	v_mfma_f32_16x16x32_bf16 v[100:103], v[162:165], v[194:197], v[100:103]
	v_mfma_f32_16x16x32_bf16 v[92:95], v[154:157], v[202:205], v[92:95]
	v_mfma_f32_16x16x32_bf16 v[84:87], v[162:165], v[202:205], v[84:87]
	v_mfma_f32_16x16x32_bf16 v[76:79], v[154:157], v[210:213], v[76:79]
	v_mfma_f32_16x16x32_bf16 v[68:71], v[162:165], v[210:213], v[68:71]
	v_mfma_f32_16x16x32_bf16 v[120:123], v[158:161], v[190:193], v[120:123]
	v_mfma_f32_16x16x32_bf16 v[116:119], v[166:169], v[190:193], v[116:119]
	v_mfma_f32_16x16x32_bf16 v[108:111], v[158:161], v[198:201], v[108:111]
	v_mfma_f32_16x16x32_bf16 v[100:103], v[166:169], v[198:201], v[100:103]
	v_mfma_f32_16x16x32_bf16 v[92:95], v[158:161], v[206:209], v[92:95]
	v_mfma_f32_16x16x32_bf16 v[84:87], v[166:169], v[206:209], v[84:87]
	v_mfma_f32_16x16x32_bf16 v[76:79], v[158:161], v[214:217], v[76:79]
	v_mfma_f32_16x16x32_bf16 v[68:71], v[166:169], v[214:217], v[68:71]
	s_setprio 0
	s_setprio 1
	v_mfma_f32_16x16x32_bf16 v[124:127], v[170:173], v[186:189], v[124:127]
	v_mfma_f32_16x16x32_bf16 v[112:115], v[178:181], v[186:189], v[112:115]
	v_mfma_f32_16x16x32_bf16 v[104:107], v[170:173], v[194:197], v[104:107]
	v_mfma_f32_16x16x32_bf16 v[96:99], v[178:181], v[194:197], v[96:99]
	v_mfma_f32_16x16x32_bf16 v[88:91], v[170:173], v[202:205], v[88:91]
	v_mfma_f32_16x16x32_bf16 v[80:83], v[178:181], v[202:205], v[80:83]
	v_mfma_f32_16x16x32_bf16 v[72:75], v[170:173], v[210:213], v[72:75]
	v_mfma_f32_16x16x32_bf16 v[64:67], v[178:181], v[210:213], v[64:67]
	v_mfma_f32_16x16x32_bf16 v[124:127], v[174:177], v[190:193], v[124:127]
	v_mfma_f32_16x16x32_bf16 v[112:115], v[182:185], v[190:193], v[112:115]
	v_mfma_f32_16x16x32_bf16 v[104:107], v[174:177], v[198:201], v[104:107]
	v_mfma_f32_16x16x32_bf16 v[96:99], v[182:185], v[198:201], v[96:99]
	v_mfma_f32_16x16x32_bf16 v[88:91], v[174:177], v[206:209], v[88:91]
	v_mfma_f32_16x16x32_bf16 v[80:83], v[182:185], v[206:209], v[80:83]
	v_mfma_f32_16x16x32_bf16 v[72:75], v[174:177], v[214:217], v[72:75]
	v_mfma_f32_16x16x32_bf16 v[64:67], v[182:185], v[214:217], v[64:67]
	s_barrier
; #define PG8_STAGE(bufoff, gbase, voff) do { _Pragma("unroll") for (int _i = 0; _i < 2; ++_i) \
;         __builtin_amdgcn_global_load_lds((const unsigned*)((const char*)(gbase) + (voff)[_i]), (PG8_LAS unsigned*)(lds + (bufoff) + ldsw + _i * 8192), 16, 0, 0); } while (0)
; #define PG8_LDA(dst, b, h) do { _Pragma("unroll") for (int m = 0; m < 4; ++m) _Pragma("unroll") for (int k = 0; k < 2; ++k) dst[m][k] = *(const PG8_LAS bf16x8*)(lds + PG8_SA(b, h) + aoff + m * 2048 + k * 1024); } while (0)
; #define PG8_LDB(dst, b, h) do { _Pragma("unroll") for (int n = 0; n < 2; ++n) _Pragma("unroll") for (int k = 0; k < 2; ++k) dst[n][k] = *(const PG8_LAS bf16x8*)(lds + PG8_SB(b, h) + boff + n * 2048 + k * 1024); } while (0)
; #define PG8_MMA(ai, bj, At, Bt) do { __builtin_amdgcn_s_setprio(1); _Pragma("unroll") for (int m = 0; m < 4; ++m) _Pragma("unroll") for (int n = 0; n < 2; ++n) _Pragma("unroll") for (int k = 0; k < 2; ++k) \
;         acc[ai][bj][m][n] = __builtin_amdgcn_mfma_f32_16x16x32_bf16(Bt[n][k], At[m][k], acc[ai][bj][m][n], 0, 0, 0); __builtin_amdgcn_s_setprio(0); } while (0)
; #define PG8_WAIT_V(n) asm volatile("s_waitcnt vmcnt(" #n ")" ::: "memory")
; template <class Epi, class Sched, bool ALIGN_EPI = false, bool SP2 = false>
; __device__ __forceinline__ void gemm_phase(PG8_LAS unsigned char* lds, const Gemm g, const Sched& S, const Epi& E) {
;     ...
;             PG8_LDB(B0, 0, 0); PG8_LDB(B1, 0, 1); PG8_SCHED; PG8_LDA(At, 0, 0); PG8_STAGE(PG8_SA(1, 1), a1 + hstep, voffA);
;             PG8_WAIT_V(8); PG8_WAIT_L(0); PG8_BAR; PG8_MMA(0, 0, At, B0); PG8_MMA(0, 1, At, B1); PG8_BAR; PG8_SCHED;
;             PG8_LDA(At, 0, 1); PG8_STAGE(PG8_SB(0, 0), b2, voffB); PG8_STAGE(PG8_SB(0, 1), b2 + hstep, voffB); PG8_STAGE(PG8_SA(0, 0), a2, voffA);
;             PG8_WAIT_V(8); PG8_WAIT_L(0); PG8_BAR; PG8_MMA(1, 0, At, B0); PG8_MMA(1, 1, At, B1); PG8_BAR; PG8_SCHED;
;             PG8_LDB(B0, 1, 0); PG8_LDB(B1, 1, 1); PG8_SCHED; PG8_LDA(At, 1, 0); PG8_STAGE(PG8_SA(0, 1), a2 + hstep, voffA);
;             PG8_WAIT_V(8); PG8_WAIT_L(0); PG8_BAR; PG8_MMA(0, 0, At, B0); PG8_MMA(0, 1, At, B1); PG8_BAR; PG8_SCHED;
;             PG8_LDA(At, 1, 1); PG8_STAGE(PG8_SB(1, 0), b3, voffB); PG8_STAGE(PG8_SB(1, 1), b3 + hstep, voffB); PG8_STAGE(PG8_SA(1, 0), a3, voffA);
;             PG8_WAIT_V(8); PG8_WAIT_L(0); PG8_BAR; PG8_MMA(1, 0, At, B0); PG8_MMA(1, 1, At, B1); PG8_BAR; PG8_SCHED;
	s_setprio 0
	s_add_i32 s42, s69, s48
	v_lshl_add_u64 v[144:145], v[144:145], 0, s[14:15]
	s_mov_b32 m0, s42
	ds_read_b128 v[186:189], v151 offset:49152
	ds_read_b128 v[190:193], v151 offset:50176
	ds_read_b128 v[194:197], v151 offset:51200
	ds_read_b128 v[198:201], v151 offset:52224
	ds_read_b128 v[202:205], v151 offset:53248
	ds_read_b128 v[206:209], v151 offset:54272
	ds_read_b128 v[210:213], v151 offset:55296
	ds_read_b128 v[214:217], v151 offset:56320
	global_load_lds_dwordx4 v[144:145], off
	s_add_i32 m0, s42, 0x2000
	s_add_u32 s40, s40, 0x40080
	v_lshl_add_u64 v[144:145], v[218:219], 0, s[14:15]
	s_addc_u32 s41, s41, 0
	s_add_i32 s42, s70, s48
	global_load_lds_dwordx4 v[144:145], off
	v_lshl_add_u64 v[144:145], s[40:41], 0, v[132:133]
	s_mov_b32 m0, s42
	s_nop 0
	global_load_lds_dwordx4 v[144:145], off
	v_lshl_add_u64 v[144:145], s[40:41], 0, v[128:129]
	s_add_i32 m0, s42, 0x2000
	s_nop 0
	global_load_lds_dwordx4 v[144:145], off
	v_lshl_add_u64 v[144:145], v[220:221], 0, s[14:15]
	s_mov_b32 m0, s54
	s_nop 0
	global_load_lds_dwordx4 v[144:145], off
	v_lshl_add_u64 v[144:145], v[222:223], 0, s[14:15]
	s_mov_b32 m0, s55
	s_nop 0
	global_load_lds_dwordx4 v[144:145], off
	s_waitcnt vmcnt(8)
	s_waitcnt lgkmcnt(0)
	s_barrier
	s_setprio 1
	v_mfma_f32_16x16x32_bf16 v[60:63], v[154:157], v[186:189], v[60:63]
	v_mfma_f32_16x16x32_bf16 v[52:55], v[162:165], v[186:189], v[52:55]
	v_mfma_f32_16x16x32_bf16 v[44:47], v[154:157], v[194:197], v[44:47]
	v_mfma_f32_16x16x32_bf16 v[36:39], v[162:165], v[194:197], v[36:39]
	v_mfma_f32_16x16x32_bf16 v[28:31], v[154:157], v[202:205], v[28:31]
	v_mfma_f32_16x16x32_bf16 v[20:23], v[162:165], v[202:205], v[20:23]
	v_mfma_f32_16x16x32_bf16 v[12:15], v[154:157], v[210:213], v[12:15]
	v_mfma_f32_16x16x32_bf16 v[4:7], v[162:165], v[210:213], v[4:7]
	v_mfma_f32_16x16x32_bf16 v[60:63], v[158:161], v[190:193], v[60:63]
	v_mfma_f32_16x16x32_bf16 v[52:55], v[166:169], v[190:193], v[52:55]
	v_mfma_f32_16x16x32_bf16 v[44:47], v[158:161], v[198:201], v[44:47]
	v_mfma_f32_16x16x32_bf16 v[36:39], v[166:169], v[198:201], v[36:39]
	v_mfma_f32_16x16x32_bf16 v[28:31], v[158:161], v[206:209], v[28:31]
	v_mfma_f32_16x16x32_bf16 v[20:23], v[166:169], v[206:209], v[20:23]
	v_mfma_f32_16x16x32_bf16 v[12:15], v[158:161], v[214:217], v[12:15]
	v_mfma_f32_16x16x32_bf16 v[4:7], v[166:169], v[214:217], v[4:7]
	s_setprio 0
	s_setprio 1
	v_mfma_f32_16x16x32_bf16 v[56:59], v[170:173], v[186:189], v[56:59]
	v_mfma_f32_16x16x32_bf16 v[48:51], v[178:181], v[186:189], v[48:51]
	v_mfma_f32_16x16x32_bf16 v[40:43], v[170:173], v[194:197], v[40:43]
	v_mfma_f32_16x16x32_bf16 v[32:35], v[178:181], v[194:197], v[32:35]
	v_mfma_f32_16x16x32_bf16 v[24:27], v[170:173], v[202:205], v[24:27]
	v_mfma_f32_16x16x32_bf16 v[16:19], v[178:181], v[202:205], v[16:19]
	v_mfma_f32_16x16x32_bf16 v[8:11], v[170:173], v[210:213], v[8:11]
	v_mfma_f32_16x16x32_bf16 v[0:3], v[178:181], v[210:213], v[0:3]
	v_mfma_f32_16x16x32_bf16 v[56:59], v[174:177], v[190:193], v[56:59]
	v_mfma_f32_16x16x32_bf16 v[48:51], v[182:185], v[190:193], v[48:51]
	v_mfma_f32_16x16x32_bf16 v[40:43], v[174:177], v[198:201], v[40:43]
	v_mfma_f32_16x16x32_bf16 v[32:35], v[182:185], v[198:201], v[32:35]
	v_mfma_f32_16x16x32_bf16 v[24:27], v[174:177], v[206:209], v[24:27]
	v_mfma_f32_16x16x32_bf16 v[16:19], v[182:185], v[206:209], v[16:19]
	v_mfma_f32_16x16x32_bf16 v[8:11], v[174:177], v[214:217], v[8:11]
	v_mfma_f32_16x16x32_bf16 v[0:3], v[182:185], v[214:217], v[0:3]
	s_barrier
	s_setprio 0
	s_add_i32 s68, s68, 2
	s_add_u32 s38, s38, 0x100
	s_addc_u32 s39, s39, 0
	s_add_u32 s66, s66, 0x100
	s_addc_u32 s67, s67, 0
.LBB0_232:
	ds_read_b128 v[154:157], v149
	ds_read_b128 v[158:161], v149 offset:1024
	ds_read_b128 v[162:165], v149 offset:2048
	ds_read_b128 v[166:169], v149 offset:3072
	ds_read_b128 v[170:173], v150
	ds_read_b128 v[174:177], v150 offset:1024
	ds_read_b128 v[178:181], v150 offset:2048
	ds_read_b128 v[182:185], v150 offset:3072
	s_add_u32 s40, s38, 0xfffc0080
	s_addc_u32 s41, s39, -1
	s_cmp_eq_u32 s68, 12
	s_cselect_b32 s43, s21, s41
	s_cselect_b32 s42, s64, s40
	s_cselect_b32 s41, s19, s67
	s_cselect_b32 s40, s65, s66
	v_lshl_add_u64 v[144:145], s[38:39], 0, v[136:137]
	s_add_i32 m0, s37, 0xc000
	ds_read_b128 v[186:189], v151
	ds_read_b128 v[190:193], v151 offset:1024
	ds_read_b128 v[194:197], v151 offset:2048
	ds_read_b128 v[198:201], v151 offset:3072
	ds_read_b128 v[202:205], v151 offset:4096
	ds_read_b128 v[206:209], v151 offset:5120
	ds_read_b128 v[210:213], v151 offset:6144
	ds_read_b128 v[214:217], v151 offset:7168
	global_load_lds_dwordx4 v[144:145], off
	v_lshl_add_u64 v[144:145], s[38:39], 0, v[138:139]
	s_add_i32 m0, s37, 0xe000
	s_nop 0
	global_load_lds_dwordx4 v[144:145], off
	s_waitcnt vmcnt(8)
	s_waitcnt lgkmcnt(0)
	s_barrier
; #define PG8_STAGE(bufoff, gbase, voff) do { _Pragma("unroll") for (int _i = 0; _i < 2; ++_i) \
;         __builtin_amdgcn_global_load_lds((const unsigned*)((const char*)(gbase) + (voff)[_i]), (PG8_LAS unsigned*)(lds + (bufoff) + ldsw + _i * 8192), 16, 0, 0); } while (0)
; #define PG8_LDA(dst, b, h) do { _Pragma("unroll") for (int m = 0; m < 4; ++m) _Pragma("unroll") for (int k = 0; k < 2; ++k) dst[m][k] = *(const PG8_LAS bf16x8*)(lds + PG8_SA(b, h) + aoff + m * 2048 + k * 1024); } while (0)
; #define PG8_MMA(ai, bj, At, Bt) do { __builtin_amdgcn_s_setprio(1); _Pragma("unroll") for (int m = 0; m < 4; ++m) _Pragma("unroll") for (int n = 0; n < 2; ++n) _Pragma("unroll") for (int k = 0; k < 2; ++k) \
;         acc[ai][bj][m][n] = __builtin_amdgcn_mfma_f32_16x16x32_bf16(Bt[n][k], At[m][k], acc[ai][bj][m][n], 0, 0, 0); __builtin_amdgcn_s_setprio(0); } while (0)
; #define PG8_WAIT_V(n) asm volatile("s_waitcnt vmcnt(" #n ")" ::: "memory")
; #define PG8_WAIT_L(n) asm volatile("s_waitcnt lgkmcnt(" #n ")" ::: "memory")
; #define PG8_BAR __builtin_amdgcn_s_barrier()
; #define PG8_SCHED __builtin_amdgcn_sched_barrier(0)
; template <class Epi, class Sched, bool ALIGN_EPI = false, bool SP2 = false>
; __device__ __forceinline__ void gemm_phase(PG8_LAS unsigned char* lds, const Gemm g, const Sched& S, const Epi& E) {
;     ...
;             PG8_WAIT_V(8); PG8_WAIT_L(0); PG8_BAR; PG8_MMA(0, 0, At, B0); PG8_MMA(0, 1, At, B1); PG8_BAR; PG8_SCHED;
;             PG8_LDA(At, 0, 1); PG8_STAGE(PG8_SB(0, 0), b2, voffB); PG8_STAGE(PG8_SB(0, 1), b2 + hstep, voffB); PG8_STAGE(PG8_SA(0, 0), a2, voffA);
;             PG8_WAIT_V(8); PG8_WAIT_L(0); PG8_BAR; PG8_MMA(1, 0, At, B0); PG8_MMA(1, 1, At, B1); PG8_BAR; PG8_SCHED;
	s_setprio 1
	v_mfma_f32_16x16x32_bf16 v[120:123], v[154:157], v[186:189], v[120:123]
	v_mfma_f32_16x16x32_bf16 v[116:119], v[162:165], v[186:189], v[116:119]
	v_mfma_f32_16x16x32_bf16 v[108:111], v[154:157], v[194:197], v[108:111]
	v_mfma_f32_16x16x32_bf16 v[100:103], v[162:165], v[194:197], v[100:103]
	v_mfma_f32_16x16x32_bf16 v[92:95], v[154:157], v[202:205], v[92:95]
	v_mfma_f32_16x16x32_bf16 v[84:87], v[162:165], v[202:205], v[84:87]
	v_mfma_f32_16x16x32_bf16 v[76:79], v[154:157], v[210:213], v[76:79]
	v_mfma_f32_16x16x32_bf16 v[68:71], v[162:165], v[210:213], v[68:71]
	v_mfma_f32_16x16x32_bf16 v[120:123], v[158:161], v[190:193], v[120:123]
	v_mfma_f32_16x16x32_bf16 v[116:119], v[166:169], v[190:193], v[116:119]
	v_mfma_f32_16x16x32_bf16 v[108:111], v[158:161], v[198:201], v[108:111]
	v_mfma_f32_16x16x32_bf16 v[100:103], v[166:169], v[198:201], v[100:103]
	v_mfma_f32_16x16x32_bf16 v[92:95], v[158:161], v[206:209], v[92:95]
	v_mfma_f32_16x16x32_bf16 v[84:87], v[166:169], v[206:209], v[84:87]
	v_mfma_f32_16x16x32_bf16 v[76:79], v[158:161], v[214:217], v[76:79]
	v_mfma_f32_16x16x32_bf16 v[68:71], v[166:169], v[214:217], v[68:71]
	s_setprio 0
	s_setprio 1
	v_mfma_f32_16x16x32_bf16 v[124:127], v[170:173], v[186:189], v[124:127]
	v_mfma_f32_16x16x32_bf16 v[112:115], v[178:181], v[186:189], v[112:115]
	v_mfma_f32_16x16x32_bf16 v[104:107], v[170:173], v[194:197], v[104:107]
	v_mfma_f32_16x16x32_bf16 v[96:99], v[178:181], v[194:197], v[96:99]
	v_mfma_f32_16x16x32_bf16 v[88:91], v[170:173], v[202:205], v[88:91]
	v_mfma_f32_16x16x32_bf16 v[80:83], v[178:181], v[202:205], v[80:83]
	v_mfma_f32_16x16x32_bf16 v[72:75], v[170:173], v[210:213], v[72:75]
	v_mfma_f32_16x16x32_bf16 v[64:67], v[178:181], v[210:213], v[64:67]
	v_mfma_f32_16x16x32_bf16 v[124:127], v[174:177], v[190:193], v[124:127]
	v_mfma_f32_16x16x32_bf16 v[112:115], v[182:185], v[190:193], v[112:115]
	v_mfma_f32_16x16x32_bf16 v[104:107], v[174:177], v[198:201], v[104:107]
	v_mfma_f32_16x16x32_bf16 v[96:99], v[182:185], v[198:201], v[96:99]
	v_mfma_f32_16x16x32_bf16 v[88:91], v[174:177], v[206:209], v[88:91]
	v_mfma_f32_16x16x32_bf16 v[80:83], v[182:185], v[206:209], v[80:83]
	v_mfma_f32_16x16x32_bf16 v[72:75], v[174:177], v[214:217], v[72:75]
	v_mfma_f32_16x16x32_bf16 v[64:67], v[182:185], v[214:217], v[64:67]
	s_barrier
	s_setprio 0
	s_add_i32 s69, s57, s48
	v_lshl_add_u64 v[144:145], s[40:41], 0, v[132:133]
	s_mov_b32 m0, s69
	ds_read_b128 v[186:189], v151 offset:16384
	ds_read_b128 v[190:193], v151 offset:17408
	ds_read_b128 v[194:197], v151 offset:18432
	ds_read_b128 v[198:201], v151 offset:19456
	ds_read_b128 v[202:205], v151 offset:20480
	ds_read_b128 v[206:209], v151 offset:21504
	ds_read_b128 v[210:213], v151 offset:22528
	ds_read_b128 v[214:217], v151 offset:23552
	global_load_lds_dwordx4 v[144:145], off
	s_add_i32 m0, s69, 0x2000
	s_add_u32 s70, s40, 0x40000
	v_lshl_add_u64 v[218:219], s[40:41], 0, v[128:129]
	s_addc_u32 s71, s41, 0
	s_add_i32 s69, s58, s48
	global_load_lds_dwordx4 v[218:219], off
	v_lshl_add_u64 v[220:221], s[70:71], 0, v[132:133]
	s_mov_b32 m0, s69
	v_lshl_add_u64 v[222:223], s[42:43], 0, v[130:131]
	global_load_lds_dwordx4 v[220:221], off
	v_lshl_add_u64 v[220:221], s[70:71], 0, v[128:129]
	s_add_i32 m0, s69, 0x2000
	s_nop 0
	global_load_lds_dwordx4 v[220:221], off
	v_lshl_add_u64 v[220:221], s[42:43], 0, v[134:135]
	s_mov_b32 m0, s37
	s_nop 0
	global_load_lds_dwordx4 v[220:221], off
	s_mov_b32 m0, s50
	s_nop 0
	global_load_lds_dwordx4 v[222:223], off
	s_waitcnt vmcnt(8)
	s_waitcnt lgkmcnt(0)
	s_barrier
	s_setprio 1
	v_mfma_f32_16x16x32_bf16 v[60:63], v[154:157], v[186:189], v[60:63]
	v_mfma_f32_16x16x32_bf16 v[52:55], v[162:165], v[186:189], v[52:55]
	v_mfma_f32_16x16x32_bf16 v[44:47], v[154:157], v[194:197], v[44:47]
	v_mfma_f32_16x16x32_bf16 v[36:39], v[162:165], v[194:197], v[36:39]
	v_mfma_f32_16x16x32_bf16 v[28:31], v[154:157], v[202:205], v[28:31]
	v_mfma_f32_16x16x32_bf16 v[20:23], v[162:165], v[202:205], v[20:23]
	v_mfma_f32_16x16x32_bf16 v[12:15], v[154:157], v[210:213], v[12:15]
	v_mfma_f32_16x16x32_bf16 v[4:7], v[162:165], v[210:213], v[4:7]
	v_mfma_f32_16x16x32_bf16 v[60:63], v[158:161], v[190:193], v[60:63]
	v_mfma_f32_16x16x32_bf16 v[52:55], v[166:169], v[190:193], v[52:55]
	v_mfma_f32_16x16x32_bf16 v[44:47], v[158:161], v[198:201], v[44:47]
	v_mfma_f32_16x16x32_bf16 v[36:39], v[166:169], v[198:201], v[36:39]
	v_mfma_f32_16x16x32_bf16 v[28:31], v[158:161], v[206:209], v[28:31]
	v_mfma_f32_16x16x32_bf16 v[20:23], v[166:169], v[206:209], v[20:23]
	v_mfma_f32_16x16x32_bf16 v[12:15], v[158:161], v[214:217], v[12:15]
	v_mfma_f32_16x16x32_bf16 v[4:7], v[166:169], v[214:217], v[4:7]
	s_setprio 0
	s_setprio 1
	v_mfma_f32_16x16x32_bf16 v[56:59], v[170:173], v[186:189], v[56:59]
	v_mfma_f32_16x16x32_bf16 v[48:51], v[178:181], v[186:189], v[48:51]
	v_mfma_f32_16x16x32_bf16 v[40:43], v[170:173], v[194:197], v[40:43]
	v_mfma_f32_16x16x32_bf16 v[32:35], v[178:181], v[194:197], v[32:35]
	v_mfma_f32_16x16x32_bf16 v[24:27], v[170:173], v[202:205], v[24:27]
	v_mfma_f32_16x16x32_bf16 v[16:19], v[178:181], v[202:205], v[16:19]
	v_mfma_f32_16x16x32_bf16 v[8:11], v[170:173], v[210:213], v[8:11]
	v_mfma_f32_16x16x32_bf16 v[0:3], v[178:181], v[210:213], v[0:3]
	v_mfma_f32_16x16x32_bf16 v[56:59], v[174:177], v[190:193], v[56:59]
	v_mfma_f32_16x16x32_bf16 v[48:51], v[182:185], v[190:193], v[48:51]
	v_mfma_f32_16x16x32_bf16 v[40:43], v[174:177], v[198:201], v[40:43]
	v_mfma_f32_16x16x32_bf16 v[32:35], v[182:185], v[198:201], v[32:35]
	v_mfma_f32_16x16x32_bf16 v[24:27], v[174:177], v[206:209], v[24:27]
	v_mfma_f32_16x16x32_bf16 v[16:19], v[182:185], v[206:209], v[16:19]
	v_mfma_f32_16x16x32_bf16 v[8:11], v[174:177], v[214:217], v[8:11]
	v_mfma_f32_16x16x32_bf16 v[0:3], v[182:185], v[214:217], v[0:3]
	s_barrier
; #define PG8_STAGE(bufoff, gbase, voff) do { _Pragma("unroll") for (int _i = 0; _i < 2; ++_i) \
;         __builtin_amdgcn_global_load_lds((const unsigned*)((const char*)(gbase) + (voff)[_i]), (PG8_LAS unsigned*)(lds + (bufoff) + ldsw + _i * 8192), 16, 0, 0); } while (0)
; #define PG8_LDA(dst, b, h) do { _Pragma("unroll") for (int m = 0; m < 4; ++m) _Pragma("unroll") for (int k = 0; k < 2; ++k) dst[m][k] = *(const PG8_LAS bf16x8*)(lds + PG8_SA(b, h) + aoff + m * 2048 + k * 1024); } while (0)
; #define PG8_LDB(dst, b, h) do { _Pragma("unroll") for (int n = 0; n < 2; ++n) _Pragma("unroll") for (int k = 0; k < 2; ++k) dst[n][k] = *(const PG8_LAS bf16x8*)(lds + PG8_SB(b, h) + boff + n * 2048 + k * 1024); } while (0)
; #define PG8_MMA(ai, bj, At, Bt) do { __builtin_amdgcn_s_setprio(1); _Pragma("unroll") for (int m = 0; m < 4; ++m) _Pragma("unroll") for (int n = 0; n < 2; ++n) _Pragma("unroll") for (int k = 0; k < 2; ++k) \
;         acc[ai][bj][m][n] = __builtin_amdgcn_mfma_f32_16x16x32_bf16(Bt[n][k], At[m][k], acc[ai][bj][m][n], 0, 0, 0); __builtin_amdgcn_s_setprio(0); } while (0)
; #define PG8_WAIT_V(n) asm volatile("s_waitcnt vmcnt(" #n ")" ::: "memory")
; #define PG8_WAIT_L(n) asm volatile("s_waitcnt lgkmcnt(" #n ")" ::: "memory")
; #define PG8_BAR __builtin_amdgcn_s_barrier()
; #define PG8_SCHED __builtin_amdgcn_sched_barrier(0)
; template <class Epi, class Sched, bool ALIGN_EPI = false, bool SP2 = false>
; __device__ __forceinline__ void gemm_phase(PG8_LAS unsigned char* lds, const Gemm g, const Sched& S, const Epi& E) {
;     ...
;             PG8_LDB(B0, 1, 0); PG8_LDB(B1, 1, 1); PG8_SCHED; PG8_LDA(At, 1, 0); PG8_STAGE(PG8_SA(0, 1), a2 + hstep, voffA);
;             PG8_WAIT_V(8); PG8_WAIT_L(0); PG8_BAR; PG8_MMA(0, 0, At, B0); PG8_MMA(0, 1, At, B1); PG8_BAR; PG8_SCHED;
	s_setprio 0
	s_add_i32 s69, 0, 0x18000
	v_add_u32_e32 v153, s69, v147
	s_add_i32 s70, 0, 0x1c000
	ds_read_b128 v[154:157], v153
	ds_read_b128 v[158:161], v153 offset:1024
	ds_read_b128 v[162:165], v153 offset:2048
	ds_read_b128 v[166:169], v153 offset:3072
	v_add_u32_e32 v153, s70, v147
	ds_read_b128 v[170:173], v153
	ds_read_b128 v[174:177], v153 offset:1024
	ds_read_b128 v[178:181], v153 offset:2048
	ds_read_b128 v[182:185], v153 offset:3072
	s_add_u32 s42, s42, 0x40000
	s_addc_u32 s43, s43, 0
	s_mov_b32 m0, s51
	v_lshl_add_u64 v[224:225], s[42:43], 0, v[134:135]
	ds_read_b128 v[186:189], v151 offset:32768
	ds_read_b128 v[190:193], v151 offset:33792
	ds_read_b128 v[194:197], v151 offset:34816
	ds_read_b128 v[198:201], v151 offset:35840
	ds_read_b128 v[202:205], v151 offset:36864
	ds_read_b128 v[206:209], v151 offset:37888
	ds_read_b128 v[210:213], v151 offset:38912
	ds_read_b128 v[214:217], v151 offset:39936
	global_load_lds_dwordx4 v[224:225], off
	v_lshl_add_u64 v[224:225], s[42:43], 0, v[130:131]
	s_mov_b32 m0, s52
	s_nop 0
	global_load_lds_dwordx4 v[224:225], off
	s_waitcnt vmcnt(8)
	s_waitcnt lgkmcnt(0)
	s_barrier
	s_setprio 1
	v_mfma_f32_16x16x32_bf16 v[120:123], v[154:157], v[186:189], v[120:123]
	v_mfma_f32_16x16x32_bf16 v[116:119], v[162:165], v[186:189], v[116:119]
	v_mfma_f32_16x16x32_bf16 v[108:111], v[154:157], v[194:197], v[108:111]
	v_mfma_f32_16x16x32_bf16 v[100:103], v[162:165], v[194:197], v[100:103]
	v_mfma_f32_16x16x32_bf16 v[92:95], v[154:157], v[202:205], v[92:95]
	v_mfma_f32_16x16x32_bf16 v[84:87], v[162:165], v[202:205], v[84:87]
	v_mfma_f32_16x16x32_bf16 v[76:79], v[154:157], v[210:213], v[76:79]
	v_mfma_f32_16x16x32_bf16 v[68:71], v[162:165], v[210:213], v[68:71]
	v_mfma_f32_16x16x32_bf16 v[120:123], v[158:161], v[190:193], v[120:123]
	v_mfma_f32_16x16x32_bf16 v[116:119], v[166:169], v[190:193], v[116:119]
	v_mfma_f32_16x16x32_bf16 v[108:111], v[158:161], v[198:201], v[108:111]
	v_mfma_f32_16x16x32_bf16 v[100:103], v[166:169], v[198:201], v[100:103]
	v_mfma_f32_16x16x32_bf16 v[92:95], v[158:161], v[206:209], v[92:95]
	v_mfma_f32_16x16x32_bf16 v[84:87], v[166:169], v[206:209], v[84:87]
	v_mfma_f32_16x16x32_bf16 v[76:79], v[158:161], v[214:217], v[76:79]
	v_mfma_f32_16x16x32_bf16 v[68:71], v[166:169], v[214:217], v[68:71]
	s_setprio 0
	s_setprio 1
	v_mfma_f32_16x16x32_bf16 v[124:127], v[170:173], v[186:189], v[124:127]
	v_mfma_f32_16x16x32_bf16 v[112:115], v[178:181], v[186:189], v[112:115]
	v_mfma_f32_16x16x32_bf16 v[104:107], v[170:173], v[194:197], v[104:107]
	v_mfma_f32_16x16x32_bf16 v[96:99], v[178:181], v[194:197], v[96:99]
	v_mfma_f32_16x16x32_bf16 v[88:91], v[170:173], v[202:205], v[88:91]
	v_mfma_f32_16x16x32_bf16 v[80:83], v[178:181], v[202:205], v[80:83]
	v_mfma_f32_16x16x32_bf16 v[72:75], v[170:173], v[210:213], v[72:75]
	v_mfma_f32_16x16x32_bf16 v[64:67], v[178:181], v[210:213], v[64:67]
	v_mfma_f32_16x16x32_bf16 v[124:127], v[174:177], v[190:193], v[124:127]
	v_mfma_f32_16x16x32_bf16 v[112:115], v[182:185], v[190:193], v[112:115]
	v_mfma_f32_16x16x32_bf16 v[104:107], v[174:177], v[198:201], v[104:107]
	v_mfma_f32_16x16x32_bf16 v[96:99], v[182:185], v[198:201], v[96:99]
	v_mfma_f32_16x16x32_bf16 v[88:91], v[174:177], v[206:209], v[88:91]
	v_mfma_f32_16x16x32_bf16 v[80:83], v[182:185], v[206:209], v[80:83]
	v_mfma_f32_16x16x32_bf16 v[72:75], v[174:177], v[214:217], v[72:75]
	v_mfma_f32_16x16x32_bf16 v[64:67], v[182:185], v[214:217], v[64:67]
	s_barrier
; #define PG8_STAGE(bufoff, gbase, voff) do { _Pragma("unroll") for (int _i = 0; _i < 2; ++_i) \
;         __builtin_amdgcn_global_load_lds((const unsigned*)((const char*)(gbase) + (voff)[_i]), (PG8_LAS unsigned*)(lds + (bufoff) + ldsw + _i * 8192), 16, 0, 0); } while (0)
; #define PG8_LDA(dst, b, h) do { _Pragma("unroll") for (int m = 0; m < 4; ++m) _Pragma("unroll") for (int k = 0; k < 2; ++k) dst[m][k] = *(const PG8_LAS bf16x8*)(lds + PG8_SA(b, h) + aoff + m * 2048 + k * 1024); } while (0)
; #define PG8_MMA(ai, bj, At, Bt) do { __builtin_amdgcn_s_setprio(1); _Pragma("unroll") for (int m = 0; m < 4; ++m) _Pragma("unroll") for (int n = 0; n < 2; ++n) _Pragma("unroll") for (int k = 0; k < 2; ++k) \
;         acc[ai][bj][m][n] = __builtin_amdgcn_mfma_f32_16x16x32_bf16(Bt[n][k], At[m][k], acc[ai][bj][m][n], 0, 0, 0); __builtin_amdgcn_s_setprio(0); } while (0)
; #define PG8_WAIT_V(n) asm volatile("s_waitcnt vmcnt(" #n ")" ::: "memory")
; #define PG8_WAIT_L(n) asm volatile("s_waitcnt lgkmcnt(" #n ")" ::: "memory")
; #define PG8_BAR __builtin_amdgcn_s_barrier()
; #define PG8_SCHED __builtin_amdgcn_sched_barrier(0)
; template <class Epi, class Sched, bool ALIGN_EPI = false, bool SP2 = false>
; __device__ __forceinline__ void gemm_phase(PG8_LAS unsigned char* lds, const Gemm g, const Sched& S, const Epi& E) {
;     ...
;             PG8_LDA(At, 1, 1); PG8_STAGE(PG8_SB(1, 0), b3, voffB); PG8_STAGE(PG8_SB(1, 1), b3 + hstep, voffB); PG8_STAGE(PG8_SA(1, 0), a3, voffA);
;             PG8_WAIT_V(8); PG8_WAIT_L(0); PG8_BAR; PG8_MMA(1, 0, At, B0); PG8_MMA(1, 1, At, B1); PG8_BAR; PG8_SCHED;
;     ...
;         if constexpr (ALIGN_EPI) { if (wr == 0) PG8_BAR; }
	s_setprio 0
	s_add_i32 s42, s69, s48
	v_lshl_add_u64 v[144:145], v[144:145], 0, s[14:15]
	s_mov_b32 m0, s42
	ds_read_b128 v[186:189], v151 offset:49152
	ds_read_b128 v[190:193], v151 offset:50176
	ds_read_b128 v[194:197], v151 offset:51200
	ds_read_b128 v[198:201], v151 offset:52224
	ds_read_b128 v[202:205], v151 offset:53248
	ds_read_b128 v[206:209], v151 offset:54272
	ds_read_b128 v[210:213], v151 offset:55296
	ds_read_b128 v[214:217], v151 offset:56320
	global_load_lds_dwordx4 v[144:145], off
	s_add_i32 m0, s42, 0x2000
	s_add_u32 s40, s40, 0x40080
	v_lshl_add_u64 v[144:145], v[218:219], 0, s[14:15]
	s_addc_u32 s41, s41, 0
	s_add_i32 s42, s70, s48
	global_load_lds_dwordx4 v[144:145], off
	v_lshl_add_u64 v[144:145], s[40:41], 0, v[132:133]
	s_mov_b32 m0, s42
	s_nop 0
	global_load_lds_dwordx4 v[144:145], off
	v_lshl_add_u64 v[144:145], s[40:41], 0, v[128:129]
	s_add_i32 m0, s42, 0x2000
	s_nop 0
	global_load_lds_dwordx4 v[144:145], off
	v_lshl_add_u64 v[144:145], v[220:221], 0, s[14:15]
	s_mov_b32 m0, s54
	s_nop 0
	global_load_lds_dwordx4 v[144:145], off
	v_lshl_add_u64 v[144:145], v[222:223], 0, s[14:15]
	s_mov_b32 m0, s55
	s_nop 0
	global_load_lds_dwordx4 v[144:145], off
	s_waitcnt vmcnt(8)
	s_waitcnt lgkmcnt(0)
	s_barrier
	s_setprio 1
	v_mfma_f32_16x16x32_bf16 v[60:63], v[154:157], v[186:189], v[60:63]
	v_mfma_f32_16x16x32_bf16 v[52:55], v[162:165], v[186:189], v[52:55]
	v_mfma_f32_16x16x32_bf16 v[44:47], v[154:157], v[194:197], v[44:47]
	v_mfma_f32_16x16x32_bf16 v[36:39], v[162:165], v[194:197], v[36:39]
	v_mfma_f32_16x16x32_bf16 v[28:31], v[154:157], v[202:205], v[28:31]
	v_mfma_f32_16x16x32_bf16 v[20:23], v[162:165], v[202:205], v[20:23]
	v_mfma_f32_16x16x32_bf16 v[12:15], v[154:157], v[210:213], v[12:15]
	v_mfma_f32_16x16x32_bf16 v[4:7], v[162:165], v[210:213], v[4:7]
	v_mfma_f32_16x16x32_bf16 v[60:63], v[158:161], v[190:193], v[60:63]
	v_mfma_f32_16x16x32_bf16 v[52:55], v[166:169], v[190:193], v[52:55]
	v_mfma_f32_16x16x32_bf16 v[44:47], v[158:161], v[198:201], v[44:47]
	v_mfma_f32_16x16x32_bf16 v[36:39], v[166:169], v[198:201], v[36:39]
	v_mfma_f32_16x16x32_bf16 v[28:31], v[158:161], v[206:209], v[28:31]
	v_mfma_f32_16x16x32_bf16 v[20:23], v[166:169], v[206:209], v[20:23]
	v_mfma_f32_16x16x32_bf16 v[12:15], v[158:161], v[214:217], v[12:15]
	v_mfma_f32_16x16x32_bf16 v[4:7], v[166:169], v[214:217], v[4:7]
	s_setprio 0
	s_setprio 1
	v_mfma_f32_16x16x32_bf16 v[56:59], v[170:173], v[186:189], v[56:59]
	v_mfma_f32_16x16x32_bf16 v[48:51], v[178:181], v[186:189], v[48:51]
	v_mfma_f32_16x16x32_bf16 v[40:43], v[170:173], v[194:197], v[40:43]
	v_mfma_f32_16x16x32_bf16 v[32:35], v[178:181], v[194:197], v[32:35]
	v_mfma_f32_16x16x32_bf16 v[24:27], v[170:173], v[202:205], v[24:27]
	v_mfma_f32_16x16x32_bf16 v[16:19], v[178:181], v[202:205], v[16:19]
	v_mfma_f32_16x16x32_bf16 v[8:11], v[170:173], v[210:213], v[8:11]
	v_mfma_f32_16x16x32_bf16 v[0:3], v[178:181], v[210:213], v[0:3]
	v_mfma_f32_16x16x32_bf16 v[56:59], v[174:177], v[190:193], v[56:59]
	v_mfma_f32_16x16x32_bf16 v[48:51], v[182:185], v[190:193], v[48:51]
	v_mfma_f32_16x16x32_bf16 v[40:43], v[174:177], v[198:201], v[40:43]
	v_mfma_f32_16x16x32_bf16 v[32:35], v[182:185], v[198:201], v[32:35]
	v_mfma_f32_16x16x32_bf16 v[24:27], v[174:177], v[206:209], v[24:27]
	v_mfma_f32_16x16x32_bf16 v[16:19], v[182:185], v[206:209], v[16:19]
	v_mfma_f32_16x16x32_bf16 v[8:11], v[174:177], v[214:217], v[8:11]
	v_mfma_f32_16x16x32_bf16 v[0:3], v[182:185], v[214:217], v[0:3]
	s_barrier
	s_setprio 0
	s_add_i32 s68, s68, 2
	s_add_u32 s38, s38, 0x100
	s_addc_u32 s39, s39, 0
	s_add_u32 s66, s66, 0x100
	s_addc_u32 s67, s67, 0
	s_cmp_gt_u32 s68, 13
	s_cbranch_scc0 .LBB0_232
	s_and_b64 vcc, exec, s[16:17]
	s_cbranch_vccz .LBB0_235
	s_barrier

; #define PG8_STAGE(bufoff, gbase, voff) do { _Pragma("unroll") for (int _i = 0; _i < 2; ++_i) \
;         __builtin_amdgcn_global_load_lds((const unsigned*)((const char*)(gbase) + (voff)[_i]), (PG8_LAS unsigned*)(lds + (bufoff) + ldsw + _i * 8192), 16, 0, 0); } while (0)
; #define PG8_LDA(dst, b, h) do { _Pragma("unroll") for (int m = 0; m < 4; ++m) _Pragma("unroll") for (int k = 0; k < 2; ++k) dst[m][k] = *(const PG8_LAS bf16x8*)(lds + PG8_SA(b, h) + aoff + m * 2048 + k * 1024); } while (0)
; #define PG8_LDB(dst, b, h) do { _Pragma("unroll") for (int n = 0; n < 2; ++n) _Pragma("unroll") for (int k = 0; k < 2; ++k) dst[n][k] = *(const PG8_LAS bf16x8*)(lds + PG8_SB(b, h) + boff + n * 2048 + k * 1024); } while (0)
; #define PG8_WAIT_V(n) asm volatile("s_waitcnt vmcnt(" #n ")" ::: "memory")
; #define PG8_WAIT_L(n) asm volatile("s_waitcnt lgkmcnt(" #n ")" ::: "memory")
; template <class Epi, class Sched, bool ALIGN_EPI = false, bool SP2 = false>
; __device__ __forceinline__ void gemm_phase(PG8_LAS unsigned char* lds, const Gemm g, const Sched& S, const Epi& E) {
;     ...
;         const bool has_next = S.next(ui + 1, nxt);
;         const char* nA = has_next ? (const char*)g.A + (size_t)nxt.pm * tstep : cA; const char* nB = has_next ? (const char*)g.Bt + (size_t)nxt.pn * tstep : cB;
;         for (int t = 0; t < nt; t += 2) {
;             const bool last = (t == nt - 2);
;             if constexpr (Epi::PREFETCH) { if (t == nt - 4) E.prefetch(cur, lds + STAGE_BYTES + 1024, tid); }
;             const char* a1 = cA + (size_t)(t + 1) * kstep;
;             const char* a2 = last ? nA : cA + (size_t)(t + 2) * kstep; const char* b2 = last ? nB : cB + (size_t)(t + 2) * kstep;
;             const char* a3 = a2 + kstep; const char* b3 = b2 + kstep;
;             if (last && has_next) S.a_ready(nxt);
;             if constexpr (SP2) {
;             PG8_LDB(B0, 0, 0); PG8_LDB(B1, 0, 1); PG8_SCHED; PG8_LDA(At, 0, 0); PG8_STAGE(PG8_SA(1, 1), a1 + hstep, voffA);
;             PG8_WAIT_V(8); PG8_WAIT_L(0); PG8_BAR; PG8_MMA(0, 0, At, B0); PG8_MMA(0, 1, At, B1); PG8_BAR; PG8_SCHED;
;             PG8_LDA(At, 0, 1); PG8_STAGE(PG8_SB(0, 0), b2, voffB); PG8_STAGE(PG8_SB(0, 1), b2 + hstep, voffB); PG8_STAGE(PG8_SA(0, 0), a2, voffA);
;             PG8_WAIT_V(8); PG8_WAIT_L(0); PG8_BAR; PG8_MMA(1, 0, At, B0); PG8_MMA(1, 1, At, B1); PG8_BAR; PG8_SCHED;
.LBB0_405:
	s_add_u32 s34, s34, 0xb0080
	s_addc_u32 s35, s35, 0
	s_add_u32 s59, s36, 0x100
	s_addc_u32 s63, s37, 0
	s_mov_b32 s64, -2
	ds_read_b128 v[112:115], v246
	ds_read_b128 v[116:119], v246 offset:1024
	ds_read_b128 v[120:123], v246 offset:2048
	ds_read_b128 v[124:127], v246 offset:3072
	ds_read_b128 v[136:139], v247
	ds_read_b128 v[140:143], v247 offset:1024
	ds_read_b128 v[152:155], v247 offset:2048
	ds_read_b128 v[156:159], v247 offset:3072
	s_add_u32 s36, s34, 0xfff50080
	s_addc_u32 s37, s35, -1
	s_cmp_eq_u32 s64, 40
	s_cselect_b32 s39, s9, s37
	s_cselect_b32 s38, s8, s36
	s_cselect_b32 s37, s23, s63
	s_cselect_b32 s36, s22, s59
	v_lshl_add_u64 v[206:207], s[34:35], 0, v[200:201]
	s_add_i32 m0, s45, 0xc000
	ds_read_b128 v[160:163], v248
	ds_read_b128 v[164:167], v248 offset:1024
	ds_read_b128 v[168:171], v248 offset:2048
	ds_read_b128 v[172:175], v248 offset:3072
	ds_read_b128 v[176:179], v248 offset:4096
	ds_read_b128 v[180:183], v248 offset:5120
	ds_read_b128 v[184:187], v248 offset:6144
	ds_read_b128 v[188:191], v248 offset:7168
	global_load_lds_dwordx4 v[206:207], off
	v_lshl_add_u64 v[206:207], s[34:35], 0, v[202:203]
	s_add_i32 m0, s45, 0xe000
	s_nop 0
	global_load_lds_dwordx4 v[206:207], off
	s_waitcnt vmcnt(8)
	s_waitcnt lgkmcnt(0)
	s_barrier
	s_setprio 1
	v_mfma_f32_16x16x32_bf16 v[148:151], v[112:115], v[160:163], 0
	v_mfma_f32_16x16x32_bf16 v[144:147], v[120:123], v[160:163], 0
	v_mfma_f32_16x16x32_bf16 v[108:111], v[112:115], v[168:171], 0
	v_mfma_f32_16x16x32_bf16 v[104:107], v[120:123], v[168:171], 0
	v_mfma_f32_16x16x32_bf16 v[92:95], v[112:115], v[176:179], 0
	v_mfma_f32_16x16x32_bf16 v[88:91], v[120:123], v[176:179], 0
	v_mfma_f32_16x16x32_bf16 v[76:79], v[112:115], v[184:187], 0
	v_mfma_f32_16x16x32_bf16 v[72:75], v[120:123], v[184:187], 0
	v_mfma_f32_16x16x32_bf16 v[148:151], v[116:119], v[164:167], v[148:151]
	v_mfma_f32_16x16x32_bf16 v[144:147], v[124:127], v[164:167], v[144:147]
	v_mfma_f32_16x16x32_bf16 v[108:111], v[116:119], v[172:175], v[108:111]
	v_mfma_f32_16x16x32_bf16 v[104:107], v[124:127], v[172:175], v[104:107]
	v_mfma_f32_16x16x32_bf16 v[92:95], v[116:119], v[180:183], v[92:95]
	v_mfma_f32_16x16x32_bf16 v[88:91], v[124:127], v[180:183], v[88:91]
	v_mfma_f32_16x16x32_bf16 v[76:79], v[116:119], v[188:191], v[76:79]
	v_mfma_f32_16x16x32_bf16 v[72:75], v[124:127], v[188:191], v[72:75]
	s_setprio 0
	s_setprio 1
	v_mfma_f32_16x16x32_bf16 v[132:135], v[136:139], v[160:163], 0
	v_mfma_f32_16x16x32_bf16 v[128:131], v[152:155], v[160:163], 0
	v_mfma_f32_16x16x32_bf16 v[100:103], v[136:139], v[168:171], 0
	v_mfma_f32_16x16x32_bf16 v[96:99], v[152:155], v[168:171], 0
	v_mfma_f32_16x16x32_bf16 v[84:87], v[136:139], v[176:179], 0
	v_mfma_f32_16x16x32_bf16 v[80:83], v[152:155], v[176:179], 0
	v_mfma_f32_16x16x32_bf16 v[68:71], v[136:139], v[184:187], 0
	v_mfma_f32_16x16x32_bf16 v[64:67], v[152:155], v[184:187], 0
	v_mfma_f32_16x16x32_bf16 v[132:135], v[140:143], v[164:167], v[132:135]
	v_mfma_f32_16x16x32_bf16 v[128:131], v[156:159], v[164:167], v[128:131]
	v_mfma_f32_16x16x32_bf16 v[100:103], v[140:143], v[172:175], v[100:103]
	v_mfma_f32_16x16x32_bf16 v[96:99], v[156:159], v[172:175], v[96:99]
	v_mfma_f32_16x16x32_bf16 v[84:87], v[140:143], v[180:183], v[84:87]
	v_mfma_f32_16x16x32_bf16 v[80:83], v[156:159], v[180:183], v[80:83]
	v_mfma_f32_16x16x32_bf16 v[68:71], v[140:143], v[188:191], v[68:71]
	v_mfma_f32_16x16x32_bf16 v[64:67], v[156:159], v[188:191], v[64:67]
	s_barrier
	s_setprio 0
	s_add_i32 s65, s53, s44
	v_lshl_add_u64 v[206:207], s[36:37], 0, v[194:195]
	s_mov_b32 m0, s65
	ds_read_b128 v[160:163], v248 offset:16384
	ds_read_b128 v[164:167], v248 offset:17408
	ds_read_b128 v[168:171], v248 offset:18432
	ds_read_b128 v[172:175], v248 offset:19456
	ds_read_b128 v[176:179], v248 offset:20480
	ds_read_b128 v[180:183], v248 offset:21504
	ds_read_b128 v[184:187], v248 offset:22528
	ds_read_b128 v[188:191], v248 offset:23552
	global_load_lds_dwordx4 v[206:207], off
	s_add_i32 m0, s65, 0x2000
	s_add_u32 s66, s36, 0xb0000
	v_lshl_add_u64 v[208:209], s[36:37], 0, v[198:199]
	s_addc_u32 s67, s37, 0
	s_add_i32 s65, s54, s44
	global_load_lds_dwordx4 v[208:209], off
	v_lshl_add_u64 v[210:211], s[66:67], 0, v[194:195]
	s_mov_b32 m0, s65
	v_lshl_add_u64 v[212:213], s[38:39], 0, v[196:197]
	global_load_lds_dwordx4 v[210:211], off
	v_lshl_add_u64 v[210:211], s[66:67], 0, v[198:199]
	s_add_i32 m0, s65, 0x2000
	s_nop 0
	global_load_lds_dwordx4 v[210:211], off
	v_lshl_add_u64 v[210:211], s[38:39], 0, v[192:193]
	s_mov_b32 m0, s45
	s_nop 0
	global_load_lds_dwordx4 v[210:211], off
	s_mov_b32 m0, s46
	s_nop 0
	global_load_lds_dwordx4 v[212:213], off
	s_waitcnt vmcnt(8)
	s_waitcnt lgkmcnt(0)
	s_barrier
; #define PG8_STAGE(bufoff, gbase, voff) do { _Pragma("unroll") for (int _i = 0; _i < 2; ++_i) \
;         __builtin_amdgcn_global_load_lds((const unsigned*)((const char*)(gbase) + (voff)[_i]), (PG8_LAS unsigned*)(lds + (bufoff) + ldsw + _i * 8192), 16, 0, 0); } while (0)
; #define PG8_LDA(dst, b, h) do { _Pragma("unroll") for (int m = 0; m < 4; ++m) _Pragma("unroll") for (int k = 0; k < 2; ++k) dst[m][k] = *(const PG8_LAS bf16x8*)(lds + PG8_SA(b, h) + aoff + m * 2048 + k * 1024); } while (0)
; #define PG8_LDB(dst, b, h) do { _Pragma("unroll") for (int n = 0; n < 2; ++n) _Pragma("unroll") for (int k = 0; k < 2; ++k) dst[n][k] = *(const PG8_LAS bf16x8*)(lds + PG8_SB(b, h) + boff + n * 2048 + k * 1024); } while (0)
; #define PG8_MMA(ai, bj, At, Bt) do { __builtin_amdgcn_s_setprio(1); _Pragma("unroll") for (int m = 0; m < 4; ++m) _Pragma("unroll") for (int n = 0; n < 2; ++n) _Pragma("unroll") for (int k = 0; k < 2; ++k) \
;         acc[ai][bj][m][n] = __builtin_amdgcn_mfma_f32_16x16x32_bf16(Bt[n][k], At[m][k], acc[ai][bj][m][n], 0, 0, 0); __builtin_amdgcn_s_setprio(0); } while (0)
; #define PG8_WAIT_V(n) asm volatile("s_waitcnt vmcnt(" #n ")" ::: "memory")
; #define PG8_WAIT_L(n) asm volatile("s_waitcnt lgkmcnt(" #n ")" ::: "memory")
; #define PG8_BAR __builtin_amdgcn_s_barrier()
; #define PG8_SCHED __builtin_amdgcn_sched_barrier(0)
; template <class Epi, class Sched, bool ALIGN_EPI = false, bool SP2 = false>
; __device__ __forceinline__ void gemm_phase(PG8_LAS unsigned char* lds, const Gemm g, const Sched& S, const Epi& E) {
;     ...
;             PG8_WAIT_V(8); PG8_WAIT_L(0); PG8_BAR; PG8_MMA(1, 0, At, B0); PG8_MMA(1, 1, At, B1); PG8_BAR; PG8_SCHED;
;             PG8_LDB(B0, 1, 0); PG8_LDB(B1, 1, 1); PG8_SCHED; PG8_LDA(At, 1, 0); PG8_STAGE(PG8_SA(0, 1), a2 + hstep, voffA);
;             PG8_WAIT_V(8); PG8_WAIT_L(0); PG8_BAR; PG8_MMA(0, 0, At, B0); PG8_MMA(0, 1, At, B1); PG8_BAR; PG8_SCHED;
	s_setprio 1
	v_mfma_f32_16x16x32_bf16 v[60:63], v[112:115], v[160:163], 0
	v_mfma_f32_16x16x32_bf16 v[56:59], v[120:123], v[160:163], 0
	v_mfma_f32_16x16x32_bf16 v[44:47], v[112:115], v[168:171], 0
	v_mfma_f32_16x16x32_bf16 v[40:43], v[120:123], v[168:171], 0
	v_mfma_f32_16x16x32_bf16 v[28:31], v[112:115], v[176:179], 0
	v_mfma_f32_16x16x32_bf16 v[24:27], v[120:123], v[176:179], 0
	v_mfma_f32_16x16x32_bf16 v[12:15], v[112:115], v[184:187], 0
	v_mfma_f32_16x16x32_bf16 v[8:11], v[120:123], v[184:187], 0
	v_mfma_f32_16x16x32_bf16 v[60:63], v[116:119], v[164:167], v[60:63]
	v_mfma_f32_16x16x32_bf16 v[56:59], v[124:127], v[164:167], v[56:59]
	v_mfma_f32_16x16x32_bf16 v[44:47], v[116:119], v[172:175], v[44:47]
	v_mfma_f32_16x16x32_bf16 v[40:43], v[124:127], v[172:175], v[40:43]
	v_mfma_f32_16x16x32_bf16 v[28:31], v[116:119], v[180:183], v[28:31]
	v_mfma_f32_16x16x32_bf16 v[24:27], v[124:127], v[180:183], v[24:27]
	v_mfma_f32_16x16x32_bf16 v[12:15], v[116:119], v[188:191], v[12:15]
	v_mfma_f32_16x16x32_bf16 v[8:11], v[124:127], v[188:191], v[8:11]
	s_setprio 0
	s_setprio 1
	v_mfma_f32_16x16x32_bf16 v[52:55], v[136:139], v[160:163], 0
	v_mfma_f32_16x16x32_bf16 v[48:51], v[152:155], v[160:163], 0
	v_mfma_f32_16x16x32_bf16 v[36:39], v[136:139], v[168:171], 0
	v_mfma_f32_16x16x32_bf16 v[32:35], v[152:155], v[168:171], 0
	v_mfma_f32_16x16x32_bf16 v[20:23], v[136:139], v[176:179], 0
	v_mfma_f32_16x16x32_bf16 v[16:19], v[152:155], v[176:179], 0
	v_mfma_f32_16x16x32_bf16 v[4:7], v[136:139], v[184:187], 0
	v_mfma_f32_16x16x32_bf16 v[0:3], v[152:155], v[184:187], 0
	v_mfma_f32_16x16x32_bf16 v[52:55], v[140:143], v[164:167], v[52:55]
	v_mfma_f32_16x16x32_bf16 v[48:51], v[156:159], v[164:167], v[48:51]
	v_mfma_f32_16x16x32_bf16 v[36:39], v[140:143], v[172:175], v[36:39]
	v_mfma_f32_16x16x32_bf16 v[32:35], v[156:159], v[172:175], v[32:35]
	v_mfma_f32_16x16x32_bf16 v[20:23], v[140:143], v[180:183], v[20:23]
	v_mfma_f32_16x16x32_bf16 v[16:19], v[156:159], v[180:183], v[16:19]
	v_mfma_f32_16x16x32_bf16 v[4:7], v[140:143], v[188:191], v[4:7]
	v_mfma_f32_16x16x32_bf16 v[0:3], v[156:159], v[188:191], v[0:3]
	s_barrier
	s_setprio 0
	s_add_i32 s65, 0, 0x18000
	s_add_i32 s66, 0, 0x1c000
	v_add_u32_e32 v124, s65, v244
	v_add_u32_e32 v156, s66, v244
	ds_read_b128 v[112:115], v124
	ds_read_b128 v[116:119], v124 offset:1024
	ds_read_b128 v[120:123], v124 offset:2048
	ds_read_b128 v[124:127], v124 offset:3072
	ds_read_b128 v[136:139], v156
	ds_read_b128 v[140:143], v156 offset:1024
	ds_read_b128 v[152:155], v156 offset:2048
	ds_read_b128 v[156:159], v156 offset:3072
	s_add_u32 s38, s38, 0xb0000
	s_addc_u32 s39, s39, 0
	s_mov_b32 m0, s47
	v_lshl_add_u64 v[214:215], s[38:39], 0, v[192:193]
	ds_read_b128 v[160:163], v248 offset:32768
	ds_read_b128 v[164:167], v248 offset:33792
	ds_read_b128 v[168:171], v248 offset:34816
	ds_read_b128 v[172:175], v248 offset:35840
	ds_read_b128 v[176:179], v248 offset:36864
	ds_read_b128 v[180:183], v248 offset:37888
	ds_read_b128 v[184:187], v248 offset:38912
	ds_read_b128 v[188:191], v248 offset:39936
	global_load_lds_dwordx4 v[214:215], off
	v_lshl_add_u64 v[214:215], s[38:39], 0, v[196:197]
	s_mov_b32 m0, s48
	s_nop 0
	global_load_lds_dwordx4 v[214:215], off
	s_waitcnt vmcnt(8)
	s_waitcnt lgkmcnt(0)
	s_barrier
	s_setprio 1
	v_mfma_f32_16x16x32_bf16 v[148:151], v[112:115], v[160:163], v[148:151]
	v_mfma_f32_16x16x32_bf16 v[144:147], v[120:123], v[160:163], v[144:147]
	v_mfma_f32_16x16x32_bf16 v[108:111], v[112:115], v[168:171], v[108:111]
	v_mfma_f32_16x16x32_bf16 v[104:107], v[120:123], v[168:171], v[104:107]
	v_mfma_f32_16x16x32_bf16 v[92:95], v[112:115], v[176:179], v[92:95]
	v_mfma_f32_16x16x32_bf16 v[88:91], v[120:123], v[176:179], v[88:91]
	v_mfma_f32_16x16x32_bf16 v[76:79], v[112:115], v[184:187], v[76:79]
	v_mfma_f32_16x16x32_bf16 v[72:75], v[120:123], v[184:187], v[72:75]
	v_mfma_f32_16x16x32_bf16 v[148:151], v[116:119], v[164:167], v[148:151]
	v_mfma_f32_16x16x32_bf16 v[144:147], v[124:127], v[164:167], v[144:147]
	v_mfma_f32_16x16x32_bf16 v[108:111], v[116:119], v[172:175], v[108:111]
	v_mfma_f32_16x16x32_bf16 v[104:107], v[124:127], v[172:175], v[104:107]
	v_mfma_f32_16x16x32_bf16 v[92:95], v[116:119], v[180:183], v[92:95]
	v_mfma_f32_16x16x32_bf16 v[88:91], v[124:127], v[180:183], v[88:91]
	v_mfma_f32_16x16x32_bf16 v[76:79], v[116:119], v[188:191], v[76:79]
	v_mfma_f32_16x16x32_bf16 v[72:75], v[124:127], v[188:191], v[72:75]
	s_setprio 0
	s_setprio 1
	v_mfma_f32_16x16x32_bf16 v[132:135], v[136:139], v[160:163], v[132:135]
	v_mfma_f32_16x16x32_bf16 v[128:131], v[152:155], v[160:163], v[128:131]
	v_mfma_f32_16x16x32_bf16 v[100:103], v[136:139], v[168:171], v[100:103]
	v_mfma_f32_16x16x32_bf16 v[96:99], v[152:155], v[168:171], v[96:99]
	v_mfma_f32_16x16x32_bf16 v[84:87], v[136:139], v[176:179], v[84:87]
	v_mfma_f32_16x16x32_bf16 v[80:83], v[152:155], v[176:179], v[80:83]
	v_mfma_f32_16x16x32_bf16 v[68:71], v[136:139], v[184:187], v[68:71]
	v_mfma_f32_16x16x32_bf16 v[64:67], v[152:155], v[184:187], v[64:67]
	v_mfma_f32_16x16x32_bf16 v[132:135], v[140:143], v[164:167], v[132:135]
	v_mfma_f32_16x16x32_bf16 v[128:131], v[156:159], v[164:167], v[128:131]
	v_mfma_f32_16x16x32_bf16 v[100:103], v[140:143], v[172:175], v[100:103]
	v_mfma_f32_16x16x32_bf16 v[96:99], v[156:159], v[172:175], v[96:99]
	v_mfma_f32_16x16x32_bf16 v[84:87], v[140:143], v[180:183], v[84:87]
	v_mfma_f32_16x16x32_bf16 v[80:83], v[156:159], v[180:183], v[80:83]
	v_mfma_f32_16x16x32_bf16 v[68:71], v[140:143], v[188:191], v[68:71]
	v_mfma_f32_16x16x32_bf16 v[64:67], v[156:159], v[188:191], v[64:67]
	s_barrier
; #define PG8_STAGE(bufoff, gbase, voff) do { _Pragma("unroll") for (int _i = 0; _i < 2; ++_i) \
;         __builtin_amdgcn_global_load_lds((const unsigned*)((const char*)(gbase) + (voff)[_i]), (PG8_LAS unsigned*)(lds + (bufoff) + ldsw + _i * 8192), 16, 0, 0); } while (0)
; #define PG8_LDA(dst, b, h) do { _Pragma("unroll") for (int m = 0; m < 4; ++m) _Pragma("unroll") for (int k = 0; k < 2; ++k) dst[m][k] = *(const PG8_LAS bf16x8*)(lds + PG8_SA(b, h) + aoff + m * 2048 + k * 1024); } while (0)
; #define PG8_LDB(dst, b, h) do { _Pragma("unroll") for (int n = 0; n < 2; ++n) _Pragma("unroll") for (int k = 0; k < 2; ++k) dst[n][k] = *(const PG8_LAS bf16x8*)(lds + PG8_SB(b, h) + boff + n * 2048 + k * 1024); } while (0)
; #define PG8_MMA(ai, bj, At, Bt) do { __builtin_amdgcn_s_setprio(1); _Pragma("unroll") for (int m = 0; m < 4; ++m) _Pragma("unroll") for (int n = 0; n < 2; ++n) _Pragma("unroll") for (int k = 0; k < 2; ++k) \
;         acc[ai][bj][m][n] = __builtin_amdgcn_mfma_f32_16x16x32_bf16(Bt[n][k], At[m][k], acc[ai][bj][m][n], 0, 0, 0); __builtin_amdgcn_s_setprio(0); } while (0)
; #define PG8_WAIT_V(n) asm volatile("s_waitcnt vmcnt(" #n ")" ::: "memory")
; template <class Epi, class Sched, bool ALIGN_EPI = false, bool SP2 = false>
; __device__ __forceinline__ void gemm_phase(PG8_LAS unsigned char* lds, const Gemm g, const Sched& S, const Epi& E) {
;     ...
;             PG8_LDB(B0, 0, 0); PG8_LDB(B1, 0, 1); PG8_SCHED; PG8_LDA(At, 0, 0); PG8_STAGE(PG8_SA(1, 1), a1 + hstep, voffA);
;             PG8_WAIT_V(8); PG8_WAIT_L(0); PG8_BAR; PG8_MMA(0, 0, At, B0); PG8_MMA(0, 1, At, B1); PG8_BAR; PG8_SCHED;
;             PG8_LDA(At, 0, 1); PG8_STAGE(PG8_SB(0, 0), b2, voffB); PG8_STAGE(PG8_SB(0, 1), b2 + hstep, voffB); PG8_STAGE(PG8_SA(0, 0), a2, voffA);
;             PG8_WAIT_V(8); PG8_WAIT_L(0); PG8_BAR; PG8_MMA(1, 0, At, B0); PG8_MMA(1, 1, At, B1); PG8_BAR; PG8_SCHED;
;             PG8_LDB(B0, 1, 0); PG8_LDB(B1, 1, 1); PG8_SCHED; PG8_LDA(At, 1, 0); PG8_STAGE(PG8_SA(0, 1), a2 + hstep, voffA);
;             PG8_WAIT_V(8); PG8_WAIT_L(0); PG8_BAR; PG8_MMA(0, 0, At, B0); PG8_MMA(0, 1, At, B1); PG8_BAR; PG8_SCHED;
;             PG8_LDA(At, 1, 1); PG8_STAGE(PG8_SB(1, 0), b3, voffB); PG8_STAGE(PG8_SB(1, 1), b3 + hstep, voffB); PG8_STAGE(PG8_SA(1, 0), a3, voffA);
;             PG8_WAIT_V(8); PG8_WAIT_L(0); PG8_BAR; PG8_MMA(1, 0, At, B0); PG8_MMA(1, 1, At, B1); PG8_BAR; PG8_SCHED;
	s_setprio 0
	s_add_i32 s38, s65, s44
	v_lshl_add_u64 v[206:207], v[206:207], 0, s[18:19]
	s_mov_b32 m0, s38
	ds_read_b128 v[160:163], v248 offset:49152
	ds_read_b128 v[164:167], v248 offset:50176
	ds_read_b128 v[168:171], v248 offset:51200
	ds_read_b128 v[172:175], v248 offset:52224
	ds_read_b128 v[176:179], v248 offset:53248
	ds_read_b128 v[180:183], v248 offset:54272
	ds_read_b128 v[184:187], v248 offset:55296
	ds_read_b128 v[188:191], v248 offset:56320
	global_load_lds_dwordx4 v[206:207], off
	s_add_i32 m0, s38, 0x2000
	s_add_u32 s36, s36, 0xb0080
	v_lshl_add_u64 v[206:207], v[208:209], 0, s[18:19]
	s_addc_u32 s37, s37, 0
	s_add_i32 s38, s66, s44
	global_load_lds_dwordx4 v[206:207], off
	v_lshl_add_u64 v[206:207], s[36:37], 0, v[194:195]
	s_mov_b32 m0, s38
	s_nop 0
	global_load_lds_dwordx4 v[206:207], off
	v_lshl_add_u64 v[206:207], s[36:37], 0, v[198:199]
	s_add_i32 m0, s38, 0x2000
	s_nop 0
	global_load_lds_dwordx4 v[206:207], off
	v_lshl_add_u64 v[206:207], v[210:211], 0, s[18:19]
	s_mov_b32 m0, s50
	s_nop 0
	global_load_lds_dwordx4 v[206:207], off
	v_lshl_add_u64 v[206:207], v[212:213], 0, s[18:19]
	s_mov_b32 m0, s51
	s_nop 0
	global_load_lds_dwordx4 v[206:207], off
	s_waitcnt vmcnt(8)
	s_waitcnt lgkmcnt(0)
	s_barrier
	s_setprio 1
	v_mfma_f32_16x16x32_bf16 v[60:63], v[112:115], v[160:163], v[60:63]
	v_mfma_f32_16x16x32_bf16 v[56:59], v[120:123], v[160:163], v[56:59]
	v_mfma_f32_16x16x32_bf16 v[44:47], v[112:115], v[168:171], v[44:47]
	v_mfma_f32_16x16x32_bf16 v[40:43], v[120:123], v[168:171], v[40:43]
	v_mfma_f32_16x16x32_bf16 v[28:31], v[112:115], v[176:179], v[28:31]
	v_mfma_f32_16x16x32_bf16 v[24:27], v[120:123], v[176:179], v[24:27]
	v_mfma_f32_16x16x32_bf16 v[12:15], v[112:115], v[184:187], v[12:15]
	v_mfma_f32_16x16x32_bf16 v[8:11], v[120:123], v[184:187], v[8:11]
	v_mfma_f32_16x16x32_bf16 v[60:63], v[116:119], v[164:167], v[60:63]
	v_mfma_f32_16x16x32_bf16 v[56:59], v[124:127], v[164:167], v[56:59]
	v_mfma_f32_16x16x32_bf16 v[44:47], v[116:119], v[172:175], v[44:47]
	v_mfma_f32_16x16x32_bf16 v[40:43], v[124:127], v[172:175], v[40:43]
	v_mfma_f32_16x16x32_bf16 v[28:31], v[116:119], v[180:183], v[28:31]
	v_mfma_f32_16x16x32_bf16 v[24:27], v[124:127], v[180:183], v[24:27]
	v_mfma_f32_16x16x32_bf16 v[12:15], v[116:119], v[188:191], v[12:15]
	v_mfma_f32_16x16x32_bf16 v[8:11], v[124:127], v[188:191], v[8:11]
	s_setprio 0
	s_setprio 1
	v_mfma_f32_16x16x32_bf16 v[52:55], v[136:139], v[160:163], v[52:55]
	v_mfma_f32_16x16x32_bf16 v[48:51], v[152:155], v[160:163], v[48:51]
	v_mfma_f32_16x16x32_bf16 v[36:39], v[136:139], v[168:171], v[36:39]
	v_mfma_f32_16x16x32_bf16 v[32:35], v[152:155], v[168:171], v[32:35]
	v_mfma_f32_16x16x32_bf16 v[20:23], v[136:139], v[176:179], v[20:23]
	v_mfma_f32_16x16x32_bf16 v[16:19], v[152:155], v[176:179], v[16:19]
	v_mfma_f32_16x16x32_bf16 v[4:7], v[136:139], v[184:187], v[4:7]
	v_mfma_f32_16x16x32_bf16 v[0:3], v[152:155], v[184:187], v[0:3]
	v_mfma_f32_16x16x32_bf16 v[52:55], v[140:143], v[164:167], v[52:55]
	v_mfma_f32_16x16x32_bf16 v[48:51], v[156:159], v[164:167], v[48:51]
	v_mfma_f32_16x16x32_bf16 v[36:39], v[140:143], v[172:175], v[36:39]
	v_mfma_f32_16x16x32_bf16 v[32:35], v[156:159], v[172:175], v[32:35]
	v_mfma_f32_16x16x32_bf16 v[20:23], v[140:143], v[180:183], v[20:23]
	v_mfma_f32_16x16x32_bf16 v[16:19], v[156:159], v[180:183], v[16:19]
	v_mfma_f32_16x16x32_bf16 v[4:7], v[140:143], v[188:191], v[4:7]
	v_mfma_f32_16x16x32_bf16 v[0:3], v[156:159], v[188:191], v[0:3]
	s_barrier
	s_setprio 0
	s_add_i32 s64, s64, 2
	s_add_u32 s34, s34, 0x100
	s_addc_u32 s35, s35, 0
	s_add_u32 s59, s59, 0x100
	s_addc_u32 s63, s63, 0
.LBB0_406:
	ds_read_b128 v[112:115], v246
	ds_read_b128 v[116:119], v246 offset:1024
	ds_read_b128 v[120:123], v246 offset:2048
	ds_read_b128 v[124:127], v246 offset:3072
	ds_read_b128 v[136:139], v247
	ds_read_b128 v[140:143], v247 offset:1024
	ds_read_b128 v[152:155], v247 offset:2048
	ds_read_b128 v[156:159], v247 offset:3072
	s_add_u32 s36, s34, 0xfff50080
	s_addc_u32 s37, s35, -1
	s_cmp_eq_u32 s64, 40
	s_cselect_b32 s39, s9, s37
	s_cselect_b32 s38, s8, s36
	s_cselect_b32 s37, s23, s63
	s_cselect_b32 s36, s22, s59
	v_lshl_add_u64 v[206:207], s[34:35], 0, v[200:201]
	s_add_i32 m0, s45, 0xc000
	ds_read_b128 v[160:163], v248
	ds_read_b128 v[164:167], v248 offset:1024
	ds_read_b128 v[168:171], v248 offset:2048
	ds_read_b128 v[172:175], v248 offset:3072
	ds_read_b128 v[176:179], v248 offset:4096
	ds_read_b128 v[180:183], v248 offset:5120
	ds_read_b128 v[184:187], v248 offset:6144
	ds_read_b128 v[188:191], v248 offset:7168
	global_load_lds_dwordx4 v[206:207], off
	v_lshl_add_u64 v[206:207], s[34:35], 0, v[202:203]
	s_add_i32 m0, s45, 0xe000
	s_nop 0
	global_load_lds_dwordx4 v[206:207], off
	s_waitcnt vmcnt(8)
	s_waitcnt lgkmcnt(0)
	s_barrier
; #define PG8_STAGE(bufoff, gbase, voff) do { _Pragma("unroll") for (int _i = 0; _i < 2; ++_i) \
;         __builtin_amdgcn_global_load_lds((const unsigned*)((const char*)(gbase) + (voff)[_i]), (PG8_LAS unsigned*)(lds + (bufoff) + ldsw + _i * 8192), 16, 0, 0); } while (0)
; #define PG8_LDA(dst, b, h) do { _Pragma("unroll") for (int m = 0; m < 4; ++m) _Pragma("unroll") for (int k = 0; k < 2; ++k) dst[m][k] = *(const PG8_LAS bf16x8*)(lds + PG8_SA(b, h) + aoff + m * 2048 + k * 1024); } while (0)
; #define PG8_MMA(ai, bj, At, Bt) do { __builtin_amdgcn_s_setprio(1); _Pragma("unroll") for (int m = 0; m < 4; ++m) _Pragma("unroll") for (int n = 0; n < 2; ++n) _Pragma("unroll") for (int k = 0; k < 2; ++k) \
;         acc[ai][bj][m][n] = __builtin_amdgcn_mfma_f32_16x16x32_bf16(Bt[n][k], At[m][k], acc[ai][bj][m][n], 0, 0, 0); __builtin_amdgcn_s_setprio(0); } while (0)
; #define PG8_WAIT_V(n) asm volatile("s_waitcnt vmcnt(" #n ")" ::: "memory")
; #define PG8_WAIT_L(n) asm volatile("s_waitcnt lgkmcnt(" #n ")" ::: "memory")
; #define PG8_BAR __builtin_amdgcn_s_barrier()
; #define PG8_SCHED __builtin_amdgcn_sched_barrier(0)
; template <class Epi, class Sched, bool ALIGN_EPI = false, bool SP2 = false>
; __device__ __forceinline__ void gemm_phase(PG8_LAS unsigned char* lds, const Gemm g, const Sched& S, const Epi& E) {
;     ...
;             PG8_WAIT_V(8); PG8_WAIT_L(0); PG8_BAR; PG8_MMA(0, 0, At, B0); PG8_MMA(0, 1, At, B1); PG8_BAR; PG8_SCHED;
;             PG8_LDA(At, 0, 1); PG8_STAGE(PG8_SB(0, 0), b2, voffB); PG8_STAGE(PG8_SB(0, 1), b2 + hstep, voffB); PG8_STAGE(PG8_SA(0, 0), a2, voffA);
;             PG8_WAIT_V(8); PG8_WAIT_L(0); PG8_BAR; PG8_MMA(1, 0, At, B0); PG8_MMA(1, 1, At, B1); PG8_BAR; PG8_SCHED;
	s_setprio 1
	v_mfma_f32_16x16x32_bf16 v[148:151], v[112:115], v[160:163], v[148:151]
	v_mfma_f32_16x16x32_bf16 v[144:147], v[120:123], v[160:163], v[144:147]
	v_mfma_f32_16x16x32_bf16 v[108:111], v[112:115], v[168:171], v[108:111]
	v_mfma_f32_16x16x32_bf16 v[104:107], v[120:123], v[168:171], v[104:107]
	v_mfma_f32_16x16x32_bf16 v[92:95], v[112:115], v[176:179], v[92:95]
	v_mfma_f32_16x16x32_bf16 v[88:91], v[120:123], v[176:179], v[88:91]
	v_mfma_f32_16x16x32_bf16 v[76:79], v[112:115], v[184:187], v[76:79]
	v_mfma_f32_16x16x32_bf16 v[72:75], v[120:123], v[184:187], v[72:75]
	v_mfma_f32_16x16x32_bf16 v[148:151], v[116:119], v[164:167], v[148:151]
	v_mfma_f32_16x16x32_bf16 v[144:147], v[124:127], v[164:167], v[144:147]
	v_mfma_f32_16x16x32_bf16 v[108:111], v[116:119], v[172:175], v[108:111]
	v_mfma_f32_16x16x32_bf16 v[104:107], v[124:127], v[172:175], v[104:107]
	v_mfma_f32_16x16x32_bf16 v[92:95], v[116:119], v[180:183], v[92:95]
	v_mfma_f32_16x16x32_bf16 v[88:91], v[124:127], v[180:183], v[88:91]
	v_mfma_f32_16x16x32_bf16 v[76:79], v[116:119], v[188:191], v[76:79]
	v_mfma_f32_16x16x32_bf16 v[72:75], v[124:127], v[188:191], v[72:75]
	s_setprio 0
	s_setprio 1
	v_mfma_f32_16x16x32_bf16 v[132:135], v[136:139], v[160:163], v[132:135]
	v_mfma_f32_16x16x32_bf16 v[128:131], v[152:155], v[160:163], v[128:131]
	v_mfma_f32_16x16x32_bf16 v[100:103], v[136:139], v[168:171], v[100:103]
	v_mfma_f32_16x16x32_bf16 v[96:99], v[152:155], v[168:171], v[96:99]
	v_mfma_f32_16x16x32_bf16 v[84:87], v[136:139], v[176:179], v[84:87]
	v_mfma_f32_16x16x32_bf16 v[80:83], v[152:155], v[176:179], v[80:83]
	v_mfma_f32_16x16x32_bf16 v[68:71], v[136:139], v[184:187], v[68:71]
	v_mfma_f32_16x16x32_bf16 v[64:67], v[152:155], v[184:187], v[64:67]
	v_mfma_f32_16x16x32_bf16 v[132:135], v[140:143], v[164:167], v[132:135]
	v_mfma_f32_16x16x32_bf16 v[128:131], v[156:159], v[164:167], v[128:131]
	v_mfma_f32_16x16x32_bf16 v[100:103], v[140:143], v[172:175], v[100:103]
	v_mfma_f32_16x16x32_bf16 v[96:99], v[156:159], v[172:175], v[96:99]
	v_mfma_f32_16x16x32_bf16 v[84:87], v[140:143], v[180:183], v[84:87]
	v_mfma_f32_16x16x32_bf16 v[80:83], v[156:159], v[180:183], v[80:83]
	v_mfma_f32_16x16x32_bf16 v[68:71], v[140:143], v[188:191], v[68:71]
	v_mfma_f32_16x16x32_bf16 v[64:67], v[156:159], v[188:191], v[64:67]
	s_barrier
	s_setprio 0
	s_add_i32 s65, s53, s44
	v_lshl_add_u64 v[206:207], s[36:37], 0, v[194:195]
	s_mov_b32 m0, s65
	ds_read_b128 v[160:163], v248 offset:16384
	ds_read_b128 v[164:167], v248 offset:17408
	ds_read_b128 v[168:171], v248 offset:18432
	ds_read_b128 v[172:175], v248 offset:19456
	ds_read_b128 v[176:179], v248 offset:20480
	ds_read_b128 v[180:183], v248 offset:21504
	ds_read_b128 v[184:187], v248 offset:22528
	ds_read_b128 v[188:191], v248 offset:23552
	global_load_lds_dwordx4 v[206:207], off
	s_add_i32 m0, s65, 0x2000
	s_add_u32 s66, s36, 0xb0000
	v_lshl_add_u64 v[208:209], s[36:37], 0, v[198:199]
	s_addc_u32 s67, s37, 0
	s_add_i32 s65, s54, s44
	global_load_lds_dwordx4 v[208:209], off
	v_lshl_add_u64 v[210:211], s[66:67], 0, v[194:195]
	s_mov_b32 m0, s65
	v_lshl_add_u64 v[212:213], s[38:39], 0, v[196:197]
	global_load_lds_dwordx4 v[210:211], off
	v_lshl_add_u64 v[210:211], s[66:67], 0, v[198:199]
	s_add_i32 m0, s65, 0x2000
	s_nop 0
	global_load_lds_dwordx4 v[210:211], off
	v_lshl_add_u64 v[210:211], s[38:39], 0, v[192:193]
	s_mov_b32 m0, s45
	s_nop 0
	global_load_lds_dwordx4 v[210:211], off
	s_mov_b32 m0, s46
	s_nop 0
	global_load_lds_dwordx4 v[212:213], off
	s_waitcnt vmcnt(8)
	s_waitcnt lgkmcnt(0)
	s_barrier
	s_setprio 1
	v_mfma_f32_16x16x32_bf16 v[60:63], v[112:115], v[160:163], v[60:63]
	v_mfma_f32_16x16x32_bf16 v[56:59], v[120:123], v[160:163], v[56:59]
	v_mfma_f32_16x16x32_bf16 v[44:47], v[112:115], v[168:171], v[44:47]
	v_mfma_f32_16x16x32_bf16 v[40:43], v[120:123], v[168:171], v[40:43]
	v_mfma_f32_16x16x32_bf16 v[28:31], v[112:115], v[176:179], v[28:31]
	v_mfma_f32_16x16x32_bf16 v[24:27], v[120:123], v[176:179], v[24:27]
	v_mfma_f32_16x16x32_bf16 v[12:15], v[112:115], v[184:187], v[12:15]
	v_mfma_f32_16x16x32_bf16 v[8:11], v[120:123], v[184:187], v[8:11]
	v_mfma_f32_16x16x32_bf16 v[60:63], v[116:119], v[164:167], v[60:63]
	v_mfma_f32_16x16x32_bf16 v[56:59], v[124:127], v[164:167], v[56:59]
	v_mfma_f32_16x16x32_bf16 v[44:47], v[116:119], v[172:175], v[44:47]
	v_mfma_f32_16x16x32_bf16 v[40:43], v[124:127], v[172:175], v[40:43]
	v_mfma_f32_16x16x32_bf16 v[28:31], v[116:119], v[180:183], v[28:31]
	v_mfma_f32_16x16x32_bf16 v[24:27], v[124:127], v[180:183], v[24:27]
	v_mfma_f32_16x16x32_bf16 v[12:15], v[116:119], v[188:191], v[12:15]
	v_mfma_f32_16x16x32_bf16 v[8:11], v[124:127], v[188:191], v[8:11]
	s_setprio 0
	s_setprio 1
	v_mfma_f32_16x16x32_bf16 v[52:55], v[136:139], v[160:163], v[52:55]
	v_mfma_f32_16x16x32_bf16 v[48:51], v[152:155], v[160:163], v[48:51]
	v_mfma_f32_16x16x32_bf16 v[36:39], v[136:139], v[168:171], v[36:39]
	v_mfma_f32_16x16x32_bf16 v[32:35], v[152:155], v[168:171], v[32:35]
	v_mfma_f32_16x16x32_bf16 v[20:23], v[136:139], v[176:179], v[20:23]
	v_mfma_f32_16x16x32_bf16 v[16:19], v[152:155], v[176:179], v[16:19]
	v_mfma_f32_16x16x32_bf16 v[4:7], v[136:139], v[184:187], v[4:7]
	v_mfma_f32_16x16x32_bf16 v[0:3], v[152:155], v[184:187], v[0:3]
	v_mfma_f32_16x16x32_bf16 v[52:55], v[140:143], v[164:167], v[52:55]
	v_mfma_f32_16x16x32_bf16 v[48:51], v[156:159], v[164:167], v[48:51]
	v_mfma_f32_16x16x32_bf16 v[36:39], v[140:143], v[172:175], v[36:39]
	v_mfma_f32_16x16x32_bf16 v[32:35], v[156:159], v[172:175], v[32:35]
	v_mfma_f32_16x16x32_bf16 v[20:23], v[140:143], v[180:183], v[20:23]
	v_mfma_f32_16x16x32_bf16 v[16:19], v[156:159], v[180:183], v[16:19]
	v_mfma_f32_16x16x32_bf16 v[4:7], v[140:143], v[188:191], v[4:7]
	v_mfma_f32_16x16x32_bf16 v[0:3], v[156:159], v[188:191], v[0:3]
	s_barrier
; #define PG8_STAGE(bufoff, gbase, voff) do { _Pragma("unroll") for (int _i = 0; _i < 2; ++_i) \
;         __builtin_amdgcn_global_load_lds((const unsigned*)((const char*)(gbase) + (voff)[_i]), (PG8_LAS unsigned*)(lds + (bufoff) + ldsw + _i * 8192), 16, 0, 0); } while (0)
; #define PG8_LDA(dst, b, h) do { _Pragma("unroll") for (int m = 0; m < 4; ++m) _Pragma("unroll") for (int k = 0; k < 2; ++k) dst[m][k] = *(const PG8_LAS bf16x8*)(lds + PG8_SA(b, h) + aoff + m * 2048 + k * 1024); } while (0)
; #define PG8_LDB(dst, b, h) do { _Pragma("unroll") for (int n = 0; n < 2; ++n) _Pragma("unroll") for (int k = 0; k < 2; ++k) dst[n][k] = *(const PG8_LAS bf16x8*)(lds + PG8_SB(b, h) + boff + n * 2048 + k * 1024); } while (0)
; #define PG8_MMA(ai, bj, At, Bt) do { __builtin_amdgcn_s_setprio(1); _Pragma("unroll") for (int m = 0; m < 4; ++m) _Pragma("unroll") for (int n = 0; n < 2; ++n) _Pragma("unroll") for (int k = 0; k < 2; ++k) \
;         acc[ai][bj][m][n] = __builtin_amdgcn_mfma_f32_16x16x32_bf16(Bt[n][k], At[m][k], acc[ai][bj][m][n], 0, 0, 0); __builtin_amdgcn_s_setprio(0); } while (0)
; #define PG8_WAIT_V(n) asm volatile("s_waitcnt vmcnt(" #n ")" ::: "memory")
; #define PG8_WAIT_L(n) asm volatile("s_waitcnt lgkmcnt(" #n ")" ::: "memory")
; #define PG8_BAR __builtin_amdgcn_s_barrier()
; #define PG8_SCHED __builtin_amdgcn_sched_barrier(0)
; template <class Epi, class Sched, bool ALIGN_EPI = false, bool SP2 = false>
; __device__ __forceinline__ void gemm_phase(PG8_LAS unsigned char* lds, const Gemm g, const Sched& S, const Epi& E) {
;     ...
;             PG8_LDB(B0, 1, 0); PG8_LDB(B1, 1, 1); PG8_SCHED; PG8_LDA(At, 1, 0); PG8_STAGE(PG8_SA(0, 1), a2 + hstep, voffA);
;             PG8_WAIT_V(8); PG8_WAIT_L(0); PG8_BAR; PG8_MMA(0, 0, At, B0); PG8_MMA(0, 1, At, B1); PG8_BAR; PG8_SCHED;
	s_setprio 0
	s_add_i32 s65, 0, 0x18000
	s_add_i32 s66, 0, 0x1c000
	v_add_u32_e32 v124, s65, v244
	v_add_u32_e32 v156, s66, v244
	ds_read_b128 v[112:115], v124
	ds_read_b128 v[116:119], v124 offset:1024
	ds_read_b128 v[120:123], v124 offset:2048
	ds_read_b128 v[124:127], v124 offset:3072
	ds_read_b128 v[136:139], v156
	ds_read_b128 v[140:143], v156 offset:1024
	ds_read_b128 v[152:155], v156 offset:2048
	ds_read_b128 v[156:159], v156 offset:3072
	s_add_u32 s38, s38, 0xb0000
	s_addc_u32 s39, s39, 0
	s_mov_b32 m0, s47
	v_lshl_add_u64 v[214:215], s[38:39], 0, v[192:193]
	ds_read_b128 v[160:163], v248 offset:32768
	ds_read_b128 v[164:167], v248 offset:33792
	ds_read_b128 v[168:171], v248 offset:34816
	ds_read_b128 v[172:175], v248 offset:35840
	ds_read_b128 v[176:179], v248 offset:36864
	ds_read_b128 v[180:183], v248 offset:37888
	ds_read_b128 v[184:187], v248 offset:38912
	ds_read_b128 v[188:191], v248 offset:39936
	global_load_lds_dwordx4 v[214:215], off
	v_lshl_add_u64 v[214:215], s[38:39], 0, v[196:197]
	s_mov_b32 m0, s48
	s_nop 0
	global_load_lds_dwordx4 v[214:215], off
	s_waitcnt vmcnt(8)
	s_waitcnt lgkmcnt(0)
	s_barrier
	s_setprio 1
	v_mfma_f32_16x16x32_bf16 v[148:151], v[112:115], v[160:163], v[148:151]
	v_mfma_f32_16x16x32_bf16 v[144:147], v[120:123], v[160:163], v[144:147]
	v_mfma_f32_16x16x32_bf16 v[108:111], v[112:115], v[168:171], v[108:111]
	v_mfma_f32_16x16x32_bf16 v[104:107], v[120:123], v[168:171], v[104:107]
	v_mfma_f32_16x16x32_bf16 v[92:95], v[112:115], v[176:179], v[92:95]
	v_mfma_f32_16x16x32_bf16 v[88:91], v[120:123], v[176:179], v[88:91]
	v_mfma_f32_16x16x32_bf16 v[76:79], v[112:115], v[184:187], v[76:79]
	v_mfma_f32_16x16x32_bf16 v[72:75], v[120:123], v[184:187], v[72:75]
	v_mfma_f32_16x16x32_bf16 v[148:151], v[116:119], v[164:167], v[148:151]
	v_mfma_f32_16x16x32_bf16 v[144:147], v[124:127], v[164:167], v[144:147]
	v_mfma_f32_16x16x32_bf16 v[108:111], v[116:119], v[172:175], v[108:111]
	v_mfma_f32_16x16x32_bf16 v[104:107], v[124:127], v[172:175], v[104:107]
	v_mfma_f32_16x16x32_bf16 v[92:95], v[116:119], v[180:183], v[92:95]
	v_mfma_f32_16x16x32_bf16 v[88:91], v[124:127], v[180:183], v[88:91]
	v_mfma_f32_16x16x32_bf16 v[76:79], v[116:119], v[188:191], v[76:79]
	v_mfma_f32_16x16x32_bf16 v[72:75], v[124:127], v[188:191], v[72:75]
	s_setprio 0
	s_setprio 1
	v_mfma_f32_16x16x32_bf16 v[132:135], v[136:139], v[160:163], v[132:135]
	v_mfma_f32_16x16x32_bf16 v[128:131], v[152:155], v[160:163], v[128:131]
	v_mfma_f32_16x16x32_bf16 v[100:103], v[136:139], v[168:171], v[100:103]
	v_mfma_f32_16x16x32_bf16 v[96:99], v[152:155], v[168:171], v[96:99]
	v_mfma_f32_16x16x32_bf16 v[84:87], v[136:139], v[176:179], v[84:87]
	v_mfma_f32_16x16x32_bf16 v[80:83], v[152:155], v[176:179], v[80:83]
	v_mfma_f32_16x16x32_bf16 v[68:71], v[136:139], v[184:187], v[68:71]
	v_mfma_f32_16x16x32_bf16 v[64:67], v[152:155], v[184:187], v[64:67]
	v_mfma_f32_16x16x32_bf16 v[132:135], v[140:143], v[164:167], v[132:135]
	v_mfma_f32_16x16x32_bf16 v[128:131], v[156:159], v[164:167], v[128:131]
	v_mfma_f32_16x16x32_bf16 v[100:103], v[140:143], v[172:175], v[100:103]
	v_mfma_f32_16x16x32_bf16 v[96:99], v[156:159], v[172:175], v[96:99]
	v_mfma_f32_16x16x32_bf16 v[84:87], v[140:143], v[180:183], v[84:87]
	v_mfma_f32_16x16x32_bf16 v[80:83], v[156:159], v[180:183], v[80:83]
	v_mfma_f32_16x16x32_bf16 v[68:71], v[140:143], v[188:191], v[68:71]
	v_mfma_f32_16x16x32_bf16 v[64:67], v[156:159], v[188:191], v[64:67]
	s_barrier
; #define PG8_STAGE(bufoff, gbase, voff) do { _Pragma("unroll") for (int _i = 0; _i < 2; ++_i) \
;         __builtin_amdgcn_global_load_lds((const unsigned*)((const char*)(gbase) + (voff)[_i]), (PG8_LAS unsigned*)(lds + (bufoff) + ldsw + _i * 8192), 16, 0, 0); } while (0)
; #define PG8_LDA(dst, b, h) do { _Pragma("unroll") for (int m = 0; m < 4; ++m) _Pragma("unroll") for (int k = 0; k < 2; ++k) dst[m][k] = *(const PG8_LAS bf16x8*)(lds + PG8_SA(b, h) + aoff + m * 2048 + k * 1024); } while (0)
; #define PG8_MMA(ai, bj, At, Bt) do { __builtin_amdgcn_s_setprio(1); _Pragma("unroll") for (int m = 0; m < 4; ++m) _Pragma("unroll") for (int n = 0; n < 2; ++n) _Pragma("unroll") for (int k = 0; k < 2; ++k) \
;         acc[ai][bj][m][n] = __builtin_amdgcn_mfma_f32_16x16x32_bf16(Bt[n][k], At[m][k], acc[ai][bj][m][n], 0, 0, 0); __builtin_amdgcn_s_setprio(0); } while (0)
; #define PG8_WAIT_V(n) asm volatile("s_waitcnt vmcnt(" #n ")" ::: "memory")
; #define PG8_WAIT_L(n) asm volatile("s_waitcnt lgkmcnt(" #n ")" ::: "memory")
; #define PG8_BAR __builtin_amdgcn_s_barrier()
; #define PG8_SCHED __builtin_amdgcn_sched_barrier(0)
; template <class Epi, class Sched, bool ALIGN_EPI = false, bool SP2 = false>
; __device__ __forceinline__ void gemm_phase(PG8_LAS unsigned char* lds, const Gemm g, const Sched& S, const Epi& E) {
;     ...
;             PG8_LDA(At, 1, 1); PG8_STAGE(PG8_SB(1, 0), b3, voffB); PG8_STAGE(PG8_SB(1, 1), b3 + hstep, voffB); PG8_STAGE(PG8_SA(1, 0), a3, voffA);
;             PG8_WAIT_V(8); PG8_WAIT_L(0); PG8_BAR; PG8_MMA(1, 0, At, B0); PG8_MMA(1, 1, At, B1); PG8_BAR; PG8_SCHED;
;     ...
;         if constexpr (ALIGN_EPI) { if (wr == 0) PG8_BAR; }
	s_setprio 0
	s_add_i32 s38, s65, s44
	v_lshl_add_u64 v[206:207], v[206:207], 0, s[18:19]
	s_mov_b32 m0, s38
	ds_read_b128 v[160:163], v248 offset:49152
	ds_read_b128 v[164:167], v248 offset:50176
	ds_read_b128 v[168:171], v248 offset:51200
	ds_read_b128 v[172:175], v248 offset:52224
	ds_read_b128 v[176:179], v248 offset:53248
	ds_read_b128 v[180:183], v248 offset:54272
	ds_read_b128 v[184:187], v248 offset:55296
	ds_read_b128 v[188:191], v248 offset:56320
	global_load_lds_dwordx4 v[206:207], off
	s_add_i32 m0, s38, 0x2000
	s_add_u32 s36, s36, 0xb0080
	v_lshl_add_u64 v[206:207], v[208:209], 0, s[18:19]
	s_addc_u32 s37, s37, 0
	s_add_i32 s38, s66, s44
	global_load_lds_dwordx4 v[206:207], off
	v_lshl_add_u64 v[206:207], s[36:37], 0, v[194:195]
	s_mov_b32 m0, s38
	s_nop 0
	global_load_lds_dwordx4 v[206:207], off
	v_lshl_add_u64 v[206:207], s[36:37], 0, v[198:199]
	s_add_i32 m0, s38, 0x2000
	s_nop 0
	global_load_lds_dwordx4 v[206:207], off
	v_lshl_add_u64 v[206:207], v[210:211], 0, s[18:19]
	s_mov_b32 m0, s50
	s_nop 0
	global_load_lds_dwordx4 v[206:207], off
	v_lshl_add_u64 v[206:207], v[212:213], 0, s[18:19]
	s_mov_b32 m0, s51
	s_nop 0
	global_load_lds_dwordx4 v[206:207], off
	s_waitcnt vmcnt(8)
	s_waitcnt lgkmcnt(0)
	s_barrier
	s_setprio 1
	v_mfma_f32_16x16x32_bf16 v[60:63], v[112:115], v[160:163], v[60:63]
	v_mfma_f32_16x16x32_bf16 v[56:59], v[120:123], v[160:163], v[56:59]
	v_mfma_f32_16x16x32_bf16 v[44:47], v[112:115], v[168:171], v[44:47]
	v_mfma_f32_16x16x32_bf16 v[40:43], v[120:123], v[168:171], v[40:43]
	v_mfma_f32_16x16x32_bf16 v[28:31], v[112:115], v[176:179], v[28:31]
	v_mfma_f32_16x16x32_bf16 v[24:27], v[120:123], v[176:179], v[24:27]
	v_mfma_f32_16x16x32_bf16 v[12:15], v[112:115], v[184:187], v[12:15]
	v_mfma_f32_16x16x32_bf16 v[8:11], v[120:123], v[184:187], v[8:11]
	v_mfma_f32_16x16x32_bf16 v[60:63], v[116:119], v[164:167], v[60:63]
	v_mfma_f32_16x16x32_bf16 v[56:59], v[124:127], v[164:167], v[56:59]
	v_mfma_f32_16x16x32_bf16 v[44:47], v[116:119], v[172:175], v[44:47]
	v_mfma_f32_16x16x32_bf16 v[40:43], v[124:127], v[172:175], v[40:43]
	v_mfma_f32_16x16x32_bf16 v[28:31], v[116:119], v[180:183], v[28:31]
	v_mfma_f32_16x16x32_bf16 v[24:27], v[124:127], v[180:183], v[24:27]
	v_mfma_f32_16x16x32_bf16 v[12:15], v[116:119], v[188:191], v[12:15]
	v_mfma_f32_16x16x32_bf16 v[8:11], v[124:127], v[188:191], v[8:11]
	s_setprio 0
	s_setprio 1
	v_mfma_f32_16x16x32_bf16 v[52:55], v[136:139], v[160:163], v[52:55]
	v_mfma_f32_16x16x32_bf16 v[48:51], v[152:155], v[160:163], v[48:51]
	v_mfma_f32_16x16x32_bf16 v[36:39], v[136:139], v[168:171], v[36:39]
	v_mfma_f32_16x16x32_bf16 v[32:35], v[152:155], v[168:171], v[32:35]
	v_mfma_f32_16x16x32_bf16 v[20:23], v[136:139], v[176:179], v[20:23]
	v_mfma_f32_16x16x32_bf16 v[16:19], v[152:155], v[176:179], v[16:19]
	v_mfma_f32_16x16x32_bf16 v[4:7], v[136:139], v[184:187], v[4:7]
	v_mfma_f32_16x16x32_bf16 v[0:3], v[152:155], v[184:187], v[0:3]
	v_mfma_f32_16x16x32_bf16 v[52:55], v[140:143], v[164:167], v[52:55]
	v_mfma_f32_16x16x32_bf16 v[48:51], v[156:159], v[164:167], v[48:51]
	v_mfma_f32_16x16x32_bf16 v[36:39], v[140:143], v[172:175], v[36:39]
	v_mfma_f32_16x16x32_bf16 v[32:35], v[156:159], v[172:175], v[32:35]
	v_mfma_f32_16x16x32_bf16 v[20:23], v[140:143], v[180:183], v[20:23]
	v_mfma_f32_16x16x32_bf16 v[16:19], v[156:159], v[180:183], v[16:19]
	v_mfma_f32_16x16x32_bf16 v[4:7], v[140:143], v[188:191], v[4:7]
	v_mfma_f32_16x16x32_bf16 v[0:3], v[156:159], v[188:191], v[0:3]
	s_barrier
	s_setprio 0
	s_add_i32 s64, s64, 2
	s_add_u32 s34, s34, 0x100
	s_addc_u32 s35, s35, 0
	s_add_u32 s59, s59, 0x100
	s_addc_u32 s63, s63, 0
	s_cmp_gt_u32 s64, 41
	s_cbranch_scc0 .LBB0_406
	s_and_b64 vcc, exec, s[20:21]
	s_cbranch_vccz .LBB0_409
	s_barrier

; #define PG8_STAGE(bufoff, gbase, voff) do { _Pragma("unroll") for (int _i = 0; _i < 2; ++_i) \
;         __builtin_amdgcn_global_load_lds((const unsigned*)((const char*)(gbase) + (voff)[_i]), (PG8_LAS unsigned*)(lds + (bufoff) + ldsw + _i * 8192), 16, 0, 0); } while (0)
; #define PG8_LDA(dst, b, h) do { _Pragma("unroll") for (int m = 0; m < 4; ++m) _Pragma("unroll") for (int k = 0; k < 2; ++k) dst[m][k] = *(const PG8_LAS bf16x8*)(lds + PG8_SA(b, h) + aoff + m * 2048 + k * 1024); } while (0)
; #define PG8_LDB(dst, b, h) do { _Pragma("unroll") for (int n = 0; n < 2; ++n) _Pragma("unroll") for (int k = 0; k < 2; ++k) dst[n][k] = *(const PG8_LAS bf16x8*)(lds + PG8_SB(b, h) + boff + n * 2048 + k * 1024); } while (0)
; #define PG8_WAIT_V(n) asm volatile("s_waitcnt vmcnt(" #n ")" ::: "memory")
; #define PG8_WAIT_L(n) asm volatile("s_waitcnt lgkmcnt(" #n ")" ::: "memory")
; template <class Epi, class Sched, bool ALIGN_EPI = false, bool SP2 = false>
; __device__ __forceinline__ void gemm_phase(PG8_LAS unsigned char* lds, const Gemm g, const Sched& S, const Epi& E) {
;     ...
;         const bool has_next = S.next(ui + 1, nxt);
;         const char* nA = has_next ? (const char*)g.A + (size_t)nxt.pm * tstep : cA; const char* nB = has_next ? (const char*)g.Bt + (size_t)nxt.pn * tstep : cB;
;         for (int t = 0; t < nt; t += 2) {
;             const bool last = (t == nt - 2);
;             if constexpr (Epi::PREFETCH) { if (t == nt - 4) E.prefetch(cur, lds + STAGE_BYTES + 1024, tid); }
;             const char* a1 = cA + (size_t)(t + 1) * kstep;
;             const char* a2 = last ? nA : cA + (size_t)(t + 2) * kstep; const char* b2 = last ? nB : cB + (size_t)(t + 2) * kstep;
;             const char* a3 = a2 + kstep; const char* b3 = b2 + kstep;
;             if (last && has_next) S.a_ready(nxt);
;             if constexpr (SP2) {
;             PG8_LDB(B0, 0, 0); PG8_LDB(B1, 0, 1); PG8_SCHED; PG8_LDA(At, 0, 0); PG8_STAGE(PG8_SA(1, 1), a1 + hstep, voffA);
;             PG8_WAIT_V(8); PG8_WAIT_L(0); PG8_BAR; PG8_MMA(0, 0, At, B0); PG8_MMA(0, 1, At, B1); PG8_BAR; PG8_SCHED;
;             PG8_LDA(At, 0, 1); PG8_STAGE(PG8_SB(0, 0), b2, voffB); PG8_STAGE(PG8_SB(0, 1), b2 + hstep, voffB); PG8_STAGE(PG8_SA(0, 0), a2, voffA);
;             PG8_WAIT_V(8); PG8_WAIT_L(0); PG8_BAR; PG8_MMA(1, 0, At, B0); PG8_MMA(1, 1, At, B1); PG8_BAR; PG8_SCHED;
.LBB0_592:
	s_ashr_i32 s37, s36, 31
	s_lshl_b64 s[38:39], s[36:37], 19
	s_add_u32 s38, s53, s38
	s_addc_u32 s39, s54, s39
	s_and_b64 s[40:41], s[4:5], exec
	s_cselect_b32 s37, s39, s45
	s_cselect_b32 s76, s38, s44
	s_ashr_i32 s35, s34, 31
	s_lshl_b64 s[40:41], s[34:35], 19
	s_add_u32 s40, s50, s40
	s_addc_u32 s41, s51, s41
	s_and_b64 s[48:49], s[4:5], exec
	s_cselect_b32 s35, s41, s47
	s_cselect_b32 s77, s40, s46
	s_add_u32 s44, s44, 0x40080
	s_addc_u32 s45, s45, 0
	s_add_u32 s78, s46, 0x100
	s_addc_u32 s79, s47, 0
	s_mov_b32 s80, -2
	ds_read_b128 v[144:147], v151
	ds_read_b128 v[156:159], v151 offset:1024
	ds_read_b128 v[160:163], v151 offset:2048
	ds_read_b128 v[164:167], v151 offset:3072
	ds_read_b128 v[168:171], v152
	ds_read_b128 v[172:175], v152 offset:1024
	ds_read_b128 v[176:179], v152 offset:2048
	ds_read_b128 v[180:183], v152 offset:3072
	s_add_u32 s46, s44, 0xfffc0080
	s_addc_u32 s47, s45, -1
	s_cmp_eq_u32 s80, 12
	s_cselect_b32 s49, s37, s47
	s_cselect_b32 s48, s76, s46
	s_cselect_b32 s47, s35, s79
	s_cselect_b32 s46, s77, s78
	v_lshl_add_u64 v[216:217], s[44:45], 0, v[136:137]
	s_add_i32 m0, s43, 0xc000
	ds_read_b128 v[184:187], v153
	ds_read_b128 v[188:191], v153 offset:1024
	ds_read_b128 v[192:195], v153 offset:2048
	ds_read_b128 v[196:199], v153 offset:3072
	ds_read_b128 v[200:203], v153 offset:4096
	ds_read_b128 v[204:207], v153 offset:5120
	ds_read_b128 v[208:211], v153 offset:6144
	ds_read_b128 v[212:215], v153 offset:7168
	global_load_lds_dwordx4 v[216:217], off
	v_lshl_add_u64 v[216:217], s[44:45], 0, v[138:139]
	s_add_i32 m0, s43, 0xe000
	s_nop 0
	global_load_lds_dwordx4 v[216:217], off
	s_waitcnt vmcnt(8)
	s_waitcnt lgkmcnt(0)
	s_barrier
	s_setprio 1
	v_mfma_f32_16x16x32_bf16 v[124:127], v[144:147], v[184:187], 0
	v_mfma_f32_16x16x32_bf16 v[120:123], v[160:163], v[184:187], 0
	v_mfma_f32_16x16x32_bf16 v[108:111], v[144:147], v[192:195], 0
	v_mfma_f32_16x16x32_bf16 v[104:107], v[160:163], v[192:195], 0
	v_mfma_f32_16x16x32_bf16 v[92:95], v[144:147], v[200:203], 0
	v_mfma_f32_16x16x32_bf16 v[88:91], v[160:163], v[200:203], 0
	v_mfma_f32_16x16x32_bf16 v[76:79], v[144:147], v[208:211], 0
	v_mfma_f32_16x16x32_bf16 v[72:75], v[160:163], v[208:211], 0
	v_mfma_f32_16x16x32_bf16 v[124:127], v[156:159], v[188:191], v[124:127]
	v_mfma_f32_16x16x32_bf16 v[120:123], v[164:167], v[188:191], v[120:123]
	v_mfma_f32_16x16x32_bf16 v[108:111], v[156:159], v[196:199], v[108:111]
	v_mfma_f32_16x16x32_bf16 v[104:107], v[164:167], v[196:199], v[104:107]
	v_mfma_f32_16x16x32_bf16 v[92:95], v[156:159], v[204:207], v[92:95]
	v_mfma_f32_16x16x32_bf16 v[88:91], v[164:167], v[204:207], v[88:91]
	v_mfma_f32_16x16x32_bf16 v[76:79], v[156:159], v[212:215], v[76:79]
	v_mfma_f32_16x16x32_bf16 v[72:75], v[164:167], v[212:215], v[72:75]
	s_setprio 0
	s_setprio 1
	v_mfma_f32_16x16x32_bf16 v[116:119], v[168:171], v[184:187], 0
	v_mfma_f32_16x16x32_bf16 v[112:115], v[176:179], v[184:187], 0
	v_mfma_f32_16x16x32_bf16 v[100:103], v[168:171], v[192:195], 0
	v_mfma_f32_16x16x32_bf16 v[96:99], v[176:179], v[192:195], 0
	v_mfma_f32_16x16x32_bf16 v[84:87], v[168:171], v[200:203], 0
	v_mfma_f32_16x16x32_bf16 v[80:83], v[176:179], v[200:203], 0
	v_mfma_f32_16x16x32_bf16 v[68:71], v[168:171], v[208:211], 0
	v_mfma_f32_16x16x32_bf16 v[64:67], v[176:179], v[208:211], 0
	v_mfma_f32_16x16x32_bf16 v[116:119], v[172:175], v[188:191], v[116:119]
	v_mfma_f32_16x16x32_bf16 v[112:115], v[180:183], v[188:191], v[112:115]
	v_mfma_f32_16x16x32_bf16 v[100:103], v[172:175], v[196:199], v[100:103]
	v_mfma_f32_16x16x32_bf16 v[96:99], v[180:183], v[196:199], v[96:99]
	v_mfma_f32_16x16x32_bf16 v[84:87], v[172:175], v[204:207], v[84:87]
	v_mfma_f32_16x16x32_bf16 v[80:83], v[180:183], v[204:207], v[80:83]
	v_mfma_f32_16x16x32_bf16 v[68:71], v[172:175], v[212:215], v[68:71]
	v_mfma_f32_16x16x32_bf16 v[64:67], v[180:183], v[212:215], v[64:67]
	s_barrier
	s_setprio 0
	s_add_i32 s81, s69, s52
	v_lshl_add_u64 v[216:217], s[46:47], 0, v[132:133]
	s_mov_b32 m0, s81
	ds_read_b128 v[184:187], v153 offset:16384
	ds_read_b128 v[188:191], v153 offset:17408
	ds_read_b128 v[192:195], v153 offset:18432
	ds_read_b128 v[196:199], v153 offset:19456
	ds_read_b128 v[200:203], v153 offset:20480
	ds_read_b128 v[204:207], v153 offset:21504
	ds_read_b128 v[208:211], v153 offset:22528
	ds_read_b128 v[212:215], v153 offset:23552
	global_load_lds_dwordx4 v[216:217], off
	s_add_i32 m0, s81, 0x2000
	s_add_u32 s82, s46, 0x40000
	v_lshl_add_u64 v[218:219], s[46:47], 0, v[128:129]
	s_addc_u32 s83, s47, 0
	s_add_i32 s81, s70, s52
	global_load_lds_dwordx4 v[218:219], off
	v_lshl_add_u64 v[220:221], s[82:83], 0, v[132:133]
	s_mov_b32 m0, s81
	v_lshl_add_u64 v[222:223], s[48:49], 0, v[130:131]
	global_load_lds_dwordx4 v[220:221], off
	v_lshl_add_u64 v[220:221], s[82:83], 0, v[128:129]
	s_add_i32 m0, s81, 0x2000
	s_nop 0
	global_load_lds_dwordx4 v[220:221], off
	v_lshl_add_u64 v[220:221], s[48:49], 0, v[134:135]
	s_mov_b32 m0, s43
	s_nop 0
	global_load_lds_dwordx4 v[220:221], off
	s_mov_b32 m0, s56
	s_nop 0
	global_load_lds_dwordx4 v[222:223], off
	s_waitcnt vmcnt(8)
	s_waitcnt lgkmcnt(0)
	s_barrier
; #define PG8_STAGE(bufoff, gbase, voff) do { _Pragma("unroll") for (int _i = 0; _i < 2; ++_i) \
;         __builtin_amdgcn_global_load_lds((const unsigned*)((const char*)(gbase) + (voff)[_i]), (PG8_LAS unsigned*)(lds + (bufoff) + ldsw + _i * 8192), 16, 0, 0); } while (0)
; #define PG8_LDA(dst, b, h) do { _Pragma("unroll") for (int m = 0; m < 4; ++m) _Pragma("unroll") for (int k = 0; k < 2; ++k) dst[m][k] = *(const PG8_LAS bf16x8*)(lds + PG8_SA(b, h) + aoff + m * 2048 + k * 1024); } while (0)
; #define PG8_LDB(dst, b, h) do { _Pragma("unroll") for (int n = 0; n < 2; ++n) _Pragma("unroll") for (int k = 0; k < 2; ++k) dst[n][k] = *(const PG8_LAS bf16x8*)(lds + PG8_SB(b, h) + boff + n * 2048 + k * 1024); } while (0)
; #define PG8_MMA(ai, bj, At, Bt) do { __builtin_amdgcn_s_setprio(1); _Pragma("unroll") for (int m = 0; m < 4; ++m) _Pragma("unroll") for (int n = 0; n < 2; ++n) _Pragma("unroll") for (int k = 0; k < 2; ++k) \
;         acc[ai][bj][m][n] = __builtin_amdgcn_mfma_f32_16x16x32_bf16(Bt[n][k], At[m][k], acc[ai][bj][m][n], 0, 0, 0); __builtin_amdgcn_s_setprio(0); } while (0)
; #define PG8_WAIT_V(n) asm volatile("s_waitcnt vmcnt(" #n ")" ::: "memory")
; #define PG8_WAIT_L(n) asm volatile("s_waitcnt lgkmcnt(" #n ")" ::: "memory")
; #define PG8_BAR __builtin_amdgcn_s_barrier()
; #define PG8_SCHED __builtin_amdgcn_sched_barrier(0)
; template <class Epi, class Sched, bool ALIGN_EPI = false, bool SP2 = false>
; __device__ __forceinline__ void gemm_phase(PG8_LAS unsigned char* lds, const Gemm g, const Sched& S, const Epi& E) {
;     ...
;             PG8_WAIT_V(8); PG8_WAIT_L(0); PG8_BAR; PG8_MMA(1, 0, At, B0); PG8_MMA(1, 1, At, B1); PG8_BAR; PG8_SCHED;
;             PG8_LDB(B0, 1, 0); PG8_LDB(B1, 1, 1); PG8_SCHED; PG8_LDA(At, 1, 0); PG8_STAGE(PG8_SA(0, 1), a2 + hstep, voffA);
;             PG8_WAIT_V(8); PG8_WAIT_L(0); PG8_BAR; PG8_MMA(0, 0, At, B0); PG8_MMA(0, 1, At, B1); PG8_BAR; PG8_SCHED;
	s_setprio 1
	v_mfma_f32_16x16x32_bf16 v[60:63], v[144:147], v[184:187], 0
	v_mfma_f32_16x16x32_bf16 v[56:59], v[160:163], v[184:187], 0
	v_mfma_f32_16x16x32_bf16 v[44:47], v[144:147], v[192:195], 0
	v_mfma_f32_16x16x32_bf16 v[40:43], v[160:163], v[192:195], 0
	v_mfma_f32_16x16x32_bf16 v[28:31], v[144:147], v[200:203], 0
	v_mfma_f32_16x16x32_bf16 v[24:27], v[160:163], v[200:203], 0
	v_mfma_f32_16x16x32_bf16 v[12:15], v[144:147], v[208:211], 0
	v_mfma_f32_16x16x32_bf16 v[8:11], v[160:163], v[208:211], 0
	v_mfma_f32_16x16x32_bf16 v[60:63], v[156:159], v[188:191], v[60:63]
	v_mfma_f32_16x16x32_bf16 v[56:59], v[164:167], v[188:191], v[56:59]
	v_mfma_f32_16x16x32_bf16 v[44:47], v[156:159], v[196:199], v[44:47]
	v_mfma_f32_16x16x32_bf16 v[40:43], v[164:167], v[196:199], v[40:43]
	v_mfma_f32_16x16x32_bf16 v[28:31], v[156:159], v[204:207], v[28:31]
	v_mfma_f32_16x16x32_bf16 v[24:27], v[164:167], v[204:207], v[24:27]
	v_mfma_f32_16x16x32_bf16 v[12:15], v[156:159], v[212:215], v[12:15]
	v_mfma_f32_16x16x32_bf16 v[8:11], v[164:167], v[212:215], v[8:11]
	s_setprio 0
	s_setprio 1
	v_mfma_f32_16x16x32_bf16 v[52:55], v[168:171], v[184:187], 0
	v_mfma_f32_16x16x32_bf16 v[48:51], v[176:179], v[184:187], 0
	v_mfma_f32_16x16x32_bf16 v[36:39], v[168:171], v[192:195], 0
	v_mfma_f32_16x16x32_bf16 v[32:35], v[176:179], v[192:195], 0
	v_mfma_f32_16x16x32_bf16 v[20:23], v[168:171], v[200:203], 0
	v_mfma_f32_16x16x32_bf16 v[16:19], v[176:179], v[200:203], 0
	v_mfma_f32_16x16x32_bf16 v[4:7], v[168:171], v[208:211], 0
	v_mfma_f32_16x16x32_bf16 v[0:3], v[176:179], v[208:211], 0
	v_mfma_f32_16x16x32_bf16 v[52:55], v[172:175], v[188:191], v[52:55]
	v_mfma_f32_16x16x32_bf16 v[48:51], v[180:183], v[188:191], v[48:51]
	v_mfma_f32_16x16x32_bf16 v[36:39], v[172:175], v[196:199], v[36:39]
	v_mfma_f32_16x16x32_bf16 v[32:35], v[180:183], v[196:199], v[32:35]
	v_mfma_f32_16x16x32_bf16 v[20:23], v[172:175], v[204:207], v[20:23]
	v_mfma_f32_16x16x32_bf16 v[16:19], v[180:183], v[204:207], v[16:19]
	v_mfma_f32_16x16x32_bf16 v[4:7], v[172:175], v[212:215], v[4:7]
	v_mfma_f32_16x16x32_bf16 v[0:3], v[180:183], v[212:215], v[0:3]
	s_barrier
	s_setprio 0
	s_add_i32 s81, 0, 0x18000
	s_add_i32 s82, 0, 0x1c000
	v_add_u32_e32 v164, s81, v149
	v_add_u32_e32 v180, s82, v149
	ds_read_b128 v[144:147], v164
	ds_read_b128 v[156:159], v164 offset:1024
	ds_read_b128 v[160:163], v164 offset:2048
	ds_read_b128 v[164:167], v164 offset:3072
	ds_read_b128 v[168:171], v180
	ds_read_b128 v[172:175], v180 offset:1024
	ds_read_b128 v[176:179], v180 offset:2048
	ds_read_b128 v[180:183], v180 offset:3072
	s_add_u32 s48, s48, 0x40000
	s_addc_u32 s49, s49, 0
	s_mov_b32 m0, s57
	v_lshl_add_u64 v[224:225], s[48:49], 0, v[134:135]
	ds_read_b128 v[184:187], v153 offset:32768
	ds_read_b128 v[188:191], v153 offset:33792
	ds_read_b128 v[192:195], v153 offset:34816
	ds_read_b128 v[196:199], v153 offset:35840
	ds_read_b128 v[200:203], v153 offset:36864
	ds_read_b128 v[204:207], v153 offset:37888
	ds_read_b128 v[208:211], v153 offset:38912
	ds_read_b128 v[212:215], v153 offset:39936
	global_load_lds_dwordx4 v[224:225], off
	v_lshl_add_u64 v[224:225], s[48:49], 0, v[130:131]
	s_mov_b32 m0, s58
	s_nop 0
	global_load_lds_dwordx4 v[224:225], off
	s_waitcnt vmcnt(8)
	s_waitcnt lgkmcnt(0)
	s_barrier
	s_setprio 1
	v_mfma_f32_16x16x32_bf16 v[124:127], v[144:147], v[184:187], v[124:127]
	v_mfma_f32_16x16x32_bf16 v[120:123], v[160:163], v[184:187], v[120:123]
	v_mfma_f32_16x16x32_bf16 v[108:111], v[144:147], v[192:195], v[108:111]
	v_mfma_f32_16x16x32_bf16 v[104:107], v[160:163], v[192:195], v[104:107]
	v_mfma_f32_16x16x32_bf16 v[92:95], v[144:147], v[200:203], v[92:95]
	v_mfma_f32_16x16x32_bf16 v[88:91], v[160:163], v[200:203], v[88:91]
	v_mfma_f32_16x16x32_bf16 v[76:79], v[144:147], v[208:211], v[76:79]
	v_mfma_f32_16x16x32_bf16 v[72:75], v[160:163], v[208:211], v[72:75]
	v_mfma_f32_16x16x32_bf16 v[124:127], v[156:159], v[188:191], v[124:127]
	v_mfma_f32_16x16x32_bf16 v[120:123], v[164:167], v[188:191], v[120:123]
	v_mfma_f32_16x16x32_bf16 v[108:111], v[156:159], v[196:199], v[108:111]
	v_mfma_f32_16x16x32_bf16 v[104:107], v[164:167], v[196:199], v[104:107]
	v_mfma_f32_16x16x32_bf16 v[92:95], v[156:159], v[204:207], v[92:95]
	v_mfma_f32_16x16x32_bf16 v[88:91], v[164:167], v[204:207], v[88:91]
	v_mfma_f32_16x16x32_bf16 v[76:79], v[156:159], v[212:215], v[76:79]
	v_mfma_f32_16x16x32_bf16 v[72:75], v[164:167], v[212:215], v[72:75]
	s_setprio 0
	s_setprio 1
	v_mfma_f32_16x16x32_bf16 v[116:119], v[168:171], v[184:187], v[116:119]
	v_mfma_f32_16x16x32_bf16 v[112:115], v[176:179], v[184:187], v[112:115]
	v_mfma_f32_16x16x32_bf16 v[100:103], v[168:171], v[192:195], v[100:103]
	v_mfma_f32_16x16x32_bf16 v[96:99], v[176:179], v[192:195], v[96:99]
	v_mfma_f32_16x16x32_bf16 v[84:87], v[168:171], v[200:203], v[84:87]
	v_mfma_f32_16x16x32_bf16 v[80:83], v[176:179], v[200:203], v[80:83]
	v_mfma_f32_16x16x32_bf16 v[68:71], v[168:171], v[208:211], v[68:71]
	v_mfma_f32_16x16x32_bf16 v[64:67], v[176:179], v[208:211], v[64:67]
	v_mfma_f32_16x16x32_bf16 v[116:119], v[172:175], v[188:191], v[116:119]
	v_mfma_f32_16x16x32_bf16 v[112:115], v[180:183], v[188:191], v[112:115]
	v_mfma_f32_16x16x32_bf16 v[100:103], v[172:175], v[196:199], v[100:103]
	v_mfma_f32_16x16x32_bf16 v[96:99], v[180:183], v[196:199], v[96:99]
	v_mfma_f32_16x16x32_bf16 v[84:87], v[172:175], v[204:207], v[84:87]
	v_mfma_f32_16x16x32_bf16 v[80:83], v[180:183], v[204:207], v[80:83]
	v_mfma_f32_16x16x32_bf16 v[68:71], v[172:175], v[212:215], v[68:71]
	v_mfma_f32_16x16x32_bf16 v[64:67], v[180:183], v[212:215], v[64:67]
	s_barrier
; #define PG8_STAGE(bufoff, gbase, voff) do { _Pragma("unroll") for (int _i = 0; _i < 2; ++_i) \
;         __builtin_amdgcn_global_load_lds((const unsigned*)((const char*)(gbase) + (voff)[_i]), (PG8_LAS unsigned*)(lds + (bufoff) + ldsw + _i * 8192), 16, 0, 0); } while (0)
; #define PG8_LDA(dst, b, h) do { _Pragma("unroll") for (int m = 0; m < 4; ++m) _Pragma("unroll") for (int k = 0; k < 2; ++k) dst[m][k] = *(const PG8_LAS bf16x8*)(lds + PG8_SA(b, h) + aoff + m * 2048 + k * 1024); } while (0)
; #define PG8_LDB(dst, b, h) do { _Pragma("unroll") for (int n = 0; n < 2; ++n) _Pragma("unroll") for (int k = 0; k < 2; ++k) dst[n][k] = *(const PG8_LAS bf16x8*)(lds + PG8_SB(b, h) + boff + n * 2048 + k * 1024); } while (0)
; #define PG8_MMA(ai, bj, At, Bt) do { __builtin_amdgcn_s_setprio(1); _Pragma("unroll") for (int m = 0; m < 4; ++m) _Pragma("unroll") for (int n = 0; n < 2; ++n) _Pragma("unroll") for (int k = 0; k < 2; ++k) \
;         acc[ai][bj][m][n] = __builtin_amdgcn_mfma_f32_16x16x32_bf16(Bt[n][k], At[m][k], acc[ai][bj][m][n], 0, 0, 0); __builtin_amdgcn_s_setprio(0); } while (0)
; #define PG8_WAIT_V(n) asm volatile("s_waitcnt vmcnt(" #n ")" ::: "memory")
; template <class Epi, class Sched, bool ALIGN_EPI = false, bool SP2 = false>
; __device__ __forceinline__ void gemm_phase(PG8_LAS unsigned char* lds, const Gemm g, const Sched& S, const Epi& E) {
;     ...
;             PG8_LDB(B0, 0, 0); PG8_LDB(B1, 0, 1); PG8_SCHED; PG8_LDA(At, 0, 0); PG8_STAGE(PG8_SA(1, 1), a1 + hstep, voffA);
;             PG8_WAIT_V(8); PG8_WAIT_L(0); PG8_BAR; PG8_MMA(0, 0, At, B0); PG8_MMA(0, 1, At, B1); PG8_BAR; PG8_SCHED;
;             PG8_LDA(At, 0, 1); PG8_STAGE(PG8_SB(0, 0), b2, voffB); PG8_STAGE(PG8_SB(0, 1), b2 + hstep, voffB); PG8_STAGE(PG8_SA(0, 0), a2, voffA);
;             PG8_WAIT_V(8); PG8_WAIT_L(0); PG8_BAR; PG8_MMA(1, 0, At, B0); PG8_MMA(1, 1, At, B1); PG8_BAR; PG8_SCHED;
;             PG8_LDB(B0, 1, 0); PG8_LDB(B1, 1, 1); PG8_SCHED; PG8_LDA(At, 1, 0); PG8_STAGE(PG8_SA(0, 1), a2 + hstep, voffA);
;             PG8_WAIT_V(8); PG8_WAIT_L(0); PG8_BAR; PG8_MMA(0, 0, At, B0); PG8_MMA(0, 1, At, B1); PG8_BAR; PG8_SCHED;
;             PG8_LDA(At, 1, 1); PG8_STAGE(PG8_SB(1, 0), b3, voffB); PG8_STAGE(PG8_SB(1, 1), b3 + hstep, voffB); PG8_STAGE(PG8_SA(1, 0), a3, voffA);
;             PG8_WAIT_V(8); PG8_WAIT_L(0); PG8_BAR; PG8_MMA(1, 0, At, B0); PG8_MMA(1, 1, At, B1); PG8_BAR; PG8_SCHED;
	s_setprio 0
	s_add_i32 s48, s81, s52
	v_lshl_add_u64 v[216:217], v[216:217], 0, s[14:15]
	s_mov_b32 m0, s48
	ds_read_b128 v[184:187], v153 offset:49152
	ds_read_b128 v[188:191], v153 offset:50176
	ds_read_b128 v[192:195], v153 offset:51200
	ds_read_b128 v[196:199], v153 offset:52224
	ds_read_b128 v[200:203], v153 offset:53248
	ds_read_b128 v[204:207], v153 offset:54272
	ds_read_b128 v[208:211], v153 offset:55296
	ds_read_b128 v[212:215], v153 offset:56320
	global_load_lds_dwordx4 v[216:217], off
	s_add_i32 m0, s48, 0x2000
	s_add_u32 s46, s46, 0x40080
	v_lshl_add_u64 v[216:217], v[218:219], 0, s[14:15]
	s_addc_u32 s47, s47, 0
	s_add_i32 s48, s82, s52
	global_load_lds_dwordx4 v[216:217], off
	v_lshl_add_u64 v[216:217], s[46:47], 0, v[132:133]
	s_mov_b32 m0, s48
	s_nop 0
	global_load_lds_dwordx4 v[216:217], off
	v_lshl_add_u64 v[216:217], s[46:47], 0, v[128:129]
	s_add_i32 m0, s48, 0x2000
	s_nop 0
	global_load_lds_dwordx4 v[216:217], off
	v_lshl_add_u64 v[216:217], v[220:221], 0, s[14:15]
	s_mov_b32 m0, s65
	s_nop 0
	global_load_lds_dwordx4 v[216:217], off
	v_lshl_add_u64 v[216:217], v[222:223], 0, s[14:15]
	s_mov_b32 m0, s66
	s_nop 0
	global_load_lds_dwordx4 v[216:217], off
	s_waitcnt vmcnt(8)
	s_waitcnt lgkmcnt(0)
	s_barrier
	s_setprio 1
	v_mfma_f32_16x16x32_bf16 v[60:63], v[144:147], v[184:187], v[60:63]
	v_mfma_f32_16x16x32_bf16 v[56:59], v[160:163], v[184:187], v[56:59]
	v_mfma_f32_16x16x32_bf16 v[44:47], v[144:147], v[192:195], v[44:47]
	v_mfma_f32_16x16x32_bf16 v[40:43], v[160:163], v[192:195], v[40:43]
	v_mfma_f32_16x16x32_bf16 v[28:31], v[144:147], v[200:203], v[28:31]
	v_mfma_f32_16x16x32_bf16 v[24:27], v[160:163], v[200:203], v[24:27]
	v_mfma_f32_16x16x32_bf16 v[12:15], v[144:147], v[208:211], v[12:15]
	v_mfma_f32_16x16x32_bf16 v[8:11], v[160:163], v[208:211], v[8:11]
	v_mfma_f32_16x16x32_bf16 v[60:63], v[156:159], v[188:191], v[60:63]
	v_mfma_f32_16x16x32_bf16 v[56:59], v[164:167], v[188:191], v[56:59]
	v_mfma_f32_16x16x32_bf16 v[44:47], v[156:159], v[196:199], v[44:47]
	v_mfma_f32_16x16x32_bf16 v[40:43], v[164:167], v[196:199], v[40:43]
	v_mfma_f32_16x16x32_bf16 v[28:31], v[156:159], v[204:207], v[28:31]
	v_mfma_f32_16x16x32_bf16 v[24:27], v[164:167], v[204:207], v[24:27]
	v_mfma_f32_16x16x32_bf16 v[12:15], v[156:159], v[212:215], v[12:15]
	v_mfma_f32_16x16x32_bf16 v[8:11], v[164:167], v[212:215], v[8:11]
	s_setprio 0
	s_setprio 1
	v_mfma_f32_16x16x32_bf16 v[52:55], v[168:171], v[184:187], v[52:55]
	v_mfma_f32_16x16x32_bf16 v[48:51], v[176:179], v[184:187], v[48:51]
	v_mfma_f32_16x16x32_bf16 v[36:39], v[168:171], v[192:195], v[36:39]
	v_mfma_f32_16x16x32_bf16 v[32:35], v[176:179], v[192:195], v[32:35]
	v_mfma_f32_16x16x32_bf16 v[20:23], v[168:171], v[200:203], v[20:23]
	v_mfma_f32_16x16x32_bf16 v[16:19], v[176:179], v[200:203], v[16:19]
	v_mfma_f32_16x16x32_bf16 v[4:7], v[168:171], v[208:211], v[4:7]
	v_mfma_f32_16x16x32_bf16 v[0:3], v[176:179], v[208:211], v[0:3]
	v_mfma_f32_16x16x32_bf16 v[52:55], v[172:175], v[188:191], v[52:55]
	v_mfma_f32_16x16x32_bf16 v[48:51], v[180:183], v[188:191], v[48:51]
	v_mfma_f32_16x16x32_bf16 v[36:39], v[172:175], v[196:199], v[36:39]
	v_mfma_f32_16x16x32_bf16 v[32:35], v[180:183], v[196:199], v[32:35]
	v_mfma_f32_16x16x32_bf16 v[20:23], v[172:175], v[204:207], v[20:23]
	v_mfma_f32_16x16x32_bf16 v[16:19], v[180:183], v[204:207], v[16:19]
	v_mfma_f32_16x16x32_bf16 v[4:7], v[172:175], v[212:215], v[4:7]
	v_mfma_f32_16x16x32_bf16 v[0:3], v[180:183], v[212:215], v[0:3]
	s_barrier
	s_setprio 0
	s_add_i32 s80, s80, 2
	s_add_u32 s44, s44, 0x100
	s_addc_u32 s45, s45, 0
	s_add_u32 s78, s78, 0x100
	s_addc_u32 s79, s79, 0
.LBB0_593:
	ds_read_b128 v[144:147], v151
	ds_read_b128 v[156:159], v151 offset:1024
	ds_read_b128 v[160:163], v151 offset:2048
	ds_read_b128 v[164:167], v151 offset:3072
	ds_read_b128 v[168:171], v152
	ds_read_b128 v[172:175], v152 offset:1024
	ds_read_b128 v[176:179], v152 offset:2048
	ds_read_b128 v[180:183], v152 offset:3072
	s_add_u32 s46, s44, 0xfffc0080
	s_addc_u32 s47, s45, -1
	s_cmp_eq_u32 s80, 12
	s_cselect_b32 s49, s37, s47
	s_cselect_b32 s48, s76, s46
	s_cselect_b32 s47, s35, s79
	s_cselect_b32 s46, s77, s78
	v_lshl_add_u64 v[216:217], s[44:45], 0, v[136:137]
	s_add_i32 m0, s43, 0xc000
	ds_read_b128 v[184:187], v153
	ds_read_b128 v[188:191], v153 offset:1024
	ds_read_b128 v[192:195], v153 offset:2048
	ds_read_b128 v[196:199], v153 offset:3072
	ds_read_b128 v[200:203], v153 offset:4096
	ds_read_b128 v[204:207], v153 offset:5120
	ds_read_b128 v[208:211], v153 offset:6144
	ds_read_b128 v[212:215], v153 offset:7168
	global_load_lds_dwordx4 v[216:217], off
	v_lshl_add_u64 v[216:217], s[44:45], 0, v[138:139]
	s_add_i32 m0, s43, 0xe000
	s_nop 0
	global_load_lds_dwordx4 v[216:217], off
	s_waitcnt vmcnt(8)
	s_waitcnt lgkmcnt(0)
	s_barrier
; #define PG8_STAGE(bufoff, gbase, voff) do { _Pragma("unroll") for (int _i = 0; _i < 2; ++_i) \
;         __builtin_amdgcn_global_load_lds((const unsigned*)((const char*)(gbase) + (voff)[_i]), (PG8_LAS unsigned*)(lds + (bufoff) + ldsw + _i * 8192), 16, 0, 0); } while (0)
; #define PG8_LDA(dst, b, h) do { _Pragma("unroll") for (int m = 0; m < 4; ++m) _Pragma("unroll") for (int k = 0; k < 2; ++k) dst[m][k] = *(const PG8_LAS bf16x8*)(lds + PG8_SA(b, h) + aoff + m * 2048 + k * 1024); } while (0)
; #define PG8_MMA(ai, bj, At, Bt) do { __builtin_amdgcn_s_setprio(1); _Pragma("unroll") for (int m = 0; m < 4; ++m) _Pragma("unroll") for (int n = 0; n < 2; ++n) _Pragma("unroll") for (int k = 0; k < 2; ++k) \
;         acc[ai][bj][m][n] = __builtin_amdgcn_mfma_f32_16x16x32_bf16(Bt[n][k], At[m][k], acc[ai][bj][m][n], 0, 0, 0); __builtin_amdgcn_s_setprio(0); } while (0)
; #define PG8_WAIT_V(n) asm volatile("s_waitcnt vmcnt(" #n ")" ::: "memory")
; #define PG8_WAIT_L(n) asm volatile("s_waitcnt lgkmcnt(" #n ")" ::: "memory")
; #define PG8_BAR __builtin_amdgcn_s_barrier()
; #define PG8_SCHED __builtin_amdgcn_sched_barrier(0)
; template <class Epi, class Sched, bool ALIGN_EPI = false, bool SP2 = false>
; __device__ __forceinline__ void gemm_phase(PG8_LAS unsigned char* lds, const Gemm g, const Sched& S, const Epi& E) {
;     ...
;             PG8_WAIT_V(8); PG8_WAIT_L(0); PG8_BAR; PG8_MMA(0, 0, At, B0); PG8_MMA(0, 1, At, B1); PG8_BAR; PG8_SCHED;
;             PG8_LDA(At, 0, 1); PG8_STAGE(PG8_SB(0, 0), b2, voffB); PG8_STAGE(PG8_SB(0, 1), b2 + hstep, voffB); PG8_STAGE(PG8_SA(0, 0), a2, voffA);
;             PG8_WAIT_V(8); PG8_WAIT_L(0); PG8_BAR; PG8_MMA(1, 0, At, B0); PG8_MMA(1, 1, At, B1); PG8_BAR; PG8_SCHED;
	s_setprio 1
	v_mfma_f32_16x16x32_bf16 v[124:127], v[144:147], v[184:187], v[124:127]
	v_mfma_f32_16x16x32_bf16 v[120:123], v[160:163], v[184:187], v[120:123]
	v_mfma_f32_16x16x32_bf16 v[108:111], v[144:147], v[192:195], v[108:111]
	v_mfma_f32_16x16x32_bf16 v[104:107], v[160:163], v[192:195], v[104:107]
	v_mfma_f32_16x16x32_bf16 v[92:95], v[144:147], v[200:203], v[92:95]
	v_mfma_f32_16x16x32_bf16 v[88:91], v[160:163], v[200:203], v[88:91]
	v_mfma_f32_16x16x32_bf16 v[76:79], v[144:147], v[208:211], v[76:79]
	v_mfma_f32_16x16x32_bf16 v[72:75], v[160:163], v[208:211], v[72:75]
	v_mfma_f32_16x16x32_bf16 v[124:127], v[156:159], v[188:191], v[124:127]
	v_mfma_f32_16x16x32_bf16 v[120:123], v[164:167], v[188:191], v[120:123]
	v_mfma_f32_16x16x32_bf16 v[108:111], v[156:159], v[196:199], v[108:111]
	v_mfma_f32_16x16x32_bf16 v[104:107], v[164:167], v[196:199], v[104:107]
	v_mfma_f32_16x16x32_bf16 v[92:95], v[156:159], v[204:207], v[92:95]
	v_mfma_f32_16x16x32_bf16 v[88:91], v[164:167], v[204:207], v[88:91]
	v_mfma_f32_16x16x32_bf16 v[76:79], v[156:159], v[212:215], v[76:79]
	v_mfma_f32_16x16x32_bf16 v[72:75], v[164:167], v[212:215], v[72:75]
	s_setprio 0
	s_setprio 1
	v_mfma_f32_16x16x32_bf16 v[116:119], v[168:171], v[184:187], v[116:119]
	v_mfma_f32_16x16x32_bf16 v[112:115], v[176:179], v[184:187], v[112:115]
	v_mfma_f32_16x16x32_bf16 v[100:103], v[168:171], v[192:195], v[100:103]
	v_mfma_f32_16x16x32_bf16 v[96:99], v[176:179], v[192:195], v[96:99]
	v_mfma_f32_16x16x32_bf16 v[84:87], v[168:171], v[200:203], v[84:87]
	v_mfma_f32_16x16x32_bf16 v[80:83], v[176:179], v[200:203], v[80:83]
	v_mfma_f32_16x16x32_bf16 v[68:71], v[168:171], v[208:211], v[68:71]
	v_mfma_f32_16x16x32_bf16 v[64:67], v[176:179], v[208:211], v[64:67]
	v_mfma_f32_16x16x32_bf16 v[116:119], v[172:175], v[188:191], v[116:119]
	v_mfma_f32_16x16x32_bf16 v[112:115], v[180:183], v[188:191], v[112:115]
	v_mfma_f32_16x16x32_bf16 v[100:103], v[172:175], v[196:199], v[100:103]
	v_mfma_f32_16x16x32_bf16 v[96:99], v[180:183], v[196:199], v[96:99]
	v_mfma_f32_16x16x32_bf16 v[84:87], v[172:175], v[204:207], v[84:87]
	v_mfma_f32_16x16x32_bf16 v[80:83], v[180:183], v[204:207], v[80:83]
	v_mfma_f32_16x16x32_bf16 v[68:71], v[172:175], v[212:215], v[68:71]
	v_mfma_f32_16x16x32_bf16 v[64:67], v[180:183], v[212:215], v[64:67]
	s_barrier
	s_setprio 0
	s_add_i32 s81, s69, s52
	v_lshl_add_u64 v[216:217], s[46:47], 0, v[132:133]
	s_mov_b32 m0, s81
	ds_read_b128 v[184:187], v153 offset:16384
	ds_read_b128 v[188:191], v153 offset:17408
	ds_read_b128 v[192:195], v153 offset:18432
	ds_read_b128 v[196:199], v153 offset:19456
	ds_read_b128 v[200:203], v153 offset:20480
	ds_read_b128 v[204:207], v153 offset:21504
	ds_read_b128 v[208:211], v153 offset:22528
	ds_read_b128 v[212:215], v153 offset:23552
	global_load_lds_dwordx4 v[216:217], off
	s_add_i32 m0, s81, 0x2000
	s_add_u32 s82, s46, 0x40000
	v_lshl_add_u64 v[218:219], s[46:47], 0, v[128:129]
	s_addc_u32 s83, s47, 0
	s_add_i32 s81, s70, s52
	global_load_lds_dwordx4 v[218:219], off
	v_lshl_add_u64 v[220:221], s[82:83], 0, v[132:133]
	s_mov_b32 m0, s81
	v_lshl_add_u64 v[222:223], s[48:49], 0, v[130:131]
	global_load_lds_dwordx4 v[220:221], off
	v_lshl_add_u64 v[220:221], s[82:83], 0, v[128:129]
	s_add_i32 m0, s81, 0x2000
	s_nop 0
	global_load_lds_dwordx4 v[220:221], off
	v_lshl_add_u64 v[220:221], s[48:49], 0, v[134:135]
	s_mov_b32 m0, s43
	s_nop 0
	global_load_lds_dwordx4 v[220:221], off
	s_mov_b32 m0, s56
	s_nop 0
	global_load_lds_dwordx4 v[222:223], off
	s_waitcnt vmcnt(8)
	s_waitcnt lgkmcnt(0)
	s_barrier
	s_setprio 1
	v_mfma_f32_16x16x32_bf16 v[60:63], v[144:147], v[184:187], v[60:63]
	v_mfma_f32_16x16x32_bf16 v[56:59], v[160:163], v[184:187], v[56:59]
	v_mfma_f32_16x16x32_bf16 v[44:47], v[144:147], v[192:195], v[44:47]
	v_mfma_f32_16x16x32_bf16 v[40:43], v[160:163], v[192:195], v[40:43]
	v_mfma_f32_16x16x32_bf16 v[28:31], v[144:147], v[200:203], v[28:31]
	v_mfma_f32_16x16x32_bf16 v[24:27], v[160:163], v[200:203], v[24:27]
	v_mfma_f32_16x16x32_bf16 v[12:15], v[144:147], v[208:211], v[12:15]
	v_mfma_f32_16x16x32_bf16 v[8:11], v[160:163], v[208:211], v[8:11]
	v_mfma_f32_16x16x32_bf16 v[60:63], v[156:159], v[188:191], v[60:63]
	v_mfma_f32_16x16x32_bf16 v[56:59], v[164:167], v[188:191], v[56:59]
	v_mfma_f32_16x16x32_bf16 v[44:47], v[156:159], v[196:199], v[44:47]
	v_mfma_f32_16x16x32_bf16 v[40:43], v[164:167], v[196:199], v[40:43]
	v_mfma_f32_16x16x32_bf16 v[28:31], v[156:159], v[204:207], v[28:31]
	v_mfma_f32_16x16x32_bf16 v[24:27], v[164:167], v[204:207], v[24:27]
	v_mfma_f32_16x16x32_bf16 v[12:15], v[156:159], v[212:215], v[12:15]
	v_mfma_f32_16x16x32_bf16 v[8:11], v[164:167], v[212:215], v[8:11]
	s_setprio 0
	s_setprio 1
	v_mfma_f32_16x16x32_bf16 v[52:55], v[168:171], v[184:187], v[52:55]
	v_mfma_f32_16x16x32_bf16 v[48:51], v[176:179], v[184:187], v[48:51]
	v_mfma_f32_16x16x32_bf16 v[36:39], v[168:171], v[192:195], v[36:39]
	v_mfma_f32_16x16x32_bf16 v[32:35], v[176:179], v[192:195], v[32:35]
	v_mfma_f32_16x16x32_bf16 v[20:23], v[168:171], v[200:203], v[20:23]
	v_mfma_f32_16x16x32_bf16 v[16:19], v[176:179], v[200:203], v[16:19]
	v_mfma_f32_16x16x32_bf16 v[4:7], v[168:171], v[208:211], v[4:7]
	v_mfma_f32_16x16x32_bf16 v[0:3], v[176:179], v[208:211], v[0:3]
	v_mfma_f32_16x16x32_bf16 v[52:55], v[172:175], v[188:191], v[52:55]
	v_mfma_f32_16x16x32_bf16 v[48:51], v[180:183], v[188:191], v[48:51]
	v_mfma_f32_16x16x32_bf16 v[36:39], v[172:175], v[196:199], v[36:39]
	v_mfma_f32_16x16x32_bf16 v[32:35], v[180:183], v[196:199], v[32:35]
	v_mfma_f32_16x16x32_bf16 v[20:23], v[172:175], v[204:207], v[20:23]
	v_mfma_f32_16x16x32_bf16 v[16:19], v[180:183], v[204:207], v[16:19]
	v_mfma_f32_16x16x32_bf16 v[4:7], v[172:175], v[212:215], v[4:7]
	v_mfma_f32_16x16x32_bf16 v[0:3], v[180:183], v[212:215], v[0:3]
	s_barrier
; #define PG8_STAGE(bufoff, gbase, voff) do { _Pragma("unroll") for (int _i = 0; _i < 2; ++_i) \
;         __builtin_amdgcn_global_load_lds((const unsigned*)((const char*)(gbase) + (voff)[_i]), (PG8_LAS unsigned*)(lds + (bufoff) + ldsw + _i * 8192), 16, 0, 0); } while (0)
; #define PG8_LDA(dst, b, h) do { _Pragma("unroll") for (int m = 0; m < 4; ++m) _Pragma("unroll") for (int k = 0; k < 2; ++k) dst[m][k] = *(const PG8_LAS bf16x8*)(lds + PG8_SA(b, h) + aoff + m * 2048 + k * 1024); } while (0)
; #define PG8_LDB(dst, b, h) do { _Pragma("unroll") for (int n = 0; n < 2; ++n) _Pragma("unroll") for (int k = 0; k < 2; ++k) dst[n][k] = *(const PG8_LAS bf16x8*)(lds + PG8_SB(b, h) + boff + n * 2048 + k * 1024); } while (0)
; #define PG8_MMA(ai, bj, At, Bt) do { __builtin_amdgcn_s_setprio(1); _Pragma("unroll") for (int m = 0; m < 4; ++m) _Pragma("unroll") for (int n = 0; n < 2; ++n) _Pragma("unroll") for (int k = 0; k < 2; ++k) \
;         acc[ai][bj][m][n] = __builtin_amdgcn_mfma_f32_16x16x32_bf16(Bt[n][k], At[m][k], acc[ai][bj][m][n], 0, 0, 0); __builtin_amdgcn_s_setprio(0); } while (0)
; #define PG8_WAIT_V(n) asm volatile("s_waitcnt vmcnt(" #n ")" ::: "memory")
; #define PG8_WAIT_L(n) asm volatile("s_waitcnt lgkmcnt(" #n ")" ::: "memory")
; #define PG8_BAR __builtin_amdgcn_s_barrier()
; #define PG8_SCHED __builtin_amdgcn_sched_barrier(0)
; template <class Epi, class Sched, bool ALIGN_EPI = false, bool SP2 = false>
; __device__ __forceinline__ void gemm_phase(PG8_LAS unsigned char* lds, const Gemm g, const Sched& S, const Epi& E) {
;     ...
;             PG8_LDB(B0, 1, 0); PG8_LDB(B1, 1, 1); PG8_SCHED; PG8_LDA(At, 1, 0); PG8_STAGE(PG8_SA(0, 1), a2 + hstep, voffA);
;             PG8_WAIT_V(8); PG8_WAIT_L(0); PG8_BAR; PG8_MMA(0, 0, At, B0); PG8_MMA(0, 1, At, B1); PG8_BAR; PG8_SCHED;
	s_setprio 0
	s_add_i32 s81, 0, 0x18000
	s_add_i32 s82, 0, 0x1c000
	v_add_u32_e32 v164, s81, v149
	v_add_u32_e32 v180, s82, v149
	ds_read_b128 v[144:147], v164
	ds_read_b128 v[156:159], v164 offset:1024
	ds_read_b128 v[160:163], v164 offset:2048
	ds_read_b128 v[164:167], v164 offset:3072
	ds_read_b128 v[168:171], v180
	ds_read_b128 v[172:175], v180 offset:1024
	ds_read_b128 v[176:179], v180 offset:2048
	ds_read_b128 v[180:183], v180 offset:3072
	s_add_u32 s48, s48, 0x40000
	s_addc_u32 s49, s49, 0
	s_mov_b32 m0, s57
	v_lshl_add_u64 v[224:225], s[48:49], 0, v[134:135]
	ds_read_b128 v[184:187], v153 offset:32768
	ds_read_b128 v[188:191], v153 offset:33792
	ds_read_b128 v[192:195], v153 offset:34816
	ds_read_b128 v[196:199], v153 offset:35840
	ds_read_b128 v[200:203], v153 offset:36864
	ds_read_b128 v[204:207], v153 offset:37888
	ds_read_b128 v[208:211], v153 offset:38912
	ds_read_b128 v[212:215], v153 offset:39936
	global_load_lds_dwordx4 v[224:225], off
	v_lshl_add_u64 v[224:225], s[48:49], 0, v[130:131]
	s_mov_b32 m0, s58
	s_nop 0
	global_load_lds_dwordx4 v[224:225], off
	s_waitcnt vmcnt(8)
	s_waitcnt lgkmcnt(0)
	s_barrier
	s_setprio 1
	v_mfma_f32_16x16x32_bf16 v[124:127], v[144:147], v[184:187], v[124:127]
	v_mfma_f32_16x16x32_bf16 v[120:123], v[160:163], v[184:187], v[120:123]
	v_mfma_f32_16x16x32_bf16 v[108:111], v[144:147], v[192:195], v[108:111]
	v_mfma_f32_16x16x32_bf16 v[104:107], v[160:163], v[192:195], v[104:107]
	v_mfma_f32_16x16x32_bf16 v[92:95], v[144:147], v[200:203], v[92:95]
	v_mfma_f32_16x16x32_bf16 v[88:91], v[160:163], v[200:203], v[88:91]
	v_mfma_f32_16x16x32_bf16 v[76:79], v[144:147], v[208:211], v[76:79]
	v_mfma_f32_16x16x32_bf16 v[72:75], v[160:163], v[208:211], v[72:75]
	v_mfma_f32_16x16x32_bf16 v[124:127], v[156:159], v[188:191], v[124:127]
	v_mfma_f32_16x16x32_bf16 v[120:123], v[164:167], v[188:191], v[120:123]
	v_mfma_f32_16x16x32_bf16 v[108:111], v[156:159], v[196:199], v[108:111]
	v_mfma_f32_16x16x32_bf16 v[104:107], v[164:167], v[196:199], v[104:107]
	v_mfma_f32_16x16x32_bf16 v[92:95], v[156:159], v[204:207], v[92:95]
	v_mfma_f32_16x16x32_bf16 v[88:91], v[164:167], v[204:207], v[88:91]
	v_mfma_f32_16x16x32_bf16 v[76:79], v[156:159], v[212:215], v[76:79]
	v_mfma_f32_16x16x32_bf16 v[72:75], v[164:167], v[212:215], v[72:75]
	s_setprio 0
	s_setprio 1
	v_mfma_f32_16x16x32_bf16 v[116:119], v[168:171], v[184:187], v[116:119]
	v_mfma_f32_16x16x32_bf16 v[112:115], v[176:179], v[184:187], v[112:115]
	v_mfma_f32_16x16x32_bf16 v[100:103], v[168:171], v[192:195], v[100:103]
	v_mfma_f32_16x16x32_bf16 v[96:99], v[176:179], v[192:195], v[96:99]
	v_mfma_f32_16x16x32_bf16 v[84:87], v[168:171], v[200:203], v[84:87]
	v_mfma_f32_16x16x32_bf16 v[80:83], v[176:179], v[200:203], v[80:83]
	v_mfma_f32_16x16x32_bf16 v[68:71], v[168:171], v[208:211], v[68:71]
	v_mfma_f32_16x16x32_bf16 v[64:67], v[176:179], v[208:211], v[64:67]
	v_mfma_f32_16x16x32_bf16 v[116:119], v[172:175], v[188:191], v[116:119]
	v_mfma_f32_16x16x32_bf16 v[112:115], v[180:183], v[188:191], v[112:115]
	v_mfma_f32_16x16x32_bf16 v[100:103], v[172:175], v[196:199], v[100:103]
	v_mfma_f32_16x16x32_bf16 v[96:99], v[180:183], v[196:199], v[96:99]
	v_mfma_f32_16x16x32_bf16 v[84:87], v[172:175], v[204:207], v[84:87]
	v_mfma_f32_16x16x32_bf16 v[80:83], v[180:183], v[204:207], v[80:83]
	v_mfma_f32_16x16x32_bf16 v[68:71], v[172:175], v[212:215], v[68:71]
	v_mfma_f32_16x16x32_bf16 v[64:67], v[180:183], v[212:215], v[64:67]
	s_barrier
; #define PG8_STAGE(bufoff, gbase, voff) do { _Pragma("unroll") for (int _i = 0; _i < 2; ++_i) \
;         __builtin_amdgcn_global_load_lds((const unsigned*)((const char*)(gbase) + (voff)[_i]), (PG8_LAS unsigned*)(lds + (bufoff) + ldsw + _i * 8192), 16, 0, 0); } while (0)
; #define PG8_LDA(dst, b, h) do { _Pragma("unroll") for (int m = 0; m < 4; ++m) _Pragma("unroll") for (int k = 0; k < 2; ++k) dst[m][k] = *(const PG8_LAS bf16x8*)(lds + PG8_SA(b, h) + aoff + m * 2048 + k * 1024); } while (0)
; #define PG8_MMA(ai, bj, At, Bt) do { __builtin_amdgcn_s_setprio(1); _Pragma("unroll") for (int m = 0; m < 4; ++m) _Pragma("unroll") for (int n = 0; n < 2; ++n) _Pragma("unroll") for (int k = 0; k < 2; ++k) \
;         acc[ai][bj][m][n] = __builtin_amdgcn_mfma_f32_16x16x32_bf16(Bt[n][k], At[m][k], acc[ai][bj][m][n], 0, 0, 0); __builtin_amdgcn_s_setprio(0); } while (0)
; #define PG8_WAIT_V(n) asm volatile("s_waitcnt vmcnt(" #n ")" ::: "memory")
; #define PG8_WAIT_L(n) asm volatile("s_waitcnt lgkmcnt(" #n ")" ::: "memory")
; #define PG8_BAR __builtin_amdgcn_s_barrier()
; #define PG8_SCHED __builtin_amdgcn_sched_barrier(0)
; template <class Epi, class Sched, bool ALIGN_EPI = false, bool SP2 = false>
; __device__ __forceinline__ void gemm_phase(PG8_LAS unsigned char* lds, const Gemm g, const Sched& S, const Epi& E) {
;     ...
;         for (int t = 0; t < nt; t += 2) {
;             const bool last = (t == nt - 2);
;             if constexpr (Epi::PREFETCH) { if (t == nt - 4) E.prefetch(cur, lds + STAGE_BYTES + 1024, tid); }
;             const char* a1 = cA + (size_t)(t + 1) * kstep;
;             const char* a2 = last ? nA : cA + (size_t)(t + 2) * kstep; const char* b2 = last ? nB : cB + (size_t)(t + 2) * kstep;
;             const char* a3 = a2 + kstep; const char* b3 = b2 + kstep;
;     ...
;             PG8_LDA(At, 1, 1); PG8_STAGE(PG8_SB(1, 0), b3, voffB); PG8_STAGE(PG8_SB(1, 1), b3 + hstep, voffB); PG8_STAGE(PG8_SA(1, 0), a3, voffA);
;             PG8_WAIT_V(8); PG8_WAIT_L(0); PG8_BAR; PG8_MMA(1, 0, At, B0); PG8_MMA(1, 1, At, B1); PG8_BAR; PG8_SCHED;
	s_setprio 0
	s_add_i32 s48, s81, s52
	v_lshl_add_u64 v[216:217], v[216:217], 0, s[14:15]
	s_mov_b32 m0, s48
	ds_read_b128 v[184:187], v153 offset:49152
	ds_read_b128 v[188:191], v153 offset:50176
	ds_read_b128 v[192:195], v153 offset:51200
	ds_read_b128 v[196:199], v153 offset:52224
	ds_read_b128 v[200:203], v153 offset:53248
	ds_read_b128 v[204:207], v153 offset:54272
	ds_read_b128 v[208:211], v153 offset:55296
	ds_read_b128 v[212:215], v153 offset:56320
	global_load_lds_dwordx4 v[216:217], off
	s_add_i32 m0, s48, 0x2000
	s_add_u32 s46, s46, 0x40080
	v_lshl_add_u64 v[216:217], v[218:219], 0, s[14:15]
	s_addc_u32 s47, s47, 0
	s_add_i32 s48, s82, s52
	global_load_lds_dwordx4 v[216:217], off
	v_lshl_add_u64 v[216:217], s[46:47], 0, v[132:133]
	s_mov_b32 m0, s48
	s_nop 0
	global_load_lds_dwordx4 v[216:217], off
	v_lshl_add_u64 v[216:217], s[46:47], 0, v[128:129]
	s_add_i32 m0, s48, 0x2000
	s_nop 0
	global_load_lds_dwordx4 v[216:217], off
	v_lshl_add_u64 v[216:217], v[220:221], 0, s[14:15]
	s_mov_b32 m0, s65
	s_nop 0
	global_load_lds_dwordx4 v[216:217], off
	v_lshl_add_u64 v[216:217], v[222:223], 0, s[14:15]
	s_mov_b32 m0, s66
	s_nop 0
	global_load_lds_dwordx4 v[216:217], off
	s_waitcnt vmcnt(8)
	s_waitcnt lgkmcnt(0)
	s_barrier
	s_setprio 1
	v_mfma_f32_16x16x32_bf16 v[60:63], v[144:147], v[184:187], v[60:63]
	v_mfma_f32_16x16x32_bf16 v[56:59], v[160:163], v[184:187], v[56:59]
	v_mfma_f32_16x16x32_bf16 v[44:47], v[144:147], v[192:195], v[44:47]
	v_mfma_f32_16x16x32_bf16 v[40:43], v[160:163], v[192:195], v[40:43]
	v_mfma_f32_16x16x32_bf16 v[28:31], v[144:147], v[200:203], v[28:31]
	v_mfma_f32_16x16x32_bf16 v[24:27], v[160:163], v[200:203], v[24:27]
	v_mfma_f32_16x16x32_bf16 v[12:15], v[144:147], v[208:211], v[12:15]
	v_mfma_f32_16x16x32_bf16 v[8:11], v[160:163], v[208:211], v[8:11]
	v_mfma_f32_16x16x32_bf16 v[60:63], v[156:159], v[188:191], v[60:63]
	v_mfma_f32_16x16x32_bf16 v[56:59], v[164:167], v[188:191], v[56:59]
	v_mfma_f32_16x16x32_bf16 v[44:47], v[156:159], v[196:199], v[44:47]
	v_mfma_f32_16x16x32_bf16 v[40:43], v[164:167], v[196:199], v[40:43]
	v_mfma_f32_16x16x32_bf16 v[28:31], v[156:159], v[204:207], v[28:31]
	v_mfma_f32_16x16x32_bf16 v[24:27], v[164:167], v[204:207], v[24:27]
	v_mfma_f32_16x16x32_bf16 v[12:15], v[156:159], v[212:215], v[12:15]
	v_mfma_f32_16x16x32_bf16 v[8:11], v[164:167], v[212:215], v[8:11]
	s_setprio 0
	s_setprio 1
	v_mfma_f32_16x16x32_bf16 v[52:55], v[168:171], v[184:187], v[52:55]
	v_mfma_f32_16x16x32_bf16 v[48:51], v[176:179], v[184:187], v[48:51]
	v_mfma_f32_16x16x32_bf16 v[36:39], v[168:171], v[192:195], v[36:39]
	v_mfma_f32_16x16x32_bf16 v[32:35], v[176:179], v[192:195], v[32:35]
	v_mfma_f32_16x16x32_bf16 v[20:23], v[168:171], v[200:203], v[20:23]
	v_mfma_f32_16x16x32_bf16 v[16:19], v[176:179], v[200:203], v[16:19]
	v_mfma_f32_16x16x32_bf16 v[4:7], v[168:171], v[208:211], v[4:7]
	v_mfma_f32_16x16x32_bf16 v[0:3], v[176:179], v[208:211], v[0:3]
	v_mfma_f32_16x16x32_bf16 v[52:55], v[172:175], v[188:191], v[52:55]
	v_mfma_f32_16x16x32_bf16 v[48:51], v[180:183], v[188:191], v[48:51]
	v_mfma_f32_16x16x32_bf16 v[36:39], v[172:175], v[196:199], v[36:39]
	v_mfma_f32_16x16x32_bf16 v[32:35], v[180:183], v[196:199], v[32:35]
	v_mfma_f32_16x16x32_bf16 v[20:23], v[172:175], v[204:207], v[20:23]
	v_mfma_f32_16x16x32_bf16 v[16:19], v[180:183], v[204:207], v[16:19]
	v_mfma_f32_16x16x32_bf16 v[4:7], v[172:175], v[212:215], v[4:7]
	v_mfma_f32_16x16x32_bf16 v[0:3], v[180:183], v[212:215], v[0:3]
	s_barrier
	s_setprio 0
	s_add_i32 s80, s80, 2
	s_add_u32 s44, s44, 0x100
	s_addc_u32 s45, s45, 0
	s_add_u32 s78, s78, 0x100
	s_addc_u32 s79, s79, 0
	s_cmp_gt_u32 s80, 13
	s_cbranch_scc0 .LBB0_593
	s_and_b64 vcc, exec, s[16:17]
	s_cbranch_vccz .LBB0_596
	s_barrier

; #define PG8_STAGE(bufoff, gbase, voff) do { _Pragma("unroll") for (int _i = 0; _i < 2; ++_i) \
;         __builtin_amdgcn_global_load_lds((const unsigned*)((const char*)(gbase) + (voff)[_i]), (PG8_LAS unsigned*)(lds + (bufoff) + ldsw + _i * 8192), 16, 0, 0); } while (0)
; #define PG8_LDA(dst, b, h) do { _Pragma("unroll") for (int m = 0; m < 4; ++m) _Pragma("unroll") for (int k = 0; k < 2; ++k) dst[m][k] = *(const PG8_LAS bf16x8*)(lds + PG8_SA(b, h) + aoff + m * 2048 + k * 1024); } while (0)
; #define PG8_LDB(dst, b, h) do { _Pragma("unroll") for (int n = 0; n < 2; ++n) _Pragma("unroll") for (int k = 0; k < 2; ++k) dst[n][k] = *(const PG8_LAS bf16x8*)(lds + PG8_SB(b, h) + boff + n * 2048 + k * 1024); } while (0)
; #define PG8_WAIT_V(n) asm volatile("s_waitcnt vmcnt(" #n ")" ::: "memory")
; #define PG8_WAIT_L(n) asm volatile("s_waitcnt lgkmcnt(" #n ")" ::: "memory")
; template <class Epi, class Sched, bool ALIGN_EPI = false, bool SP2 = false>
; __device__ __forceinline__ void gemm_phase(PG8_LAS unsigned char* lds, const Gemm g, const Sched& S, const Epi& E) {
;     ...
;         const bool has_next = S.next(ui + 1, nxt);
;         const char* nA = has_next ? (const char*)g.A + (size_t)nxt.pm * tstep : cA; const char* nB = has_next ? (const char*)g.Bt + (size_t)nxt.pn * tstep : cB;
;         for (int t = 0; t < nt; t += 2) {
;             const bool last = (t == nt - 2);
;             if constexpr (Epi::PREFETCH) { if (t == nt - 4) E.prefetch(cur, lds + STAGE_BYTES + 1024, tid); }
;             const char* a1 = cA + (size_t)(t + 1) * kstep;
;             const char* a2 = last ? nA : cA + (size_t)(t + 2) * kstep; const char* b2 = last ? nB : cB + (size_t)(t + 2) * kstep;
;             const char* a3 = a2 + kstep; const char* b3 = b2 + kstep;
;             if (last && has_next) S.a_ready(nxt);
;             if constexpr (SP2) {
;             PG8_LDB(B0, 0, 0); PG8_LDB(B1, 0, 1); PG8_SCHED; PG8_LDA(At, 0, 0); PG8_STAGE(PG8_SA(1, 1), a1 + hstep, voffA);
;             PG8_WAIT_V(8); PG8_WAIT_L(0); PG8_BAR; PG8_MMA(0, 0, At, B0); PG8_MMA(0, 1, At, B1); PG8_BAR; PG8_SCHED;
;             PG8_LDA(At, 0, 1); PG8_STAGE(PG8_SB(0, 0), b2, voffB); PG8_STAGE(PG8_SB(0, 1), b2 + hstep, voffB); PG8_STAGE(PG8_SA(0, 0), a2, voffA);
;             PG8_WAIT_V(8); PG8_WAIT_L(0); PG8_BAR; PG8_MMA(1, 0, At, B0); PG8_MMA(1, 1, At, B1); PG8_BAR; PG8_SCHED;
.LBB0_1011:
	s_ashr_i32 s23, s22, 31
	s_lshl_b64 s[34:35], s[22:23], 19
	s_add_u32 s34, s48, s34
	s_addc_u32 s35, s49, s35
	s_and_b64 s[36:37], s[6:7], exec
	s_cselect_b32 s23, s35, s43
	s_cselect_b32 s39, s34, s42
	s_ashr_i32 s21, s20, 31
	s_lshl_b64 s[36:37], s[20:21], 19
	s_add_u32 s36, s50, s36
	s_addc_u32 s37, s51, s37
	s_and_b64 s[46:47], s[6:7], exec
	s_cselect_b32 s21, s37, s45
	s_cselect_b32 s65, s36, s44
	s_add_u32 s42, s42, 0x40080
	s_addc_u32 s43, s43, 0
	s_add_u32 s66, s44, 0x100
	s_addc_u32 s67, s45, 0
	s_mov_b32 s68, -2
	ds_read_b128 v[112:115], v246
	ds_read_b128 v[116:119], v246 offset:1024
	ds_read_b128 v[120:123], v246 offset:2048
	ds_read_b128 v[124:127], v246 offset:3072
	ds_read_b128 v[136:139], v247
	ds_read_b128 v[140:143], v247 offset:1024
	ds_read_b128 v[152:155], v247 offset:2048
	ds_read_b128 v[156:159], v247 offset:3072
	s_add_u32 s44, s42, 0xfffc0080
	s_addc_u32 s45, s43, -1
	s_cmp_eq_u32 s68, 12
	s_cselect_b32 s47, s23, s45
	s_cselect_b32 s46, s39, s44
	s_cselect_b32 s45, s21, s67
	s_cselect_b32 s44, s65, s66
	v_lshl_add_u64 v[206:207], s[42:43], 0, v[200:201]
	s_add_i32 m0, s41, 0xc000
	ds_read_b128 v[160:163], v248
	ds_read_b128 v[164:167], v248 offset:1024
	ds_read_b128 v[168:171], v248 offset:2048
	ds_read_b128 v[172:175], v248 offset:3072
	ds_read_b128 v[176:179], v248 offset:4096
	ds_read_b128 v[180:183], v248 offset:5120
	ds_read_b128 v[184:187], v248 offset:6144
	ds_read_b128 v[188:191], v248 offset:7168
	global_load_lds_dwordx4 v[206:207], off
	v_lshl_add_u64 v[206:207], s[42:43], 0, v[202:203]
	s_add_i32 m0, s41, 0xe000
	s_nop 0
	global_load_lds_dwordx4 v[206:207], off
	s_waitcnt vmcnt(8)
	s_waitcnt lgkmcnt(0)
	s_barrier
	s_setprio 1
	v_mfma_f32_16x16x32_bf16 v[148:151], v[112:115], v[160:163], 0
	v_mfma_f32_16x16x32_bf16 v[144:147], v[120:123], v[160:163], 0
	v_mfma_f32_16x16x32_bf16 v[108:111], v[112:115], v[168:171], 0
	v_mfma_f32_16x16x32_bf16 v[104:107], v[120:123], v[168:171], 0
	v_mfma_f32_16x16x32_bf16 v[92:95], v[112:115], v[176:179], 0
	v_mfma_f32_16x16x32_bf16 v[88:91], v[120:123], v[176:179], 0
	v_mfma_f32_16x16x32_bf16 v[76:79], v[112:115], v[184:187], 0
	v_mfma_f32_16x16x32_bf16 v[72:75], v[120:123], v[184:187], 0
	v_mfma_f32_16x16x32_bf16 v[148:151], v[116:119], v[164:167], v[148:151]
	v_mfma_f32_16x16x32_bf16 v[144:147], v[124:127], v[164:167], v[144:147]
	v_mfma_f32_16x16x32_bf16 v[108:111], v[116:119], v[172:175], v[108:111]
	v_mfma_f32_16x16x32_bf16 v[104:107], v[124:127], v[172:175], v[104:107]
	v_mfma_f32_16x16x32_bf16 v[92:95], v[116:119], v[180:183], v[92:95]
	v_mfma_f32_16x16x32_bf16 v[88:91], v[124:127], v[180:183], v[88:91]
	v_mfma_f32_16x16x32_bf16 v[76:79], v[116:119], v[188:191], v[76:79]
	v_mfma_f32_16x16x32_bf16 v[72:75], v[124:127], v[188:191], v[72:75]
	s_setprio 0
	s_setprio 1
	v_mfma_f32_16x16x32_bf16 v[132:135], v[136:139], v[160:163], 0
	v_mfma_f32_16x16x32_bf16 v[128:131], v[152:155], v[160:163], 0
	v_mfma_f32_16x16x32_bf16 v[100:103], v[136:139], v[168:171], 0
	v_mfma_f32_16x16x32_bf16 v[96:99], v[152:155], v[168:171], 0
	v_mfma_f32_16x16x32_bf16 v[84:87], v[136:139], v[176:179], 0
	v_mfma_f32_16x16x32_bf16 v[80:83], v[152:155], v[176:179], 0
	v_mfma_f32_16x16x32_bf16 v[68:71], v[136:139], v[184:187], 0
	v_mfma_f32_16x16x32_bf16 v[64:67], v[152:155], v[184:187], 0
	v_mfma_f32_16x16x32_bf16 v[132:135], v[140:143], v[164:167], v[132:135]
	v_mfma_f32_16x16x32_bf16 v[128:131], v[156:159], v[164:167], v[128:131]
	v_mfma_f32_16x16x32_bf16 v[100:103], v[140:143], v[172:175], v[100:103]
	v_mfma_f32_16x16x32_bf16 v[96:99], v[156:159], v[172:175], v[96:99]
	v_mfma_f32_16x16x32_bf16 v[84:87], v[140:143], v[180:183], v[84:87]
	v_mfma_f32_16x16x32_bf16 v[80:83], v[156:159], v[180:183], v[80:83]
	v_mfma_f32_16x16x32_bf16 v[68:71], v[140:143], v[188:191], v[68:71]
	v_mfma_f32_16x16x32_bf16 v[64:67], v[156:159], v[188:191], v[64:67]
	s_barrier
	s_setprio 0
	s_add_i32 s69, s63, s52
	v_lshl_add_u64 v[206:207], s[44:45], 0, v[194:195]
	s_mov_b32 m0, s69
	ds_read_b128 v[160:163], v248 offset:16384
	ds_read_b128 v[164:167], v248 offset:17408
	ds_read_b128 v[168:171], v248 offset:18432
	ds_read_b128 v[172:175], v248 offset:19456
	ds_read_b128 v[176:179], v248 offset:20480
	ds_read_b128 v[180:183], v248 offset:21504
	ds_read_b128 v[184:187], v248 offset:22528
	ds_read_b128 v[188:191], v248 offset:23552
	global_load_lds_dwordx4 v[206:207], off
	s_add_i32 m0, s69, 0x2000
	s_add_u32 s70, s44, 0x40000
	v_lshl_add_u64 v[208:209], s[44:45], 0, v[198:199]
	s_addc_u32 s71, s45, 0
	s_add_i32 s69, s64, s52
	global_load_lds_dwordx4 v[208:209], off
	v_lshl_add_u64 v[210:211], s[70:71], 0, v[194:195]
	s_mov_b32 m0, s69
	v_lshl_add_u64 v[212:213], s[46:47], 0, v[196:197]
	global_load_lds_dwordx4 v[210:211], off
	v_lshl_add_u64 v[210:211], s[70:71], 0, v[198:199]
	s_add_i32 m0, s69, 0x2000
	s_nop 0
	global_load_lds_dwordx4 v[210:211], off
	v_lshl_add_u64 v[210:211], s[46:47], 0, v[192:193]
	s_mov_b32 m0, s41
	s_nop 0
	global_load_lds_dwordx4 v[210:211], off
	s_mov_b32 m0, s53
	s_nop 0
	global_load_lds_dwordx4 v[212:213], off
	s_waitcnt vmcnt(8)
	s_waitcnt lgkmcnt(0)
	s_barrier
; #define PG8_STAGE(bufoff, gbase, voff) do { _Pragma("unroll") for (int _i = 0; _i < 2; ++_i) \
;         __builtin_amdgcn_global_load_lds((const unsigned*)((const char*)(gbase) + (voff)[_i]), (PG8_LAS unsigned*)(lds + (bufoff) + ldsw + _i * 8192), 16, 0, 0); } while (0)
; #define PG8_LDA(dst, b, h) do { _Pragma("unroll") for (int m = 0; m < 4; ++m) _Pragma("unroll") for (int k = 0; k < 2; ++k) dst[m][k] = *(const PG8_LAS bf16x8*)(lds + PG8_SA(b, h) + aoff + m * 2048 + k * 1024); } while (0)
; #define PG8_LDB(dst, b, h) do { _Pragma("unroll") for (int n = 0; n < 2; ++n) _Pragma("unroll") for (int k = 0; k < 2; ++k) dst[n][k] = *(const PG8_LAS bf16x8*)(lds + PG8_SB(b, h) + boff + n * 2048 + k * 1024); } while (0)
; #define PG8_MMA(ai, bj, At, Bt) do { __builtin_amdgcn_s_setprio(1); _Pragma("unroll") for (int m = 0; m < 4; ++m) _Pragma("unroll") for (int n = 0; n < 2; ++n) _Pragma("unroll") for (int k = 0; k < 2; ++k) \
;         acc[ai][bj][m][n] = __builtin_amdgcn_mfma_f32_16x16x32_bf16(Bt[n][k], At[m][k], acc[ai][bj][m][n], 0, 0, 0); __builtin_amdgcn_s_setprio(0); } while (0)
; #define PG8_WAIT_V(n) asm volatile("s_waitcnt vmcnt(" #n ")" ::: "memory")
; #define PG8_WAIT_L(n) asm volatile("s_waitcnt lgkmcnt(" #n ")" ::: "memory")
; #define PG8_BAR __builtin_amdgcn_s_barrier()
; #define PG8_SCHED __builtin_amdgcn_sched_barrier(0)
; template <class Epi, class Sched, bool ALIGN_EPI = false, bool SP2 = false>
; __device__ __forceinline__ void gemm_phase(PG8_LAS unsigned char* lds, const Gemm g, const Sched& S, const Epi& E) {
;     ...
;             PG8_WAIT_V(8); PG8_WAIT_L(0); PG8_BAR; PG8_MMA(1, 0, At, B0); PG8_MMA(1, 1, At, B1); PG8_BAR; PG8_SCHED;
;             PG8_LDB(B0, 1, 0); PG8_LDB(B1, 1, 1); PG8_SCHED; PG8_LDA(At, 1, 0); PG8_STAGE(PG8_SA(0, 1), a2 + hstep, voffA);
;             PG8_WAIT_V(8); PG8_WAIT_L(0); PG8_BAR; PG8_MMA(0, 0, At, B0); PG8_MMA(0, 1, At, B1); PG8_BAR; PG8_SCHED;
	s_setprio 1
	v_mfma_f32_16x16x32_bf16 v[60:63], v[112:115], v[160:163], 0
	v_mfma_f32_16x16x32_bf16 v[56:59], v[120:123], v[160:163], 0
	v_mfma_f32_16x16x32_bf16 v[44:47], v[112:115], v[168:171], 0
	v_mfma_f32_16x16x32_bf16 v[40:43], v[120:123], v[168:171], 0
	v_mfma_f32_16x16x32_bf16 v[28:31], v[112:115], v[176:179], 0
	v_mfma_f32_16x16x32_bf16 v[24:27], v[120:123], v[176:179], 0
	v_mfma_f32_16x16x32_bf16 v[12:15], v[112:115], v[184:187], 0
	v_mfma_f32_16x16x32_bf16 v[8:11], v[120:123], v[184:187], 0
	v_mfma_f32_16x16x32_bf16 v[60:63], v[116:119], v[164:167], v[60:63]
	v_mfma_f32_16x16x32_bf16 v[56:59], v[124:127], v[164:167], v[56:59]
	v_mfma_f32_16x16x32_bf16 v[44:47], v[116:119], v[172:175], v[44:47]
	v_mfma_f32_16x16x32_bf16 v[40:43], v[124:127], v[172:175], v[40:43]
	v_mfma_f32_16x16x32_bf16 v[28:31], v[116:119], v[180:183], v[28:31]
	v_mfma_f32_16x16x32_bf16 v[24:27], v[124:127], v[180:183], v[24:27]
	v_mfma_f32_16x16x32_bf16 v[12:15], v[116:119], v[188:191], v[12:15]
	v_mfma_f32_16x16x32_bf16 v[8:11], v[124:127], v[188:191], v[8:11]
	s_setprio 0
	s_setprio 1
	v_mfma_f32_16x16x32_bf16 v[52:55], v[136:139], v[160:163], 0
	v_mfma_f32_16x16x32_bf16 v[48:51], v[152:155], v[160:163], 0
	v_mfma_f32_16x16x32_bf16 v[36:39], v[136:139], v[168:171], 0
	v_mfma_f32_16x16x32_bf16 v[32:35], v[152:155], v[168:171], 0
	v_mfma_f32_16x16x32_bf16 v[20:23], v[136:139], v[176:179], 0
	v_mfma_f32_16x16x32_bf16 v[16:19], v[152:155], v[176:179], 0
	v_mfma_f32_16x16x32_bf16 v[4:7], v[136:139], v[184:187], 0
	v_mfma_f32_16x16x32_bf16 v[0:3], v[152:155], v[184:187], 0
	v_mfma_f32_16x16x32_bf16 v[52:55], v[140:143], v[164:167], v[52:55]
	v_mfma_f32_16x16x32_bf16 v[48:51], v[156:159], v[164:167], v[48:51]
	v_mfma_f32_16x16x32_bf16 v[36:39], v[140:143], v[172:175], v[36:39]
	v_mfma_f32_16x16x32_bf16 v[32:35], v[156:159], v[172:175], v[32:35]
	v_mfma_f32_16x16x32_bf16 v[20:23], v[140:143], v[180:183], v[20:23]
	v_mfma_f32_16x16x32_bf16 v[16:19], v[156:159], v[180:183], v[16:19]
	v_mfma_f32_16x16x32_bf16 v[4:7], v[140:143], v[188:191], v[4:7]
	v_mfma_f32_16x16x32_bf16 v[0:3], v[156:159], v[188:191], v[0:3]
	s_barrier
	s_setprio 0
	s_add_i32 s69, 0, 0x18000
	s_add_i32 s70, 0, 0x1c000
	v_add_u32_e32 v124, s69, v244
	v_add_u32_e32 v156, s70, v244
	ds_read_b128 v[112:115], v124
	ds_read_b128 v[116:119], v124 offset:1024
	ds_read_b128 v[120:123], v124 offset:2048
	ds_read_b128 v[124:127], v124 offset:3072
	ds_read_b128 v[136:139], v156
	ds_read_b128 v[140:143], v156 offset:1024
	ds_read_b128 v[152:155], v156 offset:2048
	ds_read_b128 v[156:159], v156 offset:3072
	s_add_u32 s46, s46, 0x40000
	s_addc_u32 s47, s47, 0
	s_mov_b32 m0, s54
	v_lshl_add_u64 v[214:215], s[46:47], 0, v[192:193]
	ds_read_b128 v[160:163], v248 offset:32768
	ds_read_b128 v[164:167], v248 offset:33792
	ds_read_b128 v[168:171], v248 offset:34816
	ds_read_b128 v[172:175], v248 offset:35840
	ds_read_b128 v[176:179], v248 offset:36864
	ds_read_b128 v[180:183], v248 offset:37888
	ds_read_b128 v[184:187], v248 offset:38912
	ds_read_b128 v[188:191], v248 offset:39936
	global_load_lds_dwordx4 v[214:215], off
	v_lshl_add_u64 v[214:215], s[46:47], 0, v[196:197]
	s_mov_b32 m0, s55
	s_nop 0
	global_load_lds_dwordx4 v[214:215], off
	s_waitcnt vmcnt(8)
	s_waitcnt lgkmcnt(0)
	s_barrier
	s_setprio 1
	v_mfma_f32_16x16x32_bf16 v[148:151], v[112:115], v[160:163], v[148:151]
	v_mfma_f32_16x16x32_bf16 v[144:147], v[120:123], v[160:163], v[144:147]
	v_mfma_f32_16x16x32_bf16 v[108:111], v[112:115], v[168:171], v[108:111]
	v_mfma_f32_16x16x32_bf16 v[104:107], v[120:123], v[168:171], v[104:107]
	v_mfma_f32_16x16x32_bf16 v[92:95], v[112:115], v[176:179], v[92:95]
	v_mfma_f32_16x16x32_bf16 v[88:91], v[120:123], v[176:179], v[88:91]
	v_mfma_f32_16x16x32_bf16 v[76:79], v[112:115], v[184:187], v[76:79]
	v_mfma_f32_16x16x32_bf16 v[72:75], v[120:123], v[184:187], v[72:75]
	v_mfma_f32_16x16x32_bf16 v[148:151], v[116:119], v[164:167], v[148:151]
	v_mfma_f32_16x16x32_bf16 v[144:147], v[124:127], v[164:167], v[144:147]
	v_mfma_f32_16x16x32_bf16 v[108:111], v[116:119], v[172:175], v[108:111]
	v_mfma_f32_16x16x32_bf16 v[104:107], v[124:127], v[172:175], v[104:107]
	v_mfma_f32_16x16x32_bf16 v[92:95], v[116:119], v[180:183], v[92:95]
	v_mfma_f32_16x16x32_bf16 v[88:91], v[124:127], v[180:183], v[88:91]
	v_mfma_f32_16x16x32_bf16 v[76:79], v[116:119], v[188:191], v[76:79]
	v_mfma_f32_16x16x32_bf16 v[72:75], v[124:127], v[188:191], v[72:75]
	s_setprio 0
	s_setprio 1
	v_mfma_f32_16x16x32_bf16 v[132:135], v[136:139], v[160:163], v[132:135]
	v_mfma_f32_16x16x32_bf16 v[128:131], v[152:155], v[160:163], v[128:131]
	v_mfma_f32_16x16x32_bf16 v[100:103], v[136:139], v[168:171], v[100:103]
	v_mfma_f32_16x16x32_bf16 v[96:99], v[152:155], v[168:171], v[96:99]
	v_mfma_f32_16x16x32_bf16 v[84:87], v[136:139], v[176:179], v[84:87]
	v_mfma_f32_16x16x32_bf16 v[80:83], v[152:155], v[176:179], v[80:83]
	v_mfma_f32_16x16x32_bf16 v[68:71], v[136:139], v[184:187], v[68:71]
	v_mfma_f32_16x16x32_bf16 v[64:67], v[152:155], v[184:187], v[64:67]
	v_mfma_f32_16x16x32_bf16 v[132:135], v[140:143], v[164:167], v[132:135]
	v_mfma_f32_16x16x32_bf16 v[128:131], v[156:159], v[164:167], v[128:131]
	v_mfma_f32_16x16x32_bf16 v[100:103], v[140:143], v[172:175], v[100:103]
	v_mfma_f32_16x16x32_bf16 v[96:99], v[156:159], v[172:175], v[96:99]
	v_mfma_f32_16x16x32_bf16 v[84:87], v[140:143], v[180:183], v[84:87]
	v_mfma_f32_16x16x32_bf16 v[80:83], v[156:159], v[180:183], v[80:83]
	v_mfma_f32_16x16x32_bf16 v[68:71], v[140:143], v[188:191], v[68:71]
	v_mfma_f32_16x16x32_bf16 v[64:67], v[156:159], v[188:191], v[64:67]
	s_barrier
; #define PG8_STAGE(bufoff, gbase, voff) do { _Pragma("unroll") for (int _i = 0; _i < 2; ++_i) \
;         __builtin_amdgcn_global_load_lds((const unsigned*)((const char*)(gbase) + (voff)[_i]), (PG8_LAS unsigned*)(lds + (bufoff) + ldsw + _i * 8192), 16, 0, 0); } while (0)
; #define PG8_LDA(dst, b, h) do { _Pragma("unroll") for (int m = 0; m < 4; ++m) _Pragma("unroll") for (int k = 0; k < 2; ++k) dst[m][k] = *(const PG8_LAS bf16x8*)(lds + PG8_SA(b, h) + aoff + m * 2048 + k * 1024); } while (0)
; #define PG8_WAIT_V(n) asm volatile("s_waitcnt vmcnt(" #n ")" ::: "memory")
; #define PG8_BAR __builtin_amdgcn_s_barrier()
; template <class Epi, class Sched, bool ALIGN_EPI = false, bool SP2 = false>
; __device__ __forceinline__ void gemm_phase(PG8_LAS unsigned char* lds, const Gemm g, const Sched& S, const Epi& E) {
;     ...
;         for (int t = 0; t < nt; t += 2) {
;             const bool last = (t == nt - 2);
;             if constexpr (Epi::PREFETCH) { if (t == nt - 4) E.prefetch(cur, lds + STAGE_BYTES + 1024, tid); }
;             const char* a1 = cA + (size_t)(t + 1) * kstep;
;             const char* a2 = last ? nA : cA + (size_t)(t + 2) * kstep; const char* b2 = last ? nB : cB + (size_t)(t + 2) * kstep;
;             const char* a3 = a2 + kstep; const char* b3 = b2 + kstep;
;             if (last && has_next) S.a_ready(nxt);
;             if constexpr (SP2) {
;             PG8_LDB(B0, 0, 0); PG8_LDB(B1, 0, 1); PG8_SCHED; PG8_LDA(At, 0, 0); PG8_STAGE(PG8_SA(1, 1), a1 + hstep, voffA);
;             PG8_WAIT_V(8); PG8_WAIT_L(0); PG8_BAR; PG8_MMA(0, 0, At, B0); PG8_MMA(0, 1, At, B1); PG8_BAR; PG8_SCHED;
;             PG8_LDA(At, 0, 1); PG8_STAGE(PG8_SB(0, 0), b2, voffB); PG8_STAGE(PG8_SB(0, 1), b2 + hstep, voffB); PG8_STAGE(PG8_SA(0, 0), a2, voffA);
;             PG8_WAIT_V(8); PG8_WAIT_L(0); PG8_BAR; PG8_MMA(1, 0, At, B0); PG8_MMA(1, 1, At, B1); PG8_BAR; PG8_SCHED;
;             PG8_LDB(B0, 1, 0); PG8_LDB(B1, 1, 1); PG8_SCHED; PG8_LDA(At, 1, 0); PG8_STAGE(PG8_SA(0, 1), a2 + hstep, voffA);
;             PG8_WAIT_V(8); PG8_WAIT_L(0); PG8_BAR; PG8_MMA(0, 0, At, B0); PG8_MMA(0, 1, At, B1); PG8_BAR; PG8_SCHED;
;             PG8_LDA(At, 1, 1); PG8_STAGE(PG8_SB(1, 0), b3, voffB); PG8_STAGE(PG8_SB(1, 1), b3 + hstep, voffB); PG8_STAGE(PG8_SA(1, 0), a3, voffA);
;             PG8_WAIT_V(8); PG8_WAIT_L(0); PG8_BAR; PG8_MMA(1, 0, At, B0); PG8_MMA(1, 1, At, B1); PG8_BAR; PG8_SCHED;
	s_setprio 0
	s_add_i32 s46, s69, s52
	v_lshl_add_u64 v[206:207], v[206:207], 0, s[16:17]
	s_mov_b32 m0, s46
	ds_read_b128 v[160:163], v248 offset:49152
	ds_read_b128 v[164:167], v248 offset:50176
	ds_read_b128 v[168:171], v248 offset:51200
	ds_read_b128 v[172:175], v248 offset:52224
	ds_read_b128 v[176:179], v248 offset:53248
	ds_read_b128 v[180:183], v248 offset:54272
	ds_read_b128 v[184:187], v248 offset:55296
	ds_read_b128 v[188:191], v248 offset:56320
	global_load_lds_dwordx4 v[206:207], off
	s_add_i32 m0, s46, 0x2000
	s_add_u32 s44, s44, 0x40080
	v_lshl_add_u64 v[206:207], v[208:209], 0, s[16:17]
	s_addc_u32 s45, s45, 0
	s_add_i32 s46, s70, s52
	global_load_lds_dwordx4 v[206:207], off
	v_lshl_add_u64 v[206:207], s[44:45], 0, v[194:195]
	s_mov_b32 m0, s46
	s_nop 0
	global_load_lds_dwordx4 v[206:207], off
	v_lshl_add_u64 v[206:207], s[44:45], 0, v[198:199]
	s_add_i32 m0, s46, 0x2000
	s_nop 0
	global_load_lds_dwordx4 v[206:207], off
	v_lshl_add_u64 v[206:207], v[210:211], 0, s[16:17]
	s_mov_b32 m0, s57
	s_nop 0
	global_load_lds_dwordx4 v[206:207], off
	v_lshl_add_u64 v[206:207], v[212:213], 0, s[16:17]
	s_mov_b32 m0, s58
	s_nop 0
	global_load_lds_dwordx4 v[206:207], off
	s_waitcnt vmcnt(8)
	s_waitcnt lgkmcnt(0)
	s_barrier
	s_setprio 1
	v_mfma_f32_16x16x32_bf16 v[60:63], v[112:115], v[160:163], v[60:63]
	v_mfma_f32_16x16x32_bf16 v[56:59], v[120:123], v[160:163], v[56:59]
	v_mfma_f32_16x16x32_bf16 v[44:47], v[112:115], v[168:171], v[44:47]
	v_mfma_f32_16x16x32_bf16 v[40:43], v[120:123], v[168:171], v[40:43]
	v_mfma_f32_16x16x32_bf16 v[28:31], v[112:115], v[176:179], v[28:31]
	v_mfma_f32_16x16x32_bf16 v[24:27], v[120:123], v[176:179], v[24:27]
	v_mfma_f32_16x16x32_bf16 v[12:15], v[112:115], v[184:187], v[12:15]
	v_mfma_f32_16x16x32_bf16 v[8:11], v[120:123], v[184:187], v[8:11]
	v_mfma_f32_16x16x32_bf16 v[60:63], v[116:119], v[164:167], v[60:63]
	v_mfma_f32_16x16x32_bf16 v[56:59], v[124:127], v[164:167], v[56:59]
	v_mfma_f32_16x16x32_bf16 v[44:47], v[116:119], v[172:175], v[44:47]
	v_mfma_f32_16x16x32_bf16 v[40:43], v[124:127], v[172:175], v[40:43]
	v_mfma_f32_16x16x32_bf16 v[28:31], v[116:119], v[180:183], v[28:31]
	v_mfma_f32_16x16x32_bf16 v[24:27], v[124:127], v[180:183], v[24:27]
	v_mfma_f32_16x16x32_bf16 v[12:15], v[116:119], v[188:191], v[12:15]
	v_mfma_f32_16x16x32_bf16 v[8:11], v[124:127], v[188:191], v[8:11]
	s_setprio 0
	s_setprio 1
	v_mfma_f32_16x16x32_bf16 v[52:55], v[136:139], v[160:163], v[52:55]
	v_mfma_f32_16x16x32_bf16 v[48:51], v[152:155], v[160:163], v[48:51]
	v_mfma_f32_16x16x32_bf16 v[36:39], v[136:139], v[168:171], v[36:39]
	v_mfma_f32_16x16x32_bf16 v[32:35], v[152:155], v[168:171], v[32:35]
	v_mfma_f32_16x16x32_bf16 v[20:23], v[136:139], v[176:179], v[20:23]
	v_mfma_f32_16x16x32_bf16 v[16:19], v[152:155], v[176:179], v[16:19]
	v_mfma_f32_16x16x32_bf16 v[4:7], v[136:139], v[184:187], v[4:7]
	v_mfma_f32_16x16x32_bf16 v[0:3], v[152:155], v[184:187], v[0:3]
	v_mfma_f32_16x16x32_bf16 v[52:55], v[140:143], v[164:167], v[52:55]
	v_mfma_f32_16x16x32_bf16 v[48:51], v[156:159], v[164:167], v[48:51]
	v_mfma_f32_16x16x32_bf16 v[36:39], v[140:143], v[172:175], v[36:39]
	v_mfma_f32_16x16x32_bf16 v[32:35], v[156:159], v[172:175], v[32:35]
	v_mfma_f32_16x16x32_bf16 v[20:23], v[140:143], v[180:183], v[20:23]
	v_mfma_f32_16x16x32_bf16 v[16:19], v[156:159], v[180:183], v[16:19]
	v_mfma_f32_16x16x32_bf16 v[4:7], v[140:143], v[188:191], v[4:7]
	v_mfma_f32_16x16x32_bf16 v[0:3], v[156:159], v[188:191], v[0:3]
	s_barrier
	s_setprio 0
	s_add_i32 s68, s68, 2
	s_add_u32 s42, s42, 0x100
	s_addc_u32 s43, s43, 0
	s_add_u32 s66, s66, 0x100
	s_addc_u32 s67, s67, 0
.LBB0_1012:
	ds_read_b128 v[112:115], v246
	ds_read_b128 v[116:119], v246 offset:1024
	ds_read_b128 v[120:123], v246 offset:2048
	ds_read_b128 v[124:127], v246 offset:3072
	ds_read_b128 v[136:139], v247
	ds_read_b128 v[140:143], v247 offset:1024
	ds_read_b128 v[152:155], v247 offset:2048
	ds_read_b128 v[156:159], v247 offset:3072
	s_add_u32 s44, s42, 0xfffc0080
	s_addc_u32 s45, s43, -1
	s_cmp_eq_u32 s68, 12
	s_cselect_b32 s47, s23, s45
	s_cselect_b32 s46, s39, s44
	s_cselect_b32 s45, s21, s67
	s_cselect_b32 s44, s65, s66
	v_lshl_add_u64 v[206:207], s[42:43], 0, v[200:201]
	s_add_i32 m0, s41, 0xc000
	ds_read_b128 v[160:163], v248
	ds_read_b128 v[164:167], v248 offset:1024
	ds_read_b128 v[168:171], v248 offset:2048
	ds_read_b128 v[172:175], v248 offset:3072
	ds_read_b128 v[176:179], v248 offset:4096
	ds_read_b128 v[180:183], v248 offset:5120
	ds_read_b128 v[184:187], v248 offset:6144
	ds_read_b128 v[188:191], v248 offset:7168
	global_load_lds_dwordx4 v[206:207], off
	v_lshl_add_u64 v[206:207], s[42:43], 0, v[202:203]
	s_add_i32 m0, s41, 0xe000
	s_nop 0
	global_load_lds_dwordx4 v[206:207], off
	s_waitcnt vmcnt(8)
	s_waitcnt lgkmcnt(0)
	s_barrier
; #define PG8_STAGE(bufoff, gbase, voff) do { _Pragma("unroll") for (int _i = 0; _i < 2; ++_i) \
;         __builtin_amdgcn_global_load_lds((const unsigned*)((const char*)(gbase) + (voff)[_i]), (PG8_LAS unsigned*)(lds + (bufoff) + ldsw + _i * 8192), 16, 0, 0); } while (0)
; #define PG8_LDA(dst, b, h) do { _Pragma("unroll") for (int m = 0; m < 4; ++m) _Pragma("unroll") for (int k = 0; k < 2; ++k) dst[m][k] = *(const PG8_LAS bf16x8*)(lds + PG8_SA(b, h) + aoff + m * 2048 + k * 1024); } while (0)
; #define PG8_MMA(ai, bj, At, Bt) do { __builtin_amdgcn_s_setprio(1); _Pragma("unroll") for (int m = 0; m < 4; ++m) _Pragma("unroll") for (int n = 0; n < 2; ++n) _Pragma("unroll") for (int k = 0; k < 2; ++k) \
;         acc[ai][bj][m][n] = __builtin_amdgcn_mfma_f32_16x16x32_bf16(Bt[n][k], At[m][k], acc[ai][bj][m][n], 0, 0, 0); __builtin_amdgcn_s_setprio(0); } while (0)
; #define PG8_WAIT_V(n) asm volatile("s_waitcnt vmcnt(" #n ")" ::: "memory")
; #define PG8_WAIT_L(n) asm volatile("s_waitcnt lgkmcnt(" #n ")" ::: "memory")
; #define PG8_BAR __builtin_amdgcn_s_barrier()
; #define PG8_SCHED __builtin_amdgcn_sched_barrier(0)
; template <class Epi, class Sched, bool ALIGN_EPI = false, bool SP2 = false>
; __device__ __forceinline__ void gemm_phase(PG8_LAS unsigned char* lds, const Gemm g, const Sched& S, const Epi& E) {
;     ...
;             PG8_WAIT_V(8); PG8_WAIT_L(0); PG8_BAR; PG8_MMA(0, 0, At, B0); PG8_MMA(0, 1, At, B1); PG8_BAR; PG8_SCHED;
;             PG8_LDA(At, 0, 1); PG8_STAGE(PG8_SB(0, 0), b2, voffB); PG8_STAGE(PG8_SB(0, 1), b2 + hstep, voffB); PG8_STAGE(PG8_SA(0, 0), a2, voffA);
;             PG8_WAIT_V(8); PG8_WAIT_L(0); PG8_BAR; PG8_MMA(1, 0, At, B0); PG8_MMA(1, 1, At, B1); PG8_BAR; PG8_SCHED;
	s_setprio 1
	v_mfma_f32_16x16x32_bf16 v[148:151], v[112:115], v[160:163], v[148:151]
	v_mfma_f32_16x16x32_bf16 v[144:147], v[120:123], v[160:163], v[144:147]
	v_mfma_f32_16x16x32_bf16 v[108:111], v[112:115], v[168:171], v[108:111]
	v_mfma_f32_16x16x32_bf16 v[104:107], v[120:123], v[168:171], v[104:107]
	v_mfma_f32_16x16x32_bf16 v[92:95], v[112:115], v[176:179], v[92:95]
	v_mfma_f32_16x16x32_bf16 v[88:91], v[120:123], v[176:179], v[88:91]
	v_mfma_f32_16x16x32_bf16 v[76:79], v[112:115], v[184:187], v[76:79]
	v_mfma_f32_16x16x32_bf16 v[72:75], v[120:123], v[184:187], v[72:75]
	v_mfma_f32_16x16x32_bf16 v[148:151], v[116:119], v[164:167], v[148:151]
	v_mfma_f32_16x16x32_bf16 v[144:147], v[124:127], v[164:167], v[144:147]
	v_mfma_f32_16x16x32_bf16 v[108:111], v[116:119], v[172:175], v[108:111]
	v_mfma_f32_16x16x32_bf16 v[104:107], v[124:127], v[172:175], v[104:107]
	v_mfma_f32_16x16x32_bf16 v[92:95], v[116:119], v[180:183], v[92:95]
	v_mfma_f32_16x16x32_bf16 v[88:91], v[124:127], v[180:183], v[88:91]
	v_mfma_f32_16x16x32_bf16 v[76:79], v[116:119], v[188:191], v[76:79]
	v_mfma_f32_16x16x32_bf16 v[72:75], v[124:127], v[188:191], v[72:75]
	s_setprio 0
	s_setprio 1
	v_mfma_f32_16x16x32_bf16 v[132:135], v[136:139], v[160:163], v[132:135]
	v_mfma_f32_16x16x32_bf16 v[128:131], v[152:155], v[160:163], v[128:131]
	v_mfma_f32_16x16x32_bf16 v[100:103], v[136:139], v[168:171], v[100:103]
	v_mfma_f32_16x16x32_bf16 v[96:99], v[152:155], v[168:171], v[96:99]
	v_mfma_f32_16x16x32_bf16 v[84:87], v[136:139], v[176:179], v[84:87]
	v_mfma_f32_16x16x32_bf16 v[80:83], v[152:155], v[176:179], v[80:83]
	v_mfma_f32_16x16x32_bf16 v[68:71], v[136:139], v[184:187], v[68:71]
	v_mfma_f32_16x16x32_bf16 v[64:67], v[152:155], v[184:187], v[64:67]
	v_mfma_f32_16x16x32_bf16 v[132:135], v[140:143], v[164:167], v[132:135]
	v_mfma_f32_16x16x32_bf16 v[128:131], v[156:159], v[164:167], v[128:131]
	v_mfma_f32_16x16x32_bf16 v[100:103], v[140:143], v[172:175], v[100:103]
	v_mfma_f32_16x16x32_bf16 v[96:99], v[156:159], v[172:175], v[96:99]
	v_mfma_f32_16x16x32_bf16 v[84:87], v[140:143], v[180:183], v[84:87]
	v_mfma_f32_16x16x32_bf16 v[80:83], v[156:159], v[180:183], v[80:83]
	v_mfma_f32_16x16x32_bf16 v[68:71], v[140:143], v[188:191], v[68:71]
	v_mfma_f32_16x16x32_bf16 v[64:67], v[156:159], v[188:191], v[64:67]
	s_barrier
	s_setprio 0
	s_add_i32 s69, s63, s52
	v_lshl_add_u64 v[206:207], s[44:45], 0, v[194:195]
	s_mov_b32 m0, s69
	ds_read_b128 v[160:163], v248 offset:16384
	ds_read_b128 v[164:167], v248 offset:17408
	ds_read_b128 v[168:171], v248 offset:18432
	ds_read_b128 v[172:175], v248 offset:19456
	ds_read_b128 v[176:179], v248 offset:20480
	ds_read_b128 v[180:183], v248 offset:21504
	ds_read_b128 v[184:187], v248 offset:22528
	ds_read_b128 v[188:191], v248 offset:23552
	global_load_lds_dwordx4 v[206:207], off
	s_add_i32 m0, s69, 0x2000
	s_add_u32 s70, s44, 0x40000
	v_lshl_add_u64 v[208:209], s[44:45], 0, v[198:199]
	s_addc_u32 s71, s45, 0
	s_add_i32 s69, s64, s52
	global_load_lds_dwordx4 v[208:209], off
	v_lshl_add_u64 v[210:211], s[70:71], 0, v[194:195]
	s_mov_b32 m0, s69
	v_lshl_add_u64 v[212:213], s[46:47], 0, v[196:197]
	global_load_lds_dwordx4 v[210:211], off
	v_lshl_add_u64 v[210:211], s[70:71], 0, v[198:199]
	s_add_i32 m0, s69, 0x2000
	s_nop 0
	global_load_lds_dwordx4 v[210:211], off
	v_lshl_add_u64 v[210:211], s[46:47], 0, v[192:193]
	s_mov_b32 m0, s41
	s_nop 0
	global_load_lds_dwordx4 v[210:211], off
	s_mov_b32 m0, s53
	s_nop 0
	global_load_lds_dwordx4 v[212:213], off
	s_waitcnt vmcnt(8)
	s_waitcnt lgkmcnt(0)
	s_barrier
	s_setprio 1
	v_mfma_f32_16x16x32_bf16 v[60:63], v[112:115], v[160:163], v[60:63]
	v_mfma_f32_16x16x32_bf16 v[56:59], v[120:123], v[160:163], v[56:59]
	v_mfma_f32_16x16x32_bf16 v[44:47], v[112:115], v[168:171], v[44:47]
	v_mfma_f32_16x16x32_bf16 v[40:43], v[120:123], v[168:171], v[40:43]
	v_mfma_f32_16x16x32_bf16 v[28:31], v[112:115], v[176:179], v[28:31]
	v_mfma_f32_16x16x32_bf16 v[24:27], v[120:123], v[176:179], v[24:27]
	v_mfma_f32_16x16x32_bf16 v[12:15], v[112:115], v[184:187], v[12:15]
	v_mfma_f32_16x16x32_bf16 v[8:11], v[120:123], v[184:187], v[8:11]
	v_mfma_f32_16x16x32_bf16 v[60:63], v[116:119], v[164:167], v[60:63]
	v_mfma_f32_16x16x32_bf16 v[56:59], v[124:127], v[164:167], v[56:59]
	v_mfma_f32_16x16x32_bf16 v[44:47], v[116:119], v[172:175], v[44:47]
	v_mfma_f32_16x16x32_bf16 v[40:43], v[124:127], v[172:175], v[40:43]
	v_mfma_f32_16x16x32_bf16 v[28:31], v[116:119], v[180:183], v[28:31]
	v_mfma_f32_16x16x32_bf16 v[24:27], v[124:127], v[180:183], v[24:27]
	v_mfma_f32_16x16x32_bf16 v[12:15], v[116:119], v[188:191], v[12:15]
	v_mfma_f32_16x16x32_bf16 v[8:11], v[124:127], v[188:191], v[8:11]
	s_setprio 0
	s_setprio 1
	v_mfma_f32_16x16x32_bf16 v[52:55], v[136:139], v[160:163], v[52:55]
	v_mfma_f32_16x16x32_bf16 v[48:51], v[152:155], v[160:163], v[48:51]
	v_mfma_f32_16x16x32_bf16 v[36:39], v[136:139], v[168:171], v[36:39]
	v_mfma_f32_16x16x32_bf16 v[32:35], v[152:155], v[168:171], v[32:35]
	v_mfma_f32_16x16x32_bf16 v[20:23], v[136:139], v[176:179], v[20:23]
	v_mfma_f32_16x16x32_bf16 v[16:19], v[152:155], v[176:179], v[16:19]
	v_mfma_f32_16x16x32_bf16 v[4:7], v[136:139], v[184:187], v[4:7]
	v_mfma_f32_16x16x32_bf16 v[0:3], v[152:155], v[184:187], v[0:3]
	v_mfma_f32_16x16x32_bf16 v[52:55], v[140:143], v[164:167], v[52:55]
	v_mfma_f32_16x16x32_bf16 v[48:51], v[156:159], v[164:167], v[48:51]
	v_mfma_f32_16x16x32_bf16 v[36:39], v[140:143], v[172:175], v[36:39]
	v_mfma_f32_16x16x32_bf16 v[32:35], v[156:159], v[172:175], v[32:35]
	v_mfma_f32_16x16x32_bf16 v[20:23], v[140:143], v[180:183], v[20:23]
	v_mfma_f32_16x16x32_bf16 v[16:19], v[156:159], v[180:183], v[16:19]
	v_mfma_f32_16x16x32_bf16 v[4:7], v[140:143], v[188:191], v[4:7]
	v_mfma_f32_16x16x32_bf16 v[0:3], v[156:159], v[188:191], v[0:3]
	s_barrier
; #define PG8_STAGE(bufoff, gbase, voff) do { _Pragma("unroll") for (int _i = 0; _i < 2; ++_i) \
;         __builtin_amdgcn_global_load_lds((const unsigned*)((const char*)(gbase) + (voff)[_i]), (PG8_LAS unsigned*)(lds + (bufoff) + ldsw + _i * 8192), 16, 0, 0); } while (0)
; #define PG8_LDA(dst, b, h) do { _Pragma("unroll") for (int m = 0; m < 4; ++m) _Pragma("unroll") for (int k = 0; k < 2; ++k) dst[m][k] = *(const PG8_LAS bf16x8*)(lds + PG8_SA(b, h) + aoff + m * 2048 + k * 1024); } while (0)
; #define PG8_LDB(dst, b, h) do { _Pragma("unroll") for (int n = 0; n < 2; ++n) _Pragma("unroll") for (int k = 0; k < 2; ++k) dst[n][k] = *(const PG8_LAS bf16x8*)(lds + PG8_SB(b, h) + boff + n * 2048 + k * 1024); } while (0)
; #define PG8_MMA(ai, bj, At, Bt) do { __builtin_amdgcn_s_setprio(1); _Pragma("unroll") for (int m = 0; m < 4; ++m) _Pragma("unroll") for (int n = 0; n < 2; ++n) _Pragma("unroll") for (int k = 0; k < 2; ++k) \
;         acc[ai][bj][m][n] = __builtin_amdgcn_mfma_f32_16x16x32_bf16(Bt[n][k], At[m][k], acc[ai][bj][m][n], 0, 0, 0); __builtin_amdgcn_s_setprio(0); } while (0)
; #define PG8_WAIT_V(n) asm volatile("s_waitcnt vmcnt(" #n ")" ::: "memory")
; #define PG8_WAIT_L(n) asm volatile("s_waitcnt lgkmcnt(" #n ")" ::: "memory")
; #define PG8_BAR __builtin_amdgcn_s_barrier()
; #define PG8_SCHED __builtin_amdgcn_sched_barrier(0)
; template <class Epi, class Sched, bool ALIGN_EPI = false, bool SP2 = false>
; __device__ __forceinline__ void gemm_phase(PG8_LAS unsigned char* lds, const Gemm g, const Sched& S, const Epi& E) {
;     ...
;             PG8_LDB(B0, 1, 0); PG8_LDB(B1, 1, 1); PG8_SCHED; PG8_LDA(At, 1, 0); PG8_STAGE(PG8_SA(0, 1), a2 + hstep, voffA);
;             PG8_WAIT_V(8); PG8_WAIT_L(0); PG8_BAR; PG8_MMA(0, 0, At, B0); PG8_MMA(0, 1, At, B1); PG8_BAR; PG8_SCHED;
	s_setprio 0
	s_add_i32 s69, 0, 0x18000
	s_add_i32 s70, 0, 0x1c000
	v_add_u32_e32 v124, s69, v244
	v_add_u32_e32 v156, s70, v244
	ds_read_b128 v[112:115], v124
	ds_read_b128 v[116:119], v124 offset:1024
	ds_read_b128 v[120:123], v124 offset:2048
	ds_read_b128 v[124:127], v124 offset:3072
	ds_read_b128 v[136:139], v156
	ds_read_b128 v[140:143], v156 offset:1024
	ds_read_b128 v[152:155], v156 offset:2048
	ds_read_b128 v[156:159], v156 offset:3072
	s_add_u32 s46, s46, 0x40000
	s_addc_u32 s47, s47, 0
	s_mov_b32 m0, s54
	v_lshl_add_u64 v[214:215], s[46:47], 0, v[192:193]
	ds_read_b128 v[160:163], v248 offset:32768
	ds_read_b128 v[164:167], v248 offset:33792
	ds_read_b128 v[168:171], v248 offset:34816
	ds_read_b128 v[172:175], v248 offset:35840
	ds_read_b128 v[176:179], v248 offset:36864
	ds_read_b128 v[180:183], v248 offset:37888
	ds_read_b128 v[184:187], v248 offset:38912
	ds_read_b128 v[188:191], v248 offset:39936
	global_load_lds_dwordx4 v[214:215], off
	v_lshl_add_u64 v[214:215], s[46:47], 0, v[196:197]
	s_mov_b32 m0, s55
	s_nop 0
	global_load_lds_dwordx4 v[214:215], off
	s_waitcnt vmcnt(8)
	s_waitcnt lgkmcnt(0)
	s_barrier
	s_setprio 1
	v_mfma_f32_16x16x32_bf16 v[148:151], v[112:115], v[160:163], v[148:151]
	v_mfma_f32_16x16x32_bf16 v[144:147], v[120:123], v[160:163], v[144:147]
	v_mfma_f32_16x16x32_bf16 v[108:111], v[112:115], v[168:171], v[108:111]
	v_mfma_f32_16x16x32_bf16 v[104:107], v[120:123], v[168:171], v[104:107]
	v_mfma_f32_16x16x32_bf16 v[92:95], v[112:115], v[176:179], v[92:95]
	v_mfma_f32_16x16x32_bf16 v[88:91], v[120:123], v[176:179], v[88:91]
	v_mfma_f32_16x16x32_bf16 v[76:79], v[112:115], v[184:187], v[76:79]
	v_mfma_f32_16x16x32_bf16 v[72:75], v[120:123], v[184:187], v[72:75]
	v_mfma_f32_16x16x32_bf16 v[148:151], v[116:119], v[164:167], v[148:151]
	v_mfma_f32_16x16x32_bf16 v[144:147], v[124:127], v[164:167], v[144:147]
	v_mfma_f32_16x16x32_bf16 v[108:111], v[116:119], v[172:175], v[108:111]
	v_mfma_f32_16x16x32_bf16 v[104:107], v[124:127], v[172:175], v[104:107]
	v_mfma_f32_16x16x32_bf16 v[92:95], v[116:119], v[180:183], v[92:95]
	v_mfma_f32_16x16x32_bf16 v[88:91], v[124:127], v[180:183], v[88:91]
	v_mfma_f32_16x16x32_bf16 v[76:79], v[116:119], v[188:191], v[76:79]
	v_mfma_f32_16x16x32_bf16 v[72:75], v[124:127], v[188:191], v[72:75]
	s_setprio 0
	s_setprio 1
	v_mfma_f32_16x16x32_bf16 v[132:135], v[136:139], v[160:163], v[132:135]
	v_mfma_f32_16x16x32_bf16 v[128:131], v[152:155], v[160:163], v[128:131]
	v_mfma_f32_16x16x32_bf16 v[100:103], v[136:139], v[168:171], v[100:103]
	v_mfma_f32_16x16x32_bf16 v[96:99], v[152:155], v[168:171], v[96:99]
	v_mfma_f32_16x16x32_bf16 v[84:87], v[136:139], v[176:179], v[84:87]
	v_mfma_f32_16x16x32_bf16 v[80:83], v[152:155], v[176:179], v[80:83]
	v_mfma_f32_16x16x32_bf16 v[68:71], v[136:139], v[184:187], v[68:71]
	v_mfma_f32_16x16x32_bf16 v[64:67], v[152:155], v[184:187], v[64:67]
	v_mfma_f32_16x16x32_bf16 v[132:135], v[140:143], v[164:167], v[132:135]
	v_mfma_f32_16x16x32_bf16 v[128:131], v[156:159], v[164:167], v[128:131]
	v_mfma_f32_16x16x32_bf16 v[100:103], v[140:143], v[172:175], v[100:103]
	v_mfma_f32_16x16x32_bf16 v[96:99], v[156:159], v[172:175], v[96:99]
	v_mfma_f32_16x16x32_bf16 v[84:87], v[140:143], v[180:183], v[84:87]
	v_mfma_f32_16x16x32_bf16 v[80:83], v[156:159], v[180:183], v[80:83]
	v_mfma_f32_16x16x32_bf16 v[68:71], v[140:143], v[188:191], v[68:71]
	v_mfma_f32_16x16x32_bf16 v[64:67], v[156:159], v[188:191], v[64:67]
	s_barrier
; #define PG8_STAGE(bufoff, gbase, voff) do { _Pragma("unroll") for (int _i = 0; _i < 2; ++_i) \
;         __builtin_amdgcn_global_load_lds((const unsigned*)((const char*)(gbase) + (voff)[_i]), (PG8_LAS unsigned*)(lds + (bufoff) + ldsw + _i * 8192), 16, 0, 0); } while (0)
; #define PG8_LDA(dst, b, h) do { _Pragma("unroll") for (int m = 0; m < 4; ++m) _Pragma("unroll") for (int k = 0; k < 2; ++k) dst[m][k] = *(const PG8_LAS bf16x8*)(lds + PG8_SA(b, h) + aoff + m * 2048 + k * 1024); } while (0)
; #define PG8_MMA(ai, bj, At, Bt) do { __builtin_amdgcn_s_setprio(1); _Pragma("unroll") for (int m = 0; m < 4; ++m) _Pragma("unroll") for (int n = 0; n < 2; ++n) _Pragma("unroll") for (int k = 0; k < 2; ++k) \
;         acc[ai][bj][m][n] = __builtin_amdgcn_mfma_f32_16x16x32_bf16(Bt[n][k], At[m][k], acc[ai][bj][m][n], 0, 0, 0); __builtin_amdgcn_s_setprio(0); } while (0)
; #define PG8_WAIT_V(n) asm volatile("s_waitcnt vmcnt(" #n ")" ::: "memory")
; #define PG8_WAIT_L(n) asm volatile("s_waitcnt lgkmcnt(" #n ")" ::: "memory")
; #define PG8_BAR __builtin_amdgcn_s_barrier()
; #define PG8_SCHED __builtin_amdgcn_sched_barrier(0)
; template <class Epi, class Sched, bool ALIGN_EPI = false, bool SP2 = false>
; __device__ __forceinline__ void gemm_phase(PG8_LAS unsigned char* lds, const Gemm g, const Sched& S, const Epi& E) {
;     ...
;             PG8_LDA(At, 1, 1); PG8_STAGE(PG8_SB(1, 0), b3, voffB); PG8_STAGE(PG8_SB(1, 1), b3 + hstep, voffB); PG8_STAGE(PG8_SA(1, 0), a3, voffA);
;             PG8_WAIT_V(8); PG8_WAIT_L(0); PG8_BAR; PG8_MMA(1, 0, At, B0); PG8_MMA(1, 1, At, B1); PG8_BAR; PG8_SCHED;
	s_setprio 0
	s_add_i32 s46, s69, s52
	v_lshl_add_u64 v[206:207], v[206:207], 0, s[16:17]
	s_mov_b32 m0, s46
	ds_read_b128 v[160:163], v248 offset:49152
	ds_read_b128 v[164:167], v248 offset:50176
	ds_read_b128 v[168:171], v248 offset:51200
	ds_read_b128 v[172:175], v248 offset:52224
	ds_read_b128 v[176:179], v248 offset:53248
	ds_read_b128 v[180:183], v248 offset:54272
	ds_read_b128 v[184:187], v248 offset:55296
	ds_read_b128 v[188:191], v248 offset:56320
	global_load_lds_dwordx4 v[206:207], off
	s_add_i32 m0, s46, 0x2000
	s_add_u32 s44, s44, 0x40080
	v_lshl_add_u64 v[206:207], v[208:209], 0, s[16:17]
	s_addc_u32 s45, s45, 0
	s_add_i32 s46, s70, s52
	global_load_lds_dwordx4 v[206:207], off
	v_lshl_add_u64 v[206:207], s[44:45], 0, v[194:195]
	s_mov_b32 m0, s46
	s_nop 0
	global_load_lds_dwordx4 v[206:207], off
	v_lshl_add_u64 v[206:207], s[44:45], 0, v[198:199]
	s_add_i32 m0, s46, 0x2000
	s_nop 0
	global_load_lds_dwordx4 v[206:207], off
	v_lshl_add_u64 v[206:207], v[210:211], 0, s[16:17]
	s_mov_b32 m0, s57
	s_nop 0
	global_load_lds_dwordx4 v[206:207], off
	v_lshl_add_u64 v[206:207], v[212:213], 0, s[16:17]
	s_mov_b32 m0, s58
	s_nop 0
	global_load_lds_dwordx4 v[206:207], off
	s_waitcnt vmcnt(8)
	s_waitcnt lgkmcnt(0)
	s_barrier
	s_setprio 1
	v_mfma_f32_16x16x32_bf16 v[60:63], v[112:115], v[160:163], v[60:63]
	v_mfma_f32_16x16x32_bf16 v[56:59], v[120:123], v[160:163], v[56:59]
	v_mfma_f32_16x16x32_bf16 v[44:47], v[112:115], v[168:171], v[44:47]
	v_mfma_f32_16x16x32_bf16 v[40:43], v[120:123], v[168:171], v[40:43]
	v_mfma_f32_16x16x32_bf16 v[28:31], v[112:115], v[176:179], v[28:31]
	v_mfma_f32_16x16x32_bf16 v[24:27], v[120:123], v[176:179], v[24:27]
	v_mfma_f32_16x16x32_bf16 v[12:15], v[112:115], v[184:187], v[12:15]
	v_mfma_f32_16x16x32_bf16 v[8:11], v[120:123], v[184:187], v[8:11]
	v_mfma_f32_16x16x32_bf16 v[60:63], v[116:119], v[164:167], v[60:63]
	v_mfma_f32_16x16x32_bf16 v[56:59], v[124:127], v[164:167], v[56:59]
	v_mfma_f32_16x16x32_bf16 v[44:47], v[116:119], v[172:175], v[44:47]
	v_mfma_f32_16x16x32_bf16 v[40:43], v[124:127], v[172:175], v[40:43]
	v_mfma_f32_16x16x32_bf16 v[28:31], v[116:119], v[180:183], v[28:31]
	v_mfma_f32_16x16x32_bf16 v[24:27], v[124:127], v[180:183], v[24:27]
	v_mfma_f32_16x16x32_bf16 v[12:15], v[116:119], v[188:191], v[12:15]
	v_mfma_f32_16x16x32_bf16 v[8:11], v[124:127], v[188:191], v[8:11]
	s_setprio 0
	s_setprio 1
	v_mfma_f32_16x16x32_bf16 v[52:55], v[136:139], v[160:163], v[52:55]
	v_mfma_f32_16x16x32_bf16 v[48:51], v[152:155], v[160:163], v[48:51]
	v_mfma_f32_16x16x32_bf16 v[36:39], v[136:139], v[168:171], v[36:39]
	v_mfma_f32_16x16x32_bf16 v[32:35], v[152:155], v[168:171], v[32:35]
	v_mfma_f32_16x16x32_bf16 v[20:23], v[136:139], v[176:179], v[20:23]
	v_mfma_f32_16x16x32_bf16 v[16:19], v[152:155], v[176:179], v[16:19]
	v_mfma_f32_16x16x32_bf16 v[4:7], v[136:139], v[184:187], v[4:7]
	v_mfma_f32_16x16x32_bf16 v[0:3], v[152:155], v[184:187], v[0:3]
	v_mfma_f32_16x16x32_bf16 v[52:55], v[140:143], v[164:167], v[52:55]
	v_mfma_f32_16x16x32_bf16 v[48:51], v[156:159], v[164:167], v[48:51]
	v_mfma_f32_16x16x32_bf16 v[36:39], v[140:143], v[172:175], v[36:39]
	v_mfma_f32_16x16x32_bf16 v[32:35], v[156:159], v[172:175], v[32:35]
	v_mfma_f32_16x16x32_bf16 v[20:23], v[140:143], v[180:183], v[20:23]
	v_mfma_f32_16x16x32_bf16 v[16:19], v[156:159], v[180:183], v[16:19]
	v_mfma_f32_16x16x32_bf16 v[4:7], v[140:143], v[188:191], v[4:7]
	v_mfma_f32_16x16x32_bf16 v[0:3], v[156:159], v[188:191], v[0:3]
	s_barrier
	s_setprio 0
	s_add_i32 s68, s68, 2
	s_add_u32 s42, s42, 0x100
	s_addc_u32 s43, s43, 0
	s_add_u32 s66, s66, 0x100
	s_addc_u32 s67, s67, 0
	s_cmp_gt_u32 s68, 13
	s_cbranch_scc0 .LBB0_1012
	s_and_b64 vcc, exec, s[18:19]
	s_cbranch_vccz .LBB0_1015
	s_barrier

; #define PG8_STAGE(bufoff, gbase, voff) do { _Pragma("unroll") for (int _i = 0; _i < 2; ++_i) \
;         __builtin_amdgcn_global_load_lds((const unsigned*)((const char*)(gbase) + (voff)[_i]), (PG8_LAS unsigned*)(lds + (bufoff) + ldsw + _i * 8192), 16, 0, 0); } while (0)
; #define PG8_LDA(dst, b, h) do { _Pragma("unroll") for (int m = 0; m < 4; ++m) _Pragma("unroll") for (int k = 0; k < 2; ++k) dst[m][k] = *(const PG8_LAS bf16x8*)(lds + PG8_SA(b, h) + aoff + m * 2048 + k * 1024); } while (0)
; #define PG8_LDB(dst, b, h) do { _Pragma("unroll") for (int n = 0; n < 2; ++n) _Pragma("unroll") for (int k = 0; k < 2; ++k) dst[n][k] = *(const PG8_LAS bf16x8*)(lds + PG8_SB(b, h) + boff + n * 2048 + k * 1024); } while (0)
; #define PG8_WAIT_V(n) asm volatile("s_waitcnt vmcnt(" #n ")" ::: "memory")
; #define PG8_WAIT_L(n) asm volatile("s_waitcnt lgkmcnt(" #n ")" ::: "memory")
; template <class Epi, class Sched, bool ALIGN_EPI = false, bool SP2 = false>
; __device__ __forceinline__ void gemm_phase(PG8_LAS unsigned char* lds, const Gemm g, const Sched& S, const Epi& E) {
;     ...
;         const bool has_next = S.next(ui + 1, nxt);
;         const char* nA = has_next ? (const char*)g.A + (size_t)nxt.pm * tstep : cA; const char* nB = has_next ? (const char*)g.Bt + (size_t)nxt.pn * tstep : cB;
;         for (int t = 0; t < nt; t += 2) {
;             const bool last = (t == nt - 2);
;             if constexpr (Epi::PREFETCH) { if (t == nt - 4) E.prefetch(cur, lds + STAGE_BYTES + 1024, tid); }
;             const char* a1 = cA + (size_t)(t + 1) * kstep;
;             const char* a2 = last ? nA : cA + (size_t)(t + 2) * kstep; const char* b2 = last ? nB : cB + (size_t)(t + 2) * kstep;
;             const char* a3 = a2 + kstep; const char* b3 = b2 + kstep;
;             if (last && has_next) S.a_ready(nxt);
;             if constexpr (SP2) {
;             PG8_LDB(B0, 0, 0); PG8_LDB(B1, 0, 1); PG8_SCHED; PG8_LDA(At, 0, 0); PG8_STAGE(PG8_SA(1, 1), a1 + hstep, voffA);
;             PG8_WAIT_V(8); PG8_WAIT_L(0); PG8_BAR; PG8_MMA(0, 0, At, B0); PG8_MMA(0, 1, At, B1); PG8_BAR; PG8_SCHED;
;             PG8_LDA(At, 0, 1); PG8_STAGE(PG8_SB(0, 0), b2, voffB); PG8_STAGE(PG8_SB(0, 1), b2 + hstep, voffB); PG8_STAGE(PG8_SA(0, 0), a2, voffA);
;             PG8_WAIT_V(8); PG8_WAIT_L(0); PG8_BAR; PG8_MMA(1, 0, At, B0); PG8_MMA(1, 1, At, B1); PG8_BAR; PG8_SCHED;
.LBB0_1193:
	s_ashr_i32 s21, s20, 31
	s_lshl_b64 s[22:23], s[20:21], 19
	s_add_u32 s22, s44, s22
	s_addc_u32 s23, s45, s23
	s_and_b64 s[34:35], s[4:5], exec
	s_cselect_b32 s21, s23, s39
	s_cselect_b32 s64, s22, s38
	s_ashr_i32 s19, s18, 31
	s_lshl_b64 s[34:35], s[18:19], 19
	s_add_u32 s34, s46, s34
	s_addc_u32 s35, s47, s35
	s_and_b64 s[42:43], s[4:5], exec
	s_cselect_b32 s19, s35, s41
	s_cselect_b32 s65, s34, s40
	s_add_u32 s38, s38, 0x40080
	s_addc_u32 s39, s39, 0
	s_add_u32 s66, s40, 0x100
	s_addc_u32 s67, s41, 0
	s_mov_b32 s68, -2
	ds_read_b128 v[154:157], v149
	ds_read_b128 v[158:161], v149 offset:1024
	ds_read_b128 v[162:165], v149 offset:2048
	ds_read_b128 v[166:169], v149 offset:3072
	ds_read_b128 v[170:173], v150
	ds_read_b128 v[174:177], v150 offset:1024
	ds_read_b128 v[178:181], v150 offset:2048
	ds_read_b128 v[182:185], v150 offset:3072
	s_add_u32 s40, s38, 0xfffc0080
	s_addc_u32 s41, s39, -1
	s_cmp_eq_u32 s68, 12
	s_cselect_b32 s43, s21, s41
	s_cselect_b32 s42, s64, s40
	s_cselect_b32 s41, s19, s67
	s_cselect_b32 s40, s65, s66
	v_lshl_add_u64 v[144:145], s[38:39], 0, v[136:137]
	s_add_i32 m0, s37, 0xc000
	ds_read_b128 v[186:189], v151
	ds_read_b128 v[190:193], v151 offset:1024
	ds_read_b128 v[194:197], v151 offset:2048
	ds_read_b128 v[198:201], v151 offset:3072
	ds_read_b128 v[202:205], v151 offset:4096
	ds_read_b128 v[206:209], v151 offset:5120
	ds_read_b128 v[210:213], v151 offset:6144
	ds_read_b128 v[214:217], v151 offset:7168
	global_load_lds_dwordx4 v[144:145], off
	v_lshl_add_u64 v[144:145], s[38:39], 0, v[138:139]
	s_add_i32 m0, s37, 0xe000
	s_nop 0
	global_load_lds_dwordx4 v[144:145], off
	s_waitcnt vmcnt(8)
	s_waitcnt lgkmcnt(0)
	s_barrier
	s_setprio 1
	v_mfma_f32_16x16x32_bf16 v[120:123], v[154:157], v[186:189], 0
	v_mfma_f32_16x16x32_bf16 v[116:119], v[162:165], v[186:189], 0
	v_mfma_f32_16x16x32_bf16 v[108:111], v[154:157], v[194:197], 0
	v_mfma_f32_16x16x32_bf16 v[100:103], v[162:165], v[194:197], 0
	v_mfma_f32_16x16x32_bf16 v[92:95], v[154:157], v[202:205], 0
	v_mfma_f32_16x16x32_bf16 v[84:87], v[162:165], v[202:205], 0
	v_mfma_f32_16x16x32_bf16 v[76:79], v[154:157], v[210:213], 0
	v_mfma_f32_16x16x32_bf16 v[68:71], v[162:165], v[210:213], 0
	v_mfma_f32_16x16x32_bf16 v[120:123], v[158:161], v[190:193], v[120:123]
	v_mfma_f32_16x16x32_bf16 v[116:119], v[166:169], v[190:193], v[116:119]
	v_mfma_f32_16x16x32_bf16 v[108:111], v[158:161], v[198:201], v[108:111]
	v_mfma_f32_16x16x32_bf16 v[100:103], v[166:169], v[198:201], v[100:103]
	v_mfma_f32_16x16x32_bf16 v[92:95], v[158:161], v[206:209], v[92:95]
	v_mfma_f32_16x16x32_bf16 v[84:87], v[166:169], v[206:209], v[84:87]
	v_mfma_f32_16x16x32_bf16 v[76:79], v[158:161], v[214:217], v[76:79]
	v_mfma_f32_16x16x32_bf16 v[68:71], v[166:169], v[214:217], v[68:71]
	s_setprio 0
	s_setprio 1
	v_mfma_f32_16x16x32_bf16 v[124:127], v[170:173], v[186:189], 0
	v_mfma_f32_16x16x32_bf16 v[112:115], v[178:181], v[186:189], 0
	v_mfma_f32_16x16x32_bf16 v[104:107], v[170:173], v[194:197], 0
	v_mfma_f32_16x16x32_bf16 v[96:99], v[178:181], v[194:197], 0
	v_mfma_f32_16x16x32_bf16 v[88:91], v[170:173], v[202:205], 0
	v_mfma_f32_16x16x32_bf16 v[80:83], v[178:181], v[202:205], 0
	v_mfma_f32_16x16x32_bf16 v[72:75], v[170:173], v[210:213], 0
	v_mfma_f32_16x16x32_bf16 v[64:67], v[178:181], v[210:213], 0
	v_mfma_f32_16x16x32_bf16 v[124:127], v[174:177], v[190:193], v[124:127]
	v_mfma_f32_16x16x32_bf16 v[112:115], v[182:185], v[190:193], v[112:115]
	v_mfma_f32_16x16x32_bf16 v[104:107], v[174:177], v[198:201], v[104:107]
	v_mfma_f32_16x16x32_bf16 v[96:99], v[182:185], v[198:201], v[96:99]
	v_mfma_f32_16x16x32_bf16 v[88:91], v[174:177], v[206:209], v[88:91]
	v_mfma_f32_16x16x32_bf16 v[80:83], v[182:185], v[206:209], v[80:83]
	v_mfma_f32_16x16x32_bf16 v[72:75], v[174:177], v[214:217], v[72:75]
	v_mfma_f32_16x16x32_bf16 v[64:67], v[182:185], v[214:217], v[64:67]
	s_barrier
	s_setprio 0
	s_add_i32 s69, s57, s48
	v_lshl_add_u64 v[144:145], s[40:41], 0, v[132:133]
	s_mov_b32 m0, s69
	ds_read_b128 v[186:189], v151 offset:16384
	ds_read_b128 v[190:193], v151 offset:17408
	ds_read_b128 v[194:197], v151 offset:18432
	ds_read_b128 v[198:201], v151 offset:19456
	ds_read_b128 v[202:205], v151 offset:20480
	ds_read_b128 v[206:209], v151 offset:21504
	ds_read_b128 v[210:213], v151 offset:22528
	ds_read_b128 v[214:217], v151 offset:23552
	global_load_lds_dwordx4 v[144:145], off
	s_add_i32 m0, s69, 0x2000
	s_add_u32 s70, s40, 0x40000
	v_lshl_add_u64 v[218:219], s[40:41], 0, v[128:129]
	s_addc_u32 s71, s41, 0
	s_add_i32 s69, s58, s48
	global_load_lds_dwordx4 v[218:219], off
	v_lshl_add_u64 v[220:221], s[70:71], 0, v[132:133]
	s_mov_b32 m0, s69
	v_lshl_add_u64 v[222:223], s[42:43], 0, v[130:131]
	global_load_lds_dwordx4 v[220:221], off
	v_lshl_add_u64 v[220:221], s[70:71], 0, v[128:129]
	s_add_i32 m0, s69, 0x2000
	s_nop 0
	global_load_lds_dwordx4 v[220:221], off
	v_lshl_add_u64 v[220:221], s[42:43], 0, v[134:135]
	s_mov_b32 m0, s37
	s_nop 0
	global_load_lds_dwordx4 v[220:221], off
	s_mov_b32 m0, s50
	s_nop 0
	global_load_lds_dwordx4 v[222:223], off
	s_waitcnt vmcnt(8)
	s_waitcnt lgkmcnt(0)
	s_barrier
; #define PG8_STAGE(bufoff, gbase, voff) do { _Pragma("unroll") for (int _i = 0; _i < 2; ++_i) \
;         __builtin_amdgcn_global_load_lds((const unsigned*)((const char*)(gbase) + (voff)[_i]), (PG8_LAS unsigned*)(lds + (bufoff) + ldsw + _i * 8192), 16, 0, 0); } while (0)
; #define PG8_LDA(dst, b, h) do { _Pragma("unroll") for (int m = 0; m < 4; ++m) _Pragma("unroll") for (int k = 0; k < 2; ++k) dst[m][k] = *(const PG8_LAS bf16x8*)(lds + PG8_SA(b, h) + aoff + m * 2048 + k * 1024); } while (0)
; #define PG8_LDB(dst, b, h) do { _Pragma("unroll") for (int n = 0; n < 2; ++n) _Pragma("unroll") for (int k = 0; k < 2; ++k) dst[n][k] = *(const PG8_LAS bf16x8*)(lds + PG8_SB(b, h) + boff + n * 2048 + k * 1024); } while (0)
; #define PG8_MMA(ai, bj, At, Bt) do { __builtin_amdgcn_s_setprio(1); _Pragma("unroll") for (int m = 0; m < 4; ++m) _Pragma("unroll") for (int n = 0; n < 2; ++n) _Pragma("unroll") for (int k = 0; k < 2; ++k) \
;         acc[ai][bj][m][n] = __builtin_amdgcn_mfma_f32_16x16x32_bf16(Bt[n][k], At[m][k], acc[ai][bj][m][n], 0, 0, 0); __builtin_amdgcn_s_setprio(0); } while (0)
; #define PG8_WAIT_V(n) asm volatile("s_waitcnt vmcnt(" #n ")" ::: "memory")
; #define PG8_WAIT_L(n) asm volatile("s_waitcnt lgkmcnt(" #n ")" ::: "memory")
; #define PG8_BAR __builtin_amdgcn_s_barrier()
; #define PG8_SCHED __builtin_amdgcn_sched_barrier(0)
; template <class Epi, class Sched, bool ALIGN_EPI = false, bool SP2 = false>
; __device__ __forceinline__ void gemm_phase(PG8_LAS unsigned char* lds, const Gemm g, const Sched& S, const Epi& E) {
;     ...
;             PG8_WAIT_V(8); PG8_WAIT_L(0); PG8_BAR; PG8_MMA(1, 0, At, B0); PG8_MMA(1, 1, At, B1); PG8_BAR; PG8_SCHED;
;             PG8_LDB(B0, 1, 0); PG8_LDB(B1, 1, 1); PG8_SCHED; PG8_LDA(At, 1, 0); PG8_STAGE(PG8_SA(0, 1), a2 + hstep, voffA);
;             PG8_WAIT_V(8); PG8_WAIT_L(0); PG8_BAR; PG8_MMA(0, 0, At, B0); PG8_MMA(0, 1, At, B1); PG8_BAR; PG8_SCHED;
	s_setprio 1
	v_mfma_f32_16x16x32_bf16 v[60:63], v[154:157], v[186:189], 0
	v_mfma_f32_16x16x32_bf16 v[52:55], v[162:165], v[186:189], 0
	v_mfma_f32_16x16x32_bf16 v[44:47], v[154:157], v[194:197], 0
	v_mfma_f32_16x16x32_bf16 v[36:39], v[162:165], v[194:197], 0
	v_mfma_f32_16x16x32_bf16 v[28:31], v[154:157], v[202:205], 0
	v_mfma_f32_16x16x32_bf16 v[20:23], v[162:165], v[202:205], 0
	v_mfma_f32_16x16x32_bf16 v[12:15], v[154:157], v[210:213], 0
	v_mfma_f32_16x16x32_bf16 v[4:7], v[162:165], v[210:213], 0
	v_mfma_f32_16x16x32_bf16 v[60:63], v[158:161], v[190:193], v[60:63]
	v_mfma_f32_16x16x32_bf16 v[52:55], v[166:169], v[190:193], v[52:55]
	v_mfma_f32_16x16x32_bf16 v[44:47], v[158:161], v[198:201], v[44:47]
	v_mfma_f32_16x16x32_bf16 v[36:39], v[166:169], v[198:201], v[36:39]
	v_mfma_f32_16x16x32_bf16 v[28:31], v[158:161], v[206:209], v[28:31]
	v_mfma_f32_16x16x32_bf16 v[20:23], v[166:169], v[206:209], v[20:23]
	v_mfma_f32_16x16x32_bf16 v[12:15], v[158:161], v[214:217], v[12:15]
	v_mfma_f32_16x16x32_bf16 v[4:7], v[166:169], v[214:217], v[4:7]
	s_setprio 0
	s_setprio 1
	v_mfma_f32_16x16x32_bf16 v[56:59], v[170:173], v[186:189], 0
	v_mfma_f32_16x16x32_bf16 v[48:51], v[178:181], v[186:189], 0
	v_mfma_f32_16x16x32_bf16 v[40:43], v[170:173], v[194:197], 0
	v_mfma_f32_16x16x32_bf16 v[32:35], v[178:181], v[194:197], 0
	v_mfma_f32_16x16x32_bf16 v[24:27], v[170:173], v[202:205], 0
	v_mfma_f32_16x16x32_bf16 v[16:19], v[178:181], v[202:205], 0
	v_mfma_f32_16x16x32_bf16 v[8:11], v[170:173], v[210:213], 0
	v_mfma_f32_16x16x32_bf16 v[0:3], v[178:181], v[210:213], 0
	v_mfma_f32_16x16x32_bf16 v[56:59], v[174:177], v[190:193], v[56:59]
	v_mfma_f32_16x16x32_bf16 v[48:51], v[182:185], v[190:193], v[48:51]
	v_mfma_f32_16x16x32_bf16 v[40:43], v[174:177], v[198:201], v[40:43]
	v_mfma_f32_16x16x32_bf16 v[32:35], v[182:185], v[198:201], v[32:35]
	v_mfma_f32_16x16x32_bf16 v[24:27], v[174:177], v[206:209], v[24:27]
	v_mfma_f32_16x16x32_bf16 v[16:19], v[182:185], v[206:209], v[16:19]
	v_mfma_f32_16x16x32_bf16 v[8:11], v[174:177], v[214:217], v[8:11]
	v_mfma_f32_16x16x32_bf16 v[0:3], v[182:185], v[214:217], v[0:3]
	s_barrier
	s_setprio 0
	s_add_i32 s69, 0, 0x18000
	v_add_u32_e32 v153, s69, v147
	s_add_i32 s70, 0, 0x1c000
	ds_read_b128 v[154:157], v153
	ds_read_b128 v[158:161], v153 offset:1024
	ds_read_b128 v[162:165], v153 offset:2048
	ds_read_b128 v[166:169], v153 offset:3072
	v_add_u32_e32 v153, s70, v147
	ds_read_b128 v[170:173], v153
	ds_read_b128 v[174:177], v153 offset:1024
	ds_read_b128 v[178:181], v153 offset:2048
	ds_read_b128 v[182:185], v153 offset:3072
	s_add_u32 s42, s42, 0x40000
	s_addc_u32 s43, s43, 0
	s_mov_b32 m0, s51
	v_lshl_add_u64 v[224:225], s[42:43], 0, v[134:135]
	ds_read_b128 v[186:189], v151 offset:32768
	ds_read_b128 v[190:193], v151 offset:33792
	ds_read_b128 v[194:197], v151 offset:34816
	ds_read_b128 v[198:201], v151 offset:35840
	ds_read_b128 v[202:205], v151 offset:36864
	ds_read_b128 v[206:209], v151 offset:37888
	ds_read_b128 v[210:213], v151 offset:38912
	ds_read_b128 v[214:217], v151 offset:39936
	global_load_lds_dwordx4 v[224:225], off
	v_lshl_add_u64 v[224:225], s[42:43], 0, v[130:131]
	s_mov_b32 m0, s52
	s_nop 0
	global_load_lds_dwordx4 v[224:225], off
	s_waitcnt vmcnt(8)
	s_waitcnt lgkmcnt(0)
	s_barrier
	s_setprio 1
	v_mfma_f32_16x16x32_bf16 v[120:123], v[154:157], v[186:189], v[120:123]
	v_mfma_f32_16x16x32_bf16 v[116:119], v[162:165], v[186:189], v[116:119]
	v_mfma_f32_16x16x32_bf16 v[108:111], v[154:157], v[194:197], v[108:111]
	v_mfma_f32_16x16x32_bf16 v[100:103], v[162:165], v[194:197], v[100:103]
	v_mfma_f32_16x16x32_bf16 v[92:95], v[154:157], v[202:205], v[92:95]
	v_mfma_f32_16x16x32_bf16 v[84:87], v[162:165], v[202:205], v[84:87]
	v_mfma_f32_16x16x32_bf16 v[76:79], v[154:157], v[210:213], v[76:79]
	v_mfma_f32_16x16x32_bf16 v[68:71], v[162:165], v[210:213], v[68:71]
	v_mfma_f32_16x16x32_bf16 v[120:123], v[158:161], v[190:193], v[120:123]
	v_mfma_f32_16x16x32_bf16 v[116:119], v[166:169], v[190:193], v[116:119]
	v_mfma_f32_16x16x32_bf16 v[108:111], v[158:161], v[198:201], v[108:111]
	v_mfma_f32_16x16x32_bf16 v[100:103], v[166:169], v[198:201], v[100:103]
	v_mfma_f32_16x16x32_bf16 v[92:95], v[158:161], v[206:209], v[92:95]
	v_mfma_f32_16x16x32_bf16 v[84:87], v[166:169], v[206:209], v[84:87]
	v_mfma_f32_16x16x32_bf16 v[76:79], v[158:161], v[214:217], v[76:79]
	v_mfma_f32_16x16x32_bf16 v[68:71], v[166:169], v[214:217], v[68:71]
	s_setprio 0
	s_setprio 1
	v_mfma_f32_16x16x32_bf16 v[124:127], v[170:173], v[186:189], v[124:127]
	v_mfma_f32_16x16x32_bf16 v[112:115], v[178:181], v[186:189], v[112:115]
	v_mfma_f32_16x16x32_bf16 v[104:107], v[170:173], v[194:197], v[104:107]
	v_mfma_f32_16x16x32_bf16 v[96:99], v[178:181], v[194:197], v[96:99]
	v_mfma_f32_16x16x32_bf16 v[88:91], v[170:173], v[202:205], v[88:91]
	v_mfma_f32_16x16x32_bf16 v[80:83], v[178:181], v[202:205], v[80:83]
	v_mfma_f32_16x16x32_bf16 v[72:75], v[170:173], v[210:213], v[72:75]
	v_mfma_f32_16x16x32_bf16 v[64:67], v[178:181], v[210:213], v[64:67]
	v_mfma_f32_16x16x32_bf16 v[124:127], v[174:177], v[190:193], v[124:127]
	v_mfma_f32_16x16x32_bf16 v[112:115], v[182:185], v[190:193], v[112:115]
	v_mfma_f32_16x16x32_bf16 v[104:107], v[174:177], v[198:201], v[104:107]
	v_mfma_f32_16x16x32_bf16 v[96:99], v[182:185], v[198:201], v[96:99]
	v_mfma_f32_16x16x32_bf16 v[88:91], v[174:177], v[206:209], v[88:91]
	v_mfma_f32_16x16x32_bf16 v[80:83], v[182:185], v[206:209], v[80:83]
	v_mfma_f32_16x16x32_bf16 v[72:75], v[174:177], v[214:217], v[72:75]
	v_mfma_f32_16x16x32_bf16 v[64:67], v[182:185], v[214:217], v[64:67]
	s_barrier
; #define PG8_STAGE(bufoff, gbase, voff) do { _Pragma("unroll") for (int _i = 0; _i < 2; ++_i) \
;         __builtin_amdgcn_global_load_lds((const unsigned*)((const char*)(gbase) + (voff)[_i]), (PG8_LAS unsigned*)(lds + (bufoff) + ldsw + _i * 8192), 16, 0, 0); } while (0)
; #define PG8_LDA(dst, b, h) do { _Pragma("unroll") for (int m = 0; m < 4; ++m) _Pragma("unroll") for (int k = 0; k < 2; ++k) dst[m][k] = *(const PG8_LAS bf16x8*)(lds + PG8_SA(b, h) + aoff + m * 2048 + k * 1024); } while (0)
; #define PG8_WAIT_V(n) asm volatile("s_waitcnt vmcnt(" #n ")" ::: "memory")
; #define PG8_BAR __builtin_amdgcn_s_barrier()
; template <class Epi, class Sched, bool ALIGN_EPI = false, bool SP2 = false>
; __device__ __forceinline__ void gemm_phase(PG8_LAS unsigned char* lds, const Gemm g, const Sched& S, const Epi& E) {
;     ...
;         for (int t = 0; t < nt; t += 2) {
;             const bool last = (t == nt - 2);
;             if constexpr (Epi::PREFETCH) { if (t == nt - 4) E.prefetch(cur, lds + STAGE_BYTES + 1024, tid); }
;             const char* a1 = cA + (size_t)(t + 1) * kstep;
;             const char* a2 = last ? nA : cA + (size_t)(t + 2) * kstep; const char* b2 = last ? nB : cB + (size_t)(t + 2) * kstep;
;             const char* a3 = a2 + kstep; const char* b3 = b2 + kstep;
;             if (last && has_next) S.a_ready(nxt);
;             if constexpr (SP2) {
;             PG8_LDB(B0, 0, 0); PG8_LDB(B1, 0, 1); PG8_SCHED; PG8_LDA(At, 0, 0); PG8_STAGE(PG8_SA(1, 1), a1 + hstep, voffA);
;             PG8_WAIT_V(8); PG8_WAIT_L(0); PG8_BAR; PG8_MMA(0, 0, At, B0); PG8_MMA(0, 1, At, B1); PG8_BAR; PG8_SCHED;
;             PG8_LDA(At, 0, 1); PG8_STAGE(PG8_SB(0, 0), b2, voffB); PG8_STAGE(PG8_SB(0, 1), b2 + hstep, voffB); PG8_STAGE(PG8_SA(0, 0), a2, voffA);
;             PG8_WAIT_V(8); PG8_WAIT_L(0); PG8_BAR; PG8_MMA(1, 0, At, B0); PG8_MMA(1, 1, At, B1); PG8_BAR; PG8_SCHED;
;             PG8_LDB(B0, 1, 0); PG8_LDB(B1, 1, 1); PG8_SCHED; PG8_LDA(At, 1, 0); PG8_STAGE(PG8_SA(0, 1), a2 + hstep, voffA);
;             PG8_WAIT_V(8); PG8_WAIT_L(0); PG8_BAR; PG8_MMA(0, 0, At, B0); PG8_MMA(0, 1, At, B1); PG8_BAR; PG8_SCHED;
;             PG8_LDA(At, 1, 1); PG8_STAGE(PG8_SB(1, 0), b3, voffB); PG8_STAGE(PG8_SB(1, 1), b3 + hstep, voffB); PG8_STAGE(PG8_SA(1, 0), a3, voffA);
;             PG8_WAIT_V(8); PG8_WAIT_L(0); PG8_BAR; PG8_MMA(1, 0, At, B0); PG8_MMA(1, 1, At, B1); PG8_BAR; PG8_SCHED;
	s_setprio 0
	s_add_i32 s42, s69, s48
	v_lshl_add_u64 v[144:145], v[144:145], 0, s[14:15]
	s_mov_b32 m0, s42
	ds_read_b128 v[186:189], v151 offset:49152
	ds_read_b128 v[190:193], v151 offset:50176
	ds_read_b128 v[194:197], v151 offset:51200
	ds_read_b128 v[198:201], v151 offset:52224
	ds_read_b128 v[202:205], v151 offset:53248
	ds_read_b128 v[206:209], v151 offset:54272
	ds_read_b128 v[210:213], v151 offset:55296
	ds_read_b128 v[214:217], v151 offset:56320
	global_load_lds_dwordx4 v[144:145], off
	s_add_i32 m0, s42, 0x2000
	s_add_u32 s40, s40, 0x40080
	v_lshl_add_u64 v[144:145], v[218:219], 0, s[14:15]
	s_addc_u32 s41, s41, 0
	s_add_i32 s42, s70, s48
	global_load_lds_dwordx4 v[144:145], off
	v_lshl_add_u64 v[144:145], s[40:41], 0, v[132:133]
	s_mov_b32 m0, s42
	s_nop 0
	global_load_lds_dwordx4 v[144:145], off
	v_lshl_add_u64 v[144:145], s[40:41], 0, v[128:129]
	s_add_i32 m0, s42, 0x2000
	s_nop 0
	global_load_lds_dwordx4 v[144:145], off
	v_lshl_add_u64 v[144:145], v[220:221], 0, s[14:15]
	s_mov_b32 m0, s53
	s_nop 0
	global_load_lds_dwordx4 v[144:145], off
	v_lshl_add_u64 v[144:145], v[222:223], 0, s[14:15]
	s_mov_b32 m0, s54
	s_nop 0
	global_load_lds_dwordx4 v[144:145], off
	s_waitcnt vmcnt(8)
	s_waitcnt lgkmcnt(0)
	s_barrier
	s_setprio 1
	v_mfma_f32_16x16x32_bf16 v[60:63], v[154:157], v[186:189], v[60:63]
	v_mfma_f32_16x16x32_bf16 v[52:55], v[162:165], v[186:189], v[52:55]
	v_mfma_f32_16x16x32_bf16 v[44:47], v[154:157], v[194:197], v[44:47]
	v_mfma_f32_16x16x32_bf16 v[36:39], v[162:165], v[194:197], v[36:39]
	v_mfma_f32_16x16x32_bf16 v[28:31], v[154:157], v[202:205], v[28:31]
	v_mfma_f32_16x16x32_bf16 v[20:23], v[162:165], v[202:205], v[20:23]
	v_mfma_f32_16x16x32_bf16 v[12:15], v[154:157], v[210:213], v[12:15]
	v_mfma_f32_16x16x32_bf16 v[4:7], v[162:165], v[210:213], v[4:7]
	v_mfma_f32_16x16x32_bf16 v[60:63], v[158:161], v[190:193], v[60:63]
	v_mfma_f32_16x16x32_bf16 v[52:55], v[166:169], v[190:193], v[52:55]
	v_mfma_f32_16x16x32_bf16 v[44:47], v[158:161], v[198:201], v[44:47]
	v_mfma_f32_16x16x32_bf16 v[36:39], v[166:169], v[198:201], v[36:39]
	v_mfma_f32_16x16x32_bf16 v[28:31], v[158:161], v[206:209], v[28:31]
	v_mfma_f32_16x16x32_bf16 v[20:23], v[166:169], v[206:209], v[20:23]
	v_mfma_f32_16x16x32_bf16 v[12:15], v[158:161], v[214:217], v[12:15]
	v_mfma_f32_16x16x32_bf16 v[4:7], v[166:169], v[214:217], v[4:7]
	s_setprio 0
	s_setprio 1
	v_mfma_f32_16x16x32_bf16 v[56:59], v[170:173], v[186:189], v[56:59]
	v_mfma_f32_16x16x32_bf16 v[48:51], v[178:181], v[186:189], v[48:51]
	v_mfma_f32_16x16x32_bf16 v[40:43], v[170:173], v[194:197], v[40:43]
	v_mfma_f32_16x16x32_bf16 v[32:35], v[178:181], v[194:197], v[32:35]
	v_mfma_f32_16x16x32_bf16 v[24:27], v[170:173], v[202:205], v[24:27]
	v_mfma_f32_16x16x32_bf16 v[16:19], v[178:181], v[202:205], v[16:19]
	v_mfma_f32_16x16x32_bf16 v[8:11], v[170:173], v[210:213], v[8:11]
	v_mfma_f32_16x16x32_bf16 v[0:3], v[178:181], v[210:213], v[0:3]
	v_mfma_f32_16x16x32_bf16 v[56:59], v[174:177], v[190:193], v[56:59]
	v_mfma_f32_16x16x32_bf16 v[48:51], v[182:185], v[190:193], v[48:51]
	v_mfma_f32_16x16x32_bf16 v[40:43], v[174:177], v[198:201], v[40:43]
	v_mfma_f32_16x16x32_bf16 v[32:35], v[182:185], v[198:201], v[32:35]
	v_mfma_f32_16x16x32_bf16 v[24:27], v[174:177], v[206:209], v[24:27]
	v_mfma_f32_16x16x32_bf16 v[16:19], v[182:185], v[206:209], v[16:19]
	v_mfma_f32_16x16x32_bf16 v[8:11], v[174:177], v[214:217], v[8:11]
	v_mfma_f32_16x16x32_bf16 v[0:3], v[182:185], v[214:217], v[0:3]
	s_barrier
	s_setprio 0
	s_add_i32 s68, s68, 2
	s_add_u32 s38, s38, 0x100
	s_addc_u32 s39, s39, 0
	s_add_u32 s66, s66, 0x100
	s_addc_u32 s67, s67, 0
.LBB0_1194:
	ds_read_b128 v[154:157], v149
	ds_read_b128 v[158:161], v149 offset:1024
	ds_read_b128 v[162:165], v149 offset:2048
	ds_read_b128 v[166:169], v149 offset:3072
	ds_read_b128 v[170:173], v150
	ds_read_b128 v[174:177], v150 offset:1024
	ds_read_b128 v[178:181], v150 offset:2048
	ds_read_b128 v[182:185], v150 offset:3072
	s_add_u32 s40, s38, 0xfffc0080
	s_addc_u32 s41, s39, -1
	s_cmp_eq_u32 s68, 12
	s_cselect_b32 s43, s21, s41
	s_cselect_b32 s42, s64, s40
	s_cselect_b32 s41, s19, s67
	s_cselect_b32 s40, s65, s66
	v_lshl_add_u64 v[144:145], s[38:39], 0, v[136:137]
	s_add_i32 m0, s37, 0xc000
	ds_read_b128 v[186:189], v151
	ds_read_b128 v[190:193], v151 offset:1024
	ds_read_b128 v[194:197], v151 offset:2048
	ds_read_b128 v[198:201], v151 offset:3072
	ds_read_b128 v[202:205], v151 offset:4096
	ds_read_b128 v[206:209], v151 offset:5120
	ds_read_b128 v[210:213], v151 offset:6144
	ds_read_b128 v[214:217], v151 offset:7168
	global_load_lds_dwordx4 v[144:145], off
	v_lshl_add_u64 v[144:145], s[38:39], 0, v[138:139]
	s_add_i32 m0, s37, 0xe000
	s_nop 0
	global_load_lds_dwordx4 v[144:145], off
	s_waitcnt vmcnt(8)
	s_waitcnt lgkmcnt(0)
	s_barrier
; #define PG8_STAGE(bufoff, gbase, voff) do { _Pragma("unroll") for (int _i = 0; _i < 2; ++_i) \
;         __builtin_amdgcn_global_load_lds((const unsigned*)((const char*)(gbase) + (voff)[_i]), (PG8_LAS unsigned*)(lds + (bufoff) + ldsw + _i * 8192), 16, 0, 0); } while (0)
; #define PG8_LDA(dst, b, h) do { _Pragma("unroll") for (int m = 0; m < 4; ++m) _Pragma("unroll") for (int k = 0; k < 2; ++k) dst[m][k] = *(const PG8_LAS bf16x8*)(lds + PG8_SA(b, h) + aoff + m * 2048 + k * 1024); } while (0)
; #define PG8_MMA(ai, bj, At, Bt) do { __builtin_amdgcn_s_setprio(1); _Pragma("unroll") for (int m = 0; m < 4; ++m) _Pragma("unroll") for (int n = 0; n < 2; ++n) _Pragma("unroll") for (int k = 0; k < 2; ++k) \
;         acc[ai][bj][m][n] = __builtin_amdgcn_mfma_f32_16x16x32_bf16(Bt[n][k], At[m][k], acc[ai][bj][m][n], 0, 0, 0); __builtin_amdgcn_s_setprio(0); } while (0)
; #define PG8_WAIT_V(n) asm volatile("s_waitcnt vmcnt(" #n ")" ::: "memory")
; #define PG8_WAIT_L(n) asm volatile("s_waitcnt lgkmcnt(" #n ")" ::: "memory")
; #define PG8_BAR __builtin_amdgcn_s_barrier()
; #define PG8_SCHED __builtin_amdgcn_sched_barrier(0)
; template <class Epi, class Sched, bool ALIGN_EPI = false, bool SP2 = false>
; __device__ __forceinline__ void gemm_phase(PG8_LAS unsigned char* lds, const Gemm g, const Sched& S, const Epi& E) {
;     ...
;             PG8_WAIT_V(8); PG8_WAIT_L(0); PG8_BAR; PG8_MMA(0, 0, At, B0); PG8_MMA(0, 1, At, B1); PG8_BAR; PG8_SCHED;
;             PG8_LDA(At, 0, 1); PG8_STAGE(PG8_SB(0, 0), b2, voffB); PG8_STAGE(PG8_SB(0, 1), b2 + hstep, voffB); PG8_STAGE(PG8_SA(0, 0), a2, voffA);
;             PG8_WAIT_V(8); PG8_WAIT_L(0); PG8_BAR; PG8_MMA(1, 0, At, B0); PG8_MMA(1, 1, At, B1); PG8_BAR; PG8_SCHED;
	s_setprio 1
	v_mfma_f32_16x16x32_bf16 v[120:123], v[154:157], v[186:189], v[120:123]
	v_mfma_f32_16x16x32_bf16 v[116:119], v[162:165], v[186:189], v[116:119]
	v_mfma_f32_16x16x32_bf16 v[108:111], v[154:157], v[194:197], v[108:111]
	v_mfma_f32_16x16x32_bf16 v[100:103], v[162:165], v[194:197], v[100:103]
	v_mfma_f32_16x16x32_bf16 v[92:95], v[154:157], v[202:205], v[92:95]
	v_mfma_f32_16x16x32_bf16 v[84:87], v[162:165], v[202:205], v[84:87]
	v_mfma_f32_16x16x32_bf16 v[76:79], v[154:157], v[210:213], v[76:79]
	v_mfma_f32_16x16x32_bf16 v[68:71], v[162:165], v[210:213], v[68:71]
	v_mfma_f32_16x16x32_bf16 v[120:123], v[158:161], v[190:193], v[120:123]
	v_mfma_f32_16x16x32_bf16 v[116:119], v[166:169], v[190:193], v[116:119]
	v_mfma_f32_16x16x32_bf16 v[108:111], v[158:161], v[198:201], v[108:111]
	v_mfma_f32_16x16x32_bf16 v[100:103], v[166:169], v[198:201], v[100:103]
	v_mfma_f32_16x16x32_bf16 v[92:95], v[158:161], v[206:209], v[92:95]
	v_mfma_f32_16x16x32_bf16 v[84:87], v[166:169], v[206:209], v[84:87]
	v_mfma_f32_16x16x32_bf16 v[76:79], v[158:161], v[214:217], v[76:79]
	v_mfma_f32_16x16x32_bf16 v[68:71], v[166:169], v[214:217], v[68:71]
	s_setprio 0
	s_setprio 1
	v_mfma_f32_16x16x32_bf16 v[124:127], v[170:173], v[186:189], v[124:127]
	v_mfma_f32_16x16x32_bf16 v[112:115], v[178:181], v[186:189], v[112:115]
	v_mfma_f32_16x16x32_bf16 v[104:107], v[170:173], v[194:197], v[104:107]
	v_mfma_f32_16x16x32_bf16 v[96:99], v[178:181], v[194:197], v[96:99]
	v_mfma_f32_16x16x32_bf16 v[88:91], v[170:173], v[202:205], v[88:91]
	v_mfma_f32_16x16x32_bf16 v[80:83], v[178:181], v[202:205], v[80:83]
	v_mfma_f32_16x16x32_bf16 v[72:75], v[170:173], v[210:213], v[72:75]
	v_mfma_f32_16x16x32_bf16 v[64:67], v[178:181], v[210:213], v[64:67]
	v_mfma_f32_16x16x32_bf16 v[124:127], v[174:177], v[190:193], v[124:127]
	v_mfma_f32_16x16x32_bf16 v[112:115], v[182:185], v[190:193], v[112:115]
	v_mfma_f32_16x16x32_bf16 v[104:107], v[174:177], v[198:201], v[104:107]
	v_mfma_f32_16x16x32_bf16 v[96:99], v[182:185], v[198:201], v[96:99]
	v_mfma_f32_16x16x32_bf16 v[88:91], v[174:177], v[206:209], v[88:91]
	v_mfma_f32_16x16x32_bf16 v[80:83], v[182:185], v[206:209], v[80:83]
	v_mfma_f32_16x16x32_bf16 v[72:75], v[174:177], v[214:217], v[72:75]
	v_mfma_f32_16x16x32_bf16 v[64:67], v[182:185], v[214:217], v[64:67]
	s_barrier
	s_setprio 0
	s_add_i32 s69, s57, s48
	v_lshl_add_u64 v[144:145], s[40:41], 0, v[132:133]
	s_mov_b32 m0, s69
	ds_read_b128 v[186:189], v151 offset:16384
	ds_read_b128 v[190:193], v151 offset:17408
	ds_read_b128 v[194:197], v151 offset:18432
	ds_read_b128 v[198:201], v151 offset:19456
	ds_read_b128 v[202:205], v151 offset:20480
	ds_read_b128 v[206:209], v151 offset:21504
	ds_read_b128 v[210:213], v151 offset:22528
	ds_read_b128 v[214:217], v151 offset:23552
	global_load_lds_dwordx4 v[144:145], off
	s_add_i32 m0, s69, 0x2000
	s_add_u32 s70, s40, 0x40000
	v_lshl_add_u64 v[218:219], s[40:41], 0, v[128:129]
	s_addc_u32 s71, s41, 0
	s_add_i32 s69, s58, s48
	global_load_lds_dwordx4 v[218:219], off
	v_lshl_add_u64 v[220:221], s[70:71], 0, v[132:133]
	s_mov_b32 m0, s69
	v_lshl_add_u64 v[222:223], s[42:43], 0, v[130:131]
	global_load_lds_dwordx4 v[220:221], off
	v_lshl_add_u64 v[220:221], s[70:71], 0, v[128:129]
	s_add_i32 m0, s69, 0x2000
	s_nop 0
	global_load_lds_dwordx4 v[220:221], off
	v_lshl_add_u64 v[220:221], s[42:43], 0, v[134:135]
	s_mov_b32 m0, s37
	s_nop 0
	global_load_lds_dwordx4 v[220:221], off
	s_mov_b32 m0, s50
	s_nop 0
	global_load_lds_dwordx4 v[222:223], off
	s_waitcnt vmcnt(8)
	s_waitcnt lgkmcnt(0)
	s_barrier
	s_setprio 1
	v_mfma_f32_16x16x32_bf16 v[60:63], v[154:157], v[186:189], v[60:63]
	v_mfma_f32_16x16x32_bf16 v[52:55], v[162:165], v[186:189], v[52:55]
	v_mfma_f32_16x16x32_bf16 v[44:47], v[154:157], v[194:197], v[44:47]
	v_mfma_f32_16x16x32_bf16 v[36:39], v[162:165], v[194:197], v[36:39]
	v_mfma_f32_16x16x32_bf16 v[28:31], v[154:157], v[202:205], v[28:31]
	v_mfma_f32_16x16x32_bf16 v[20:23], v[162:165], v[202:205], v[20:23]
	v_mfma_f32_16x16x32_bf16 v[12:15], v[154:157], v[210:213], v[12:15]
	v_mfma_f32_16x16x32_bf16 v[4:7], v[162:165], v[210:213], v[4:7]
	v_mfma_f32_16x16x32_bf16 v[60:63], v[158:161], v[190:193], v[60:63]
	v_mfma_f32_16x16x32_bf16 v[52:55], v[166:169], v[190:193], v[52:55]
	v_mfma_f32_16x16x32_bf16 v[44:47], v[158:161], v[198:201], v[44:47]
	v_mfma_f32_16x16x32_bf16 v[36:39], v[166:169], v[198:201], v[36:39]
	v_mfma_f32_16x16x32_bf16 v[28:31], v[158:161], v[206:209], v[28:31]
	v_mfma_f32_16x16x32_bf16 v[20:23], v[166:169], v[206:209], v[20:23]
	v_mfma_f32_16x16x32_bf16 v[12:15], v[158:161], v[214:217], v[12:15]
	v_mfma_f32_16x16x32_bf16 v[4:7], v[166:169], v[214:217], v[4:7]
	s_setprio 0
	s_setprio 1
	v_mfma_f32_16x16x32_bf16 v[56:59], v[170:173], v[186:189], v[56:59]
	v_mfma_f32_16x16x32_bf16 v[48:51], v[178:181], v[186:189], v[48:51]
	v_mfma_f32_16x16x32_bf16 v[40:43], v[170:173], v[194:197], v[40:43]
	v_mfma_f32_16x16x32_bf16 v[32:35], v[178:181], v[194:197], v[32:35]
	v_mfma_f32_16x16x32_bf16 v[24:27], v[170:173], v[202:205], v[24:27]
	v_mfma_f32_16x16x32_bf16 v[16:19], v[178:181], v[202:205], v[16:19]
	v_mfma_f32_16x16x32_bf16 v[8:11], v[170:173], v[210:213], v[8:11]
	v_mfma_f32_16x16x32_bf16 v[0:3], v[178:181], v[210:213], v[0:3]
	v_mfma_f32_16x16x32_bf16 v[56:59], v[174:177], v[190:193], v[56:59]
	v_mfma_f32_16x16x32_bf16 v[48:51], v[182:185], v[190:193], v[48:51]
	v_mfma_f32_16x16x32_bf16 v[40:43], v[174:177], v[198:201], v[40:43]
	v_mfma_f32_16x16x32_bf16 v[32:35], v[182:185], v[198:201], v[32:35]
	v_mfma_f32_16x16x32_bf16 v[24:27], v[174:177], v[206:209], v[24:27]
	v_mfma_f32_16x16x32_bf16 v[16:19], v[182:185], v[206:209], v[16:19]
	v_mfma_f32_16x16x32_bf16 v[8:11], v[174:177], v[214:217], v[8:11]
	v_mfma_f32_16x16x32_bf16 v[0:3], v[182:185], v[214:217], v[0:3]
	s_barrier
; #define PG8_STAGE(bufoff, gbase, voff) do { _Pragma("unroll") for (int _i = 0; _i < 2; ++_i) \
;         __builtin_amdgcn_global_load_lds((const unsigned*)((const char*)(gbase) + (voff)[_i]), (PG8_LAS unsigned*)(lds + (bufoff) + ldsw + _i * 8192), 16, 0, 0); } while (0)
; #define PG8_LDA(dst, b, h) do { _Pragma("unroll") for (int m = 0; m < 4; ++m) _Pragma("unroll") for (int k = 0; k < 2; ++k) dst[m][k] = *(const PG8_LAS bf16x8*)(lds + PG8_SA(b, h) + aoff + m * 2048 + k * 1024); } while (0)
; #define PG8_LDB(dst, b, h) do { _Pragma("unroll") for (int n = 0; n < 2; ++n) _Pragma("unroll") for (int k = 0; k < 2; ++k) dst[n][k] = *(const PG8_LAS bf16x8*)(lds + PG8_SB(b, h) + boff + n * 2048 + k * 1024); } while (0)
; #define PG8_MMA(ai, bj, At, Bt) do { __builtin_amdgcn_s_setprio(1); _Pragma("unroll") for (int m = 0; m < 4; ++m) _Pragma("unroll") for (int n = 0; n < 2; ++n) _Pragma("unroll") for (int k = 0; k < 2; ++k) \
;         acc[ai][bj][m][n] = __builtin_amdgcn_mfma_f32_16x16x32_bf16(Bt[n][k], At[m][k], acc[ai][bj][m][n], 0, 0, 0); __builtin_amdgcn_s_setprio(0); } while (0)
; #define PG8_WAIT_V(n) asm volatile("s_waitcnt vmcnt(" #n ")" ::: "memory")
; #define PG8_WAIT_L(n) asm volatile("s_waitcnt lgkmcnt(" #n ")" ::: "memory")
; #define PG8_BAR __builtin_amdgcn_s_barrier()
; #define PG8_SCHED __builtin_amdgcn_sched_barrier(0)
; template <class Epi, class Sched, bool ALIGN_EPI = false, bool SP2 = false>
; __device__ __forceinline__ void gemm_phase(PG8_LAS unsigned char* lds, const Gemm g, const Sched& S, const Epi& E) {
;     ...
;             PG8_LDB(B0, 1, 0); PG8_LDB(B1, 1, 1); PG8_SCHED; PG8_LDA(At, 1, 0); PG8_STAGE(PG8_SA(0, 1), a2 + hstep, voffA);
;             PG8_WAIT_V(8); PG8_WAIT_L(0); PG8_BAR; PG8_MMA(0, 0, At, B0); PG8_MMA(0, 1, At, B1); PG8_BAR; PG8_SCHED;
	s_setprio 0
	s_add_i32 s69, 0, 0x18000
	v_add_u32_e32 v153, s69, v147
	s_add_i32 s70, 0, 0x1c000
	ds_read_b128 v[154:157], v153
	ds_read_b128 v[158:161], v153 offset:1024
	ds_read_b128 v[162:165], v153 offset:2048
	ds_read_b128 v[166:169], v153 offset:3072
	v_add_u32_e32 v153, s70, v147
	ds_read_b128 v[170:173], v153
	ds_read_b128 v[174:177], v153 offset:1024
	ds_read_b128 v[178:181], v153 offset:2048
	ds_read_b128 v[182:185], v153 offset:3072
	s_add_u32 s42, s42, 0x40000
	s_addc_u32 s43, s43, 0
	s_mov_b32 m0, s51
	v_lshl_add_u64 v[224:225], s[42:43], 0, v[134:135]
	ds_read_b128 v[186:189], v151 offset:32768
	ds_read_b128 v[190:193], v151 offset:33792
	ds_read_b128 v[194:197], v151 offset:34816
	ds_read_b128 v[198:201], v151 offset:35840
	ds_read_b128 v[202:205], v151 offset:36864
	ds_read_b128 v[206:209], v151 offset:37888
	ds_read_b128 v[210:213], v151 offset:38912
	ds_read_b128 v[214:217], v151 offset:39936
	global_load_lds_dwordx4 v[224:225], off
	v_lshl_add_u64 v[224:225], s[42:43], 0, v[130:131]
	s_mov_b32 m0, s52
	s_nop 0
	global_load_lds_dwordx4 v[224:225], off
	s_waitcnt vmcnt(8)
	s_waitcnt lgkmcnt(0)
	s_barrier
	s_setprio 1
	v_mfma_f32_16x16x32_bf16 v[120:123], v[154:157], v[186:189], v[120:123]
	v_mfma_f32_16x16x32_bf16 v[116:119], v[162:165], v[186:189], v[116:119]
	v_mfma_f32_16x16x32_bf16 v[108:111], v[154:157], v[194:197], v[108:111]
	v_mfma_f32_16x16x32_bf16 v[100:103], v[162:165], v[194:197], v[100:103]
	v_mfma_f32_16x16x32_bf16 v[92:95], v[154:157], v[202:205], v[92:95]
	v_mfma_f32_16x16x32_bf16 v[84:87], v[162:165], v[202:205], v[84:87]
	v_mfma_f32_16x16x32_bf16 v[76:79], v[154:157], v[210:213], v[76:79]
	v_mfma_f32_16x16x32_bf16 v[68:71], v[162:165], v[210:213], v[68:71]
	v_mfma_f32_16x16x32_bf16 v[120:123], v[158:161], v[190:193], v[120:123]
	v_mfma_f32_16x16x32_bf16 v[116:119], v[166:169], v[190:193], v[116:119]
	v_mfma_f32_16x16x32_bf16 v[108:111], v[158:161], v[198:201], v[108:111]
	v_mfma_f32_16x16x32_bf16 v[100:103], v[166:169], v[198:201], v[100:103]
	v_mfma_f32_16x16x32_bf16 v[92:95], v[158:161], v[206:209], v[92:95]
	v_mfma_f32_16x16x32_bf16 v[84:87], v[166:169], v[206:209], v[84:87]
	v_mfma_f32_16x16x32_bf16 v[76:79], v[158:161], v[214:217], v[76:79]
	v_mfma_f32_16x16x32_bf16 v[68:71], v[166:169], v[214:217], v[68:71]
	s_setprio 0
	s_setprio 1
	v_mfma_f32_16x16x32_bf16 v[124:127], v[170:173], v[186:189], v[124:127]
	v_mfma_f32_16x16x32_bf16 v[112:115], v[178:181], v[186:189], v[112:115]
	v_mfma_f32_16x16x32_bf16 v[104:107], v[170:173], v[194:197], v[104:107]
	v_mfma_f32_16x16x32_bf16 v[96:99], v[178:181], v[194:197], v[96:99]
	v_mfma_f32_16x16x32_bf16 v[88:91], v[170:173], v[202:205], v[88:91]
	v_mfma_f32_16x16x32_bf16 v[80:83], v[178:181], v[202:205], v[80:83]
	v_mfma_f32_16x16x32_bf16 v[72:75], v[170:173], v[210:213], v[72:75]
	v_mfma_f32_16x16x32_bf16 v[64:67], v[178:181], v[210:213], v[64:67]
	v_mfma_f32_16x16x32_bf16 v[124:127], v[174:177], v[190:193], v[124:127]
	v_mfma_f32_16x16x32_bf16 v[112:115], v[182:185], v[190:193], v[112:115]
	v_mfma_f32_16x16x32_bf16 v[104:107], v[174:177], v[198:201], v[104:107]
	v_mfma_f32_16x16x32_bf16 v[96:99], v[182:185], v[198:201], v[96:99]
	v_mfma_f32_16x16x32_bf16 v[88:91], v[174:177], v[206:209], v[88:91]
	v_mfma_f32_16x16x32_bf16 v[80:83], v[182:185], v[206:209], v[80:83]
	v_mfma_f32_16x16x32_bf16 v[72:75], v[174:177], v[214:217], v[72:75]
	v_mfma_f32_16x16x32_bf16 v[64:67], v[182:185], v[214:217], v[64:67]
	s_barrier
; #define PG8_STAGE(bufoff, gbase, voff) do { _Pragma("unroll") for (int _i = 0; _i < 2; ++_i) \
;         __builtin_amdgcn_global_load_lds((const unsigned*)((const char*)(gbase) + (voff)[_i]), (PG8_LAS unsigned*)(lds + (bufoff) + ldsw + _i * 8192), 16, 0, 0); } while (0)
; #define PG8_LDA(dst, b, h) do { _Pragma("unroll") for (int m = 0; m < 4; ++m) _Pragma("unroll") for (int k = 0; k < 2; ++k) dst[m][k] = *(const PG8_LAS bf16x8*)(lds + PG8_SA(b, h) + aoff + m * 2048 + k * 1024); } while (0)
; #define PG8_MMA(ai, bj, At, Bt) do { __builtin_amdgcn_s_setprio(1); _Pragma("unroll") for (int m = 0; m < 4; ++m) _Pragma("unroll") for (int n = 0; n < 2; ++n) _Pragma("unroll") for (int k = 0; k < 2; ++k) \
;         acc[ai][bj][m][n] = __builtin_amdgcn_mfma_f32_16x16x32_bf16(Bt[n][k], At[m][k], acc[ai][bj][m][n], 0, 0, 0); __builtin_amdgcn_s_setprio(0); } while (0)
; #define PG8_WAIT_V(n) asm volatile("s_waitcnt vmcnt(" #n ")" ::: "memory")
; #define PG8_WAIT_L(n) asm volatile("s_waitcnt lgkmcnt(" #n ")" ::: "memory")
; #define PG8_BAR __builtin_amdgcn_s_barrier()
; #define PG8_SCHED __builtin_amdgcn_sched_barrier(0)
; template <class Epi, class Sched, bool ALIGN_EPI = false, bool SP2 = false>
; __device__ __forceinline__ void gemm_phase(PG8_LAS unsigned char* lds, const Gemm g, const Sched& S, const Epi& E) {
;     ...
;             PG8_LDA(At, 1, 1); PG8_STAGE(PG8_SB(1, 0), b3, voffB); PG8_STAGE(PG8_SB(1, 1), b3 + hstep, voffB); PG8_STAGE(PG8_SA(1, 0), a3, voffA);
;             PG8_WAIT_V(8); PG8_WAIT_L(0); PG8_BAR; PG8_MMA(1, 0, At, B0); PG8_MMA(1, 1, At, B1); PG8_BAR; PG8_SCHED;
	s_setprio 0
	s_add_i32 s42, s69, s48
	v_lshl_add_u64 v[144:145], v[144:145], 0, s[14:15]
	s_mov_b32 m0, s42
	ds_read_b128 v[186:189], v151 offset:49152
	ds_read_b128 v[190:193], v151 offset:50176
	ds_read_b128 v[194:197], v151 offset:51200
	ds_read_b128 v[198:201], v151 offset:52224
	ds_read_b128 v[202:205], v151 offset:53248
	ds_read_b128 v[206:209], v151 offset:54272
	ds_read_b128 v[210:213], v151 offset:55296
	ds_read_b128 v[214:217], v151 offset:56320
	global_load_lds_dwordx4 v[144:145], off
	s_add_i32 m0, s42, 0x2000
	s_add_u32 s40, s40, 0x40080
	v_lshl_add_u64 v[144:145], v[218:219], 0, s[14:15]
	s_addc_u32 s41, s41, 0
	s_add_i32 s42, s70, s48
	global_load_lds_dwordx4 v[144:145], off
	v_lshl_add_u64 v[144:145], s[40:41], 0, v[132:133]
	s_mov_b32 m0, s42
	s_nop 0
	global_load_lds_dwordx4 v[144:145], off
	v_lshl_add_u64 v[144:145], s[40:41], 0, v[128:129]
	s_add_i32 m0, s42, 0x2000
	s_nop 0
	global_load_lds_dwordx4 v[144:145], off
	v_lshl_add_u64 v[144:145], v[220:221], 0, s[14:15]
	s_mov_b32 m0, s53
	s_nop 0
	global_load_lds_dwordx4 v[144:145], off
	v_lshl_add_u64 v[144:145], v[222:223], 0, s[14:15]
	s_mov_b32 m0, s54
	s_nop 0
	global_load_lds_dwordx4 v[144:145], off
	s_waitcnt vmcnt(8)
	s_waitcnt lgkmcnt(0)
	s_barrier
	s_setprio 1
	v_mfma_f32_16x16x32_bf16 v[60:63], v[154:157], v[186:189], v[60:63]
	v_mfma_f32_16x16x32_bf16 v[52:55], v[162:165], v[186:189], v[52:55]
	v_mfma_f32_16x16x32_bf16 v[44:47], v[154:157], v[194:197], v[44:47]
	v_mfma_f32_16x16x32_bf16 v[36:39], v[162:165], v[194:197], v[36:39]
	v_mfma_f32_16x16x32_bf16 v[28:31], v[154:157], v[202:205], v[28:31]
	v_mfma_f32_16x16x32_bf16 v[20:23], v[162:165], v[202:205], v[20:23]
	v_mfma_f32_16x16x32_bf16 v[12:15], v[154:157], v[210:213], v[12:15]
	v_mfma_f32_16x16x32_bf16 v[4:7], v[162:165], v[210:213], v[4:7]
	v_mfma_f32_16x16x32_bf16 v[60:63], v[158:161], v[190:193], v[60:63]
	v_mfma_f32_16x16x32_bf16 v[52:55], v[166:169], v[190:193], v[52:55]
	v_mfma_f32_16x16x32_bf16 v[44:47], v[158:161], v[198:201], v[44:47]
	v_mfma_f32_16x16x32_bf16 v[36:39], v[166:169], v[198:201], v[36:39]
	v_mfma_f32_16x16x32_bf16 v[28:31], v[158:161], v[206:209], v[28:31]
	v_mfma_f32_16x16x32_bf16 v[20:23], v[166:169], v[206:209], v[20:23]
	v_mfma_f32_16x16x32_bf16 v[12:15], v[158:161], v[214:217], v[12:15]
	v_mfma_f32_16x16x32_bf16 v[4:7], v[166:169], v[214:217], v[4:7]
	s_setprio 0
	s_setprio 1
	v_mfma_f32_16x16x32_bf16 v[56:59], v[170:173], v[186:189], v[56:59]
	v_mfma_f32_16x16x32_bf16 v[48:51], v[178:181], v[186:189], v[48:51]
	v_mfma_f32_16x16x32_bf16 v[40:43], v[170:173], v[194:197], v[40:43]
	v_mfma_f32_16x16x32_bf16 v[32:35], v[178:181], v[194:197], v[32:35]
	v_mfma_f32_16x16x32_bf16 v[24:27], v[170:173], v[202:205], v[24:27]
	v_mfma_f32_16x16x32_bf16 v[16:19], v[178:181], v[202:205], v[16:19]
	v_mfma_f32_16x16x32_bf16 v[8:11], v[170:173], v[210:213], v[8:11]
	v_mfma_f32_16x16x32_bf16 v[0:3], v[178:181], v[210:213], v[0:3]
	v_mfma_f32_16x16x32_bf16 v[56:59], v[174:177], v[190:193], v[56:59]
	v_mfma_f32_16x16x32_bf16 v[48:51], v[182:185], v[190:193], v[48:51]
	v_mfma_f32_16x16x32_bf16 v[40:43], v[174:177], v[198:201], v[40:43]
	v_mfma_f32_16x16x32_bf16 v[32:35], v[182:185], v[198:201], v[32:35]
	v_mfma_f32_16x16x32_bf16 v[24:27], v[174:177], v[206:209], v[24:27]
	v_mfma_f32_16x16x32_bf16 v[16:19], v[182:185], v[206:209], v[16:19]
	v_mfma_f32_16x16x32_bf16 v[8:11], v[174:177], v[214:217], v[8:11]
	v_mfma_f32_16x16x32_bf16 v[0:3], v[182:185], v[214:217], v[0:3]
	s_barrier
	s_setprio 0
	s_add_i32 s68, s68, 2
	s_add_u32 s38, s38, 0x100
	s_addc_u32 s39, s39, 0
	s_add_u32 s66, s66, 0x100
	s_addc_u32 s67, s67, 0
	s_cmp_gt_u32 s68, 13
	s_cbranch_scc0 .LBB0_1194
	s_and_b64 vcc, exec, s[16:17]
	s_cbranch_vccz .LBB0_1197
	s_barrier

; #define PG8_STAGE(bufoff, gbase, voff) do { _Pragma("unroll") for (int _i = 0; _i < 2; ++_i) \
;         __builtin_amdgcn_global_load_lds((const unsigned*)((const char*)(gbase) + (voff)[_i]), (PG8_LAS unsigned*)(lds + (bufoff) + ldsw + _i * 8192), 16, 0, 0); } while (0)
; #define PG8_LDA(dst, b, h) do { _Pragma("unroll") for (int m = 0; m < 4; ++m) _Pragma("unroll") for (int k = 0; k < 2; ++k) dst[m][k] = *(const PG8_LAS bf16x8*)(lds + PG8_SA(b, h) + aoff + m * 2048 + k * 1024); } while (0)
; #define PG8_LDB(dst, b, h) do { _Pragma("unroll") for (int n = 0; n < 2; ++n) _Pragma("unroll") for (int k = 0; k < 2; ++k) dst[n][k] = *(const PG8_LAS bf16x8*)(lds + PG8_SB(b, h) + boff + n * 2048 + k * 1024); } while (0)
; #define PG8_WAIT_V(n) asm volatile("s_waitcnt vmcnt(" #n ")" ::: "memory")
; #define PG8_WAIT_L(n) asm volatile("s_waitcnt lgkmcnt(" #n ")" ::: "memory")
; template <class Epi, class Sched, bool ALIGN_EPI = false, bool SP2 = false>
; __device__ __forceinline__ void gemm_phase(PG8_LAS unsigned char* lds, const Gemm g, const Sched& S, const Epi& E) {
;     ...
;         const bool has_next = S.next(ui + 1, nxt);
;         const char* nA = has_next ? (const char*)g.A + (size_t)nxt.pm * tstep : cA; const char* nB = has_next ? (const char*)g.Bt + (size_t)nxt.pn * tstep : cB;
;         for (int t = 0; t < nt; t += 2) {
;             const bool last = (t == nt - 2);
;             if constexpr (Epi::PREFETCH) { if (t == nt - 4) E.prefetch(cur, lds + STAGE_BYTES + 1024, tid); }
;             const char* a1 = cA + (size_t)(t + 1) * kstep;
;             const char* a2 = last ? nA : cA + (size_t)(t + 2) * kstep; const char* b2 = last ? nB : cB + (size_t)(t + 2) * kstep;
;             const char* a3 = a2 + kstep; const char* b3 = b2 + kstep;
;             if (last && has_next) S.a_ready(nxt);
;             if constexpr (SP2) {
;             PG8_LDB(B0, 0, 0); PG8_LDB(B1, 0, 1); PG8_SCHED; PG8_LDA(At, 0, 0); PG8_STAGE(PG8_SA(1, 1), a1 + hstep, voffA);
;             PG8_WAIT_V(8); PG8_WAIT_L(0); PG8_BAR; PG8_MMA(0, 0, At, B0); PG8_MMA(0, 1, At, B1); PG8_BAR; PG8_SCHED;
;             PG8_LDA(At, 0, 1); PG8_STAGE(PG8_SB(0, 0), b2, voffB); PG8_STAGE(PG8_SB(0, 1), b2 + hstep, voffB); PG8_STAGE(PG8_SA(0, 0), a2, voffA);
;             PG8_WAIT_V(8); PG8_WAIT_L(0); PG8_BAR; PG8_MMA(1, 0, At, B0); PG8_MMA(1, 1, At, B1); PG8_BAR; PG8_SCHED;
.LBB0_1905:
	s_ashr_i32 s21, s20, 31
	s_lshl_b64 s[22:23], s[20:21], 19
	s_add_u32 s22, s44, s22
	s_addc_u32 s23, s45, s23
	s_and_b64 s[34:35], s[4:5], exec
	s_cselect_b32 s21, s23, s39
	s_cselect_b32 s64, s22, s38
	s_ashr_i32 s19, s18, 31
	s_lshl_b64 s[34:35], s[18:19], 19
	s_add_u32 s34, s46, s34
	s_addc_u32 s35, s47, s35
	s_and_b64 s[42:43], s[4:5], exec
	s_cselect_b32 s19, s35, s41
	s_cselect_b32 s65, s34, s40
	s_add_u32 s38, s38, 0x40080
	s_addc_u32 s39, s39, 0
	s_add_u32 s66, s40, 0x100
	s_addc_u32 s67, s41, 0
	s_mov_b32 s68, -2
	ds_read_b128 v[144:147], v151
	ds_read_b128 v[156:159], v151 offset:1024
	ds_read_b128 v[160:163], v151 offset:2048
	ds_read_b128 v[164:167], v151 offset:3072
	ds_read_b128 v[168:171], v152
	ds_read_b128 v[172:175], v152 offset:1024
	ds_read_b128 v[176:179], v152 offset:2048
	ds_read_b128 v[180:183], v152 offset:3072
	s_add_u32 s40, s38, 0xfffc0080
	s_addc_u32 s41, s39, -1
	s_cmp_eq_u32 s68, 12
	s_cselect_b32 s43, s21, s41
	s_cselect_b32 s42, s64, s40
	s_cselect_b32 s41, s19, s67
	s_cselect_b32 s40, s65, s66
	v_lshl_add_u64 v[216:217], s[38:39], 0, v[136:137]
	s_add_i32 m0, s37, 0xc000
	ds_read_b128 v[184:187], v153
	ds_read_b128 v[188:191], v153 offset:1024
	ds_read_b128 v[192:195], v153 offset:2048
	ds_read_b128 v[196:199], v153 offset:3072
	ds_read_b128 v[200:203], v153 offset:4096
	ds_read_b128 v[204:207], v153 offset:5120
	ds_read_b128 v[208:211], v153 offset:6144
	ds_read_b128 v[212:215], v153 offset:7168
	global_load_lds_dwordx4 v[216:217], off
	v_lshl_add_u64 v[216:217], s[38:39], 0, v[138:139]
	s_add_i32 m0, s37, 0xe000
	s_nop 0
	global_load_lds_dwordx4 v[216:217], off
	s_waitcnt vmcnt(8)
	s_waitcnt lgkmcnt(0)
	s_barrier
	s_setprio 1
	v_mfma_f32_16x16x32_bf16 v[124:127], v[144:147], v[184:187], 0
	v_mfma_f32_16x16x32_bf16 v[120:123], v[160:163], v[184:187], 0
	v_mfma_f32_16x16x32_bf16 v[108:111], v[144:147], v[192:195], 0
	v_mfma_f32_16x16x32_bf16 v[104:107], v[160:163], v[192:195], 0
	v_mfma_f32_16x16x32_bf16 v[92:95], v[144:147], v[200:203], 0
	v_mfma_f32_16x16x32_bf16 v[88:91], v[160:163], v[200:203], 0
	v_mfma_f32_16x16x32_bf16 v[76:79], v[144:147], v[208:211], 0
	v_mfma_f32_16x16x32_bf16 v[72:75], v[160:163], v[208:211], 0
	v_mfma_f32_16x16x32_bf16 v[124:127], v[156:159], v[188:191], v[124:127]
	v_mfma_f32_16x16x32_bf16 v[120:123], v[164:167], v[188:191], v[120:123]
	v_mfma_f32_16x16x32_bf16 v[108:111], v[156:159], v[196:199], v[108:111]
	v_mfma_f32_16x16x32_bf16 v[104:107], v[164:167], v[196:199], v[104:107]
	v_mfma_f32_16x16x32_bf16 v[92:95], v[156:159], v[204:207], v[92:95]
	v_mfma_f32_16x16x32_bf16 v[88:91], v[164:167], v[204:207], v[88:91]
	v_mfma_f32_16x16x32_bf16 v[76:79], v[156:159], v[212:215], v[76:79]
	v_mfma_f32_16x16x32_bf16 v[72:75], v[164:167], v[212:215], v[72:75]
	s_setprio 0
	s_setprio 1
	v_mfma_f32_16x16x32_bf16 v[116:119], v[168:171], v[184:187], 0
	v_mfma_f32_16x16x32_bf16 v[112:115], v[176:179], v[184:187], 0
	v_mfma_f32_16x16x32_bf16 v[100:103], v[168:171], v[192:195], 0
	v_mfma_f32_16x16x32_bf16 v[96:99], v[176:179], v[192:195], 0
	v_mfma_f32_16x16x32_bf16 v[84:87], v[168:171], v[200:203], 0
	v_mfma_f32_16x16x32_bf16 v[80:83], v[176:179], v[200:203], 0
	v_mfma_f32_16x16x32_bf16 v[68:71], v[168:171], v[208:211], 0
	v_mfma_f32_16x16x32_bf16 v[64:67], v[176:179], v[208:211], 0
	v_mfma_f32_16x16x32_bf16 v[116:119], v[172:175], v[188:191], v[116:119]
	v_mfma_f32_16x16x32_bf16 v[112:115], v[180:183], v[188:191], v[112:115]
	v_mfma_f32_16x16x32_bf16 v[100:103], v[172:175], v[196:199], v[100:103]
	v_mfma_f32_16x16x32_bf16 v[96:99], v[180:183], v[196:199], v[96:99]
	v_mfma_f32_16x16x32_bf16 v[84:87], v[172:175], v[204:207], v[84:87]
	v_mfma_f32_16x16x32_bf16 v[80:83], v[180:183], v[204:207], v[80:83]
	v_mfma_f32_16x16x32_bf16 v[68:71], v[172:175], v[212:215], v[68:71]
	v_mfma_f32_16x16x32_bf16 v[64:67], v[180:183], v[212:215], v[64:67]
	s_barrier
	s_setprio 0
	s_add_i32 s69, s57, s48
	v_lshl_add_u64 v[216:217], s[40:41], 0, v[132:133]
	s_mov_b32 m0, s69
	ds_read_b128 v[184:187], v153 offset:16384
	ds_read_b128 v[188:191], v153 offset:17408
	ds_read_b128 v[192:195], v153 offset:18432
	ds_read_b128 v[196:199], v153 offset:19456
	ds_read_b128 v[200:203], v153 offset:20480
	ds_read_b128 v[204:207], v153 offset:21504
	ds_read_b128 v[208:211], v153 offset:22528
	ds_read_b128 v[212:215], v153 offset:23552
	global_load_lds_dwordx4 v[216:217], off
	s_add_i32 m0, s69, 0x2000
	s_add_u32 s70, s40, 0x40000
	v_lshl_add_u64 v[218:219], s[40:41], 0, v[128:129]
	s_addc_u32 s71, s41, 0
	s_add_i32 s69, s58, s48
	global_load_lds_dwordx4 v[218:219], off
	v_lshl_add_u64 v[220:221], s[70:71], 0, v[132:133]
	s_mov_b32 m0, s69
	v_lshl_add_u64 v[222:223], s[42:43], 0, v[130:131]
	global_load_lds_dwordx4 v[220:221], off
	v_lshl_add_u64 v[220:221], s[70:71], 0, v[128:129]
	s_add_i32 m0, s69, 0x2000
	s_nop 0
	global_load_lds_dwordx4 v[220:221], off
	v_lshl_add_u64 v[220:221], s[42:43], 0, v[134:135]
	s_mov_b32 m0, s37
	s_nop 0
	global_load_lds_dwordx4 v[220:221], off
	s_mov_b32 m0, s50
	s_nop 0
	global_load_lds_dwordx4 v[222:223], off
	s_waitcnt vmcnt(8)
	s_waitcnt lgkmcnt(0)
	s_barrier
; #define PG8_STAGE(bufoff, gbase, voff) do { _Pragma("unroll") for (int _i = 0; _i < 2; ++_i) \
;         __builtin_amdgcn_global_load_lds((const unsigned*)((const char*)(gbase) + (voff)[_i]), (PG8_LAS unsigned*)(lds + (bufoff) + ldsw + _i * 8192), 16, 0, 0); } while (0)
; #define PG8_LDA(dst, b, h) do { _Pragma("unroll") for (int m = 0; m < 4; ++m) _Pragma("unroll") for (int k = 0; k < 2; ++k) dst[m][k] = *(const PG8_LAS bf16x8*)(lds + PG8_SA(b, h) + aoff + m * 2048 + k * 1024); } while (0)
; #define PG8_LDB(dst, b, h) do { _Pragma("unroll") for (int n = 0; n < 2; ++n) _Pragma("unroll") for (int k = 0; k < 2; ++k) dst[n][k] = *(const PG8_LAS bf16x8*)(lds + PG8_SB(b, h) + boff + n * 2048 + k * 1024); } while (0)
; #define PG8_MMA(ai, bj, At, Bt) do { __builtin_amdgcn_s_setprio(1); _Pragma("unroll") for (int m = 0; m < 4; ++m) _Pragma("unroll") for (int n = 0; n < 2; ++n) _Pragma("unroll") for (int k = 0; k < 2; ++k) \
;         acc[ai][bj][m][n] = __builtin_amdgcn_mfma_f32_16x16x32_bf16(Bt[n][k], At[m][k], acc[ai][bj][m][n], 0, 0, 0); __builtin_amdgcn_s_setprio(0); } while (0)
; #define PG8_WAIT_V(n) asm volatile("s_waitcnt vmcnt(" #n ")" ::: "memory")
; #define PG8_WAIT_L(n) asm volatile("s_waitcnt lgkmcnt(" #n ")" ::: "memory")
; #define PG8_BAR __builtin_amdgcn_s_barrier()
; #define PG8_SCHED __builtin_amdgcn_sched_barrier(0)
; template <class Epi, class Sched, bool ALIGN_EPI = false, bool SP2 = false>
; __device__ __forceinline__ void gemm_phase(PG8_LAS unsigned char* lds, const Gemm g, const Sched& S, const Epi& E) {
;     ...
;             PG8_WAIT_V(8); PG8_WAIT_L(0); PG8_BAR; PG8_MMA(1, 0, At, B0); PG8_MMA(1, 1, At, B1); PG8_BAR; PG8_SCHED;
;             PG8_LDB(B0, 1, 0); PG8_LDB(B1, 1, 1); PG8_SCHED; PG8_LDA(At, 1, 0); PG8_STAGE(PG8_SA(0, 1), a2 + hstep, voffA);
;             PG8_WAIT_V(8); PG8_WAIT_L(0); PG8_BAR; PG8_MMA(0, 0, At, B0); PG8_MMA(0, 1, At, B1); PG8_BAR; PG8_SCHED;
	s_setprio 1
	v_mfma_f32_16x16x32_bf16 v[60:63], v[144:147], v[184:187], 0
	v_mfma_f32_16x16x32_bf16 v[56:59], v[160:163], v[184:187], 0
	v_mfma_f32_16x16x32_bf16 v[44:47], v[144:147], v[192:195], 0
	v_mfma_f32_16x16x32_bf16 v[40:43], v[160:163], v[192:195], 0
	v_mfma_f32_16x16x32_bf16 v[28:31], v[144:147], v[200:203], 0
	v_mfma_f32_16x16x32_bf16 v[24:27], v[160:163], v[200:203], 0
	v_mfma_f32_16x16x32_bf16 v[12:15], v[144:147], v[208:211], 0
	v_mfma_f32_16x16x32_bf16 v[8:11], v[160:163], v[208:211], 0
	v_mfma_f32_16x16x32_bf16 v[60:63], v[156:159], v[188:191], v[60:63]
	v_mfma_f32_16x16x32_bf16 v[56:59], v[164:167], v[188:191], v[56:59]
	v_mfma_f32_16x16x32_bf16 v[44:47], v[156:159], v[196:199], v[44:47]
	v_mfma_f32_16x16x32_bf16 v[40:43], v[164:167], v[196:199], v[40:43]
	v_mfma_f32_16x16x32_bf16 v[28:31], v[156:159], v[204:207], v[28:31]
	v_mfma_f32_16x16x32_bf16 v[24:27], v[164:167], v[204:207], v[24:27]
	v_mfma_f32_16x16x32_bf16 v[12:15], v[156:159], v[212:215], v[12:15]
	v_mfma_f32_16x16x32_bf16 v[8:11], v[164:167], v[212:215], v[8:11]
	s_setprio 0
	s_setprio 1
	v_mfma_f32_16x16x32_bf16 v[52:55], v[168:171], v[184:187], 0
	v_mfma_f32_16x16x32_bf16 v[48:51], v[176:179], v[184:187], 0
	v_mfma_f32_16x16x32_bf16 v[36:39], v[168:171], v[192:195], 0
	v_mfma_f32_16x16x32_bf16 v[32:35], v[176:179], v[192:195], 0
	v_mfma_f32_16x16x32_bf16 v[20:23], v[168:171], v[200:203], 0
	v_mfma_f32_16x16x32_bf16 v[16:19], v[176:179], v[200:203], 0
	v_mfma_f32_16x16x32_bf16 v[4:7], v[168:171], v[208:211], 0
	v_mfma_f32_16x16x32_bf16 v[0:3], v[176:179], v[208:211], 0
	v_mfma_f32_16x16x32_bf16 v[52:55], v[172:175], v[188:191], v[52:55]
	v_mfma_f32_16x16x32_bf16 v[48:51], v[180:183], v[188:191], v[48:51]
	v_mfma_f32_16x16x32_bf16 v[36:39], v[172:175], v[196:199], v[36:39]
	v_mfma_f32_16x16x32_bf16 v[32:35], v[180:183], v[196:199], v[32:35]
	v_mfma_f32_16x16x32_bf16 v[20:23], v[172:175], v[204:207], v[20:23]
	v_mfma_f32_16x16x32_bf16 v[16:19], v[180:183], v[204:207], v[16:19]
	v_mfma_f32_16x16x32_bf16 v[4:7], v[172:175], v[212:215], v[4:7]
	v_mfma_f32_16x16x32_bf16 v[0:3], v[180:183], v[212:215], v[0:3]
	s_barrier
	s_setprio 0
	s_add_i32 s69, 0, 0x18000
	s_add_i32 s70, 0, 0x1c000
	v_add_u32_e32 v164, s69, v149
	v_add_u32_e32 v180, s70, v149
	ds_read_b128 v[144:147], v164
	ds_read_b128 v[156:159], v164 offset:1024
	ds_read_b128 v[160:163], v164 offset:2048
	ds_read_b128 v[164:167], v164 offset:3072
	ds_read_b128 v[168:171], v180
	ds_read_b128 v[172:175], v180 offset:1024
	ds_read_b128 v[176:179], v180 offset:2048
	ds_read_b128 v[180:183], v180 offset:3072
	s_add_u32 s42, s42, 0x40000
	s_addc_u32 s43, s43, 0
	s_mov_b32 m0, s51
	v_lshl_add_u64 v[224:225], s[42:43], 0, v[134:135]
	ds_read_b128 v[184:187], v153 offset:32768
	ds_read_b128 v[188:191], v153 offset:33792
	ds_read_b128 v[192:195], v153 offset:34816
	ds_read_b128 v[196:199], v153 offset:35840
	ds_read_b128 v[200:203], v153 offset:36864
	ds_read_b128 v[204:207], v153 offset:37888
	ds_read_b128 v[208:211], v153 offset:38912
	ds_read_b128 v[212:215], v153 offset:39936
	global_load_lds_dwordx4 v[224:225], off
	v_lshl_add_u64 v[224:225], s[42:43], 0, v[130:131]
	s_mov_b32 m0, s52
	s_nop 0
	global_load_lds_dwordx4 v[224:225], off
	s_waitcnt vmcnt(8)
	s_waitcnt lgkmcnt(0)
	s_barrier
	s_setprio 1
	v_mfma_f32_16x16x32_bf16 v[124:127], v[144:147], v[184:187], v[124:127]
	v_mfma_f32_16x16x32_bf16 v[120:123], v[160:163], v[184:187], v[120:123]
	v_mfma_f32_16x16x32_bf16 v[108:111], v[144:147], v[192:195], v[108:111]
	v_mfma_f32_16x16x32_bf16 v[104:107], v[160:163], v[192:195], v[104:107]
	v_mfma_f32_16x16x32_bf16 v[92:95], v[144:147], v[200:203], v[92:95]
	v_mfma_f32_16x16x32_bf16 v[88:91], v[160:163], v[200:203], v[88:91]
	v_mfma_f32_16x16x32_bf16 v[76:79], v[144:147], v[208:211], v[76:79]
	v_mfma_f32_16x16x32_bf16 v[72:75], v[160:163], v[208:211], v[72:75]
	v_mfma_f32_16x16x32_bf16 v[124:127], v[156:159], v[188:191], v[124:127]
	v_mfma_f32_16x16x32_bf16 v[120:123], v[164:167], v[188:191], v[120:123]
	v_mfma_f32_16x16x32_bf16 v[108:111], v[156:159], v[196:199], v[108:111]
	v_mfma_f32_16x16x32_bf16 v[104:107], v[164:167], v[196:199], v[104:107]
	v_mfma_f32_16x16x32_bf16 v[92:95], v[156:159], v[204:207], v[92:95]
	v_mfma_f32_16x16x32_bf16 v[88:91], v[164:167], v[204:207], v[88:91]
	v_mfma_f32_16x16x32_bf16 v[76:79], v[156:159], v[212:215], v[76:79]
	v_mfma_f32_16x16x32_bf16 v[72:75], v[164:167], v[212:215], v[72:75]
	s_setprio 0
	s_setprio 1
	v_mfma_f32_16x16x32_bf16 v[116:119], v[168:171], v[184:187], v[116:119]
	v_mfma_f32_16x16x32_bf16 v[112:115], v[176:179], v[184:187], v[112:115]
	v_mfma_f32_16x16x32_bf16 v[100:103], v[168:171], v[192:195], v[100:103]
	v_mfma_f32_16x16x32_bf16 v[96:99], v[176:179], v[192:195], v[96:99]
	v_mfma_f32_16x16x32_bf16 v[84:87], v[168:171], v[200:203], v[84:87]
	v_mfma_f32_16x16x32_bf16 v[80:83], v[176:179], v[200:203], v[80:83]
	v_mfma_f32_16x16x32_bf16 v[68:71], v[168:171], v[208:211], v[68:71]
	v_mfma_f32_16x16x32_bf16 v[64:67], v[176:179], v[208:211], v[64:67]
	v_mfma_f32_16x16x32_bf16 v[116:119], v[172:175], v[188:191], v[116:119]
	v_mfma_f32_16x16x32_bf16 v[112:115], v[180:183], v[188:191], v[112:115]
	v_mfma_f32_16x16x32_bf16 v[100:103], v[172:175], v[196:199], v[100:103]
	v_mfma_f32_16x16x32_bf16 v[96:99], v[180:183], v[196:199], v[96:99]
	v_mfma_f32_16x16x32_bf16 v[84:87], v[172:175], v[204:207], v[84:87]
	v_mfma_f32_16x16x32_bf16 v[80:83], v[180:183], v[204:207], v[80:83]
	v_mfma_f32_16x16x32_bf16 v[68:71], v[172:175], v[212:215], v[68:71]
	v_mfma_f32_16x16x32_bf16 v[64:67], v[180:183], v[212:215], v[64:67]
	s_barrier
; #define PG8_STAGE(bufoff, gbase, voff) do { _Pragma("unroll") for (int _i = 0; _i < 2; ++_i) \
;         __builtin_amdgcn_global_load_lds((const unsigned*)((const char*)(gbase) + (voff)[_i]), (PG8_LAS unsigned*)(lds + (bufoff) + ldsw + _i * 8192), 16, 0, 0); } while (0)
; #define PG8_LDA(dst, b, h) do { _Pragma("unroll") for (int m = 0; m < 4; ++m) _Pragma("unroll") for (int k = 0; k < 2; ++k) dst[m][k] = *(const PG8_LAS bf16x8*)(lds + PG8_SA(b, h) + aoff + m * 2048 + k * 1024); } while (0)
; #define PG8_WAIT_V(n) asm volatile("s_waitcnt vmcnt(" #n ")" ::: "memory")
; #define PG8_BAR __builtin_amdgcn_s_barrier()
; template <class Epi, class Sched, bool ALIGN_EPI = false, bool SP2 = false>
; __device__ __forceinline__ void gemm_phase(PG8_LAS unsigned char* lds, const Gemm g, const Sched& S, const Epi& E) {
;     ...
;         for (int t = 0; t < nt; t += 2) {
;             const bool last = (t == nt - 2);
;             if constexpr (Epi::PREFETCH) { if (t == nt - 4) E.prefetch(cur, lds + STAGE_BYTES + 1024, tid); }
;             const char* a1 = cA + (size_t)(t + 1) * kstep;
;             const char* a2 = last ? nA : cA + (size_t)(t + 2) * kstep; const char* b2 = last ? nB : cB + (size_t)(t + 2) * kstep;
;             const char* a3 = a2 + kstep; const char* b3 = b2 + kstep;
;             if (last && has_next) S.a_ready(nxt);
;             if constexpr (SP2) {
;             PG8_LDB(B0, 0, 0); PG8_LDB(B1, 0, 1); PG8_SCHED; PG8_LDA(At, 0, 0); PG8_STAGE(PG8_SA(1, 1), a1 + hstep, voffA);
;             PG8_WAIT_V(8); PG8_WAIT_L(0); PG8_BAR; PG8_MMA(0, 0, At, B0); PG8_MMA(0, 1, At, B1); PG8_BAR; PG8_SCHED;
;             PG8_LDA(At, 0, 1); PG8_STAGE(PG8_SB(0, 0), b2, voffB); PG8_STAGE(PG8_SB(0, 1), b2 + hstep, voffB); PG8_STAGE(PG8_SA(0, 0), a2, voffA);
;             PG8_WAIT_V(8); PG8_WAIT_L(0); PG8_BAR; PG8_MMA(1, 0, At, B0); PG8_MMA(1, 1, At, B1); PG8_BAR; PG8_SCHED;
;             PG8_LDB(B0, 1, 0); PG8_LDB(B1, 1, 1); PG8_SCHED; PG8_LDA(At, 1, 0); PG8_STAGE(PG8_SA(0, 1), a2 + hstep, voffA);
;             PG8_WAIT_V(8); PG8_WAIT_L(0); PG8_BAR; PG8_MMA(0, 0, At, B0); PG8_MMA(0, 1, At, B1); PG8_BAR; PG8_SCHED;
;             PG8_LDA(At, 1, 1); PG8_STAGE(PG8_SB(1, 0), b3, voffB); PG8_STAGE(PG8_SB(1, 1), b3 + hstep, voffB); PG8_STAGE(PG8_SA(1, 0), a3, voffA);
;             PG8_WAIT_V(8); PG8_WAIT_L(0); PG8_BAR; PG8_MMA(1, 0, At, B0); PG8_MMA(1, 1, At, B1); PG8_BAR; PG8_SCHED;
	s_setprio 0
	s_add_i32 s42, s69, s48
	v_lshl_add_u64 v[216:217], v[216:217], 0, s[14:15]
	s_mov_b32 m0, s42
	ds_read_b128 v[184:187], v153 offset:49152
	ds_read_b128 v[188:191], v153 offset:50176
	ds_read_b128 v[192:195], v153 offset:51200
	ds_read_b128 v[196:199], v153 offset:52224
	ds_read_b128 v[200:203], v153 offset:53248
	ds_read_b128 v[204:207], v153 offset:54272
	ds_read_b128 v[208:211], v153 offset:55296
	ds_read_b128 v[212:215], v153 offset:56320
	global_load_lds_dwordx4 v[216:217], off
	s_add_i32 m0, s42, 0x2000
	s_add_u32 s40, s40, 0x40080
	v_lshl_add_u64 v[216:217], v[218:219], 0, s[14:15]
	s_addc_u32 s41, s41, 0
	s_add_i32 s42, s70, s48
	global_load_lds_dwordx4 v[216:217], off
	v_lshl_add_u64 v[216:217], s[40:41], 0, v[132:133]
	s_mov_b32 m0, s42
	s_nop 0
	global_load_lds_dwordx4 v[216:217], off
	v_lshl_add_u64 v[216:217], s[40:41], 0, v[128:129]
	s_add_i32 m0, s42, 0x2000
	s_nop 0
	global_load_lds_dwordx4 v[216:217], off
	v_lshl_add_u64 v[216:217], v[220:221], 0, s[14:15]
	s_mov_b32 m0, s53
	s_nop 0
	global_load_lds_dwordx4 v[216:217], off
	v_lshl_add_u64 v[216:217], v[222:223], 0, s[14:15]
	s_mov_b32 m0, s54
	s_nop 0
	global_load_lds_dwordx4 v[216:217], off
	s_waitcnt vmcnt(8)
	s_waitcnt lgkmcnt(0)
	s_barrier
	s_setprio 1
	v_mfma_f32_16x16x32_bf16 v[60:63], v[144:147], v[184:187], v[60:63]
	v_mfma_f32_16x16x32_bf16 v[56:59], v[160:163], v[184:187], v[56:59]
	v_mfma_f32_16x16x32_bf16 v[44:47], v[144:147], v[192:195], v[44:47]
	v_mfma_f32_16x16x32_bf16 v[40:43], v[160:163], v[192:195], v[40:43]
	v_mfma_f32_16x16x32_bf16 v[28:31], v[144:147], v[200:203], v[28:31]
	v_mfma_f32_16x16x32_bf16 v[24:27], v[160:163], v[200:203], v[24:27]
	v_mfma_f32_16x16x32_bf16 v[12:15], v[144:147], v[208:211], v[12:15]
	v_mfma_f32_16x16x32_bf16 v[8:11], v[160:163], v[208:211], v[8:11]
	v_mfma_f32_16x16x32_bf16 v[60:63], v[156:159], v[188:191], v[60:63]
	v_mfma_f32_16x16x32_bf16 v[56:59], v[164:167], v[188:191], v[56:59]
	v_mfma_f32_16x16x32_bf16 v[44:47], v[156:159], v[196:199], v[44:47]
	v_mfma_f32_16x16x32_bf16 v[40:43], v[164:167], v[196:199], v[40:43]
	v_mfma_f32_16x16x32_bf16 v[28:31], v[156:159], v[204:207], v[28:31]
	v_mfma_f32_16x16x32_bf16 v[24:27], v[164:167], v[204:207], v[24:27]
	v_mfma_f32_16x16x32_bf16 v[12:15], v[156:159], v[212:215], v[12:15]
	v_mfma_f32_16x16x32_bf16 v[8:11], v[164:167], v[212:215], v[8:11]
	s_setprio 0
	s_setprio 1
	v_mfma_f32_16x16x32_bf16 v[52:55], v[168:171], v[184:187], v[52:55]
	v_mfma_f32_16x16x32_bf16 v[48:51], v[176:179], v[184:187], v[48:51]
	v_mfma_f32_16x16x32_bf16 v[36:39], v[168:171], v[192:195], v[36:39]
	v_mfma_f32_16x16x32_bf16 v[32:35], v[176:179], v[192:195], v[32:35]
	v_mfma_f32_16x16x32_bf16 v[20:23], v[168:171], v[200:203], v[20:23]
	v_mfma_f32_16x16x32_bf16 v[16:19], v[176:179], v[200:203], v[16:19]
	v_mfma_f32_16x16x32_bf16 v[4:7], v[168:171], v[208:211], v[4:7]
	v_mfma_f32_16x16x32_bf16 v[0:3], v[176:179], v[208:211], v[0:3]
	v_mfma_f32_16x16x32_bf16 v[52:55], v[172:175], v[188:191], v[52:55]
	v_mfma_f32_16x16x32_bf16 v[48:51], v[180:183], v[188:191], v[48:51]
	v_mfma_f32_16x16x32_bf16 v[36:39], v[172:175], v[196:199], v[36:39]
	v_mfma_f32_16x16x32_bf16 v[32:35], v[180:183], v[196:199], v[32:35]
	v_mfma_f32_16x16x32_bf16 v[20:23], v[172:175], v[204:207], v[20:23]
	v_mfma_f32_16x16x32_bf16 v[16:19], v[180:183], v[204:207], v[16:19]
	v_mfma_f32_16x16x32_bf16 v[4:7], v[172:175], v[212:215], v[4:7]
	v_mfma_f32_16x16x32_bf16 v[0:3], v[180:183], v[212:215], v[0:3]
	s_barrier
	s_setprio 0
	s_add_i32 s68, s68, 2
	s_add_u32 s38, s38, 0x100
	s_addc_u32 s39, s39, 0
	s_add_u32 s66, s66, 0x100
	s_addc_u32 s67, s67, 0
.LBB0_1906:
	ds_read_b128 v[144:147], v151
	ds_read_b128 v[156:159], v151 offset:1024
	ds_read_b128 v[160:163], v151 offset:2048
	ds_read_b128 v[164:167], v151 offset:3072
	ds_read_b128 v[168:171], v152
	ds_read_b128 v[172:175], v152 offset:1024
	ds_read_b128 v[176:179], v152 offset:2048
	ds_read_b128 v[180:183], v152 offset:3072
	s_add_u32 s40, s38, 0xfffc0080
	s_addc_u32 s41, s39, -1
	s_cmp_eq_u32 s68, 12
	s_cselect_b32 s43, s21, s41
	s_cselect_b32 s42, s64, s40
	s_cselect_b32 s41, s19, s67
	s_cselect_b32 s40, s65, s66
	v_lshl_add_u64 v[216:217], s[38:39], 0, v[136:137]
	s_add_i32 m0, s37, 0xc000
	ds_read_b128 v[184:187], v153
	ds_read_b128 v[188:191], v153 offset:1024
	ds_read_b128 v[192:195], v153 offset:2048
	ds_read_b128 v[196:199], v153 offset:3072
	ds_read_b128 v[200:203], v153 offset:4096
	ds_read_b128 v[204:207], v153 offset:5120
	ds_read_b128 v[208:211], v153 offset:6144
	ds_read_b128 v[212:215], v153 offset:7168
	global_load_lds_dwordx4 v[216:217], off
	v_lshl_add_u64 v[216:217], s[38:39], 0, v[138:139]
	s_add_i32 m0, s37, 0xe000
	s_nop 0
	global_load_lds_dwordx4 v[216:217], off
	s_waitcnt vmcnt(8)
	s_waitcnt lgkmcnt(0)
	s_barrier
; #define PG8_STAGE(bufoff, gbase, voff) do { _Pragma("unroll") for (int _i = 0; _i < 2; ++_i) \
;         __builtin_amdgcn_global_load_lds((const unsigned*)((const char*)(gbase) + (voff)[_i]), (PG8_LAS unsigned*)(lds + (bufoff) + ldsw + _i * 8192), 16, 0, 0); } while (0)
; #define PG8_LDA(dst, b, h) do { _Pragma("unroll") for (int m = 0; m < 4; ++m) _Pragma("unroll") for (int k = 0; k < 2; ++k) dst[m][k] = *(const PG8_LAS bf16x8*)(lds + PG8_SA(b, h) + aoff + m * 2048 + k * 1024); } while (0)
; #define PG8_MMA(ai, bj, At, Bt) do { __builtin_amdgcn_s_setprio(1); _Pragma("unroll") for (int m = 0; m < 4; ++m) _Pragma("unroll") for (int n = 0; n < 2; ++n) _Pragma("unroll") for (int k = 0; k < 2; ++k) \
;         acc[ai][bj][m][n] = __builtin_amdgcn_mfma_f32_16x16x32_bf16(Bt[n][k], At[m][k], acc[ai][bj][m][n], 0, 0, 0); __builtin_amdgcn_s_setprio(0); } while (0)
; #define PG8_WAIT_V(n) asm volatile("s_waitcnt vmcnt(" #n ")" ::: "memory")
; #define PG8_WAIT_L(n) asm volatile("s_waitcnt lgkmcnt(" #n ")" ::: "memory")
; #define PG8_BAR __builtin_amdgcn_s_barrier()
; #define PG8_SCHED __builtin_amdgcn_sched_barrier(0)
; template <class Epi, class Sched, bool ALIGN_EPI = false, bool SP2 = false>
; __device__ __forceinline__ void gemm_phase(PG8_LAS unsigned char* lds, const Gemm g, const Sched& S, const Epi& E) {
;     ...
;             PG8_WAIT_V(8); PG8_WAIT_L(0); PG8_BAR; PG8_MMA(0, 0, At, B0); PG8_MMA(0, 1, At, B1); PG8_BAR; PG8_SCHED;
;             PG8_LDA(At, 0, 1); PG8_STAGE(PG8_SB(0, 0), b2, voffB); PG8_STAGE(PG8_SB(0, 1), b2 + hstep, voffB); PG8_STAGE(PG8_SA(0, 0), a2, voffA);
;             PG8_WAIT_V(8); PG8_WAIT_L(0); PG8_BAR; PG8_MMA(1, 0, At, B0); PG8_MMA(1, 1, At, B1); PG8_BAR; PG8_SCHED;
	s_setprio 1
	v_mfma_f32_16x16x32_bf16 v[124:127], v[144:147], v[184:187], v[124:127]
	v_mfma_f32_16x16x32_bf16 v[120:123], v[160:163], v[184:187], v[120:123]
	v_mfma_f32_16x16x32_bf16 v[108:111], v[144:147], v[192:195], v[108:111]
	v_mfma_f32_16x16x32_bf16 v[104:107], v[160:163], v[192:195], v[104:107]
	v_mfma_f32_16x16x32_bf16 v[92:95], v[144:147], v[200:203], v[92:95]
	v_mfma_f32_16x16x32_bf16 v[88:91], v[160:163], v[200:203], v[88:91]
	v_mfma_f32_16x16x32_bf16 v[76:79], v[144:147], v[208:211], v[76:79]
	v_mfma_f32_16x16x32_bf16 v[72:75], v[160:163], v[208:211], v[72:75]
	v_mfma_f32_16x16x32_bf16 v[124:127], v[156:159], v[188:191], v[124:127]
	v_mfma_f32_16x16x32_bf16 v[120:123], v[164:167], v[188:191], v[120:123]
	v_mfma_f32_16x16x32_bf16 v[108:111], v[156:159], v[196:199], v[108:111]
	v_mfma_f32_16x16x32_bf16 v[104:107], v[164:167], v[196:199], v[104:107]
	v_mfma_f32_16x16x32_bf16 v[92:95], v[156:159], v[204:207], v[92:95]
	v_mfma_f32_16x16x32_bf16 v[88:91], v[164:167], v[204:207], v[88:91]
	v_mfma_f32_16x16x32_bf16 v[76:79], v[156:159], v[212:215], v[76:79]
	v_mfma_f32_16x16x32_bf16 v[72:75], v[164:167], v[212:215], v[72:75]
	s_setprio 0
	s_setprio 1
	v_mfma_f32_16x16x32_bf16 v[116:119], v[168:171], v[184:187], v[116:119]
	v_mfma_f32_16x16x32_bf16 v[112:115], v[176:179], v[184:187], v[112:115]
	v_mfma_f32_16x16x32_bf16 v[100:103], v[168:171], v[192:195], v[100:103]
	v_mfma_f32_16x16x32_bf16 v[96:99], v[176:179], v[192:195], v[96:99]
	v_mfma_f32_16x16x32_bf16 v[84:87], v[168:171], v[200:203], v[84:87]
	v_mfma_f32_16x16x32_bf16 v[80:83], v[176:179], v[200:203], v[80:83]
	v_mfma_f32_16x16x32_bf16 v[68:71], v[168:171], v[208:211], v[68:71]
	v_mfma_f32_16x16x32_bf16 v[64:67], v[176:179], v[208:211], v[64:67]
	v_mfma_f32_16x16x32_bf16 v[116:119], v[172:175], v[188:191], v[116:119]
	v_mfma_f32_16x16x32_bf16 v[112:115], v[180:183], v[188:191], v[112:115]
	v_mfma_f32_16x16x32_bf16 v[100:103], v[172:175], v[196:199], v[100:103]
	v_mfma_f32_16x16x32_bf16 v[96:99], v[180:183], v[196:199], v[96:99]
	v_mfma_f32_16x16x32_bf16 v[84:87], v[172:175], v[204:207], v[84:87]
	v_mfma_f32_16x16x32_bf16 v[80:83], v[180:183], v[204:207], v[80:83]
	v_mfma_f32_16x16x32_bf16 v[68:71], v[172:175], v[212:215], v[68:71]
	v_mfma_f32_16x16x32_bf16 v[64:67], v[180:183], v[212:215], v[64:67]
	s_barrier
	s_setprio 0
	s_add_i32 s69, s57, s48
	v_lshl_add_u64 v[216:217], s[40:41], 0, v[132:133]
	s_mov_b32 m0, s69
	ds_read_b128 v[184:187], v153 offset:16384
	ds_read_b128 v[188:191], v153 offset:17408
	ds_read_b128 v[192:195], v153 offset:18432
	ds_read_b128 v[196:199], v153 offset:19456
	ds_read_b128 v[200:203], v153 offset:20480
	ds_read_b128 v[204:207], v153 offset:21504
	ds_read_b128 v[208:211], v153 offset:22528
	ds_read_b128 v[212:215], v153 offset:23552
	global_load_lds_dwordx4 v[216:217], off
	s_add_i32 m0, s69, 0x2000
	s_add_u32 s70, s40, 0x40000
	v_lshl_add_u64 v[218:219], s[40:41], 0, v[128:129]
	s_addc_u32 s71, s41, 0
	s_add_i32 s69, s58, s48
	global_load_lds_dwordx4 v[218:219], off
	v_lshl_add_u64 v[220:221], s[70:71], 0, v[132:133]
	s_mov_b32 m0, s69
	v_lshl_add_u64 v[222:223], s[42:43], 0, v[130:131]
	global_load_lds_dwordx4 v[220:221], off
	v_lshl_add_u64 v[220:221], s[70:71], 0, v[128:129]
	s_add_i32 m0, s69, 0x2000
	s_nop 0
	global_load_lds_dwordx4 v[220:221], off
	v_lshl_add_u64 v[220:221], s[42:43], 0, v[134:135]
	s_mov_b32 m0, s37
	s_nop 0
	global_load_lds_dwordx4 v[220:221], off
	s_mov_b32 m0, s50
	s_nop 0
	global_load_lds_dwordx4 v[222:223], off
	s_waitcnt vmcnt(8)
	s_waitcnt lgkmcnt(0)
	s_barrier
	s_setprio 1
	v_mfma_f32_16x16x32_bf16 v[60:63], v[144:147], v[184:187], v[60:63]
	v_mfma_f32_16x16x32_bf16 v[56:59], v[160:163], v[184:187], v[56:59]
	v_mfma_f32_16x16x32_bf16 v[44:47], v[144:147], v[192:195], v[44:47]
	v_mfma_f32_16x16x32_bf16 v[40:43], v[160:163], v[192:195], v[40:43]
	v_mfma_f32_16x16x32_bf16 v[28:31], v[144:147], v[200:203], v[28:31]
	v_mfma_f32_16x16x32_bf16 v[24:27], v[160:163], v[200:203], v[24:27]
	v_mfma_f32_16x16x32_bf16 v[12:15], v[144:147], v[208:211], v[12:15]
	v_mfma_f32_16x16x32_bf16 v[8:11], v[160:163], v[208:211], v[8:11]
	v_mfma_f32_16x16x32_bf16 v[60:63], v[156:159], v[188:191], v[60:63]
	v_mfma_f32_16x16x32_bf16 v[56:59], v[164:167], v[188:191], v[56:59]
	v_mfma_f32_16x16x32_bf16 v[44:47], v[156:159], v[196:199], v[44:47]
	v_mfma_f32_16x16x32_bf16 v[40:43], v[164:167], v[196:199], v[40:43]
	v_mfma_f32_16x16x32_bf16 v[28:31], v[156:159], v[204:207], v[28:31]
	v_mfma_f32_16x16x32_bf16 v[24:27], v[164:167], v[204:207], v[24:27]
	v_mfma_f32_16x16x32_bf16 v[12:15], v[156:159], v[212:215], v[12:15]
	v_mfma_f32_16x16x32_bf16 v[8:11], v[164:167], v[212:215], v[8:11]
	s_setprio 0
	s_setprio 1
	v_mfma_f32_16x16x32_bf16 v[52:55], v[168:171], v[184:187], v[52:55]
	v_mfma_f32_16x16x32_bf16 v[48:51], v[176:179], v[184:187], v[48:51]
	v_mfma_f32_16x16x32_bf16 v[36:39], v[168:171], v[192:195], v[36:39]
	v_mfma_f32_16x16x32_bf16 v[32:35], v[176:179], v[192:195], v[32:35]
	v_mfma_f32_16x16x32_bf16 v[20:23], v[168:171], v[200:203], v[20:23]
	v_mfma_f32_16x16x32_bf16 v[16:19], v[176:179], v[200:203], v[16:19]
	v_mfma_f32_16x16x32_bf16 v[4:7], v[168:171], v[208:211], v[4:7]
	v_mfma_f32_16x16x32_bf16 v[0:3], v[176:179], v[208:211], v[0:3]
	v_mfma_f32_16x16x32_bf16 v[52:55], v[172:175], v[188:191], v[52:55]
	v_mfma_f32_16x16x32_bf16 v[48:51], v[180:183], v[188:191], v[48:51]
	v_mfma_f32_16x16x32_bf16 v[36:39], v[172:175], v[196:199], v[36:39]
	v_mfma_f32_16x16x32_bf16 v[32:35], v[180:183], v[196:199], v[32:35]
	v_mfma_f32_16x16x32_bf16 v[20:23], v[172:175], v[204:207], v[20:23]
	v_mfma_f32_16x16x32_bf16 v[16:19], v[180:183], v[204:207], v[16:19]
	v_mfma_f32_16x16x32_bf16 v[4:7], v[172:175], v[212:215], v[4:7]
	v_mfma_f32_16x16x32_bf16 v[0:3], v[180:183], v[212:215], v[0:3]
	s_barrier
; #define PG8_STAGE(bufoff, gbase, voff) do { _Pragma("unroll") for (int _i = 0; _i < 2; ++_i) \
;         __builtin_amdgcn_global_load_lds((const unsigned*)((const char*)(gbase) + (voff)[_i]), (PG8_LAS unsigned*)(lds + (bufoff) + ldsw + _i * 8192), 16, 0, 0); } while (0)
; #define PG8_LDA(dst, b, h) do { _Pragma("unroll") for (int m = 0; m < 4; ++m) _Pragma("unroll") for (int k = 0; k < 2; ++k) dst[m][k] = *(const PG8_LAS bf16x8*)(lds + PG8_SA(b, h) + aoff + m * 2048 + k * 1024); } while (0)
; #define PG8_LDB(dst, b, h) do { _Pragma("unroll") for (int n = 0; n < 2; ++n) _Pragma("unroll") for (int k = 0; k < 2; ++k) dst[n][k] = *(const PG8_LAS bf16x8*)(lds + PG8_SB(b, h) + boff + n * 2048 + k * 1024); } while (0)
; #define PG8_MMA(ai, bj, At, Bt) do { __builtin_amdgcn_s_setprio(1); _Pragma("unroll") for (int m = 0; m < 4; ++m) _Pragma("unroll") for (int n = 0; n < 2; ++n) _Pragma("unroll") for (int k = 0; k < 2; ++k) \
;         acc[ai][bj][m][n] = __builtin_amdgcn_mfma_f32_16x16x32_bf16(Bt[n][k], At[m][k], acc[ai][bj][m][n], 0, 0, 0); __builtin_amdgcn_s_setprio(0); } while (0)
; #define PG8_WAIT_V(n) asm volatile("s_waitcnt vmcnt(" #n ")" ::: "memory")
; #define PG8_WAIT_L(n) asm volatile("s_waitcnt lgkmcnt(" #n ")" ::: "memory")
; #define PG8_BAR __builtin_amdgcn_s_barrier()
; #define PG8_SCHED __builtin_amdgcn_sched_barrier(0)
; template <class Epi, class Sched, bool ALIGN_EPI = false, bool SP2 = false>
; __device__ __forceinline__ void gemm_phase(PG8_LAS unsigned char* lds, const Gemm g, const Sched& S, const Epi& E) {
;     ...
;             PG8_LDB(B0, 1, 0); PG8_LDB(B1, 1, 1); PG8_SCHED; PG8_LDA(At, 1, 0); PG8_STAGE(PG8_SA(0, 1), a2 + hstep, voffA);
;             PG8_WAIT_V(8); PG8_WAIT_L(0); PG8_BAR; PG8_MMA(0, 0, At, B0); PG8_MMA(0, 1, At, B1); PG8_BAR; PG8_SCHED;
	s_setprio 0
	s_add_i32 s69, 0, 0x18000
	s_add_i32 s70, 0, 0x1c000
	v_add_u32_e32 v164, s69, v149
	v_add_u32_e32 v180, s70, v149
	ds_read_b128 v[144:147], v164
	ds_read_b128 v[156:159], v164 offset:1024
	ds_read_b128 v[160:163], v164 offset:2048
	ds_read_b128 v[164:167], v164 offset:3072
	ds_read_b128 v[168:171], v180
	ds_read_b128 v[172:175], v180 offset:1024
	ds_read_b128 v[176:179], v180 offset:2048
	ds_read_b128 v[180:183], v180 offset:3072
	s_add_u32 s42, s42, 0x40000
	s_addc_u32 s43, s43, 0
	s_mov_b32 m0, s51
	v_lshl_add_u64 v[224:225], s[42:43], 0, v[134:135]
	ds_read_b128 v[184:187], v153 offset:32768
	ds_read_b128 v[188:191], v153 offset:33792
	ds_read_b128 v[192:195], v153 offset:34816
	ds_read_b128 v[196:199], v153 offset:35840
	ds_read_b128 v[200:203], v153 offset:36864
	ds_read_b128 v[204:207], v153 offset:37888
	ds_read_b128 v[208:211], v153 offset:38912
	ds_read_b128 v[212:215], v153 offset:39936
	global_load_lds_dwordx4 v[224:225], off
	v_lshl_add_u64 v[224:225], s[42:43], 0, v[130:131]
	s_mov_b32 m0, s52
	s_nop 0
	global_load_lds_dwordx4 v[224:225], off
	s_waitcnt vmcnt(8)
	s_waitcnt lgkmcnt(0)
	s_barrier
	s_setprio 1
	v_mfma_f32_16x16x32_bf16 v[124:127], v[144:147], v[184:187], v[124:127]
	v_mfma_f32_16x16x32_bf16 v[120:123], v[160:163], v[184:187], v[120:123]
	v_mfma_f32_16x16x32_bf16 v[108:111], v[144:147], v[192:195], v[108:111]
	v_mfma_f32_16x16x32_bf16 v[104:107], v[160:163], v[192:195], v[104:107]
	v_mfma_f32_16x16x32_bf16 v[92:95], v[144:147], v[200:203], v[92:95]
	v_mfma_f32_16x16x32_bf16 v[88:91], v[160:163], v[200:203], v[88:91]
	v_mfma_f32_16x16x32_bf16 v[76:79], v[144:147], v[208:211], v[76:79]
	v_mfma_f32_16x16x32_bf16 v[72:75], v[160:163], v[208:211], v[72:75]
	v_mfma_f32_16x16x32_bf16 v[124:127], v[156:159], v[188:191], v[124:127]
	v_mfma_f32_16x16x32_bf16 v[120:123], v[164:167], v[188:191], v[120:123]
	v_mfma_f32_16x16x32_bf16 v[108:111], v[156:159], v[196:199], v[108:111]
	v_mfma_f32_16x16x32_bf16 v[104:107], v[164:167], v[196:199], v[104:107]
	v_mfma_f32_16x16x32_bf16 v[92:95], v[156:159], v[204:207], v[92:95]
	v_mfma_f32_16x16x32_bf16 v[88:91], v[164:167], v[204:207], v[88:91]
	v_mfma_f32_16x16x32_bf16 v[76:79], v[156:159], v[212:215], v[76:79]
	v_mfma_f32_16x16x32_bf16 v[72:75], v[164:167], v[212:215], v[72:75]
	s_setprio 0
	s_setprio 1
	v_mfma_f32_16x16x32_bf16 v[116:119], v[168:171], v[184:187], v[116:119]
	v_mfma_f32_16x16x32_bf16 v[112:115], v[176:179], v[184:187], v[112:115]
	v_mfma_f32_16x16x32_bf16 v[100:103], v[168:171], v[192:195], v[100:103]
	v_mfma_f32_16x16x32_bf16 v[96:99], v[176:179], v[192:195], v[96:99]
	v_mfma_f32_16x16x32_bf16 v[84:87], v[168:171], v[200:203], v[84:87]
	v_mfma_f32_16x16x32_bf16 v[80:83], v[176:179], v[200:203], v[80:83]
	v_mfma_f32_16x16x32_bf16 v[68:71], v[168:171], v[208:211], v[68:71]
	v_mfma_f32_16x16x32_bf16 v[64:67], v[176:179], v[208:211], v[64:67]
	v_mfma_f32_16x16x32_bf16 v[116:119], v[172:175], v[188:191], v[116:119]
	v_mfma_f32_16x16x32_bf16 v[112:115], v[180:183], v[188:191], v[112:115]
	v_mfma_f32_16x16x32_bf16 v[100:103], v[172:175], v[196:199], v[100:103]
	v_mfma_f32_16x16x32_bf16 v[96:99], v[180:183], v[196:199], v[96:99]
	v_mfma_f32_16x16x32_bf16 v[84:87], v[172:175], v[204:207], v[84:87]
	v_mfma_f32_16x16x32_bf16 v[80:83], v[180:183], v[204:207], v[80:83]
	v_mfma_f32_16x16x32_bf16 v[68:71], v[172:175], v[212:215], v[68:71]
	v_mfma_f32_16x16x32_bf16 v[64:67], v[180:183], v[212:215], v[64:67]
	s_barrier
; #define PG8_STAGE(bufoff, gbase, voff) do { _Pragma("unroll") for (int _i = 0; _i < 2; ++_i) \
;         __builtin_amdgcn_global_load_lds((const unsigned*)((const char*)(gbase) + (voff)[_i]), (PG8_LAS unsigned*)(lds + (bufoff) + ldsw + _i * 8192), 16, 0, 0); } while (0)
; #define PG8_LDA(dst, b, h) do { _Pragma("unroll") for (int m = 0; m < 4; ++m) _Pragma("unroll") for (int k = 0; k < 2; ++k) dst[m][k] = *(const PG8_LAS bf16x8*)(lds + PG8_SA(b, h) + aoff + m * 2048 + k * 1024); } while (0)
; #define PG8_MMA(ai, bj, At, Bt) do { __builtin_amdgcn_s_setprio(1); _Pragma("unroll") for (int m = 0; m < 4; ++m) _Pragma("unroll") for (int n = 0; n < 2; ++n) _Pragma("unroll") for (int k = 0; k < 2; ++k) \
;         acc[ai][bj][m][n] = __builtin_amdgcn_mfma_f32_16x16x32_bf16(Bt[n][k], At[m][k], acc[ai][bj][m][n], 0, 0, 0); __builtin_amdgcn_s_setprio(0); } while (0)
; #define PG8_WAIT_V(n) asm volatile("s_waitcnt vmcnt(" #n ")" ::: "memory")
; #define PG8_WAIT_L(n) asm volatile("s_waitcnt lgkmcnt(" #n ")" ::: "memory")
; #define PG8_BAR __builtin_amdgcn_s_barrier()
; #define PG8_SCHED __builtin_amdgcn_sched_barrier(0)
; template <class Epi, class Sched, bool ALIGN_EPI = false, bool SP2 = false>
; __device__ __forceinline__ void gemm_phase(PG8_LAS unsigned char* lds, const Gemm g, const Sched& S, const Epi& E) {
;     ...
;             PG8_LDA(At, 1, 1); PG8_STAGE(PG8_SB(1, 0), b3, voffB); PG8_STAGE(PG8_SB(1, 1), b3 + hstep, voffB); PG8_STAGE(PG8_SA(1, 0), a3, voffA);
;             PG8_WAIT_V(8); PG8_WAIT_L(0); PG8_BAR; PG8_MMA(1, 0, At, B0); PG8_MMA(1, 1, At, B1); PG8_BAR; PG8_SCHED;
	s_setprio 0
	s_add_i32 s42, s69, s48
	v_lshl_add_u64 v[216:217], v[216:217], 0, s[14:15]
	s_mov_b32 m0, s42
	ds_read_b128 v[184:187], v153 offset:49152
	ds_read_b128 v[188:191], v153 offset:50176
	ds_read_b128 v[192:195], v153 offset:51200
	ds_read_b128 v[196:199], v153 offset:52224
	ds_read_b128 v[200:203], v153 offset:53248
	ds_read_b128 v[204:207], v153 offset:54272
	ds_read_b128 v[208:211], v153 offset:55296
	ds_read_b128 v[212:215], v153 offset:56320
	global_load_lds_dwordx4 v[216:217], off
	s_add_i32 m0, s42, 0x2000
	s_add_u32 s40, s40, 0x40080
	v_lshl_add_u64 v[216:217], v[218:219], 0, s[14:15]
	s_addc_u32 s41, s41, 0
	s_add_i32 s42, s70, s48
	global_load_lds_dwordx4 v[216:217], off
	v_lshl_add_u64 v[216:217], s[40:41], 0, v[132:133]
	s_mov_b32 m0, s42
	s_nop 0
	global_load_lds_dwordx4 v[216:217], off
	v_lshl_add_u64 v[216:217], s[40:41], 0, v[128:129]
	s_add_i32 m0, s42, 0x2000
	s_nop 0
	global_load_lds_dwordx4 v[216:217], off
	v_lshl_add_u64 v[216:217], v[220:221], 0, s[14:15]
	s_mov_b32 m0, s53
	s_nop 0
	global_load_lds_dwordx4 v[216:217], off
	v_lshl_add_u64 v[216:217], v[222:223], 0, s[14:15]
	s_mov_b32 m0, s54
	s_nop 0
	global_load_lds_dwordx4 v[216:217], off
	s_waitcnt vmcnt(8)
	s_waitcnt lgkmcnt(0)
	s_barrier
	s_setprio 1
	v_mfma_f32_16x16x32_bf16 v[60:63], v[144:147], v[184:187], v[60:63]
	v_mfma_f32_16x16x32_bf16 v[56:59], v[160:163], v[184:187], v[56:59]
	v_mfma_f32_16x16x32_bf16 v[44:47], v[144:147], v[192:195], v[44:47]
	v_mfma_f32_16x16x32_bf16 v[40:43], v[160:163], v[192:195], v[40:43]
	v_mfma_f32_16x16x32_bf16 v[28:31], v[144:147], v[200:203], v[28:31]
	v_mfma_f32_16x16x32_bf16 v[24:27], v[160:163], v[200:203], v[24:27]
	v_mfma_f32_16x16x32_bf16 v[12:15], v[144:147], v[208:211], v[12:15]
	v_mfma_f32_16x16x32_bf16 v[8:11], v[160:163], v[208:211], v[8:11]
	v_mfma_f32_16x16x32_bf16 v[60:63], v[156:159], v[188:191], v[60:63]
	v_mfma_f32_16x16x32_bf16 v[56:59], v[164:167], v[188:191], v[56:59]
	v_mfma_f32_16x16x32_bf16 v[44:47], v[156:159], v[196:199], v[44:47]
	v_mfma_f32_16x16x32_bf16 v[40:43], v[164:167], v[196:199], v[40:43]
	v_mfma_f32_16x16x32_bf16 v[28:31], v[156:159], v[204:207], v[28:31]
	v_mfma_f32_16x16x32_bf16 v[24:27], v[164:167], v[204:207], v[24:27]
	v_mfma_f32_16x16x32_bf16 v[12:15], v[156:159], v[212:215], v[12:15]
	v_mfma_f32_16x16x32_bf16 v[8:11], v[164:167], v[212:215], v[8:11]
	s_setprio 0
	s_setprio 1
	v_mfma_f32_16x16x32_bf16 v[52:55], v[168:171], v[184:187], v[52:55]
	v_mfma_f32_16x16x32_bf16 v[48:51], v[176:179], v[184:187], v[48:51]
	v_mfma_f32_16x16x32_bf16 v[36:39], v[168:171], v[192:195], v[36:39]
	v_mfma_f32_16x16x32_bf16 v[32:35], v[176:179], v[192:195], v[32:35]
	v_mfma_f32_16x16x32_bf16 v[20:23], v[168:171], v[200:203], v[20:23]
	v_mfma_f32_16x16x32_bf16 v[16:19], v[176:179], v[200:203], v[16:19]
	v_mfma_f32_16x16x32_bf16 v[4:7], v[168:171], v[208:211], v[4:7]
	v_mfma_f32_16x16x32_bf16 v[0:3], v[176:179], v[208:211], v[0:3]
	v_mfma_f32_16x16x32_bf16 v[52:55], v[172:175], v[188:191], v[52:55]
	v_mfma_f32_16x16x32_bf16 v[48:51], v[180:183], v[188:191], v[48:51]
	v_mfma_f32_16x16x32_bf16 v[36:39], v[172:175], v[196:199], v[36:39]
	v_mfma_f32_16x16x32_bf16 v[32:35], v[180:183], v[196:199], v[32:35]
	v_mfma_f32_16x16x32_bf16 v[20:23], v[172:175], v[204:207], v[20:23]
	v_mfma_f32_16x16x32_bf16 v[16:19], v[180:183], v[204:207], v[16:19]
	v_mfma_f32_16x16x32_bf16 v[4:7], v[172:175], v[212:215], v[4:7]
	v_mfma_f32_16x16x32_bf16 v[0:3], v[180:183], v[212:215], v[0:3]
	s_barrier
	s_setprio 0
	s_add_i32 s68, s68, 2
	s_add_u32 s38, s38, 0x100
	s_addc_u32 s39, s39, 0
	s_add_u32 s66, s66, 0x100
	s_addc_u32 s67, s67, 0
	s_cmp_gt_u32 s68, 13
	s_cbranch_scc0 .LBB0_1906
	s_and_b64 vcc, exec, s[16:17]
	s_cbranch_vccz .LBB0_1909
	s_barrier

; #define PG8_STAGE(bufoff, gbase, voff) do { _Pragma("unroll") for (int _i = 0; _i < 2; ++_i) \
;         __builtin_amdgcn_global_load_lds((const unsigned*)((const char*)(gbase) + (voff)[_i]), (PG8_LAS unsigned*)(lds + (bufoff) + ldsw + _i * 8192), 16, 0, 0); } while (0)
; #define PG8_LDA(dst, b, h) do { _Pragma("unroll") for (int m = 0; m < 4; ++m) _Pragma("unroll") for (int k = 0; k < 2; ++k) dst[m][k] = *(const PG8_LAS bf16x8*)(lds + PG8_SA(b, h) + aoff + m * 2048 + k * 1024); } while (0)
; #define PG8_LDB(dst, b, h) do { _Pragma("unroll") for (int n = 0; n < 2; ++n) _Pragma("unroll") for (int k = 0; k < 2; ++k) dst[n][k] = *(const PG8_LAS bf16x8*)(lds + PG8_SB(b, h) + boff + n * 2048 + k * 1024); } while (0)
; #define PG8_WAIT_V(n) asm volatile("s_waitcnt vmcnt(" #n ")" ::: "memory")
; #define PG8_WAIT_L(n) asm volatile("s_waitcnt lgkmcnt(" #n ")" ::: "memory")
; template <class Epi, class Sched, bool ALIGN_EPI = false, bool SP2 = false>
; __device__ __forceinline__ void gemm_phase(PG8_LAS unsigned char* lds, const Gemm g, const Sched& S, const Epi& E) {
;     ...
;         const bool has_next = S.next(ui + 1, nxt);
;         const char* nA = has_next ? (const char*)g.A + (size_t)nxt.pm * tstep : cA; const char* nB = has_next ? (const char*)g.Bt + (size_t)nxt.pn * tstep : cB;
;         for (int t = 0; t < nt; t += 2) {
;             const bool last = (t == nt - 2);
;             if constexpr (Epi::PREFETCH) { if (t == nt - 4) E.prefetch(cur, lds + STAGE_BYTES + 1024, tid); }
;             const char* a1 = cA + (size_t)(t + 1) * kstep;
;             const char* a2 = last ? nA : cA + (size_t)(t + 2) * kstep; const char* b2 = last ? nB : cB + (size_t)(t + 2) * kstep;
;             const char* a3 = a2 + kstep; const char* b3 = b2 + kstep;
;             if (last && has_next) S.a_ready(nxt);
;             if constexpr (SP2) {
;             PG8_LDB(B0, 0, 0); PG8_LDB(B1, 0, 1); PG8_SCHED; PG8_LDA(At, 0, 0); PG8_STAGE(PG8_SA(1, 1), a1 + hstep, voffA);
;             PG8_WAIT_V(8); PG8_WAIT_L(0); PG8_BAR; PG8_MMA(0, 0, At, B0); PG8_MMA(0, 1, At, B1); PG8_BAR; PG8_SCHED;
;             PG8_LDA(At, 0, 1); PG8_STAGE(PG8_SB(0, 0), b2, voffB); PG8_STAGE(PG8_SB(0, 1), b2 + hstep, voffB); PG8_STAGE(PG8_SA(0, 0), a2, voffA);
;             PG8_WAIT_V(8); PG8_WAIT_L(0); PG8_BAR; PG8_MMA(1, 0, At, B0); PG8_MMA(1, 1, At, B1); PG8_BAR; PG8_SCHED;
.LBB0_2596:
	s_add_u32 s38, s38, 0xb0080
	s_addc_u32 s39, s39, 0
	s_add_u32 s66, s40, 0x100
	s_addc_u32 s67, s41, 0
	s_mov_b32 s68, -2
	ds_read_b128 v[128:131], v201
	ds_read_b128 v[132:135], v201 offset:1024
	ds_read_b128 v[136:139], v201 offset:2048
	ds_read_b128 v[140:143], v201 offset:3072
	ds_read_b128 v[144:147], v202
	ds_read_b128 v[148:151], v202 offset:1024
	ds_read_b128 v[152:155], v202 offset:2048
	ds_read_b128 v[156:159], v202 offset:3072
	s_add_u32 s40, s38, 0xfff50080
	s_addc_u32 s41, s39, -1
	s_cmp_eq_u32 s68, 40
	s_cselect_b32 s43, s7, s41
	s_cselect_b32 s42, s6, s40
	s_cselect_b32 s41, s37, s67
	s_cselect_b32 s40, s36, s66
	v_lshl_add_u64 v[196:197], s[38:39], 0, v[176:177]
	s_add_i32 m0, s49, 0xc000
	ds_read_b128 v[160:163], v203
	ds_read_b128 v[164:167], v203 offset:1024
	ds_read_b128 v[184:187], v203 offset:2048
	ds_read_b128 v[188:191], v203 offset:3072
	ds_read_b128 v[192:195], v203 offset:4096
	ds_read_b128 v[204:207], v203 offset:5120
	ds_read_b128 v[208:211], v203 offset:6144
	ds_read_b128 v[212:215], v203 offset:7168
	global_load_lds_dwordx4 v[196:197], off
	v_lshl_add_u64 v[196:197], s[38:39], 0, v[178:179]
	s_add_i32 m0, s49, 0xe000
	s_nop 0
	global_load_lds_dwordx4 v[196:197], off
	s_waitcnt vmcnt(8)
	s_waitcnt lgkmcnt(0)
	s_barrier
	s_setprio 1
	v_mfma_f32_16x16x32_bf16 v[124:127], v[128:131], v[160:163], 0
	v_mfma_f32_16x16x32_bf16 v[120:123], v[136:139], v[160:163], 0
	v_mfma_f32_16x16x32_bf16 v[116:119], v[128:131], v[184:187], 0
	v_mfma_f32_16x16x32_bf16 v[104:107], v[136:139], v[184:187], 0
	v_mfma_f32_16x16x32_bf16 v[92:95], v[128:131], v[192:195], 0
	v_mfma_f32_16x16x32_bf16 v[88:91], v[136:139], v[192:195], 0
	v_mfma_f32_16x16x32_bf16 v[76:79], v[128:131], v[208:211], 0
	v_mfma_f32_16x16x32_bf16 v[72:75], v[136:139], v[208:211], 0
	v_mfma_f32_16x16x32_bf16 v[124:127], v[132:135], v[164:167], v[124:127]
	v_mfma_f32_16x16x32_bf16 v[120:123], v[140:143], v[164:167], v[120:123]
	v_mfma_f32_16x16x32_bf16 v[116:119], v[132:135], v[188:191], v[116:119]
	v_mfma_f32_16x16x32_bf16 v[104:107], v[140:143], v[188:191], v[104:107]
	v_mfma_f32_16x16x32_bf16 v[92:95], v[132:135], v[204:207], v[92:95]
	v_mfma_f32_16x16x32_bf16 v[88:91], v[140:143], v[204:207], v[88:91]
	v_mfma_f32_16x16x32_bf16 v[76:79], v[132:135], v[212:215], v[76:79]
	v_mfma_f32_16x16x32_bf16 v[72:75], v[140:143], v[212:215], v[72:75]
	s_setprio 0
	s_setprio 1
	v_mfma_f32_16x16x32_bf16 v[112:115], v[144:147], v[160:163], 0
	v_mfma_f32_16x16x32_bf16 v[108:111], v[152:155], v[160:163], 0
	v_mfma_f32_16x16x32_bf16 v[100:103], v[144:147], v[184:187], 0
	v_mfma_f32_16x16x32_bf16 v[96:99], v[152:155], v[184:187], 0
	v_mfma_f32_16x16x32_bf16 v[84:87], v[144:147], v[192:195], 0
	v_mfma_f32_16x16x32_bf16 v[80:83], v[152:155], v[192:195], 0
	v_mfma_f32_16x16x32_bf16 v[68:71], v[144:147], v[208:211], 0
	v_mfma_f32_16x16x32_bf16 v[64:67], v[152:155], v[208:211], 0
	v_mfma_f32_16x16x32_bf16 v[112:115], v[148:151], v[164:167], v[112:115]
	v_mfma_f32_16x16x32_bf16 v[108:111], v[156:159], v[164:167], v[108:111]
	v_mfma_f32_16x16x32_bf16 v[100:103], v[148:151], v[188:191], v[100:103]
	v_mfma_f32_16x16x32_bf16 v[96:99], v[156:159], v[188:191], v[96:99]
	v_mfma_f32_16x16x32_bf16 v[84:87], v[148:151], v[204:207], v[84:87]
	v_mfma_f32_16x16x32_bf16 v[80:83], v[156:159], v[204:207], v[80:83]
	v_mfma_f32_16x16x32_bf16 v[68:71], v[148:151], v[212:215], v[68:71]
	v_mfma_f32_16x16x32_bf16 v[64:67], v[156:159], v[212:215], v[64:67]
	s_barrier
	s_setprio 0
	s_add_i32 s69, s57, s48
	v_lshl_add_u64 v[196:197], s[40:41], 0, v[170:171]
	s_mov_b32 m0, s69
	ds_read_b128 v[160:163], v203 offset:16384
	ds_read_b128 v[164:167], v203 offset:17408
	ds_read_b128 v[184:187], v203 offset:18432
	ds_read_b128 v[188:191], v203 offset:19456
	ds_read_b128 v[192:195], v203 offset:20480
	ds_read_b128 v[204:207], v203 offset:21504
	ds_read_b128 v[208:211], v203 offset:22528
	ds_read_b128 v[212:215], v203 offset:23552
	global_load_lds_dwordx4 v[196:197], off
	s_add_i32 m0, s69, 0x2000
	s_add_u32 s70, s40, 0xb0000
	v_lshl_add_u64 v[216:217], s[40:41], 0, v[174:175]
	s_addc_u32 s71, s41, 0
	s_add_i32 s69, s58, s48
	global_load_lds_dwordx4 v[216:217], off
	v_lshl_add_u64 v[218:219], s[70:71], 0, v[170:171]
	s_mov_b32 m0, s69
	v_lshl_add_u64 v[220:221], s[42:43], 0, v[172:173]
	global_load_lds_dwordx4 v[218:219], off
	v_lshl_add_u64 v[218:219], s[70:71], 0, v[174:175]
	s_add_i32 m0, s69, 0x2000
	s_nop 0
	global_load_lds_dwordx4 v[218:219], off
	v_lshl_add_u64 v[218:219], s[42:43], 0, v[168:169]
	s_mov_b32 m0, s49
	s_nop 0
	global_load_lds_dwordx4 v[218:219], off
	s_mov_b32 m0, s50
	s_nop 0
	global_load_lds_dwordx4 v[220:221], off
	s_waitcnt vmcnt(8)
	s_waitcnt lgkmcnt(0)
	s_barrier
; #define PG8_STAGE(bufoff, gbase, voff) do { _Pragma("unroll") for (int _i = 0; _i < 2; ++_i) \
;         __builtin_amdgcn_global_load_lds((const unsigned*)((const char*)(gbase) + (voff)[_i]), (PG8_LAS unsigned*)(lds + (bufoff) + ldsw + _i * 8192), 16, 0, 0); } while (0)
; #define PG8_LDA(dst, b, h) do { _Pragma("unroll") for (int m = 0; m < 4; ++m) _Pragma("unroll") for (int k = 0; k < 2; ++k) dst[m][k] = *(const PG8_LAS bf16x8*)(lds + PG8_SA(b, h) + aoff + m * 2048 + k * 1024); } while (0)
; #define PG8_LDB(dst, b, h) do { _Pragma("unroll") for (int n = 0; n < 2; ++n) _Pragma("unroll") for (int k = 0; k < 2; ++k) dst[n][k] = *(const PG8_LAS bf16x8*)(lds + PG8_SB(b, h) + boff + n * 2048 + k * 1024); } while (0)
; #define PG8_MMA(ai, bj, At, Bt) do { __builtin_amdgcn_s_setprio(1); _Pragma("unroll") for (int m = 0; m < 4; ++m) _Pragma("unroll") for (int n = 0; n < 2; ++n) _Pragma("unroll") for (int k = 0; k < 2; ++k) \
;         acc[ai][bj][m][n] = __builtin_amdgcn_mfma_f32_16x16x32_bf16(Bt[n][k], At[m][k], acc[ai][bj][m][n], 0, 0, 0); __builtin_amdgcn_s_setprio(0); } while (0)
; #define PG8_WAIT_V(n) asm volatile("s_waitcnt vmcnt(" #n ")" ::: "memory")
; #define PG8_WAIT_L(n) asm volatile("s_waitcnt lgkmcnt(" #n ")" ::: "memory")
; #define PG8_BAR __builtin_amdgcn_s_barrier()
; #define PG8_SCHED __builtin_amdgcn_sched_barrier(0)
; template <class Epi, class Sched, bool ALIGN_EPI = false, bool SP2 = false>
; __device__ __forceinline__ void gemm_phase(PG8_LAS unsigned char* lds, const Gemm g, const Sched& S, const Epi& E) {
;     ...
;             PG8_WAIT_V(8); PG8_WAIT_L(0); PG8_BAR; PG8_MMA(1, 0, At, B0); PG8_MMA(1, 1, At, B1); PG8_BAR; PG8_SCHED;
;             PG8_LDB(B0, 1, 0); PG8_LDB(B1, 1, 1); PG8_SCHED; PG8_LDA(At, 1, 0); PG8_STAGE(PG8_SA(0, 1), a2 + hstep, voffA);
;             PG8_WAIT_V(8); PG8_WAIT_L(0); PG8_BAR; PG8_MMA(0, 0, At, B0); PG8_MMA(0, 1, At, B1); PG8_BAR; PG8_SCHED;
	s_setprio 1
	v_mfma_f32_16x16x32_bf16 v[60:63], v[128:131], v[160:163], 0
	v_mfma_f32_16x16x32_bf16 v[56:59], v[136:139], v[160:163], 0
	v_mfma_f32_16x16x32_bf16 v[44:47], v[128:131], v[184:187], 0
	v_mfma_f32_16x16x32_bf16 v[40:43], v[136:139], v[184:187], 0
	v_mfma_f32_16x16x32_bf16 v[28:31], v[128:131], v[192:195], 0
	v_mfma_f32_16x16x32_bf16 v[24:27], v[136:139], v[192:195], 0
	v_mfma_f32_16x16x32_bf16 v[12:15], v[128:131], v[208:211], 0
	v_mfma_f32_16x16x32_bf16 v[8:11], v[136:139], v[208:211], 0
	v_mfma_f32_16x16x32_bf16 v[60:63], v[132:135], v[164:167], v[60:63]
	v_mfma_f32_16x16x32_bf16 v[56:59], v[140:143], v[164:167], v[56:59]
	v_mfma_f32_16x16x32_bf16 v[44:47], v[132:135], v[188:191], v[44:47]
	v_mfma_f32_16x16x32_bf16 v[40:43], v[140:143], v[188:191], v[40:43]
	v_mfma_f32_16x16x32_bf16 v[28:31], v[132:135], v[204:207], v[28:31]
	v_mfma_f32_16x16x32_bf16 v[24:27], v[140:143], v[204:207], v[24:27]
	v_mfma_f32_16x16x32_bf16 v[12:15], v[132:135], v[212:215], v[12:15]
	v_mfma_f32_16x16x32_bf16 v[8:11], v[140:143], v[212:215], v[8:11]
	s_setprio 0
	s_setprio 1
	v_mfma_f32_16x16x32_bf16 v[52:55], v[144:147], v[160:163], 0
	v_mfma_f32_16x16x32_bf16 v[48:51], v[152:155], v[160:163], 0
	v_mfma_f32_16x16x32_bf16 v[36:39], v[144:147], v[184:187], 0
	v_mfma_f32_16x16x32_bf16 v[32:35], v[152:155], v[184:187], 0
	v_mfma_f32_16x16x32_bf16 v[20:23], v[144:147], v[192:195], 0
	v_mfma_f32_16x16x32_bf16 v[16:19], v[152:155], v[192:195], 0
	v_mfma_f32_16x16x32_bf16 v[4:7], v[144:147], v[208:211], 0
	v_mfma_f32_16x16x32_bf16 v[0:3], v[152:155], v[208:211], 0
	v_mfma_f32_16x16x32_bf16 v[52:55], v[148:151], v[164:167], v[52:55]
	v_mfma_f32_16x16x32_bf16 v[48:51], v[156:159], v[164:167], v[48:51]
	v_mfma_f32_16x16x32_bf16 v[36:39], v[148:151], v[188:191], v[36:39]
	v_mfma_f32_16x16x32_bf16 v[32:35], v[156:159], v[188:191], v[32:35]
	v_mfma_f32_16x16x32_bf16 v[20:23], v[148:151], v[204:207], v[20:23]
	v_mfma_f32_16x16x32_bf16 v[16:19], v[156:159], v[204:207], v[16:19]
	v_mfma_f32_16x16x32_bf16 v[4:7], v[148:151], v[212:215], v[4:7]
	v_mfma_f32_16x16x32_bf16 v[0:3], v[156:159], v[212:215], v[0:3]
	s_barrier
	s_setprio 0
	s_add_i32 s69, 0, 0x18000
	s_add_i32 s70, 0, 0x1c000
	v_add_u32_e32 v140, s69, v199
	v_add_u32_e32 v156, s70, v199
	ds_read_b128 v[128:131], v140
	ds_read_b128 v[132:135], v140 offset:1024
	ds_read_b128 v[136:139], v140 offset:2048
	ds_read_b128 v[140:143], v140 offset:3072
	ds_read_b128 v[144:147], v156
	ds_read_b128 v[148:151], v156 offset:1024
	ds_read_b128 v[152:155], v156 offset:2048
	ds_read_b128 v[156:159], v156 offset:3072
	s_add_u32 s42, s42, 0xb0000
	s_addc_u32 s43, s43, 0
	s_mov_b32 m0, s51
	v_lshl_add_u64 v[222:223], s[42:43], 0, v[168:169]
	ds_read_b128 v[160:163], v203 offset:32768
	ds_read_b128 v[164:167], v203 offset:33792
	ds_read_b128 v[184:187], v203 offset:34816
	ds_read_b128 v[188:191], v203 offset:35840
	ds_read_b128 v[192:195], v203 offset:36864
	ds_read_b128 v[204:207], v203 offset:37888
	ds_read_b128 v[208:211], v203 offset:38912
	ds_read_b128 v[212:215], v203 offset:39936
	global_load_lds_dwordx4 v[222:223], off
	v_lshl_add_u64 v[222:223], s[42:43], 0, v[172:173]
	s_mov_b32 m0, s52
	s_nop 0
	global_load_lds_dwordx4 v[222:223], off
	s_waitcnt vmcnt(8)
	s_waitcnt lgkmcnt(0)
	s_barrier
	s_setprio 1
	v_mfma_f32_16x16x32_bf16 v[124:127], v[128:131], v[160:163], v[124:127]
	v_mfma_f32_16x16x32_bf16 v[120:123], v[136:139], v[160:163], v[120:123]
	v_mfma_f32_16x16x32_bf16 v[116:119], v[128:131], v[184:187], v[116:119]
	v_mfma_f32_16x16x32_bf16 v[104:107], v[136:139], v[184:187], v[104:107]
	v_mfma_f32_16x16x32_bf16 v[92:95], v[128:131], v[192:195], v[92:95]
	v_mfma_f32_16x16x32_bf16 v[88:91], v[136:139], v[192:195], v[88:91]
	v_mfma_f32_16x16x32_bf16 v[76:79], v[128:131], v[208:211], v[76:79]
	v_mfma_f32_16x16x32_bf16 v[72:75], v[136:139], v[208:211], v[72:75]
	v_mfma_f32_16x16x32_bf16 v[124:127], v[132:135], v[164:167], v[124:127]
	v_mfma_f32_16x16x32_bf16 v[120:123], v[140:143], v[164:167], v[120:123]
	v_mfma_f32_16x16x32_bf16 v[116:119], v[132:135], v[188:191], v[116:119]
	v_mfma_f32_16x16x32_bf16 v[104:107], v[140:143], v[188:191], v[104:107]
	v_mfma_f32_16x16x32_bf16 v[92:95], v[132:135], v[204:207], v[92:95]
	v_mfma_f32_16x16x32_bf16 v[88:91], v[140:143], v[204:207], v[88:91]
	v_mfma_f32_16x16x32_bf16 v[76:79], v[132:135], v[212:215], v[76:79]
	v_mfma_f32_16x16x32_bf16 v[72:75], v[140:143], v[212:215], v[72:75]
	s_setprio 0
	s_setprio 1
	v_mfma_f32_16x16x32_bf16 v[112:115], v[144:147], v[160:163], v[112:115]
	v_mfma_f32_16x16x32_bf16 v[108:111], v[152:155], v[160:163], v[108:111]
	v_mfma_f32_16x16x32_bf16 v[100:103], v[144:147], v[184:187], v[100:103]
	v_mfma_f32_16x16x32_bf16 v[96:99], v[152:155], v[184:187], v[96:99]
	v_mfma_f32_16x16x32_bf16 v[84:87], v[144:147], v[192:195], v[84:87]
	v_mfma_f32_16x16x32_bf16 v[80:83], v[152:155], v[192:195], v[80:83]
	v_mfma_f32_16x16x32_bf16 v[68:71], v[144:147], v[208:211], v[68:71]
	v_mfma_f32_16x16x32_bf16 v[64:67], v[152:155], v[208:211], v[64:67]
	v_mfma_f32_16x16x32_bf16 v[112:115], v[148:151], v[164:167], v[112:115]
	v_mfma_f32_16x16x32_bf16 v[108:111], v[156:159], v[164:167], v[108:111]
	v_mfma_f32_16x16x32_bf16 v[100:103], v[148:151], v[188:191], v[100:103]
	v_mfma_f32_16x16x32_bf16 v[96:99], v[156:159], v[188:191], v[96:99]
	v_mfma_f32_16x16x32_bf16 v[84:87], v[148:151], v[204:207], v[84:87]
	v_mfma_f32_16x16x32_bf16 v[80:83], v[156:159], v[204:207], v[80:83]
	v_mfma_f32_16x16x32_bf16 v[68:71], v[148:151], v[212:215], v[68:71]
	v_mfma_f32_16x16x32_bf16 v[64:67], v[156:159], v[212:215], v[64:67]
	s_barrier
; #define PG8_STAGE(bufoff, gbase, voff) do { _Pragma("unroll") for (int _i = 0; _i < 2; ++_i) \
;         __builtin_amdgcn_global_load_lds((const unsigned*)((const char*)(gbase) + (voff)[_i]), (PG8_LAS unsigned*)(lds + (bufoff) + ldsw + _i * 8192), 16, 0, 0); } while (0)
; #define PG8_LDA(dst, b, h) do { _Pragma("unroll") for (int m = 0; m < 4; ++m) _Pragma("unroll") for (int k = 0; k < 2; ++k) dst[m][k] = *(const PG8_LAS bf16x8*)(lds + PG8_SA(b, h) + aoff + m * 2048 + k * 1024); } while (0)
; #define PG8_WAIT_V(n) asm volatile("s_waitcnt vmcnt(" #n ")" ::: "memory")
; #define PG8_BAR __builtin_amdgcn_s_barrier()
; template <class Epi, class Sched, bool ALIGN_EPI = false, bool SP2 = false>
; __device__ __forceinline__ void gemm_phase(PG8_LAS unsigned char* lds, const Gemm g, const Sched& S, const Epi& E) {
;     ...
;         for (int t = 0; t < nt; t += 2) {
;             const bool last = (t == nt - 2);
;             if constexpr (Epi::PREFETCH) { if (t == nt - 4) E.prefetch(cur, lds + STAGE_BYTES + 1024, tid); }
;             const char* a1 = cA + (size_t)(t + 1) * kstep;
;             const char* a2 = last ? nA : cA + (size_t)(t + 2) * kstep; const char* b2 = last ? nB : cB + (size_t)(t + 2) * kstep;
;             const char* a3 = a2 + kstep; const char* b3 = b2 + kstep;
;             if (last && has_next) S.a_ready(nxt);
;             if constexpr (SP2) {
;             PG8_LDB(B0, 0, 0); PG8_LDB(B1, 0, 1); PG8_SCHED; PG8_LDA(At, 0, 0); PG8_STAGE(PG8_SA(1, 1), a1 + hstep, voffA);
;             PG8_WAIT_V(8); PG8_WAIT_L(0); PG8_BAR; PG8_MMA(0, 0, At, B0); PG8_MMA(0, 1, At, B1); PG8_BAR; PG8_SCHED;
;             PG8_LDA(At, 0, 1); PG8_STAGE(PG8_SB(0, 0), b2, voffB); PG8_STAGE(PG8_SB(0, 1), b2 + hstep, voffB); PG8_STAGE(PG8_SA(0, 0), a2, voffA);
;             PG8_WAIT_V(8); PG8_WAIT_L(0); PG8_BAR; PG8_MMA(1, 0, At, B0); PG8_MMA(1, 1, At, B1); PG8_BAR; PG8_SCHED;
;             PG8_LDB(B0, 1, 0); PG8_LDB(B1, 1, 1); PG8_SCHED; PG8_LDA(At, 1, 0); PG8_STAGE(PG8_SA(0, 1), a2 + hstep, voffA);
;             PG8_WAIT_V(8); PG8_WAIT_L(0); PG8_BAR; PG8_MMA(0, 0, At, B0); PG8_MMA(0, 1, At, B1); PG8_BAR; PG8_SCHED;
;             PG8_LDA(At, 1, 1); PG8_STAGE(PG8_SB(1, 0), b3, voffB); PG8_STAGE(PG8_SB(1, 1), b3 + hstep, voffB); PG8_STAGE(PG8_SA(1, 0), a3, voffA);
;             PG8_WAIT_V(8); PG8_WAIT_L(0); PG8_BAR; PG8_MMA(1, 0, At, B0); PG8_MMA(1, 1, At, B1); PG8_BAR; PG8_SCHED;
	s_setprio 0
	s_add_i32 s42, s69, s48
	v_lshl_add_u64 v[196:197], v[196:197], 0, s[14:15]
	s_mov_b32 m0, s42
	ds_read_b128 v[160:163], v203 offset:49152
	ds_read_b128 v[164:167], v203 offset:50176
	ds_read_b128 v[184:187], v203 offset:51200
	ds_read_b128 v[188:191], v203 offset:52224
	ds_read_b128 v[192:195], v203 offset:53248
	ds_read_b128 v[204:207], v203 offset:54272
	ds_read_b128 v[208:211], v203 offset:55296
	ds_read_b128 v[212:215], v203 offset:56320
	global_load_lds_dwordx4 v[196:197], off
	s_add_i32 m0, s42, 0x2000
	s_add_u32 s40, s40, 0xb0080
	v_lshl_add_u64 v[196:197], v[216:217], 0, s[14:15]
	s_addc_u32 s41, s41, 0
	s_add_i32 s42, s70, s48
	global_load_lds_dwordx4 v[196:197], off
	v_lshl_add_u64 v[196:197], s[40:41], 0, v[170:171]
	s_mov_b32 m0, s42
	s_nop 0
	global_load_lds_dwordx4 v[196:197], off
	v_lshl_add_u64 v[196:197], s[40:41], 0, v[174:175]
	s_add_i32 m0, s42, 0x2000
	s_nop 0
	global_load_lds_dwordx4 v[196:197], off
	v_lshl_add_u64 v[196:197], v[218:219], 0, s[14:15]
	s_mov_b32 m0, s54
	s_nop 0
	global_load_lds_dwordx4 v[196:197], off
	v_lshl_add_u64 v[196:197], v[220:221], 0, s[14:15]
	s_mov_b32 m0, s55
	s_nop 0
	global_load_lds_dwordx4 v[196:197], off
	s_waitcnt vmcnt(8)
	s_waitcnt lgkmcnt(0)
	s_barrier
	s_setprio 1
	v_mfma_f32_16x16x32_bf16 v[60:63], v[128:131], v[160:163], v[60:63]
	v_mfma_f32_16x16x32_bf16 v[56:59], v[136:139], v[160:163], v[56:59]
	v_mfma_f32_16x16x32_bf16 v[44:47], v[128:131], v[184:187], v[44:47]
	v_mfma_f32_16x16x32_bf16 v[40:43], v[136:139], v[184:187], v[40:43]
	v_mfma_f32_16x16x32_bf16 v[28:31], v[128:131], v[192:195], v[28:31]
	v_mfma_f32_16x16x32_bf16 v[24:27], v[136:139], v[192:195], v[24:27]
	v_mfma_f32_16x16x32_bf16 v[12:15], v[128:131], v[208:211], v[12:15]
	v_mfma_f32_16x16x32_bf16 v[8:11], v[136:139], v[208:211], v[8:11]
	v_mfma_f32_16x16x32_bf16 v[60:63], v[132:135], v[164:167], v[60:63]
	v_mfma_f32_16x16x32_bf16 v[56:59], v[140:143], v[164:167], v[56:59]
	v_mfma_f32_16x16x32_bf16 v[44:47], v[132:135], v[188:191], v[44:47]
	v_mfma_f32_16x16x32_bf16 v[40:43], v[140:143], v[188:191], v[40:43]
	v_mfma_f32_16x16x32_bf16 v[28:31], v[132:135], v[204:207], v[28:31]
	v_mfma_f32_16x16x32_bf16 v[24:27], v[140:143], v[204:207], v[24:27]
	v_mfma_f32_16x16x32_bf16 v[12:15], v[132:135], v[212:215], v[12:15]
	v_mfma_f32_16x16x32_bf16 v[8:11], v[140:143], v[212:215], v[8:11]
	s_setprio 0
	s_setprio 1
	v_mfma_f32_16x16x32_bf16 v[52:55], v[144:147], v[160:163], v[52:55]
	v_mfma_f32_16x16x32_bf16 v[48:51], v[152:155], v[160:163], v[48:51]
	v_mfma_f32_16x16x32_bf16 v[36:39], v[144:147], v[184:187], v[36:39]
	v_mfma_f32_16x16x32_bf16 v[32:35], v[152:155], v[184:187], v[32:35]
	v_mfma_f32_16x16x32_bf16 v[20:23], v[144:147], v[192:195], v[20:23]
	v_mfma_f32_16x16x32_bf16 v[16:19], v[152:155], v[192:195], v[16:19]
	v_mfma_f32_16x16x32_bf16 v[4:7], v[144:147], v[208:211], v[4:7]
	v_mfma_f32_16x16x32_bf16 v[0:3], v[152:155], v[208:211], v[0:3]
	v_mfma_f32_16x16x32_bf16 v[52:55], v[148:151], v[164:167], v[52:55]
	v_mfma_f32_16x16x32_bf16 v[48:51], v[156:159], v[164:167], v[48:51]
	v_mfma_f32_16x16x32_bf16 v[36:39], v[148:151], v[188:191], v[36:39]
	v_mfma_f32_16x16x32_bf16 v[32:35], v[156:159], v[188:191], v[32:35]
	v_mfma_f32_16x16x32_bf16 v[20:23], v[148:151], v[204:207], v[20:23]
	v_mfma_f32_16x16x32_bf16 v[16:19], v[156:159], v[204:207], v[16:19]
	v_mfma_f32_16x16x32_bf16 v[4:7], v[148:151], v[212:215], v[4:7]
	v_mfma_f32_16x16x32_bf16 v[0:3], v[156:159], v[212:215], v[0:3]
	s_barrier
	s_setprio 0
	s_add_i32 s68, s68, 2
	s_add_u32 s38, s38, 0x100
	s_addc_u32 s39, s39, 0
	s_add_u32 s66, s66, 0x100
	s_addc_u32 s67, s67, 0
.LBB0_2597:
	ds_read_b128 v[128:131], v201
	ds_read_b128 v[132:135], v201 offset:1024
	ds_read_b128 v[136:139], v201 offset:2048
	ds_read_b128 v[140:143], v201 offset:3072
	ds_read_b128 v[144:147], v202
	ds_read_b128 v[148:151], v202 offset:1024
	ds_read_b128 v[152:155], v202 offset:2048
	ds_read_b128 v[156:159], v202 offset:3072
	s_add_u32 s40, s38, 0xfff50080
	s_addc_u32 s41, s39, -1
	s_cmp_eq_u32 s68, 40
	s_cselect_b32 s43, s7, s41
	s_cselect_b32 s42, s6, s40
	s_cselect_b32 s41, s37, s67
	s_cselect_b32 s40, s36, s66
	v_lshl_add_u64 v[196:197], s[38:39], 0, v[176:177]
	s_add_i32 m0, s49, 0xc000
	ds_read_b128 v[160:163], v203
	ds_read_b128 v[164:167], v203 offset:1024
	ds_read_b128 v[184:187], v203 offset:2048
	ds_read_b128 v[188:191], v203 offset:3072
	ds_read_b128 v[192:195], v203 offset:4096
	ds_read_b128 v[204:207], v203 offset:5120
	ds_read_b128 v[208:211], v203 offset:6144
	ds_read_b128 v[212:215], v203 offset:7168
	global_load_lds_dwordx4 v[196:197], off
	v_lshl_add_u64 v[196:197], s[38:39], 0, v[178:179]
	s_add_i32 m0, s49, 0xe000
	s_nop 0
	global_load_lds_dwordx4 v[196:197], off
	s_waitcnt vmcnt(8)
	s_waitcnt lgkmcnt(0)
	s_barrier
; #define PG8_STAGE(bufoff, gbase, voff) do { _Pragma("unroll") for (int _i = 0; _i < 2; ++_i) \
;         __builtin_amdgcn_global_load_lds((const unsigned*)((const char*)(gbase) + (voff)[_i]), (PG8_LAS unsigned*)(lds + (bufoff) + ldsw + _i * 8192), 16, 0, 0); } while (0)
; #define PG8_LDA(dst, b, h) do { _Pragma("unroll") for (int m = 0; m < 4; ++m) _Pragma("unroll") for (int k = 0; k < 2; ++k) dst[m][k] = *(const PG8_LAS bf16x8*)(lds + PG8_SA(b, h) + aoff + m * 2048 + k * 1024); } while (0)
; #define PG8_MMA(ai, bj, At, Bt) do { __builtin_amdgcn_s_setprio(1); _Pragma("unroll") for (int m = 0; m < 4; ++m) _Pragma("unroll") for (int n = 0; n < 2; ++n) _Pragma("unroll") for (int k = 0; k < 2; ++k) \
;         acc[ai][bj][m][n] = __builtin_amdgcn_mfma_f32_16x16x32_bf16(Bt[n][k], At[m][k], acc[ai][bj][m][n], 0, 0, 0); __builtin_amdgcn_s_setprio(0); } while (0)
; #define PG8_WAIT_V(n) asm volatile("s_waitcnt vmcnt(" #n ")" ::: "memory")
; #define PG8_WAIT_L(n) asm volatile("s_waitcnt lgkmcnt(" #n ")" ::: "memory")
; #define PG8_BAR __builtin_amdgcn_s_barrier()
; #define PG8_SCHED __builtin_amdgcn_sched_barrier(0)
; template <class Epi, class Sched, bool ALIGN_EPI = false, bool SP2 = false>
; __device__ __forceinline__ void gemm_phase(PG8_LAS unsigned char* lds, const Gemm g, const Sched& S, const Epi& E) {
;     ...
;             PG8_WAIT_V(8); PG8_WAIT_L(0); PG8_BAR; PG8_MMA(0, 0, At, B0); PG8_MMA(0, 1, At, B1); PG8_BAR; PG8_SCHED;
;             PG8_LDA(At, 0, 1); PG8_STAGE(PG8_SB(0, 0), b2, voffB); PG8_STAGE(PG8_SB(0, 1), b2 + hstep, voffB); PG8_STAGE(PG8_SA(0, 0), a2, voffA);
;             PG8_WAIT_V(8); PG8_WAIT_L(0); PG8_BAR; PG8_MMA(1, 0, At, B0); PG8_MMA(1, 1, At, B1); PG8_BAR; PG8_SCHED;
	s_setprio 1
	v_mfma_f32_16x16x32_bf16 v[124:127], v[128:131], v[160:163], v[124:127]
	v_mfma_f32_16x16x32_bf16 v[120:123], v[136:139], v[160:163], v[120:123]
	v_mfma_f32_16x16x32_bf16 v[116:119], v[128:131], v[184:187], v[116:119]
	v_mfma_f32_16x16x32_bf16 v[104:107], v[136:139], v[184:187], v[104:107]
	v_mfma_f32_16x16x32_bf16 v[92:95], v[128:131], v[192:195], v[92:95]
	v_mfma_f32_16x16x32_bf16 v[88:91], v[136:139], v[192:195], v[88:91]
	v_mfma_f32_16x16x32_bf16 v[76:79], v[128:131], v[208:211], v[76:79]
	v_mfma_f32_16x16x32_bf16 v[72:75], v[136:139], v[208:211], v[72:75]
	v_mfma_f32_16x16x32_bf16 v[124:127], v[132:135], v[164:167], v[124:127]
	v_mfma_f32_16x16x32_bf16 v[120:123], v[140:143], v[164:167], v[120:123]
	v_mfma_f32_16x16x32_bf16 v[116:119], v[132:135], v[188:191], v[116:119]
	v_mfma_f32_16x16x32_bf16 v[104:107], v[140:143], v[188:191], v[104:107]
	v_mfma_f32_16x16x32_bf16 v[92:95], v[132:135], v[204:207], v[92:95]
	v_mfma_f32_16x16x32_bf16 v[88:91], v[140:143], v[204:207], v[88:91]
	v_mfma_f32_16x16x32_bf16 v[76:79], v[132:135], v[212:215], v[76:79]
	v_mfma_f32_16x16x32_bf16 v[72:75], v[140:143], v[212:215], v[72:75]
	s_setprio 0
	s_setprio 1
	v_mfma_f32_16x16x32_bf16 v[112:115], v[144:147], v[160:163], v[112:115]
	v_mfma_f32_16x16x32_bf16 v[108:111], v[152:155], v[160:163], v[108:111]
	v_mfma_f32_16x16x32_bf16 v[100:103], v[144:147], v[184:187], v[100:103]
	v_mfma_f32_16x16x32_bf16 v[96:99], v[152:155], v[184:187], v[96:99]
	v_mfma_f32_16x16x32_bf16 v[84:87], v[144:147], v[192:195], v[84:87]
	v_mfma_f32_16x16x32_bf16 v[80:83], v[152:155], v[192:195], v[80:83]
	v_mfma_f32_16x16x32_bf16 v[68:71], v[144:147], v[208:211], v[68:71]
	v_mfma_f32_16x16x32_bf16 v[64:67], v[152:155], v[208:211], v[64:67]
	v_mfma_f32_16x16x32_bf16 v[112:115], v[148:151], v[164:167], v[112:115]
	v_mfma_f32_16x16x32_bf16 v[108:111], v[156:159], v[164:167], v[108:111]
	v_mfma_f32_16x16x32_bf16 v[100:103], v[148:151], v[188:191], v[100:103]
	v_mfma_f32_16x16x32_bf16 v[96:99], v[156:159], v[188:191], v[96:99]
	v_mfma_f32_16x16x32_bf16 v[84:87], v[148:151], v[204:207], v[84:87]
	v_mfma_f32_16x16x32_bf16 v[80:83], v[156:159], v[204:207], v[80:83]
	v_mfma_f32_16x16x32_bf16 v[68:71], v[148:151], v[212:215], v[68:71]
	v_mfma_f32_16x16x32_bf16 v[64:67], v[156:159], v[212:215], v[64:67]
	s_barrier
	s_setprio 0
	s_add_i32 s69, s57, s48
	v_lshl_add_u64 v[196:197], s[40:41], 0, v[170:171]
	s_mov_b32 m0, s69
	ds_read_b128 v[160:163], v203 offset:16384
	ds_read_b128 v[164:167], v203 offset:17408
	ds_read_b128 v[184:187], v203 offset:18432
	ds_read_b128 v[188:191], v203 offset:19456
	ds_read_b128 v[192:195], v203 offset:20480
	ds_read_b128 v[204:207], v203 offset:21504
	ds_read_b128 v[208:211], v203 offset:22528
	ds_read_b128 v[212:215], v203 offset:23552
	global_load_lds_dwordx4 v[196:197], off
	s_add_i32 m0, s69, 0x2000
	s_add_u32 s70, s40, 0xb0000
	v_lshl_add_u64 v[216:217], s[40:41], 0, v[174:175]
	s_addc_u32 s71, s41, 0
	s_add_i32 s69, s58, s48
	global_load_lds_dwordx4 v[216:217], off
	v_lshl_add_u64 v[218:219], s[70:71], 0, v[170:171]
	s_mov_b32 m0, s69
	v_lshl_add_u64 v[220:221], s[42:43], 0, v[172:173]
	global_load_lds_dwordx4 v[218:219], off
	v_lshl_add_u64 v[218:219], s[70:71], 0, v[174:175]
	s_add_i32 m0, s69, 0x2000
	s_nop 0
	global_load_lds_dwordx4 v[218:219], off
	v_lshl_add_u64 v[218:219], s[42:43], 0, v[168:169]
	s_mov_b32 m0, s49
	s_nop 0
	global_load_lds_dwordx4 v[218:219], off
	s_mov_b32 m0, s50
	s_nop 0
	global_load_lds_dwordx4 v[220:221], off
	s_waitcnt vmcnt(8)
	s_waitcnt lgkmcnt(0)
	s_barrier
	s_setprio 1
	v_mfma_f32_16x16x32_bf16 v[60:63], v[128:131], v[160:163], v[60:63]
	v_mfma_f32_16x16x32_bf16 v[56:59], v[136:139], v[160:163], v[56:59]
	v_mfma_f32_16x16x32_bf16 v[44:47], v[128:131], v[184:187], v[44:47]
	v_mfma_f32_16x16x32_bf16 v[40:43], v[136:139], v[184:187], v[40:43]
	v_mfma_f32_16x16x32_bf16 v[28:31], v[128:131], v[192:195], v[28:31]
	v_mfma_f32_16x16x32_bf16 v[24:27], v[136:139], v[192:195], v[24:27]
	v_mfma_f32_16x16x32_bf16 v[12:15], v[128:131], v[208:211], v[12:15]
	v_mfma_f32_16x16x32_bf16 v[8:11], v[136:139], v[208:211], v[8:11]
	v_mfma_f32_16x16x32_bf16 v[60:63], v[132:135], v[164:167], v[60:63]
	v_mfma_f32_16x16x32_bf16 v[56:59], v[140:143], v[164:167], v[56:59]
	v_mfma_f32_16x16x32_bf16 v[44:47], v[132:135], v[188:191], v[44:47]
	v_mfma_f32_16x16x32_bf16 v[40:43], v[140:143], v[188:191], v[40:43]
	v_mfma_f32_16x16x32_bf16 v[28:31], v[132:135], v[204:207], v[28:31]
	v_mfma_f32_16x16x32_bf16 v[24:27], v[140:143], v[204:207], v[24:27]
	v_mfma_f32_16x16x32_bf16 v[12:15], v[132:135], v[212:215], v[12:15]
	v_mfma_f32_16x16x32_bf16 v[8:11], v[140:143], v[212:215], v[8:11]
	s_setprio 0
	s_setprio 1
	v_mfma_f32_16x16x32_bf16 v[52:55], v[144:147], v[160:163], v[52:55]
	v_mfma_f32_16x16x32_bf16 v[48:51], v[152:155], v[160:163], v[48:51]
	v_mfma_f32_16x16x32_bf16 v[36:39], v[144:147], v[184:187], v[36:39]
	v_mfma_f32_16x16x32_bf16 v[32:35], v[152:155], v[184:187], v[32:35]
	v_mfma_f32_16x16x32_bf16 v[20:23], v[144:147], v[192:195], v[20:23]
	v_mfma_f32_16x16x32_bf16 v[16:19], v[152:155], v[192:195], v[16:19]
	v_mfma_f32_16x16x32_bf16 v[4:7], v[144:147], v[208:211], v[4:7]
	v_mfma_f32_16x16x32_bf16 v[0:3], v[152:155], v[208:211], v[0:3]
	v_mfma_f32_16x16x32_bf16 v[52:55], v[148:151], v[164:167], v[52:55]
	v_mfma_f32_16x16x32_bf16 v[48:51], v[156:159], v[164:167], v[48:51]
	v_mfma_f32_16x16x32_bf16 v[36:39], v[148:151], v[188:191], v[36:39]
	v_mfma_f32_16x16x32_bf16 v[32:35], v[156:159], v[188:191], v[32:35]
	v_mfma_f32_16x16x32_bf16 v[20:23], v[148:151], v[204:207], v[20:23]
	v_mfma_f32_16x16x32_bf16 v[16:19], v[156:159], v[204:207], v[16:19]
	v_mfma_f32_16x16x32_bf16 v[4:7], v[148:151], v[212:215], v[4:7]
	v_mfma_f32_16x16x32_bf16 v[0:3], v[156:159], v[212:215], v[0:3]
	s_barrier
; #define PG8_STAGE(bufoff, gbase, voff) do { _Pragma("unroll") for (int _i = 0; _i < 2; ++_i) \
;         __builtin_amdgcn_global_load_lds((const unsigned*)((const char*)(gbase) + (voff)[_i]), (PG8_LAS unsigned*)(lds + (bufoff) + ldsw + _i * 8192), 16, 0, 0); } while (0)
; #define PG8_LDA(dst, b, h) do { _Pragma("unroll") for (int m = 0; m < 4; ++m) _Pragma("unroll") for (int k = 0; k < 2; ++k) dst[m][k] = *(const PG8_LAS bf16x8*)(lds + PG8_SA(b, h) + aoff + m * 2048 + k * 1024); } while (0)
; #define PG8_LDB(dst, b, h) do { _Pragma("unroll") for (int n = 0; n < 2; ++n) _Pragma("unroll") for (int k = 0; k < 2; ++k) dst[n][k] = *(const PG8_LAS bf16x8*)(lds + PG8_SB(b, h) + boff + n * 2048 + k * 1024); } while (0)
; #define PG8_MMA(ai, bj, At, Bt) do { __builtin_amdgcn_s_setprio(1); _Pragma("unroll") for (int m = 0; m < 4; ++m) _Pragma("unroll") for (int n = 0; n < 2; ++n) _Pragma("unroll") for (int k = 0; k < 2; ++k) \
;         acc[ai][bj][m][n] = __builtin_amdgcn_mfma_f32_16x16x32_bf16(Bt[n][k], At[m][k], acc[ai][bj][m][n], 0, 0, 0); __builtin_amdgcn_s_setprio(0); } while (0)
; #define PG8_WAIT_V(n) asm volatile("s_waitcnt vmcnt(" #n ")" ::: "memory")
; #define PG8_WAIT_L(n) asm volatile("s_waitcnt lgkmcnt(" #n ")" ::: "memory")
; #define PG8_BAR __builtin_amdgcn_s_barrier()
; #define PG8_SCHED __builtin_amdgcn_sched_barrier(0)
; template <class Epi, class Sched, bool ALIGN_EPI = false, bool SP2 = false>
; __device__ __forceinline__ void gemm_phase(PG8_LAS unsigned char* lds, const Gemm g, const Sched& S, const Epi& E) {
;     ...
;             PG8_LDB(B0, 1, 0); PG8_LDB(B1, 1, 1); PG8_SCHED; PG8_LDA(At, 1, 0); PG8_STAGE(PG8_SA(0, 1), a2 + hstep, voffA);
;             PG8_WAIT_V(8); PG8_WAIT_L(0); PG8_BAR; PG8_MMA(0, 0, At, B0); PG8_MMA(0, 1, At, B1); PG8_BAR; PG8_SCHED;
	s_setprio 0
	s_add_i32 s69, 0, 0x18000
	s_add_i32 s70, 0, 0x1c000
	v_add_u32_e32 v140, s69, v199
	v_add_u32_e32 v156, s70, v199
	ds_read_b128 v[128:131], v140
	ds_read_b128 v[132:135], v140 offset:1024
	ds_read_b128 v[136:139], v140 offset:2048
	ds_read_b128 v[140:143], v140 offset:3072
	ds_read_b128 v[144:147], v156
	ds_read_b128 v[148:151], v156 offset:1024
	ds_read_b128 v[152:155], v156 offset:2048
	ds_read_b128 v[156:159], v156 offset:3072
	s_add_u32 s42, s42, 0xb0000
	s_addc_u32 s43, s43, 0
	s_mov_b32 m0, s51
	v_lshl_add_u64 v[222:223], s[42:43], 0, v[168:169]
	ds_read_b128 v[160:163], v203 offset:32768
	ds_read_b128 v[164:167], v203 offset:33792
	ds_read_b128 v[184:187], v203 offset:34816
	ds_read_b128 v[188:191], v203 offset:35840
	ds_read_b128 v[192:195], v203 offset:36864
	ds_read_b128 v[204:207], v203 offset:37888
	ds_read_b128 v[208:211], v203 offset:38912
	ds_read_b128 v[212:215], v203 offset:39936
	global_load_lds_dwordx4 v[222:223], off
	v_lshl_add_u64 v[222:223], s[42:43], 0, v[172:173]
	s_mov_b32 m0, s52
	s_nop 0
	global_load_lds_dwordx4 v[222:223], off
	s_waitcnt vmcnt(8)
	s_waitcnt lgkmcnt(0)
	s_barrier
	s_setprio 1
	v_mfma_f32_16x16x32_bf16 v[124:127], v[128:131], v[160:163], v[124:127]
	v_mfma_f32_16x16x32_bf16 v[120:123], v[136:139], v[160:163], v[120:123]
	v_mfma_f32_16x16x32_bf16 v[116:119], v[128:131], v[184:187], v[116:119]
	v_mfma_f32_16x16x32_bf16 v[104:107], v[136:139], v[184:187], v[104:107]
	v_mfma_f32_16x16x32_bf16 v[92:95], v[128:131], v[192:195], v[92:95]
	v_mfma_f32_16x16x32_bf16 v[88:91], v[136:139], v[192:195], v[88:91]
	v_mfma_f32_16x16x32_bf16 v[76:79], v[128:131], v[208:211], v[76:79]
	v_mfma_f32_16x16x32_bf16 v[72:75], v[136:139], v[208:211], v[72:75]
	v_mfma_f32_16x16x32_bf16 v[124:127], v[132:135], v[164:167], v[124:127]
	v_mfma_f32_16x16x32_bf16 v[120:123], v[140:143], v[164:167], v[120:123]
	v_mfma_f32_16x16x32_bf16 v[116:119], v[132:135], v[188:191], v[116:119]
	v_mfma_f32_16x16x32_bf16 v[104:107], v[140:143], v[188:191], v[104:107]
	v_mfma_f32_16x16x32_bf16 v[92:95], v[132:135], v[204:207], v[92:95]
	v_mfma_f32_16x16x32_bf16 v[88:91], v[140:143], v[204:207], v[88:91]
	v_mfma_f32_16x16x32_bf16 v[76:79], v[132:135], v[212:215], v[76:79]
	v_mfma_f32_16x16x32_bf16 v[72:75], v[140:143], v[212:215], v[72:75]
	s_setprio 0
	s_setprio 1
	v_mfma_f32_16x16x32_bf16 v[112:115], v[144:147], v[160:163], v[112:115]
	v_mfma_f32_16x16x32_bf16 v[108:111], v[152:155], v[160:163], v[108:111]
	v_mfma_f32_16x16x32_bf16 v[100:103], v[144:147], v[184:187], v[100:103]
	v_mfma_f32_16x16x32_bf16 v[96:99], v[152:155], v[184:187], v[96:99]
	v_mfma_f32_16x16x32_bf16 v[84:87], v[144:147], v[192:195], v[84:87]
	v_mfma_f32_16x16x32_bf16 v[80:83], v[152:155], v[192:195], v[80:83]
	v_mfma_f32_16x16x32_bf16 v[68:71], v[144:147], v[208:211], v[68:71]
	v_mfma_f32_16x16x32_bf16 v[64:67], v[152:155], v[208:211], v[64:67]
	v_mfma_f32_16x16x32_bf16 v[112:115], v[148:151], v[164:167], v[112:115]
	v_mfma_f32_16x16x32_bf16 v[108:111], v[156:159], v[164:167], v[108:111]
	v_mfma_f32_16x16x32_bf16 v[100:103], v[148:151], v[188:191], v[100:103]
	v_mfma_f32_16x16x32_bf16 v[96:99], v[156:159], v[188:191], v[96:99]
	v_mfma_f32_16x16x32_bf16 v[84:87], v[148:151], v[204:207], v[84:87]
	v_mfma_f32_16x16x32_bf16 v[80:83], v[156:159], v[204:207], v[80:83]
	v_mfma_f32_16x16x32_bf16 v[68:71], v[148:151], v[212:215], v[68:71]
	v_mfma_f32_16x16x32_bf16 v[64:67], v[156:159], v[212:215], v[64:67]
	s_barrier
; #define PG8_STAGE(bufoff, gbase, voff) do { _Pragma("unroll") for (int _i = 0; _i < 2; ++_i) \
;         __builtin_amdgcn_global_load_lds((const unsigned*)((const char*)(gbase) + (voff)[_i]), (PG8_LAS unsigned*)(lds + (bufoff) + ldsw + _i * 8192), 16, 0, 0); } while (0)
; #define PG8_LDA(dst, b, h) do { _Pragma("unroll") for (int m = 0; m < 4; ++m) _Pragma("unroll") for (int k = 0; k < 2; ++k) dst[m][k] = *(const PG8_LAS bf16x8*)(lds + PG8_SA(b, h) + aoff + m * 2048 + k * 1024); } while (0)
; #define PG8_MMA(ai, bj, At, Bt) do { __builtin_amdgcn_s_setprio(1); _Pragma("unroll") for (int m = 0; m < 4; ++m) _Pragma("unroll") for (int n = 0; n < 2; ++n) _Pragma("unroll") for (int k = 0; k < 2; ++k) \
;         acc[ai][bj][m][n] = __builtin_amdgcn_mfma_f32_16x16x32_bf16(Bt[n][k], At[m][k], acc[ai][bj][m][n], 0, 0, 0); __builtin_amdgcn_s_setprio(0); } while (0)
; #define PG8_WAIT_V(n) asm volatile("s_waitcnt vmcnt(" #n ")" ::: "memory")
; #define PG8_WAIT_L(n) asm volatile("s_waitcnt lgkmcnt(" #n ")" ::: "memory")
; #define PG8_BAR __builtin_amdgcn_s_barrier()
; #define PG8_SCHED __builtin_amdgcn_sched_barrier(0)
; template <class Epi, class Sched, bool ALIGN_EPI = false, bool SP2 = false>
; __device__ __forceinline__ void gemm_phase(PG8_LAS unsigned char* lds, const Gemm g, const Sched& S, const Epi& E) {
;     ...
;             PG8_LDA(At, 1, 1); PG8_STAGE(PG8_SB(1, 0), b3, voffB); PG8_STAGE(PG8_SB(1, 1), b3 + hstep, voffB); PG8_STAGE(PG8_SA(1, 0), a3, voffA);
;             PG8_WAIT_V(8); PG8_WAIT_L(0); PG8_BAR; PG8_MMA(1, 0, At, B0); PG8_MMA(1, 1, At, B1); PG8_BAR; PG8_SCHED;
	s_setprio 0
	s_add_i32 s42, s69, s48
	v_lshl_add_u64 v[196:197], v[196:197], 0, s[14:15]
	s_mov_b32 m0, s42
	ds_read_b128 v[160:163], v203 offset:49152
	ds_read_b128 v[164:167], v203 offset:50176
	ds_read_b128 v[184:187], v203 offset:51200
	ds_read_b128 v[188:191], v203 offset:52224
	ds_read_b128 v[192:195], v203 offset:53248
	ds_read_b128 v[204:207], v203 offset:54272
	ds_read_b128 v[208:211], v203 offset:55296
	ds_read_b128 v[212:215], v203 offset:56320
	global_load_lds_dwordx4 v[196:197], off
	s_add_i32 m0, s42, 0x2000
	s_add_u32 s40, s40, 0xb0080
	v_lshl_add_u64 v[196:197], v[216:217], 0, s[14:15]
	s_addc_u32 s41, s41, 0
	s_add_i32 s42, s70, s48
	global_load_lds_dwordx4 v[196:197], off
	v_lshl_add_u64 v[196:197], s[40:41], 0, v[170:171]
	s_mov_b32 m0, s42
	s_nop 0
	global_load_lds_dwordx4 v[196:197], off
	v_lshl_add_u64 v[196:197], s[40:41], 0, v[174:175]
	s_add_i32 m0, s42, 0x2000
	s_nop 0
	global_load_lds_dwordx4 v[196:197], off
	v_lshl_add_u64 v[196:197], v[218:219], 0, s[14:15]
	s_mov_b32 m0, s54
	s_nop 0
	global_load_lds_dwordx4 v[196:197], off
	v_lshl_add_u64 v[196:197], v[220:221], 0, s[14:15]
	s_mov_b32 m0, s55
	s_nop 0
	global_load_lds_dwordx4 v[196:197], off
	s_waitcnt vmcnt(8)
	s_waitcnt lgkmcnt(0)
	s_barrier
	s_setprio 1
	v_mfma_f32_16x16x32_bf16 v[60:63], v[128:131], v[160:163], v[60:63]
	v_mfma_f32_16x16x32_bf16 v[56:59], v[136:139], v[160:163], v[56:59]
	v_mfma_f32_16x16x32_bf16 v[44:47], v[128:131], v[184:187], v[44:47]
	v_mfma_f32_16x16x32_bf16 v[40:43], v[136:139], v[184:187], v[40:43]
	v_mfma_f32_16x16x32_bf16 v[28:31], v[128:131], v[192:195], v[28:31]
	v_mfma_f32_16x16x32_bf16 v[24:27], v[136:139], v[192:195], v[24:27]
	v_mfma_f32_16x16x32_bf16 v[12:15], v[128:131], v[208:211], v[12:15]
	v_mfma_f32_16x16x32_bf16 v[8:11], v[136:139], v[208:211], v[8:11]
	v_mfma_f32_16x16x32_bf16 v[60:63], v[132:135], v[164:167], v[60:63]
	v_mfma_f32_16x16x32_bf16 v[56:59], v[140:143], v[164:167], v[56:59]
	v_mfma_f32_16x16x32_bf16 v[44:47], v[132:135], v[188:191], v[44:47]
	v_mfma_f32_16x16x32_bf16 v[40:43], v[140:143], v[188:191], v[40:43]
	v_mfma_f32_16x16x32_bf16 v[28:31], v[132:135], v[204:207], v[28:31]
	v_mfma_f32_16x16x32_bf16 v[24:27], v[140:143], v[204:207], v[24:27]
	v_mfma_f32_16x16x32_bf16 v[12:15], v[132:135], v[212:215], v[12:15]
	v_mfma_f32_16x16x32_bf16 v[8:11], v[140:143], v[212:215], v[8:11]
	s_setprio 0
	s_setprio 1
	v_mfma_f32_16x16x32_bf16 v[52:55], v[144:147], v[160:163], v[52:55]
	v_mfma_f32_16x16x32_bf16 v[48:51], v[152:155], v[160:163], v[48:51]
	v_mfma_f32_16x16x32_bf16 v[36:39], v[144:147], v[184:187], v[36:39]
	v_mfma_f32_16x16x32_bf16 v[32:35], v[152:155], v[184:187], v[32:35]
	v_mfma_f32_16x16x32_bf16 v[20:23], v[144:147], v[192:195], v[20:23]
	v_mfma_f32_16x16x32_bf16 v[16:19], v[152:155], v[192:195], v[16:19]
	v_mfma_f32_16x16x32_bf16 v[4:7], v[144:147], v[208:211], v[4:7]
	v_mfma_f32_16x16x32_bf16 v[0:3], v[152:155], v[208:211], v[0:3]
	v_mfma_f32_16x16x32_bf16 v[52:55], v[148:151], v[164:167], v[52:55]
	v_mfma_f32_16x16x32_bf16 v[48:51], v[156:159], v[164:167], v[48:51]
	v_mfma_f32_16x16x32_bf16 v[36:39], v[148:151], v[188:191], v[36:39]
	v_mfma_f32_16x16x32_bf16 v[32:35], v[156:159], v[188:191], v[32:35]
	v_mfma_f32_16x16x32_bf16 v[20:23], v[148:151], v[204:207], v[20:23]
	v_mfma_f32_16x16x32_bf16 v[16:19], v[156:159], v[204:207], v[16:19]
	v_mfma_f32_16x16x32_bf16 v[4:7], v[148:151], v[212:215], v[4:7]
	v_mfma_f32_16x16x32_bf16 v[0:3], v[156:159], v[212:215], v[0:3]
	s_barrier
	s_setprio 0
	s_add_i32 s68, s68, 2
	s_add_u32 s38, s38, 0x100
	s_addc_u32 s39, s39, 0
	s_add_u32 s66, s66, 0x100
	s_addc_u32 s67, s67, 0
	s_cmp_gt_u32 s68, 41
	s_cbranch_scc0 .LBB0_2597
	s_and_b64 vcc, exec, s[16:17]
	s_cbranch_vccz .LBB0_2600
	s_barrier
